# xor-16 ds_bpermute exchanges feeding in-place add/max replaced by v_permlane16_swap (52 sites)
# speedup vs baseline: 1.0256x; 1.0076x over previous
.LBB0_251:
	v_lshl_add_u32 v177, s38, 8, v172
	v_add_u32_e32 v48, v177, v174
	v_add_u32_e32 v140, 0x40a0, v48
	v_mov_b32_e32 v141, v49
	v_lshl_add_u64 v[138:139], v[48:49], 2, s[22:23]
	v_lshl_add_u64 v[140:141], v[140:141], 2, s[22:23]
	global_load_dword v168, v[138:139], off
	global_load_dword v152, v[140:141], off
	v_add_u32_e32 v138, 0x4000, v48
	v_mov_b32_e32 v139, v49
	v_add_u32_e32 v156, 0x40b0, v48
	v_mov_b32_e32 v157, v49
	v_lshl_add_u64 v[138:139], v[138:139], 2, s[22:23]
	v_lshl_add_u64 v[156:157], v[156:157], 2, s[22:23]
	global_load_dword v170, v[138:139], off
	v_add_u32_e32 v140, 0x80a0, v48
	global_load_dword v156, v[156:157], off
	v_add_u32_e32 v138, 0x8000, v48
	v_mov_b32_e32 v139, v49
	v_lshl_add_u64 v[138:139], v[138:139], 2, s[22:23]
	global_load_dword v169, v[138:139], off
	v_add_u32_e32 v138, 0xc000, v48
	v_mov_b32_e32 v139, v49
	v_lshl_add_u64 v[138:139], v[138:139], 2, s[22:23]
	global_load_dword v171, v[138:139], off
	v_or_b32_e32 v138, 16, v48
	v_mov_b32_e32 v139, v49
	v_lshl_add_u64 v[138:139], v[138:139], 2, s[22:23]
	global_load_dword v150, v[138:139], off
	v_add_u32_e32 v138, 0x4010, v48
	v_mov_b32_e32 v139, v49
	v_lshl_add_u64 v[138:139], v[138:139], 2, s[22:23]
	global_load_dword v166, v[138:139], off
	v_add_u32_e32 v138, 0x8010, v48
	v_mov_b32_e32 v139, v49
	v_lshl_add_u64 v[138:139], v[138:139], 2, s[22:23]
	global_load_dword v151, v[138:139], off
	v_add_u32_e32 v138, 0xc010, v48
	v_mov_b32_e32 v139, v49
	v_lshl_add_u64 v[138:139], v[138:139], 2, s[22:23]
	global_load_dword v167, v[138:139], off
	v_or_b32_e32 v138, 32, v48
	v_mov_b32_e32 v139, v49
	v_lshl_add_u64 v[138:139], v[138:139], 2, s[22:23]
	global_load_dword v146, v[138:139], off
	v_add_u32_e32 v138, 0x4020, v48
	v_mov_b32_e32 v139, v49
	v_lshl_add_u64 v[138:139], v[138:139], 2, s[22:23]
	global_load_dword v162, v[138:139], off
	v_add_u32_e32 v138, 0x8020, v48
	v_mov_b32_e32 v139, v49
	v_lshl_add_u64 v[138:139], v[138:139], 2, s[22:23]
	global_load_dword v147, v[138:139], off
	v_add_u32_e32 v138, 0xc020, v48
	v_mov_b32_e32 v139, v49
	v_lshl_add_u64 v[138:139], v[138:139], 2, s[22:23]
	global_load_dword v163, v[138:139], off
	v_or_b32_e32 v138, 48, v48
	v_mov_b32_e32 v139, v49
	v_lshl_add_u64 v[138:139], v[138:139], 2, s[22:23]
	global_load_dword v148, v[138:139], off
	v_add_u32_e32 v138, 0x4030, v48
	v_mov_b32_e32 v139, v49
	v_lshl_add_u64 v[138:139], v[138:139], 2, s[22:23]
	global_load_dword v164, v[138:139], off
	v_add_u32_e32 v138, 0x8030, v48
	v_mov_b32_e32 v139, v49
	v_lshl_add_u64 v[138:139], v[138:139], 2, s[22:23]
	global_load_dword v149, v[138:139], off
	v_add_u32_e32 v138, 0xc030, v48
	v_mov_b32_e32 v139, v49
	v_lshl_add_u64 v[138:139], v[138:139], 2, s[22:23]
	global_load_dword v165, v[138:139], off
	v_add_u32_e32 v138, 0x80, v48
	v_mov_b32_e32 v139, v49
	v_lshl_add_u64 v[138:139], v[138:139], 2, s[22:23]
	global_load_dword v142, v[138:139], off
	v_add_u32_e32 v138, 0x4080, v48
	v_mov_b32_e32 v139, v49
	v_lshl_add_u64 v[138:139], v[138:139], 2, s[22:23]
	global_load_dword v158, v[138:139], off
	v_add_u32_e32 v138, 0x8080, v48
	v_mov_b32_e32 v139, v49
	v_lshl_add_u64 v[138:139], v[138:139], 2, s[22:23]
	global_load_dword v143, v[138:139], off
	v_add_u32_e32 v138, 0xc080, v48
	v_mov_b32_e32 v139, v49
	v_lshl_add_u64 v[138:139], v[138:139], 2, s[22:23]
	global_load_dword v159, v[138:139], off
	v_add_u32_e32 v138, 0x90, v48
	v_mov_b32_e32 v139, v49
	v_lshl_add_u64 v[138:139], v[138:139], 2, s[22:23]
	global_load_dword v144, v[138:139], off
	v_add_u32_e32 v138, 0x4090, v48
	v_mov_b32_e32 v139, v49
	v_lshl_add_u64 v[138:139], v[138:139], 2, s[22:23]
	global_load_dword v160, v[138:139], off
	v_add_u32_e32 v138, 0x8090, v48
	v_mov_b32_e32 v139, v49
	v_lshl_add_u64 v[138:139], v[138:139], 2, s[22:23]
	global_load_dword v145, v[138:139], off
	v_add_u32_e32 v138, 0xc090, v48
	v_mov_b32_e32 v139, v49
	v_lshl_add_u64 v[138:139], v[138:139], 2, s[22:23]
	global_load_dword v161, v[138:139], off
	v_add_u32_e32 v138, 0xa0, v48
	v_mov_b32_e32 v139, v49
	v_mov_b32_e32 v141, v49
	v_lshl_add_u64 v[138:139], v[138:139], 2, s[22:23]
	v_lshl_add_u64 v[140:141], v[140:141], 2, s[22:23]
	global_load_dword v138, v[138:139], off
	v_add_u32_e32 v178, 0x80b0, v48
	global_load_dword v139, v[140:141], off
	v_add_u32_e32 v140, 0xc0a0, v48
	v_mov_b32_e32 v141, v49
	v_lshl_add_u64 v[140:141], v[140:141], 2, s[22:23]
	global_load_dword v153, v[140:141], off
	v_add_u32_e32 v140, 0xb0, v48
	v_mov_b32_e32 v141, v49
	v_mov_b32_e32 v179, v49
	v_lshl_add_u64 v[140:141], v[140:141], 2, s[22:23]
	v_lshl_add_u64 v[178:179], v[178:179], 2, s[22:23]
	v_add_u32_e32 v48, 0xc0b0, v48
	global_load_dword v140, v[140:141], off
	s_waitcnt vmcnt(0)
	v_pk_add_f32 v[168:169], v[168:169], v[170:171]
	global_load_dword v141, v[178:179], off
	v_lshl_add_u64 v[178:179], v[48:49], 2, s[22:23]
	global_load_dword v157, v[178:179], off
	v_and_b32_e32 v178, 64, v205
	v_xor_b32_e32 v48, 16, v205
	v_add_u32_e32 v178, 64, v178
	v_cmp_lt_i32_e32 vcc, v48, v178
	v_pk_add_f32 v[150:151], v[150:151], v[166:167]
	s_mov_b32 s6, 0x358637bd
	v_cndmask_b32_e32 v48, v205, v48, vcc
	v_lshlrev_b32_e32 v178, 2, v48
	v_add_f32_e32 v48, v168, v169
	ds_bpermute_b32 v168, v178, v48
	v_pk_add_f32 v[146:147], v[146:147], v[162:163]
	v_mov_b64_e32 v[166:167], s[6:7]
	v_add_f32_e32 v146, v146, v147
	ds_bpermute_b32 v147, v178, v146
	s_waitcnt lgkmcnt(1)
	v_add_f32_e32 v169, v48, v168
	v_add_f32_e32 v48, v150, v151
	ds_bpermute_b32 v150, v178, v48
	v_mov_b32_e32 v171, v169
	s_waitcnt lgkmcnt(1)
	v_add_f32_e32 v147, v146, v147
	v_permlane32_swap_b32_e32 v169, v171
	s_waitcnt lgkmcnt(0)
	v_add_f32_e32 v168, v48, v150
	v_mov_b32_e32 v170, v168
	s_nop 1
	v_permlane32_swap_b32_e32 v168, v170
	v_pk_add_f32 v[148:149], v[148:149], v[164:165]
	v_pk_add_f32 v[150:151], v[168:169], v[170:171]
	v_add_f32_e32 v146, v148, v149
	v_pk_fma_f32 v[168:169], v[150:151], s[36:37], v[166:167] op_sel_hi:[1,0,0]
	v_mov_b32_e32 v163, v147
	v_mul_f32_e32 v48, 0x4b800000, v169
	v_cmp_gt_f32_e64 s[38:39], s75, v169
	s_waitcnt lgkmcnt(0)
	v_mov_b32_e32 v148, v146
	s_nop 1
	v_permlane16_swap_b32_e32 v146, v148
	v_add_f32_e32 v146, v146, v148
	v_mov_b32_e32 v162, v146
	v_cndmask_b32_e64 v48, v169, v48, s[38:39]
	v_rsq_f32_e32 v48, v48
	v_permlane32_swap_b32_e32 v147, v163
	v_permlane32_swap_b32_e32 v146, v162
	v_pk_add_f32 v[142:143], v[142:143], v[158:159]
	v_pk_add_f32 v[146:147], v[146:147], v[162:163]
	v_add_f32_e32 v142, v142, v143
	ds_bpermute_b32 v143, v178, v142
	v_mul_f32_e32 v150, 0x45800000, v48
	v_pk_fma_f32 v[146:147], v[146:147], s[36:37], v[166:167] op_sel_hi:[1,0,0]
	v_cmp_gt_f32_e32 vcc, s75, v168
	v_cndmask_b32_e64 v150, v48, v150, s[38:39]
	s_waitcnt lgkmcnt(0)
	v_add_f32_e32 v143, v142, v143
	v_mul_f32_e32 v48, 0x4b800000, v168
	v_mul_f32_e32 v148, 0x4b800000, v147
	v_cmp_gt_f32_e64 s[38:39], s75, v147
	v_cndmask_b32_e32 v48, v168, v48, vcc
	v_rsq_f32_e32 v48, v48
	v_cndmask_b32_e64 v147, v147, v148, s[38:39]
	v_pk_add_f32 v[144:145], v[144:145], v[160:161]
	v_rsq_f32_e32 v147, v147
	v_add_f32_e32 v142, v144, v145
	v_mov_b32_e32 v159, v143
	s_nop 1
	v_permlane32_swap_b32_e32 v143, v159
	v_mul_f32_e32 v151, 0x45800000, v48
	s_waitcnt lgkmcnt(0)
	v_mov_b32_e32 v144, v142
	s_nop 1
	v_permlane16_swap_b32_e32 v142, v144
	v_add_f32_e32 v142, v142, v144
	v_mov_b32_e32 v158, v142
	s_nop 1
	v_permlane32_swap_b32_e32 v142, v158
	v_pk_add_f32 v[138:139], v[138:139], v[152:153]
	v_pk_add_f32 v[142:143], v[142:143], v[158:159]
	v_add_f32_e32 v138, v138, v139
	ds_bpermute_b32 v139, v178, v138
	v_mul_f32_e32 v148, 0x45800000, v147
	v_pk_fma_f32 v[142:143], v[142:143], s[36:37], v[166:167] op_sel_hi:[1,0,0]
	v_cndmask_b32_e32 v48, v48, v151, vcc
	v_cmp_gt_f32_e32 vcc, s75, v146
	s_waitcnt lgkmcnt(0)
	v_add_f32_e32 v139, v138, v139
	v_cndmask_b32_e64 v148, v147, v148, s[38:39]
	v_mul_f32_e32 v147, 0x4b800000, v146
	s_waitcnt vmcnt(0)
	v_pk_add_f32 v[140:141], v[140:141], v[156:157]
	v_mul_f32_e32 v144, 0x4b800000, v143
	v_add_f32_e32 v138, v140, v141
	v_cmp_gt_f32_e64 s[38:39], s75, v143
	v_cndmask_b32_e32 v146, v146, v147, vcc
	v_rsq_f32_e32 v146, v146
	v_cndmask_b32_e64 v143, v143, v144, s[38:39]
	v_rsq_f32_e32 v143, v143
	s_waitcnt lgkmcnt(0)
	v_mov_b32_e32 v140, v138
	s_nop 1
	v_permlane16_swap_b32_e32 v138, v140
	v_add_f32_e32 v138, v138, v140
	v_mov_b32_e32 v153, v139
	v_mov_b32_e32 v152, v138
	s_nop 0
	v_permlane32_swap_b32_e32 v139, v153
	v_permlane32_swap_b32_e32 v138, v152
	v_pk_add_f32 v[138:139], v[138:139], v[152:153]
	v_mul_f32_e32 v147, 0x45800000, v146
	v_mul_f32_e32 v144, 0x45800000, v143
	v_pk_fma_f32 v[138:139], v[138:139], s[36:37], v[166:167] op_sel_hi:[1,0,0]
	v_cndmask_b32_e32 v146, v146, v147, vcc
	v_cmp_gt_f32_e32 vcc, s75, v142
	v_cndmask_b32_e64 v144, v143, v144, s[38:39]
	v_mul_f32_e32 v143, 0x4b800000, v142
	v_mul_f32_e32 v140, 0x4b800000, v139
	v_cmp_gt_f32_e64 s[38:39], s75, v139
	v_cndmask_b32_e32 v142, v142, v143, vcc
	v_rsq_f32_e32 v142, v142
	v_cndmask_b32_e64 v139, v139, v140, s[38:39]
	v_rsq_f32_e32 v139, v139
	v_pk_mul_f32 v[126:127], v[126:127], v[150:151] op_sel_hi:[1,0]
	v_mul_f32_e32 v143, 0x45800000, v142
	v_cndmask_b32_e32 v142, v142, v143, vcc
	v_mul_f32_e32 v140, 0x45800000, v139
	v_cmp_gt_f32_e32 vcc, s75, v138
	v_cndmask_b32_e64 v140, v139, v140, s[38:39]
	v_mul_f32_e32 v139, 0x4b800000, v138
	v_cndmask_b32_e32 v138, v138, v139, vcc
	v_rsq_f32_e32 v138, v138
	v_pk_mul_f32 v[122:123], v[122:123], v[150:151] op_sel_hi:[1,0]
	v_pk_mul_f32 v[124:125], v[124:125], v[150:151] op_sel_hi:[1,0]
	v_pk_mul_f32 v[122:123], v[126:127], v[122:123]
	v_mul_f32_e32 v139, 0x45800000, v138
	v_cndmask_b32_e32 v138, v138, v139, vcc
	v_mul_f32_e32 v139, 0xbfb8aa3b, v126
	v_mul_f32_e32 v126, 0xbfb8aa3b, v127
	v_exp_f32_e32 v126, v126
	v_exp_f32_e32 v139, v139
	v_pk_mul_f32 v[118:119], v[118:119], v[150:151] op_sel_hi:[1,0]
	v_pk_mul_f32 v[114:115], v[114:115], v[150:151] op_sel_hi:[1,0]
	v_add_f32_e32 v126, 1.0, v126
	v_rcp_f32_e32 v157, v126
	v_pk_mul_f32 v[126:127], v[128:129], v[150:151] op_sel_hi:[1,0]
	v_add_f32_e32 v139, 1.0, v139
	v_mul_f32_e32 v128, 0xbfb8aa3b, v126
	v_pk_mul_f32 v[124:125], v[126:127], v[124:125]
	v_mul_f32_e32 v126, 0xbfb8aa3b, v127
	v_exp_f32_e32 v128, v128
	v_exp_f32_e32 v126, v126
	v_rcp_f32_e32 v156, v139
	v_pk_mul_f32 v[114:115], v[118:119], v[114:115]
	v_add_f32_e32 v128, 1.0, v128
	v_add_f32_e32 v126, 1.0, v126
	v_rcp_f32_e32 v128, v128
	v_rcp_f32_e32 v129, v126
	v_pk_mul_f32 v[122:123], v[122:123], v[156:157]
	v_pk_mul_f32 v[116:117], v[116:117], v[150:151] op_sel_hi:[1,0]
	v_cvt_pk_bf16_f32 v122, v122, v123
	v_pk_mul_f32 v[124:125], v[124:125], v[128:129]
	v_lshl_or_b32 v152, s18, 7, v175
	v_cvt_pk_bf16_f32 v123, v124, v125
	v_mul_f32_e32 v124, 0xbfb8aa3b, v118
	v_mul_f32_e32 v118, 0xbfb8aa3b, v119
	v_exp_f32_e32 v118, v118
	v_exp_f32_e32 v124, v124
	s_movk_i32 s6, 0xb00
	v_pk_mul_f32 v[110:111], v[110:111], v[48:49] op_sel_hi:[1,0]
	v_add_f32_e32 v118, 1.0, v118
	v_rcp_f32_e32 v125, v118
	v_pk_mul_f32 v[118:119], v[120:121], v[150:151] op_sel_hi:[1,0]
	v_add_f32_e32 v124, 1.0, v124
	v_mul_f32_e32 v120, 0xbfb8aa3b, v118
	v_pk_mul_f32 v[116:117], v[118:119], v[116:117]
	v_mul_f32_e32 v118, 0xbfb8aa3b, v119
	v_exp_f32_e32 v120, v120
	v_exp_f32_e32 v118, v118
	v_rcp_f32_e32 v124, v124
	v_pk_mul_f32 v[106:107], v[106:107], v[48:49] op_sel_hi:[1,0]
	v_add_f32_e32 v120, 1.0, v120
	v_add_f32_e32 v118, 1.0, v118
	v_rcp_f32_e32 v120, v120
	v_rcp_f32_e32 v121, v118
	v_pk_mul_f32 v[114:115], v[114:115], v[124:125]
	v_pk_mul_f32 v[106:107], v[110:111], v[106:107]
	v_cvt_pk_bf16_f32 v124, v114, v115
	v_mad_u64_u32 v[114:115], s[20:21], v177, s6, v[152:153]
	v_pk_mul_f32 v[116:117], v[116:117], v[120:121]
	v_mov_b32_e32 v115, v49
	v_cvt_pk_bf16_f32 v125, v116, v117
	v_lshl_add_u64 v[116:117], v[114:115], 1, s[12:13]
	v_mul_f32_e32 v115, 0xbfb8aa3b, v110
	v_mul_f32_e32 v110, 0xbfb8aa3b, v111
	v_exp_f32_e32 v110, v110
	global_store_dwordx4 v[116:117], v[122:125], off
	s_nop 1
	v_pk_mul_f32 v[108:109], v[108:109], v[48:49] op_sel_hi:[1,0]
	v_exp_f32_e32 v115, v115
	v_add_f32_e32 v110, 1.0, v110
	v_rcp_f32_e32 v117, v110
	v_pk_mul_f32 v[110:111], v[112:113], v[48:49] op_sel_hi:[1,0]
	v_add_f32_e32 v115, 1.0, v115
	v_mul_f32_e32 v112, 0xbfb8aa3b, v110
	v_pk_mul_f32 v[108:109], v[110:111], v[108:109]
	v_mul_f32_e32 v110, 0xbfb8aa3b, v111
	v_exp_f32_e32 v112, v112
	v_exp_f32_e32 v110, v110
	v_rcp_f32_e32 v116, v115
	v_pk_mul_f32 v[102:103], v[102:103], v[48:49] op_sel_hi:[1,0]
	v_add_f32_e32 v112, 1.0, v112
	v_add_f32_e32 v110, 1.0, v110
	v_rcp_f32_e32 v112, v112
	v_rcp_f32_e32 v113, v110
	v_pk_mul_f32 v[106:107], v[106:107], v[116:117]
	v_pk_mul_f32 v[98:99], v[98:99], v[48:49] op_sel_hi:[1,0]
	v_cvt_pk_bf16_f32 v106, v106, v107
	v_pk_mul_f32 v[108:109], v[108:109], v[112:113]
	v_pk_mul_f32 v[98:99], v[102:103], v[98:99]
	v_cvt_pk_bf16_f32 v107, v108, v109
	v_mul_f32_e32 v108, 0xbfb8aa3b, v102
	v_mul_f32_e32 v102, 0xbfb8aa3b, v103
	v_exp_f32_e32 v102, v102
	v_exp_f32_e32 v108, v108
	v_pk_mul_f32 v[100:101], v[100:101], v[48:49] op_sel_hi:[1,0]
	v_pk_mul_f32 v[94:95], v[94:95], v[148:149] op_sel_hi:[1,0]
	v_add_f32_e32 v102, 1.0, v102
	v_rcp_f32_e32 v109, v102
	v_pk_mul_f32 v[102:103], v[104:105], v[48:49] op_sel_hi:[1,0]
	v_add_f32_e32 v108, 1.0, v108
	v_mul_f32_e32 v48, 0xbfb8aa3b, v103
	v_exp_f32_e32 v48, v48
	v_rcp_f32_e32 v108, v108
	v_mul_f32_e32 v104, 0xbfb8aa3b, v102
	v_exp_f32_e32 v104, v104
	v_add_f32_e32 v48, 1.0, v48
	v_pk_mul_f32 v[98:99], v[98:99], v[108:109]
	v_rcp_f32_e32 v105, v48
	v_add_u32_e32 v48, 0xb000, v114
	v_add_f32_e32 v104, 1.0, v104
	v_cvt_pk_bf16_f32 v108, v98, v99
	v_lshl_add_u64 v[98:99], v[48:49], 1, s[12:13]
	v_mul_f32_e32 v48, 0xbfb8aa3b, v94
	v_rcp_f32_e32 v104, v104
	v_exp_f32_e32 v48, v48
	v_pk_mul_f32 v[100:101], v[102:103], v[100:101]
	v_pk_mul_f32 v[90:91], v[90:91], v[148:149] op_sel_hi:[1,0]
	v_pk_mul_f32 v[100:101], v[100:101], v[104:105]
	v_add_f32_e32 v48, 1.0, v48
	v_cvt_pk_bf16_f32 v109, v100, v101
	global_store_dwordx4 v[98:99], v[106:109], off
	s_nop 1
	v_rcp_f32_e32 v98, v48
	v_mul_f32_e32 v48, 0xbfb8aa3b, v95
	v_exp_f32_e32 v48, v48
	v_pk_mul_f32 v[90:91], v[94:95], v[90:91]
	v_pk_mul_f32 v[94:95], v[96:97], v[148:149] op_sel_hi:[1,0]
	v_pk_mul_f32 v[86:87], v[86:87], v[148:149] op_sel_hi:[1,0]
	v_add_f32_e32 v48, 1.0, v48
	v_rcp_f32_e32 v99, v48
	v_mul_f32_e32 v48, 0xbfb8aa3b, v94
	v_exp_f32_e32 v48, v48
	v_pk_mul_f32 v[92:93], v[92:93], v[148:149] op_sel_hi:[1,0]
	v_pk_mul_f32 v[90:91], v[90:91], v[98:99]
	v_pk_mul_f32 v[92:93], v[94:95], v[92:93]
	v_add_f32_e32 v48, 1.0, v48
	v_rcp_f32_e32 v96, v48
	v_mul_f32_e32 v48, 0xbfb8aa3b, v95
	v_exp_f32_e32 v48, v48
	v_cvt_pk_bf16_f32 v90, v90, v91
	v_pk_mul_f32 v[82:83], v[82:83], v[148:149] op_sel_hi:[1,0]
	v_pk_mul_f32 v[78:79], v[78:79], v[146:147] op_sel_hi:[1,0]
	v_add_f32_e32 v48, 1.0, v48
	v_rcp_f32_e32 v97, v48
	v_mul_f32_e32 v48, 0xbfb8aa3b, v86
	v_exp_f32_e32 v48, v48
	v_pk_mul_f32 v[82:83], v[86:87], v[82:83]
	v_pk_mul_f32 v[92:93], v[92:93], v[96:97]
	v_pk_mul_f32 v[84:85], v[84:85], v[148:149] op_sel_hi:[1,0]
	v_add_f32_e32 v48, 1.0, v48
	v_cvt_pk_bf16_f32 v91, v92, v93
	v_rcp_f32_e32 v92, v48
	v_mul_f32_e32 v48, 0xbfb8aa3b, v87
	v_exp_f32_e32 v48, v48
	v_pk_mul_f32 v[86:87], v[88:89], v[148:149] op_sel_hi:[1,0]
	v_pk_mul_f32 v[74:75], v[74:75], v[146:147] op_sel_hi:[1,0]
	v_pk_mul_f32 v[84:85], v[86:87], v[84:85]
	v_add_f32_e32 v48, 1.0, v48
	v_rcp_f32_e32 v93, v48
	v_mul_f32_e32 v48, 0xbfb8aa3b, v86
	v_exp_f32_e32 v48, v48
	v_pk_mul_f32 v[74:75], v[78:79], v[74:75]
	v_pk_mul_f32 v[82:83], v[82:83], v[92:93]
	v_pk_mul_f32 v[70:71], v[70:71], v[146:147] op_sel_hi:[1,0]
	v_add_f32_e32 v48, 1.0, v48
	v_rcp_f32_e32 v88, v48
	v_mul_f32_e32 v48, 0xbfb8aa3b, v87
	v_exp_f32_e32 v48, v48
	v_cvt_pk_bf16_f32 v92, v82, v83
	v_pk_mul_f32 v[76:77], v[76:77], v[146:147] op_sel_hi:[1,0]
	v_pk_mul_f32 v[66:67], v[66:67], v[146:147] op_sel_hi:[1,0]
	v_add_f32_e32 v48, 1.0, v48
	v_rcp_f32_e32 v89, v48
	v_add_u32_e32 v48, 0x16000, v114
	v_lshl_add_u64 v[82:83], v[48:49], 1, s[12:13]
	v_mul_f32_e32 v48, 0xbfb8aa3b, v78
	v_exp_f32_e32 v48, v48
	v_pk_mul_f32 v[84:85], v[84:85], v[88:89]
	v_pk_mul_f32 v[66:67], v[70:71], v[66:67]
	v_cvt_pk_bf16_f32 v93, v84, v85
	v_add_f32_e32 v48, 1.0, v48
	global_store_dwordx4 v[82:83], v[90:93], off
	s_nop 1
	v_rcp_f32_e32 v82, v48
	v_mul_f32_e32 v48, 0xbfb8aa3b, v79
	v_exp_f32_e32 v48, v48
	v_pk_mul_f32 v[78:79], v[80:81], v[146:147] op_sel_hi:[1,0]
	v_pk_mul_f32 v[62:63], v[62:63], v[144:145] op_sel_hi:[1,0]
	v_pk_mul_f32 v[76:77], v[78:79], v[76:77]
	v_add_f32_e32 v48, 1.0, v48
	v_rcp_f32_e32 v83, v48
	v_mul_f32_e32 v48, 0xbfb8aa3b, v78
	v_exp_f32_e32 v48, v48
	v_pk_mul_f32 v[68:69], v[68:69], v[146:147] op_sel_hi:[1,0]
	v_pk_mul_f32 v[74:75], v[74:75], v[82:83]
	v_pk_mul_f32 v[58:59], v[58:59], v[144:145] op_sel_hi:[1,0]
	v_add_f32_e32 v48, 1.0, v48
	v_rcp_f32_e32 v80, v48
	v_mul_f32_e32 v48, 0xbfb8aa3b, v79
	v_exp_f32_e32 v48, v48
	v_cvt_pk_bf16_f32 v74, v74, v75
	v_pk_mul_f32 v[58:59], v[62:63], v[58:59]
	v_pk_mul_f32 v[54:55], v[54:55], v[144:145] op_sel_hi:[1,0]
	v_add_f32_e32 v48, 1.0, v48
	v_rcp_f32_e32 v81, v48
	v_mul_f32_e32 v48, 0xbfb8aa3b, v70
	v_exp_f32_e32 v48, v48
	v_pk_mul_f32 v[60:61], v[60:61], v[144:145] op_sel_hi:[1,0]
	v_pk_mul_f32 v[76:77], v[76:77], v[80:81]
	v_pk_mul_f32 v[50:51], v[50:51], v[144:145] op_sel_hi:[1,0]
	v_add_f32_e32 v48, 1.0, v48
	v_cvt_pk_bf16_f32 v75, v76, v77
	v_rcp_f32_e32 v76, v48
	v_mul_f32_e32 v48, 0xbfb8aa3b, v71
	v_exp_f32_e32 v48, v48
	v_pk_mul_f32 v[70:71], v[72:73], v[146:147] op_sel_hi:[1,0]
	v_pk_mul_f32 v[50:51], v[54:55], v[50:51]
	v_pk_mul_f32 v[68:69], v[70:71], v[68:69]
	v_add_f32_e32 v48, 1.0, v48
	v_rcp_f32_e32 v77, v48
	v_mul_f32_e32 v48, 0xbfb8aa3b, v70
	v_exp_f32_e32 v48, v48
	v_pk_mul_f32 v[44:45], v[44:45], v[142:143] op_sel_hi:[1,0]
	v_pk_mul_f32 v[66:67], v[66:67], v[76:77]
	v_pk_mul_f32 v[40:41], v[40:41], v[142:143] op_sel_hi:[1,0]
	v_add_f32_e32 v48, 1.0, v48
	v_rcp_f32_e32 v72, v48
	v_mul_f32_e32 v48, 0xbfb8aa3b, v71
	v_exp_f32_e32 v48, v48
	v_cvt_pk_bf16_f32 v76, v66, v67
	v_pk_mul_f32 v[40:41], v[44:45], v[40:41]
	v_pk_mul_f32 v[52:53], v[52:53], v[144:145] op_sel_hi:[1,0]
	v_add_f32_e32 v48, 1.0, v48
	v_rcp_f32_e32 v73, v48
	v_add_u32_e32 v48, 0x21000, v114
	v_lshl_add_u64 v[66:67], v[48:49], 1, s[12:13]
	v_mul_f32_e32 v48, 0xbfb8aa3b, v62
	v_exp_f32_e32 v48, v48
	v_pk_mul_f32 v[68:69], v[68:69], v[72:73]
	v_pk_mul_f32 v[42:43], v[42:43], v[142:143] op_sel_hi:[1,0]
	v_cvt_pk_bf16_f32 v77, v68, v69
	v_add_f32_e32 v48, 1.0, v48
	global_store_dwordx4 v[66:67], v[74:77], off
	s_nop 1
	v_rcp_f32_e32 v66, v48
	v_mul_f32_e32 v48, 0xbfb8aa3b, v63
	v_exp_f32_e32 v48, v48
	v_pk_mul_f32 v[62:63], v[64:65], v[144:145] op_sel_hi:[1,0]
	v_pk_mul_f32 v[36:37], v[36:37], v[142:143] op_sel_hi:[1,0]
	v_pk_mul_f32 v[60:61], v[62:63], v[60:61]
	v_add_f32_e32 v48, 1.0, v48
	v_rcp_f32_e32 v67, v48
	v_mul_f32_e32 v48, 0xbfb8aa3b, v62
	v_exp_f32_e32 v48, v48
	v_pk_mul_f32 v[32:33], v[32:33], v[142:143] op_sel_hi:[1,0]
	v_pk_mul_f32 v[58:59], v[58:59], v[66:67]
	v_pk_mul_f32 v[32:33], v[36:37], v[32:33]
	v_add_f32_e32 v48, 1.0, v48
	v_rcp_f32_e32 v64, v48
	v_mul_f32_e32 v48, 0xbfb8aa3b, v63
	v_exp_f32_e32 v48, v48
	v_cvt_pk_bf16_f32 v58, v58, v59
	v_pk_mul_f32 v[34:35], v[34:35], v[142:143] op_sel_hi:[1,0]
	v_pk_mul_f32 v[28:29], v[28:29], v[140:141] op_sel_hi:[1,0]
	v_add_f32_e32 v48, 1.0, v48
	v_rcp_f32_e32 v65, v48
	v_mul_f32_e32 v48, 0xbfb8aa3b, v54
	v_exp_f32_e32 v48, v48
	v_pk_mul_f32 v[24:25], v[24:25], v[140:141] op_sel_hi:[1,0]
	v_pk_mul_f32 v[60:61], v[60:61], v[64:65]
	v_pk_mul_f32 v[24:25], v[28:29], v[24:25]
	v_add_f32_e32 v48, 1.0, v48
	v_cvt_pk_bf16_f32 v59, v60, v61
	v_rcp_f32_e32 v60, v48
	v_mul_f32_e32 v48, 0xbfb8aa3b, v55
	v_exp_f32_e32 v48, v48
	v_pk_mul_f32 v[54:55], v[56:57], v[144:145] op_sel_hi:[1,0]
	v_pk_mul_f32 v[26:27], v[26:27], v[140:141] op_sel_hi:[1,0]
	v_pk_mul_f32 v[52:53], v[54:55], v[52:53]
	v_add_f32_e32 v48, 1.0, v48
	v_rcp_f32_e32 v61, v48
	v_mul_f32_e32 v48, 0xbfb8aa3b, v54
	v_exp_f32_e32 v48, v48
	v_pk_mul_f32 v[20:21], v[20:21], v[140:141] op_sel_hi:[1,0]
	v_pk_mul_f32 v[50:51], v[50:51], v[60:61]
	v_pk_mul_f32 v[16:17], v[16:17], v[140:141] op_sel_hi:[1,0]
	v_add_f32_e32 v48, 1.0, v48
	v_rcp_f32_e32 v56, v48
	v_mul_f32_e32 v48, 0xbfb8aa3b, v55
	v_exp_f32_e32 v48, v48
	v_cvt_pk_bf16_f32 v60, v50, v51
	v_pk_mul_f32 v[16:17], v[20:21], v[16:17]
	v_pk_mul_f32 v[18:19], v[18:19], v[140:141] op_sel_hi:[1,0]
	v_add_f32_e32 v48, 1.0, v48
	v_rcp_f32_e32 v57, v48
	v_add_u32_e32 v48, 0x58000, v114
	v_lshl_add_u64 v[50:51], v[48:49], 1, s[12:13]
	v_mul_f32_e32 v48, 0xbfb8aa3b, v44
	v_mul_f32_e32 v44, 0xbfb8aa3b, v45
	v_exp_f32_e32 v44, v44
	v_pk_mul_f32 v[52:53], v[52:53], v[56:57]
	v_exp_f32_e32 v48, v48
	v_cvt_pk_bf16_f32 v61, v52, v53
	v_add_f32_e32 v44, 1.0, v44
	global_store_dwordx4 v[50:51], v[58:61], off
	s_nop 1
	v_rcp_f32_e32 v51, v44
	v_pk_mul_f32 v[44:45], v[46:47], v[142:143] op_sel_hi:[1,0]
	v_add_f32_e32 v48, 1.0, v48
	v_mul_f32_e32 v46, 0xbfb8aa3b, v44
	v_pk_mul_f32 v[42:43], v[44:45], v[42:43]
	v_mul_f32_e32 v44, 0xbfb8aa3b, v45
	v_exp_f32_e32 v46, v46
	v_exp_f32_e32 v44, v44
	v_rcp_f32_e32 v50, v48
	v_add_u32_e32 v48, 0x63000, v114
	v_add_f32_e32 v46, 1.0, v46
	v_add_f32_e32 v44, 1.0, v44
	v_rcp_f32_e32 v46, v46
	v_rcp_f32_e32 v47, v44
	v_pk_mul_f32 v[40:41], v[40:41], v[50:51]
	v_pk_mul_f32 v[12:13], v[12:13], v[138:139] op_sel_hi:[1,0]
	v_cvt_pk_bf16_f32 v40, v40, v41
	v_pk_mul_f32 v[42:43], v[42:43], v[46:47]
	v_pk_mul_f32 v[8:9], v[8:9], v[138:139] op_sel_hi:[1,0]
	v_cvt_pk_bf16_f32 v41, v42, v43
	v_mul_f32_e32 v42, 0xbfb8aa3b, v36
	v_mul_f32_e32 v36, 0xbfb8aa3b, v37
	v_exp_f32_e32 v36, v36
	v_exp_f32_e32 v42, v42
	v_pk_mul_f32 v[8:9], v[12:13], v[8:9]
	v_pk_mul_f32 v[10:11], v[10:11], v[138:139] op_sel_hi:[1,0]
	v_add_f32_e32 v36, 1.0, v36
	v_rcp_f32_e32 v43, v36
	v_pk_mul_f32 v[36:37], v[38:39], v[142:143] op_sel_hi:[1,0]
	v_add_f32_e32 v42, 1.0, v42
	v_mul_f32_e32 v38, 0xbfb8aa3b, v36
	v_pk_mul_f32 v[34:35], v[36:37], v[34:35]
	v_mul_f32_e32 v36, 0xbfb8aa3b, v37
	v_exp_f32_e32 v38, v38
	v_exp_f32_e32 v36, v36
	v_rcp_f32_e32 v42, v42
	v_pk_mul_f32 v[4:5], v[4:5], v[138:139] op_sel_hi:[1,0]
	v_add_f32_e32 v38, 1.0, v38
	v_add_f32_e32 v36, 1.0, v36
	v_rcp_f32_e32 v38, v38
	v_rcp_f32_e32 v39, v36
	v_pk_mul_f32 v[32:33], v[32:33], v[42:43]
	v_pk_mul_f32 v[0:1], v[0:1], v[138:139] op_sel_hi:[1,0]
	v_cvt_pk_bf16_f32 v42, v32, v33
	v_pk_mul_f32 v[34:35], v[34:35], v[38:39]
	v_lshl_add_u64 v[32:33], v[48:49], 1, s[12:13]
	v_cvt_pk_bf16_f32 v43, v34, v35
	global_store_dwordx4 v[32:33], v[40:43], off
	s_nop 1
	v_mul_f32_e32 v32, 0xbfb8aa3b, v28
	v_mul_f32_e32 v28, 0xbfb8aa3b, v29
	v_exp_f32_e32 v28, v28
	v_exp_f32_e32 v32, v32
	v_add_u32_e32 v48, 0x6e000, v114
	v_pk_mul_f32 v[0:1], v[4:5], v[0:1]
	v_add_f32_e32 v28, 1.0, v28
	v_rcp_f32_e32 v33, v28
	v_pk_mul_f32 v[28:29], v[30:31], v[140:141] op_sel_hi:[1,0]
	v_add_f32_e32 v32, 1.0, v32
	v_mul_f32_e32 v30, 0xbfb8aa3b, v28
	v_pk_mul_f32 v[26:27], v[28:29], v[26:27]
	v_mul_f32_e32 v28, 0xbfb8aa3b, v29
	v_exp_f32_e32 v30, v30
	v_exp_f32_e32 v28, v28
	v_rcp_f32_e32 v32, v32
	v_pk_mul_f32 v[2:3], v[2:3], v[138:139] op_sel_hi:[1,0]
	v_add_f32_e32 v30, 1.0, v30
	v_add_f32_e32 v28, 1.0, v28
	v_rcp_f32_e32 v30, v30
	v_rcp_f32_e32 v31, v28
	v_pk_mul_f32 v[24:25], v[24:25], v[32:33]
	s_mov_b64 s[38:39], -1
	v_cvt_pk_bf16_f32 v24, v24, v25
	v_pk_mul_f32 v[26:27], v[26:27], v[30:31]
	s_andn2_b64 vcc, exec, s[48:49]
	v_cvt_pk_bf16_f32 v25, v26, v27
	v_mul_f32_e32 v26, 0xbfb8aa3b, v20
	v_mul_f32_e32 v20, 0xbfb8aa3b, v21
	v_exp_f32_e32 v20, v20
	v_exp_f32_e32 v26, v26
	v_add_f32_e32 v20, 1.0, v20
	v_rcp_f32_e32 v27, v20
	v_pk_mul_f32 v[20:21], v[22:23], v[140:141] op_sel_hi:[1,0]
	v_add_f32_e32 v26, 1.0, v26
	v_mul_f32_e32 v22, 0xbfb8aa3b, v20
	v_pk_mul_f32 v[18:19], v[20:21], v[18:19]
	v_mul_f32_e32 v20, 0xbfb8aa3b, v21
	v_exp_f32_e32 v22, v22
	v_exp_f32_e32 v20, v20
	v_rcp_f32_e32 v26, v26
	v_add_f32_e32 v22, 1.0, v22
	v_add_f32_e32 v20, 1.0, v20
	v_rcp_f32_e32 v22, v22
	v_rcp_f32_e32 v23, v20
	v_pk_mul_f32 v[16:17], v[16:17], v[26:27]
	v_pk_mul_f32 v[18:19], v[18:19], v[22:23]
	v_cvt_pk_bf16_f32 v26, v16, v17
	v_lshl_add_u64 v[16:17], v[48:49], 1, s[12:13]
	v_cvt_pk_bf16_f32 v27, v18, v19
	global_store_dwordx4 v[16:17], v[24:27], off
	s_nop 1
	v_mul_f32_e32 v16, 0xbfb8aa3b, v12
	v_mul_f32_e32 v12, 0xbfb8aa3b, v13
	v_exp_f32_e32 v12, v12
	v_exp_f32_e32 v16, v16
	v_add_u32_e32 v48, 0x79000, v114
	v_add_f32_e32 v12, 1.0, v12
	v_rcp_f32_e32 v17, v12
	v_pk_mul_f32 v[12:13], v[14:15], v[138:139] op_sel_hi:[1,0]
	v_add_f32_e32 v16, 1.0, v16
	v_mul_f32_e32 v14, 0xbfb8aa3b, v12
	v_pk_mul_f32 v[10:11], v[12:13], v[10:11]
	v_mul_f32_e32 v12, 0xbfb8aa3b, v13
	v_exp_f32_e32 v14, v14
	v_exp_f32_e32 v12, v12
	v_rcp_f32_e32 v16, v16
	v_add_f32_e32 v14, 1.0, v14
	v_add_f32_e32 v12, 1.0, v12
	v_rcp_f32_e32 v14, v14
	v_rcp_f32_e32 v15, v12
	v_pk_mul_f32 v[8:9], v[8:9], v[16:17]
	v_pk_mul_f32 v[10:11], v[10:11], v[14:15]
	v_cvt_pk_bf16_f32 v8, v8, v9
	v_cvt_pk_bf16_f32 v9, v10, v11
	v_mul_f32_e32 v10, 0xbfb8aa3b, v4
	v_mul_f32_e32 v4, 0xbfb8aa3b, v5
	v_exp_f32_e32 v4, v4
	v_exp_f32_e32 v10, v10
	v_add_f32_e32 v4, 1.0, v4
	v_rcp_f32_e32 v11, v4
	v_pk_mul_f32 v[4:5], v[6:7], v[138:139] op_sel_hi:[1,0]
	v_add_f32_e32 v10, 1.0, v10
	v_mul_f32_e32 v6, 0xbfb8aa3b, v4
	v_pk_mul_f32 v[2:3], v[4:5], v[2:3]
	v_mul_f32_e32 v4, 0xbfb8aa3b, v5
	v_exp_f32_e32 v6, v6
	v_exp_f32_e32 v4, v4
	v_rcp_f32_e32 v10, v10
	v_add_f32_e32 v6, 1.0, v6
	v_add_f32_e32 v4, 1.0, v4
	v_rcp_f32_e32 v6, v6
	v_rcp_f32_e32 v7, v4
	v_pk_mul_f32 v[0:1], v[0:1], v[10:11]
	v_pk_mul_f32 v[2:3], v[2:3], v[6:7]
	v_cvt_pk_bf16_f32 v10, v0, v1
	v_cvt_pk_bf16_f32 v11, v2, v3
	v_lshl_add_u64 v[0:1], v[48:49], 1, s[12:13]
	global_store_dwordx4 v[0:1], v[8:11], off
	s_nop 1
	s_cbranch_vccnz .LBB0_244
	s_andn2_b64 vcc, exec, s[40:41]
	s_cbranch_vccnz .LBB0_243
	s_barrier
	s_branch .LBB0_243

.LBB0_475:
	v_lshl_add_u32 v122, s33, 8, v182
	s_lshl_b32 s6, s18, 8
	v_lshl_add_u32 v48, v122, 10, s6
	v_or_b32_e32 v48, v48, v184
	v_lshl_add_u64 v[194:195], v[48:49], 1, s[16:17]
	global_load_dwordx4 v[186:189], v[194:195], off
	s_lshl_b32 s6, s18, 16
	s_or_b32 s6, s6, s65
	v_add_u32_e32 v168, s6, v122
	v_or_b32_e32 v122, 0x80, v48
	v_mov_b32_e32 v123, v49
	v_lshl_add_u64 v[196:197], v[122:123], 1, s[16:17]
	global_load_dwordx4 v[190:193], v[196:197], off
	v_add_u32_e32 v122, 0x4000, v48
	v_lshl_add_u64 v[180:181], v[122:123], 1, s[16:17]
	v_add_u32_e32 v122, 0x4080, v48
	v_lshl_add_u64 v[178:179], v[122:123], 1, s[16:17]
	v_add_u32_e32 v122, 0x8000, v48
	v_lshl_add_u64 v[176:177], v[122:123], 1, s[16:17]
	v_add_u32_e32 v122, 0x8080, v48
	v_lshl_add_u64 v[174:175], v[122:123], 1, s[16:17]
	v_add_u32_e32 v122, 0xc000, v48
	v_add_u32_e32 v130, 0xc080, v48
	v_mov_b32_e32 v131, v49
	v_lshl_add_u64 v[172:173], v[122:123], 1, s[16:17]
	v_lshl_add_u64 v[170:171], v[130:131], 1, s[16:17]
	global_load_dwordx4 v[150:153], v[180:181], off
	global_load_dwordx4 v[146:149], v[178:179], off
	global_load_dwordx4 v[142:145], v[176:177], off
	global_load_dwordx4 v[138:141], v[174:175], off
	global_load_dwordx4 v[122:125], v[172:173], off
	global_load_dwordx4 v[130:133], v[170:171], off
	s_waitcnt vmcnt(0)
	v_lshlrev_b32_e32 v198, 16, v186
	v_and_b32_e32 v199, 0xffff0000, v186
	v_lshlrev_b32_e32 v186, 16, v187
	v_and_b32_e32 v187, 0xffff0000, v187
	v_pk_fma_f32 v[136:137], v[136:137], 0.5, v[186:187] op_sel_hi:[1,0,1]
	v_pk_fma_f32 v[134:135], v[134:135], 0.5, v[198:199] op_sel_hi:[1,0,1]
	v_lshlrev_b32_e32 v186, 16, v188
	v_and_b32_e32 v187, 0xffff0000, v188
	v_lshlrev_b32_e32 v188, 16, v189
	v_and_b32_e32 v189, 0xffff0000, v189
	v_pk_fma_f32 v[188:189], v[128:129], 0.5, v[188:189] op_sel_hi:[1,0,1]
	v_pk_fma_f32 v[186:187], v[126:127], 0.5, v[186:187] op_sel_hi:[1,0,1]
	v_cvt_pk_bf16_f32 v126, v134, v135
	v_cvt_pk_bf16_f32 v127, v136, v137
	v_cvt_pk_bf16_f32 v128, v186, v187
	v_cvt_pk_bf16_f32 v129, v188, v189
	global_store_dwordx4 v[194:195], v[126:129], off
	s_nop 1
	v_mul_f32_e32 v126, v135, v135
	v_mul_f32_e32 v127, v137, v137
	v_fmac_f32_e32 v126, v134, v134
	v_fmac_f32_e32 v127, v136, v136
	v_add_f32_e32 v126, v126, v127
	v_mul_f32_e32 v127, v187, v187
	v_mul_f32_e32 v128, v189, v189
	v_fmac_f32_e32 v127, v186, v186
	v_fmac_f32_e32 v128, v188, v188
	v_add_f32_e32 v127, v127, v128
	v_add_f32_e32 v134, v126, v127
	v_lshlrev_b32_e32 v126, 16, v190
	v_and_b32_e32 v127, 0xffff0000, v190
	v_lshlrev_b32_e32 v128, 16, v191
	v_and_b32_e32 v129, 0xffff0000, v191
	v_pk_fma_f32 v[120:121], v[120:121], 0.5, v[128:129] op_sel_hi:[1,0,1]
	v_pk_fma_f32 v[118:119], v[118:119], 0.5, v[126:127] op_sel_hi:[1,0,1]
	v_lshlrev_b32_e32 v126, 16, v192
	v_and_b32_e32 v127, 0xffff0000, v192
	v_lshlrev_b32_e32 v128, 16, v193
	v_and_b32_e32 v129, 0xffff0000, v193
	v_pk_fma_f32 v[128:129], v[116:117], 0.5, v[128:129] op_sel_hi:[1,0,1]
	v_pk_fma_f32 v[126:127], v[114:115], 0.5, v[126:127] op_sel_hi:[1,0,1]
	v_cvt_pk_bf16_f32 v114, v118, v119
	v_cvt_pk_bf16_f32 v115, v120, v121
	v_cvt_pk_bf16_f32 v116, v126, v127
	v_cvt_pk_bf16_f32 v117, v128, v129
	global_store_dwordx4 v[196:197], v[114:117], off
	s_nop 1
	v_mul_f32_e32 v114, v119, v119
	v_mul_f32_e32 v115, v121, v121
	v_fmac_f32_e32 v114, v118, v118
	v_fmac_f32_e32 v115, v120, v120
	v_add_f32_e32 v114, v114, v115
	v_mul_f32_e32 v115, v127, v127
	v_mul_f32_e32 v116, v129, v129
	v_fmac_f32_e32 v115, v126, v126
	v_fmac_f32_e32 v116, v128, v128
	v_add_f32_e32 v115, v115, v116
	v_add_f32_e32 v114, v114, v115
	v_and_b32_e32 v116, 64, v205
	v_add_f32_e32 v115, v134, v114
	v_xor_b32_e32 v114, 16, v205
	v_add_u32_e32 v116, 64, v116
	v_cmp_lt_i32_e32 vcc, v114, v116
	s_nop 1
	v_cndmask_b32_e32 v114, v205, v114, vcc
	v_lshlrev_b32_e32 v114, 2, v114
	s_waitcnt lgkmcnt(0)
	v_mov_b32_e32 v116, v115
	s_nop 1
	v_permlane16_swap_b32_e32 v115, v116
	v_add_f32_e32 v115, v115, v116
	v_mov_b32_e32 v116, v115
	s_nop 1
	v_permlane32_swap_b32_e32 v115, v116
	s_and_saveexec_b64 s[50:51], s[38:39]
	s_cbranch_execz .LBB0_477
	v_mov_b32_e32 v169, v49
	v_lshl_add_u64 v[118:119], v[168:169], 2, s[22:23]
	v_add_f32_e32 v115, v115, v116
	global_store_dword v[118:119], v115, off

.LBB0_836:
	s_or_b32 s24, s44, s91
	v_mad_u64_u32 v[0:1], s[6:7], s24, v211, v[16:17]
	s_or_b32 s6, s24, 1
	s_nop 0
	v_mad_u64_u32 v[2:3], s[6:7], s6, v211, v[16:17]
	s_or_b32 s6, s24, 2
	s_nop 0
	v_mad_u64_u32 v[4:5], s[6:7], s6, v211, v[16:17]
	s_or_b32 s6, s24, 3
	s_nop 0
	v_mad_u64_u32 v[6:7], s[6:7], s6, v211, v[16:17]
	s_or_b32 s6, s24, 4
	s_nop 0
	v_mad_u64_u32 v[8:9], s[6:7], s6, v211, v[16:17]
	s_or_b32 s6, s24, 5
	s_nop 0
	v_mad_u64_u32 v[10:11], s[6:7], s6, v211, v[16:17]
	s_or_b32 s6, s24, 6
	s_nop 0
	v_mad_u64_u32 v[22:23], s[6:7], s6, v211, v[16:17]
	s_or_b32 s6, s24, 7
	s_nop 0
	v_mad_u64_u32 v[24:25], s[6:7], s6, v211, v[16:17]
	s_or_b32 s6, s24, 8
	s_nop 0
	v_mad_u64_u32 v[26:27], s[6:7], s6, v211, v[16:17]
	s_or_b32 s6, s24, 9
	s_nop 0
	v_mad_u64_u32 v[28:29], s[6:7], s6, v211, v[16:17]
	s_or_b32 s6, s24, 10
	s_nop 0
	v_mad_u64_u32 v[30:31], s[6:7], s6, v211, v[16:17]
	s_or_b32 s6, s24, 11
	s_nop 0
	v_mad_u64_u32 v[32:33], s[6:7], s6, v211, v[16:17]
	s_or_b32 s6, s24, 12
	s_nop 0
	v_mad_u64_u32 v[34:35], s[6:7], s6, v211, v[16:17]
	s_or_b32 s6, s24, 13
	s_nop 0
	v_mad_u64_u32 v[36:37], s[6:7], s6, v211, v[16:17]
	s_or_b32 s6, s24, 14
	s_nop 0
	v_mad_u64_u32 v[38:39], s[6:7], s6, v211, v[16:17]
	s_or_b32 s6, s24, 15
	s_nop 0
	v_mad_u64_u32 v[40:41], s[6:7], s6, v211, v[16:17]
	s_or_b32 s6, s24, 16
	s_nop 0
	v_mad_u64_u32 v[42:43], s[6:7], s6, v211, v[16:17]
	s_or_b32 s6, s24, 17
	s_nop 0
	v_mad_u64_u32 v[44:45], s[6:7], s6, v211, v[16:17]
	s_or_b32 s6, s24, 18
	s_nop 0
	v_mad_u64_u32 v[46:47], s[6:7], s6, v211, v[16:17]
	s_or_b32 s6, s24, 19
	s_nop 0
	v_mad_u64_u32 v[50:51], s[6:7], s6, v211, v[16:17]
	s_or_b32 s6, s24, 20
	s_nop 0
	v_mad_u64_u32 v[52:53], s[6:7], s6, v211, v[16:17]
	s_or_b32 s6, s24, 21
	s_nop 0
	v_mad_u64_u32 v[54:55], s[6:7], s6, v211, v[16:17]
	s_or_b32 s6, s24, 22
	s_nop 0
	v_mad_u64_u32 v[56:57], s[6:7], s6, v211, v[16:17]
	s_or_b32 s6, s24, 23
	s_nop 0
	v_mad_u64_u32 v[58:59], s[6:7], s6, v211, v[16:17]
	s_or_b32 s6, s24, 24
	s_nop 0
	v_mad_u64_u32 v[60:61], s[6:7], s6, v211, v[16:17]
	s_or_b32 s6, s24, 25
	s_nop 0
	v_mad_u64_u32 v[62:63], s[6:7], s6, v211, v[16:17]
	s_or_b32 s6, s24, 26
	s_nop 0
	v_mad_u64_u32 v[64:65], s[6:7], s6, v211, v[16:17]
	s_or_b32 s6, s24, 27
	s_nop 0
	v_mad_u64_u32 v[66:67], s[6:7], s6, v211, v[16:17]
	s_or_b32 s6, s24, 28
	s_nop 0
	v_mad_u64_u32 v[68:69], s[6:7], s6, v211, v[16:17]
	s_or_b32 s6, s24, 29
	s_nop 0
	v_mad_u64_u32 v[70:71], s[6:7], s6, v211, v[16:17]
	s_or_b32 s6, s24, 30
	s_nop 0
	v_mad_u64_u32 v[72:73], s[6:7], s6, v211, v[16:17]
	s_or_b32 s6, s24, 31
	s_mul_i32 s8, s45, 0xc00
	v_mad_u64_u32 v[106:107], s[6:7], s6, v211, v[16:17]
	v_add_u32_e32 v107, s8, v107
	global_load_ushort v108, v[106:107], off offset:1856
	v_add_u32_e32 v1, s8, v1
	v_add_u32_e32 v3, s8, v3
	v_add_u32_e32 v5, s8, v5
	v_add_u32_e32 v7, s8, v7
	v_add_u32_e32 v9, s8, v9
	v_add_u32_e32 v11, s8, v11
	v_add_u32_e32 v23, s8, v23
	v_add_u32_e32 v25, s8, v25
	v_add_u32_e32 v27, s8, v27
	v_add_u32_e32 v29, s8, v29
	v_add_u32_e32 v31, s8, v31
	v_add_u32_e32 v33, s8, v33
	v_add_u32_e32 v35, s8, v35
	v_add_u32_e32 v37, s8, v37
	v_add_u32_e32 v39, s8, v39
	v_add_u32_e32 v41, s8, v41
	v_add_u32_e32 v43, s8, v43
	v_add_u32_e32 v45, s8, v45
	v_add_u32_e32 v47, s8, v47
	v_add_u32_e32 v51, s8, v51
	v_add_u32_e32 v53, s8, v53
	v_add_u32_e32 v55, s8, v55
	v_add_u32_e32 v57, s8, v57
	v_add_u32_e32 v59, s8, v59
	v_add_u32_e32 v61, s8, v61
	v_add_u32_e32 v63, s8, v63
	v_add_u32_e32 v65, s8, v65
	v_add_u32_e32 v67, s8, v67
	v_add_u32_e32 v69, s8, v69
	v_add_u32_e32 v71, s8, v71
	v_add_u32_e32 v73, s8, v73
	global_load_ushort v106, v[106:107], off offset:832
	v_readlane_b32 s6, v255, 37
	global_load_ushort v107, v[72:73], off offset:1856
	s_mul_i32 s6, s6, 0xf800
	global_load_ushort v72, v[72:73], off offset:832
	s_add_u32 s6, s54, s6
	global_load_ushort v73, v[70:71], off offset:1856
	s_addc_u32 s7, s55, 0
	global_load_ushort v70, v[70:71], off offset:832
	s_add_u32 s40, s56, s42
	global_load_ushort v71, v[68:69], off offset:1856
	s_addc_u32 s41, s57, s43
	global_load_ushort v68, v[68:69], off offset:832
	s_movk_i32 s8, 0xc00
	global_load_ushort v69, v[66:67], off offset:1856
	s_waitcnt vmcnt(8)
	v_lshlrev_b32_e32 v108, 16, v108
	global_load_ushort v66, v[66:67], off offset:832
	v_mul_f32_e32 v108, 0xbfb8aa3b, v108
	global_load_ushort v67, v[64:65], off offset:1856
	v_exp_f32_e32 v108, v108
	global_load_ushort v64, v[64:65], off offset:832
	v_add_f32_e32 v108, 1.0, v108
	global_load_ushort v65, v[62:63], off offset:1856
	v_rcp_f32_e32 v108, v108
	global_load_ushort v62, v[62:63], off offset:832
	s_waitcnt vmcnt(12)
	v_lshlrev_b32_e32 v106, 16, v106
	global_load_ushort v63, v[60:61], off offset:1856
	v_mul_f32_e32 v106, v108, v106
	global_load_ushort v60, v[60:61], off offset:832
	v_lshl_add_u64 v[108:109], s[6:7], 0, v[20:21]
	global_load_ushort v61, v[58:59], off offset:1856
	s_movk_i32 s6, 0x1000
	global_load_ushort v58, v[58:59], off offset:832
	v_add_co_u32_e32 v110, vcc, s6, v108
	global_load_ushort v59, v[56:57], off offset:1856
	s_nop 0
	v_addc_co_u32_e32 v111, vcc, 0, v109, vcc
	global_load_ushort v56, v[56:57], off offset:832
	s_movk_i32 s6, 0x2000
	global_load_ushort v57, v[54:55], off offset:1856
	v_add_co_u32_e32 v112, vcc, s6, v108
	global_load_ushort v54, v[54:55], off offset:832
	s_nop 0
	v_addc_co_u32_e32 v113, vcc, 0, v109, vcc
	global_load_ushort v55, v[52:53], off offset:1856
	s_movk_i32 s6, 0x3000
	global_load_ushort v52, v[52:53], off offset:832
	s_waitcnt vmcnt(19)
	v_lshlrev_b32_e32 v73, 16, v73
	global_load_ushort v53, v[50:51], off offset:1856
	s_waitcnt vmcnt(18)
	v_lshlrev_b32_e32 v71, 16, v71
	global_load_ushort v50, v[50:51], off offset:832
	s_waitcnt vmcnt(17)
	v_lshlrev_b32_e32 v69, 16, v69
	global_load_ushort v51, v[46:47], off offset:1856
	v_lshlrev_b32_e32 v107, 16, v107
	global_load_ushort v46, v[46:47], off offset:832
	v_mul_f32_e32 v73, 0xbfb8aa3b, v73
	global_load_ushort v47, v[44:45], off offset:1856
	v_mul_f32_e32 v71, 0xbfb8aa3b, v71
	global_load_ushort v44, v[44:45], off offset:832
	v_mul_f32_e32 v69, 0xbfb8aa3b, v69
	global_load_ushort v45, v[42:43], off offset:1856
	v_mul_f32_e32 v107, 0xbfb8aa3b, v107
	global_load_ushort v42, v[42:43], off offset:832
	v_exp_f32_e32 v73, v73
	global_load_ushort v43, v[40:41], off offset:1856
	v_exp_f32_e32 v71, v71
	global_load_ushort v40, v[40:41], off offset:832
	v_exp_f32_e32 v69, v69
	global_load_ushort v41, v[38:39], off offset:1856
	v_exp_f32_e32 v107, v107
	global_load_ushort v38, v[38:39], off offset:832
	v_add_f32_e32 v73, 1.0, v73
	global_load_ushort v39, v[36:37], off offset:1856
	v_add_f32_e32 v71, 1.0, v71
	global_load_ushort v36, v[36:37], off offset:832
	s_waitcnt vmcnt(27)
	v_lshlrev_b32_e32 v67, 16, v67
	global_load_ushort v37, v[34:35], off offset:1856
	v_mul_f32_e32 v67, 0xbfb8aa3b, v67
	global_load_ushort v34, v[34:35], off offset:832
	v_exp_f32_e32 v67, v67
	global_load_ushort v35, v[32:33], off offset:1856
	s_waitcnt vmcnt(28)
	v_lshlrev_b32_e32 v65, 16, v65
	global_load_ushort v32, v[32:33], off offset:832
	v_mul_f32_e32 v65, 0xbfb8aa3b, v65
	global_load_ushort v33, v[30:31], off offset:1856
	v_exp_f32_e32 v65, v65
	global_load_ushort v30, v[30:31], off offset:832
	v_add_f32_e32 v69, 1.0, v69
	global_load_ushort v31, v[28:29], off offset:1856
	v_add_f32_e32 v67, 1.0, v67
	global_load_ushort v28, v[28:29], off offset:832
	v_add_f32_e32 v65, 1.0, v65
	global_load_ushort v29, v[26:27], off offset:1856
	v_add_f32_e32 v107, 1.0, v107
	global_load_ushort v26, v[26:27], off offset:832
	v_rcp_f32_e32 v73, v73
	global_load_ushort v27, v[24:25], off offset:1856
	v_rcp_f32_e32 v71, v71
	global_load_ushort v24, v[24:25], off offset:832
	v_rcp_f32_e32 v69, v69
	global_load_ushort v25, v[22:23], off offset:1856
	v_rcp_f32_e32 v67, v67
	global_load_ushort v22, v[22:23], off offset:832
	v_rcp_f32_e32 v65, v65
	global_load_ushort v23, v[10:11], off offset:1856
	s_waitcnt vmcnt(38)
	v_lshlrev_b32_e32 v63, 16, v63
	global_load_ushort v10, v[10:11], off offset:832
	v_mul_f32_e32 v63, 0xbfb8aa3b, v63
	global_load_ushort v11, v[8:9], off offset:1856
	s_waitcnt vmcnt(38)
	v_lshlrev_b32_e32 v61, 16, v61
	global_load_ushort v8, v[8:9], off offset:832
	v_mul_f32_e32 v61, 0xbfb8aa3b, v61
	global_load_ushort v9, v[6:7], off offset:1856
	s_waitcnt vmcnt(38)
	v_lshlrev_b32_e32 v59, 16, v59
	global_load_ushort v6, v[6:7], off offset:832
	v_mul_f32_e32 v59, 0xbfb8aa3b, v59
	global_load_ushort v7, v[4:5], off offset:1856
	v_exp_f32_e32 v63, v63
	global_load_ushort v4, v[4:5], off offset:832
	s_waitcnt vmcnt(39)
	v_lshlrev_b32_e32 v57, 16, v57
	global_load_ushort v5, v[2:3], off offset:1856
	v_mul_f32_e32 v57, 0xbfb8aa3b, v57
	global_load_ushort v2, v[2:3], off offset:832
	v_exp_f32_e32 v61, v61
	global_load_ushort v3, v[0:1], off offset:1856
	s_waitcnt vmcnt(40)
	v_lshlrev_b32_e32 v55, 16, v55
	global_load_ushort v0, v[0:1], off offset:832
	v_mul_f32_e32 v55, 0xbfb8aa3b, v55
	s_waitcnt vmcnt(39)
	v_lshlrev_b32_e32 v53, 16, v53
	v_mul_f32_e32 v53, 0xbfb8aa3b, v53
	v_exp_f32_e32 v55, v55
	v_exp_f32_e32 v53, v53
	s_waitcnt vmcnt(37)
	v_lshlrev_b32_e32 v51, 16, v51
	v_mul_f32_e32 v51, 0xbfb8aa3b, v51
	v_exp_f32_e32 v51, v51
	v_exp_f32_e32 v59, v59
	s_waitcnt vmcnt(35)
	v_lshlrev_b32_e32 v47, 16, v47
	v_mul_f32_e32 v47, 0xbfb8aa3b, v47
	v_exp_f32_e32 v47, v47
	v_exp_f32_e32 v57, v57
	s_waitcnt vmcnt(33)
	v_lshlrev_b32_e32 v45, 16, v45
	v_mul_f32_e32 v45, 0xbfb8aa3b, v45
	v_exp_f32_e32 v45, v45
	v_add_f32_e32 v55, 1.0, v55
	s_waitcnt vmcnt(31)
	v_lshlrev_b32_e32 v43, 16, v43
	v_mul_f32_e32 v43, 0xbfb8aa3b, v43
	v_exp_f32_e32 v43, v43
	v_add_f32_e32 v45, 1.0, v45
	s_waitcnt vmcnt(29)
	v_lshlrev_b32_e32 v41, 16, v41
	v_mul_f32_e32 v41, 0xbfb8aa3b, v41
	v_exp_f32_e32 v41, v41
	v_add_f32_e32 v43, 1.0, v43
	s_waitcnt vmcnt(27)
	v_lshlrev_b32_e32 v39, 16, v39
	v_mul_f32_e32 v39, 0xbfb8aa3b, v39
	v_exp_f32_e32 v39, v39
	v_add_f32_e32 v41, 1.0, v41
	s_waitcnt vmcnt(25)
	v_lshlrev_b32_e32 v37, 16, v37
	v_mul_f32_e32 v37, 0xbfb8aa3b, v37
	v_exp_f32_e32 v37, v37
	s_waitcnt vmcnt(24)
	v_lshlrev_b32_e32 v34, 16, v34
	s_waitcnt vmcnt(23)
	v_lshlrev_b32_e32 v35, 16, v35
	v_mul_f32_e32 v35, 0xbfb8aa3b, v35
	v_add_f32_e32 v37, 1.0, v37
	v_rcp_f32_e32 v37, v37
	s_waitcnt vmcnt(21)
	v_lshlrev_b32_e32 v33, 16, v33
	v_mul_f32_e32 v33, 0xbfb8aa3b, v33
	v_exp_f32_e32 v35, v35
	v_exp_f32_e32 v33, v33
	s_waitcnt vmcnt(19)
	v_lshlrev_b32_e32 v31, 16, v31
	v_mul_f32_e32 v31, 0xbfb8aa3b, v31
	v_exp_f32_e32 v31, v31
	v_mul_f32_e32 v34, v37, v34
	s_waitcnt vmcnt(17)
	v_lshlrev_b32_e32 v29, 16, v29
	v_mul_f32_e32 v29, 0xbfb8aa3b, v29
	v_exp_f32_e32 v29, v29
	v_add_f32_e32 v35, 1.0, v35
	s_waitcnt vmcnt(15)
	v_lshlrev_b32_e32 v27, 16, v27
	v_mul_f32_e32 v27, 0xbfb8aa3b, v27
	v_exp_f32_e32 v27, v27
	v_add_f32_e32 v33, 1.0, v33
	s_waitcnt vmcnt(13)
	v_lshlrev_b32_e32 v25, 16, v25
	v_mul_f32_e32 v25, 0xbfb8aa3b, v25
	v_exp_f32_e32 v25, v25
	v_add_f32_e32 v27, 1.0, v27
	s_waitcnt vmcnt(11)
	v_lshlrev_b32_e32 v23, 16, v23
	v_mul_f32_e32 v23, 0xbfb8aa3b, v23
	v_exp_f32_e32 v23, v23
	v_add_f32_e32 v25, 1.0, v25
	s_waitcnt vmcnt(9)
	v_lshlrev_b32_e32 v11, 16, v11
	v_mul_f32_e32 v11, 0xbfb8aa3b, v11
	v_exp_f32_e32 v11, v11
	v_add_f32_e32 v23, 1.0, v23
	s_waitcnt vmcnt(7)
	v_lshlrev_b32_e32 v9, 16, v9
	v_mul_f32_e32 v9, 0xbfb8aa3b, v9
	v_exp_f32_e32 v9, v9
	v_add_f32_e32 v11, 1.0, v11
	s_waitcnt vmcnt(5)
	v_lshlrev_b32_e32 v7, 16, v7
	v_mul_f32_e32 v7, 0xbfb8aa3b, v7
	v_exp_f32_e32 v7, v7
	v_add_f32_e32 v9, 1.0, v9
	s_waitcnt vmcnt(3)
	v_lshlrev_b32_e32 v5, 16, v5
	v_mul_f32_e32 v5, 0xbfb8aa3b, v5
	v_exp_f32_e32 v5, v5
	v_add_f32_e32 v7, 1.0, v7
	s_waitcnt vmcnt(1)
	v_lshlrev_b32_e32 v3, 16, v3
	v_mul_f32_e32 v3, 0xbfb8aa3b, v3
	v_exp_f32_e32 v3, v3
	v_add_f32_e32 v5, 1.0, v5
	v_rcp_f32_e32 v9, v9
	v_rcp_f32_e32 v7, v7
	v_add_f32_e32 v3, 1.0, v3
	v_rcp_f32_e32 v5, v5
	v_rcp_f32_e32 v3, v3
	v_lshlrev_b32_e32 v6, 16, v6
	v_lshlrev_b32_e32 v4, 16, v4
	v_lshlrev_b32_e32 v2, 16, v2
	s_waitcnt vmcnt(0)
	v_lshlrev_b32_e32 v0, 16, v0
	v_rcp_f32_e32 v27, v27
	v_rcp_f32_e32 v25, v25
	v_rcp_f32_e32 v23, v23
	v_rcp_f32_e32 v11, v11
	v_mul_f32_e32 v6, v9, v6
	v_mul_f32_e32 v4, v7, v4
	v_mul_f32_e32 v2, v5, v2
	v_mul_f32_e32 v37, v3, v0
	global_load_dword v0, v[108:109], off
	global_load_dword v1, v[108:109], off offset:2048
	global_load_dword v3, v[112:113], off offset:-4096
	global_load_dword v5, v[110:111], off offset:2048
	global_load_dword v7, v[112:113], off
	global_load_dword v9, v[112:113], off offset:2048
	v_add_co_u32_e32 v110, vcc, s6, v108
	s_movk_i32 s6, 0x4000
	s_nop 0
	v_addc_co_u32_e32 v111, vcc, 0, v109, vcc
	v_add_co_u32_e32 v112, vcc, s6, v108
	v_add_f32_e32 v31, 1.0, v31
	v_add_f32_e32 v29, 1.0, v29
	v_lshlrev_b32_e32 v24, 16, v24
	v_lshlrev_b32_e32 v22, 16, v22
	v_lshlrev_b32_e32 v10, 16, v10
	v_lshlrev_b32_e32 v8, 16, v8
	v_addc_co_u32_e32 v113, vcc, 0, v109, vcc
	s_movk_i32 s6, 0x5000
	v_rcp_f32_e32 v35, v35
	v_rcp_f32_e32 v33, v33
	v_rcp_f32_e32 v31, v31
	v_rcp_f32_e32 v29, v29
	v_mul_f32_e32 v24, v27, v24
	v_mul_f32_e32 v22, v25, v22
	v_mul_f32_e32 v10, v23, v10
	v_mul_f32_e32 v8, v11, v8
	global_load_dword v11, v[112:113], off offset:-4096
	global_load_dword v23, v[110:111], off offset:2048
	global_load_dword v25, v[112:113], off
	global_load_dword v27, v[112:113], off offset:2048
	v_add_co_u32_e32 v110, vcc, s6, v108
	s_movk_i32 s6, 0x6000
	s_nop 0
	v_addc_co_u32_e32 v111, vcc, 0, v109, vcc
	v_add_co_u32_e32 v112, vcc, s6, v108
	v_add_f32_e32 v39, 1.0, v39
	v_lshlrev_b32_e32 v32, 16, v32
	v_lshlrev_b32_e32 v30, 16, v30
	v_lshlrev_b32_e32 v28, 16, v28
	v_lshlrev_b32_e32 v26, 16, v26
	v_addc_co_u32_e32 v113, vcc, 0, v109, vcc
	s_movk_i32 s6, 0x7000
	v_rcp_f32_e32 v45, v45
	v_rcp_f32_e32 v43, v43
	v_rcp_f32_e32 v41, v41
	v_rcp_f32_e32 v39, v39
	v_mul_f32_e32 v32, v35, v32
	v_mul_f32_e32 v30, v33, v30
	v_mul_f32_e32 v28, v31, v28
	v_mul_f32_e32 v26, v29, v26
	global_load_dword v29, v[112:113], off offset:-4096
	global_load_dword v31, v[110:111], off offset:2048
	global_load_dword v33, v[112:113], off
	global_load_dword v35, v[112:113], off offset:2048
	v_add_co_u32_e32 v110, vcc, s6, v108
	s_mov_b32 s6, 0x8000
	s_nop 0
	v_addc_co_u32_e32 v111, vcc, 0, v109, vcc
	v_add_co_u32_e32 v112, vcc, s6, v108
	v_add_f32_e32 v53, 1.0, v53
	v_add_f32_e32 v51, 1.0, v51
	v_add_f32_e32 v47, 1.0, v47
	v_lshlrev_b32_e32 v42, 16, v42
	v_lshlrev_b32_e32 v40, 16, v40
	v_lshlrev_b32_e32 v38, 16, v38
	v_lshlrev_b32_e32 v36, 16, v36
	v_addc_co_u32_e32 v113, vcc, 0, v109, vcc
	s_mov_b32 s6, 0x9000
	v_rcp_f32_e32 v55, v55
	v_rcp_f32_e32 v53, v53
	v_rcp_f32_e32 v51, v51
	v_rcp_f32_e32 v47, v47
	v_mul_f32_e32 v42, v45, v42
	v_mul_f32_e32 v40, v43, v40
	v_mul_f32_e32 v38, v41, v38
	v_mul_f32_e32 v36, v39, v36
	global_load_dword v39, v[112:113], off offset:-4096
	global_load_dword v41, v[110:111], off offset:2048
	global_load_dword v43, v[112:113], off
	global_load_dword v45, v[112:113], off offset:2048
	v_add_co_u32_e32 v110, vcc, s6, v108
	s_mov_b32 s6, 0xa000
	s_nop 0
	v_addc_co_u32_e32 v111, vcc, 0, v109, vcc
	v_add_co_u32_e32 v112, vcc, s6, v108
	v_add_f32_e32 v63, 1.0, v63
	v_add_f32_e32 v61, 1.0, v61
	v_add_f32_e32 v59, 1.0, v59
	v_add_f32_e32 v57, 1.0, v57
	v_lshlrev_b32_e32 v52, 16, v52
	v_lshlrev_b32_e32 v50, 16, v50
	v_lshlrev_b32_e32 v46, 16, v46
	v_lshlrev_b32_e32 v44, 16, v44
	v_addc_co_u32_e32 v113, vcc, 0, v109, vcc
	s_mov_b32 s6, 0xb000
	v_rcp_f32_e32 v63, v63
	v_rcp_f32_e32 v61, v61
	v_rcp_f32_e32 v59, v59
	v_rcp_f32_e32 v57, v57
	v_mul_f32_e32 v52, v55, v52
	v_mul_f32_e32 v50, v53, v50
	v_mul_f32_e32 v46, v51, v46
	v_mul_f32_e32 v44, v47, v44
	global_load_dword v47, v[112:113], off offset:-4096
	global_load_dword v51, v[110:111], off offset:2048
	global_load_dword v53, v[112:113], off
	global_load_dword v55, v[112:113], off offset:2048
	v_add_co_u32_e32 v110, vcc, s6, v108
	s_mov_b32 s6, 0xc000
	s_nop 0
	v_addc_co_u32_e32 v111, vcc, 0, v109, vcc
	v_add_co_u32_e32 v112, vcc, s6, v108
	v_lshlrev_b32_e32 v60, 16, v60
	v_lshlrev_b32_e32 v58, 16, v58
	v_lshlrev_b32_e32 v56, 16, v56
	v_lshlrev_b32_e32 v54, 16, v54
	v_addc_co_u32_e32 v113, vcc, 0, v109, vcc
	s_mov_b32 s6, 0xd000
	v_mul_f32_e32 v60, v63, v60
	v_mul_f32_e32 v58, v61, v58
	v_mul_f32_e32 v56, v59, v56
	v_mul_f32_e32 v54, v57, v54
	global_load_dword v57, v[112:113], off offset:-4096
	global_load_dword v59, v[110:111], off offset:2048
	global_load_dword v61, v[112:113], off
	global_load_dword v63, v[112:113], off offset:2048
	v_add_co_u32_e32 v110, vcc, s6, v108
	s_mov_b32 s6, 0xe000
	s_nop 0
	v_addc_co_u32_e32 v111, vcc, 0, v109, vcc
	v_add_co_u32_e32 v112, vcc, s6, v108
	v_rcp_f32_e32 v107, v107
	s_nop 0
	v_addc_co_u32_e32 v113, vcc, 0, v109, vcc
	s_mov_b32 s6, 0xf000
	v_add_co_u32_e32 v108, vcc, s6, v108
	s_add_u32 s6, s52, s42
	v_lshlrev_b32_e32 v70, 16, v70
	v_lshlrev_b32_e32 v68, 16, v68
	v_lshlrev_b32_e32 v66, 16, v66
	v_lshlrev_b32_e32 v64, 16, v64
	v_lshlrev_b32_e32 v62, 16, v62
	v_addc_co_u32_e32 v109, vcc, 0, v109, vcc
	s_addc_u32 s7, s53, s43
	v_lshlrev_b32_e32 v72, 16, v72
	v_mul_f32_e32 v70, v73, v70
	v_mul_f32_e32 v68, v71, v68
	v_mul_f32_e32 v66, v69, v66
	v_mul_f32_e32 v64, v67, v64
	v_mul_f32_e32 v62, v65, v62
	global_load_dword v65, v[112:113], off offset:-4096
	global_load_dword v67, v[110:111], off offset:2048
	global_load_dword v69, v[112:113], off
	global_load_dword v71, v[112:113], off offset:2048
	global_load_dword v73, v[108:109], off
	v_lshl_add_u64 v[108:109], s[6:7], 0, v[20:21]
	v_mul_f32_e32 v72, v107, v72
	global_load_dword v107, v[108:109], off
	s_add_u32 s50, s50, s42
	s_addc_u32 s51, s51, s43
	s_waitcnt vmcnt(0)
	v_fma_f32 v105, v105, v0, v107
	v_fmac_f32_e32 v105, v100, v1
	v_fma_f32 v100, v100, v0, v107
	v_fmac_f32_e32 v100, v104, v1
	v_fmac_f32_e32 v105, v104, v3
	v_fmac_f32_e32 v100, v98, v3
	v_fmac_f32_e32 v105, v98, v5
	v_fmac_f32_e32 v100, v103, v5
	v_fmac_f32_e32 v105, v103, v7
	v_fmac_f32_e32 v100, v96, v7
	v_fmac_f32_e32 v105, v96, v9
	v_fmac_f32_e32 v100, v102, v9
	v_fmac_f32_e32 v105, v102, v11
	v_fmac_f32_e32 v100, v94, v11
	v_fmac_f32_e32 v105, v94, v23
	v_fmac_f32_e32 v100, v101, v23
	v_fmac_f32_e32 v105, v101, v25
	v_fmac_f32_e32 v100, v92, v25
	v_fmac_f32_e32 v105, v92, v27
	v_fmac_f32_e32 v100, v99, v27
	v_fmac_f32_e32 v105, v99, v29
	v_fmac_f32_e32 v100, v90, v29
	v_fmac_f32_e32 v105, v90, v31
	v_fmac_f32_e32 v100, v97, v31
	v_fmac_f32_e32 v105, v97, v33
	v_fmac_f32_e32 v100, v88, v33
	v_fmac_f32_e32 v105, v88, v35
	v_fmac_f32_e32 v100, v95, v35
	v_fmac_f32_e32 v105, v95, v39
	v_fmac_f32_e32 v100, v86, v39
	v_fmac_f32_e32 v105, v86, v41
	v_fmac_f32_e32 v100, v93, v41
	v_fmac_f32_e32 v105, v93, v43
	v_fmac_f32_e32 v100, v84, v43
	v_fmac_f32_e32 v105, v84, v45
	v_fmac_f32_e32 v100, v91, v45
	v_fmac_f32_e32 v105, v91, v47
	v_fmac_f32_e32 v100, v82, v47
	v_fmac_f32_e32 v105, v82, v51
	v_fmac_f32_e32 v100, v89, v51
	v_fmac_f32_e32 v105, v89, v53
	v_fmac_f32_e32 v100, v80, v53
	v_fmac_f32_e32 v105, v80, v55
	v_fmac_f32_e32 v100, v87, v55
	v_fmac_f32_e32 v105, v87, v57
	v_fmac_f32_e32 v100, v79, v57
	v_fmac_f32_e32 v105, v79, v59
	v_fmac_f32_e32 v100, v85, v59
	v_fmac_f32_e32 v105, v85, v61
	v_fmac_f32_e32 v100, v78, v61
	v_fmac_f32_e32 v105, v78, v63
	v_fmac_f32_e32 v100, v83, v63
	v_fmac_f32_e32 v105, v83, v65
	v_fmac_f32_e32 v100, v77, v65
	v_fmac_f32_e32 v105, v77, v67
	v_fmac_f32_e32 v100, v81, v67
	v_fmac_f32_e32 v105, v81, v69
	v_fmac_f32_e32 v100, v48, v69
	v_fmac_f32_e32 v105, v48, v71
	v_fmac_f32_e32 v100, v37, v71
	v_fmac_f32_e32 v105, v37, v73
	v_fmac_f32_e32 v100, v2, v73
	ds_write2st64_b32 v15, v105, v100 offset1:8
	v_fma_f32 v100, v104, v0, v107
	v_fmac_f32_e32 v100, v98, v1
	v_fma_f32 v98, v98, v0, v107
	v_fmac_f32_e32 v98, v103, v1
	v_fmac_f32_e32 v100, v103, v3
	v_fmac_f32_e32 v98, v96, v3
	v_fmac_f32_e32 v100, v96, v5
	v_fmac_f32_e32 v98, v102, v5
	v_fmac_f32_e32 v100, v102, v7
	v_fmac_f32_e32 v98, v94, v7
	v_fmac_f32_e32 v100, v94, v9
	v_fmac_f32_e32 v98, v101, v9
	v_fmac_f32_e32 v100, v101, v11
	v_fmac_f32_e32 v98, v92, v11
	v_fmac_f32_e32 v100, v92, v23
	v_fmac_f32_e32 v98, v99, v23
	v_fmac_f32_e32 v100, v99, v25
	v_fmac_f32_e32 v98, v90, v25
	v_fmac_f32_e32 v100, v90, v27
	v_fmac_f32_e32 v98, v97, v27
	v_fmac_f32_e32 v100, v97, v29
	v_fmac_f32_e32 v98, v88, v29
	v_fmac_f32_e32 v100, v88, v31
	v_fmac_f32_e32 v98, v95, v31
	v_fmac_f32_e32 v100, v95, v33
	v_fmac_f32_e32 v98, v86, v33
	v_fmac_f32_e32 v100, v86, v35
	v_fmac_f32_e32 v98, v93, v35
	v_fmac_f32_e32 v100, v93, v39
	v_fmac_f32_e32 v98, v84, v39
	v_fmac_f32_e32 v100, v84, v41
	v_fmac_f32_e32 v98, v91, v41
	v_fmac_f32_e32 v100, v91, v43
	v_fmac_f32_e32 v98, v82, v43
	v_fmac_f32_e32 v100, v82, v45
	v_fmac_f32_e32 v98, v89, v45
	v_fmac_f32_e32 v100, v89, v47
	v_fmac_f32_e32 v98, v80, v47
	v_fmac_f32_e32 v100, v80, v51
	v_fmac_f32_e32 v98, v87, v51
	v_fmac_f32_e32 v100, v87, v53
	v_fmac_f32_e32 v98, v79, v53
	v_fmac_f32_e32 v100, v79, v55
	v_fmac_f32_e32 v98, v85, v55
	v_fmac_f32_e32 v100, v85, v57
	v_fmac_f32_e32 v98, v78, v57
	v_fmac_f32_e32 v100, v78, v59
	v_fmac_f32_e32 v98, v83, v59
	v_fmac_f32_e32 v100, v83, v61
	v_fmac_f32_e32 v98, v77, v61
	v_fmac_f32_e32 v100, v77, v63
	v_fmac_f32_e32 v98, v81, v63
	v_fmac_f32_e32 v100, v81, v65
	v_fmac_f32_e32 v98, v48, v65
	v_fmac_f32_e32 v100, v48, v67
	v_fmac_f32_e32 v98, v37, v67
	v_fmac_f32_e32 v100, v37, v69
	v_fmac_f32_e32 v98, v2, v69
	v_fmac_f32_e32 v100, v2, v71
	v_fmac_f32_e32 v98, v4, v71
	v_fmac_f32_e32 v100, v4, v73
	v_fmac_f32_e32 v98, v6, v73
	ds_write2st64_b32 v15, v100, v98 offset0:16 offset1:24
	v_fma_f32 v98, v103, v0, v107
	v_fmac_f32_e32 v98, v96, v1
	v_fma_f32 v96, v96, v0, v107
	v_fmac_f32_e32 v96, v102, v1
	v_fmac_f32_e32 v98, v102, v3
	v_fmac_f32_e32 v96, v94, v3
	v_fmac_f32_e32 v98, v94, v5
	v_fmac_f32_e32 v96, v101, v5
	v_fmac_f32_e32 v98, v101, v7
	v_fmac_f32_e32 v96, v92, v7
	v_fmac_f32_e32 v98, v92, v9
	v_fmac_f32_e32 v96, v99, v9
	v_fmac_f32_e32 v98, v99, v11
	v_fmac_f32_e32 v96, v90, v11
	v_fmac_f32_e32 v98, v90, v23
	v_fmac_f32_e32 v96, v97, v23
	v_fmac_f32_e32 v98, v97, v25
	v_fmac_f32_e32 v96, v88, v25
	v_fmac_f32_e32 v98, v88, v27
	v_fmac_f32_e32 v96, v95, v27
	v_fmac_f32_e32 v98, v95, v29
	v_fmac_f32_e32 v96, v86, v29
	v_fmac_f32_e32 v98, v86, v31
	v_fmac_f32_e32 v96, v93, v31
	v_fmac_f32_e32 v98, v93, v33
	v_fmac_f32_e32 v96, v84, v33
	v_fmac_f32_e32 v98, v84, v35
	v_fmac_f32_e32 v96, v91, v35
	v_fmac_f32_e32 v98, v91, v39
	v_fmac_f32_e32 v96, v82, v39
	v_fmac_f32_e32 v98, v82, v41
	v_fmac_f32_e32 v96, v89, v41
	v_fmac_f32_e32 v98, v89, v43
	v_fmac_f32_e32 v96, v80, v43
	v_fmac_f32_e32 v98, v80, v45
	v_fmac_f32_e32 v96, v87, v45
	v_fmac_f32_e32 v98, v87, v47
	v_fmac_f32_e32 v96, v79, v47
	v_fmac_f32_e32 v98, v79, v51
	v_fmac_f32_e32 v96, v85, v51
	v_fmac_f32_e32 v98, v85, v53
	v_fmac_f32_e32 v96, v78, v53
	v_fmac_f32_e32 v98, v78, v55
	v_fmac_f32_e32 v96, v83, v55
	v_fmac_f32_e32 v98, v83, v57
	v_fmac_f32_e32 v96, v77, v57
	v_fmac_f32_e32 v98, v77, v59
	v_fmac_f32_e32 v96, v81, v59
	v_fmac_f32_e32 v98, v81, v61
	v_fmac_f32_e32 v96, v48, v61
	v_fmac_f32_e32 v98, v48, v63
	v_fmac_f32_e32 v96, v37, v63
	v_fmac_f32_e32 v98, v37, v65
	v_fmac_f32_e32 v96, v2, v65
	v_fmac_f32_e32 v98, v2, v67
	v_fmac_f32_e32 v96, v4, v67
	v_fmac_f32_e32 v98, v4, v69
	v_fmac_f32_e32 v96, v6, v69
	v_fmac_f32_e32 v98, v6, v71
	v_fmac_f32_e32 v96, v8, v71
	v_fmac_f32_e32 v98, v8, v73
	v_fmac_f32_e32 v96, v10, v73
	ds_write2st64_b32 v15, v98, v96 offset0:32 offset1:40
	v_fma_f32 v96, v102, v0, v107
	v_fmac_f32_e32 v96, v94, v1
	v_fma_f32 v94, v94, v0, v107
	v_fmac_f32_e32 v94, v101, v1
	v_fmac_f32_e32 v96, v101, v3
	v_fmac_f32_e32 v94, v92, v3
	v_fmac_f32_e32 v96, v92, v5
	v_fmac_f32_e32 v94, v99, v5
	v_fmac_f32_e32 v96, v99, v7
	v_fmac_f32_e32 v94, v90, v7
	v_fmac_f32_e32 v96, v90, v9
	v_fmac_f32_e32 v94, v97, v9
	v_fmac_f32_e32 v96, v97, v11
	v_fmac_f32_e32 v94, v88, v11
	v_fmac_f32_e32 v96, v88, v23
	v_fmac_f32_e32 v94, v95, v23
	v_fmac_f32_e32 v96, v95, v25
	v_fmac_f32_e32 v94, v86, v25
	v_fmac_f32_e32 v96, v86, v27
	v_fmac_f32_e32 v94, v93, v27
	v_fmac_f32_e32 v96, v93, v29
	v_fmac_f32_e32 v94, v84, v29
	v_fmac_f32_e32 v96, v84, v31
	v_fmac_f32_e32 v94, v91, v31
	v_fmac_f32_e32 v96, v91, v33
	v_fmac_f32_e32 v94, v82, v33
	v_fmac_f32_e32 v96, v82, v35
	v_fmac_f32_e32 v94, v89, v35
	v_fmac_f32_e32 v96, v89, v39
	v_fmac_f32_e32 v94, v80, v39
	v_fmac_f32_e32 v96, v80, v41
	v_fmac_f32_e32 v94, v87, v41
	v_fmac_f32_e32 v96, v87, v43
	v_fmac_f32_e32 v94, v79, v43
	v_fmac_f32_e32 v96, v79, v45
	v_fmac_f32_e32 v94, v85, v45
	v_fmac_f32_e32 v96, v85, v47
	v_fmac_f32_e32 v94, v78, v47
	v_fmac_f32_e32 v96, v78, v51
	v_fmac_f32_e32 v94, v83, v51
	v_fmac_f32_e32 v96, v83, v53
	v_fmac_f32_e32 v94, v77, v53
	v_fmac_f32_e32 v96, v77, v55
	v_fmac_f32_e32 v94, v81, v55
	v_fmac_f32_e32 v96, v81, v57
	v_fmac_f32_e32 v94, v48, v57
	v_fmac_f32_e32 v96, v48, v59
	v_fmac_f32_e32 v94, v37, v59
	v_fmac_f32_e32 v96, v37, v61
	v_fmac_f32_e32 v94, v2, v61
	v_fmac_f32_e32 v96, v2, v63
	v_fmac_f32_e32 v94, v4, v63
	v_fmac_f32_e32 v96, v4, v65
	v_fmac_f32_e32 v94, v6, v65
	v_fmac_f32_e32 v96, v6, v67
	v_fmac_f32_e32 v94, v8, v67
	v_fmac_f32_e32 v96, v8, v69
	v_fmac_f32_e32 v94, v10, v69
	v_fmac_f32_e32 v96, v10, v71
	v_fmac_f32_e32 v94, v22, v71
	v_fmac_f32_e32 v96, v22, v73
	v_fmac_f32_e32 v94, v24, v73
	ds_write2st64_b32 v15, v96, v94 offset0:48 offset1:56
	v_fma_f32 v94, v101, v0, v107
	v_fmac_f32_e32 v94, v92, v1
	v_fma_f32 v92, v92, v0, v107
	v_fmac_f32_e32 v92, v99, v1
	v_fmac_f32_e32 v94, v99, v3
	v_fmac_f32_e32 v92, v90, v3
	v_fmac_f32_e32 v94, v90, v5
	v_fmac_f32_e32 v92, v97, v5
	v_fmac_f32_e32 v94, v97, v7
	v_fmac_f32_e32 v92, v88, v7
	v_fmac_f32_e32 v94, v88, v9
	v_fmac_f32_e32 v92, v95, v9
	v_fmac_f32_e32 v94, v95, v11
	v_fmac_f32_e32 v92, v86, v11
	v_fmac_f32_e32 v94, v86, v23
	v_fmac_f32_e32 v92, v93, v23
	v_fmac_f32_e32 v94, v93, v25
	v_fmac_f32_e32 v92, v84, v25
	v_fmac_f32_e32 v94, v84, v27
	v_fmac_f32_e32 v92, v91, v27
	v_fmac_f32_e32 v94, v91, v29
	v_fmac_f32_e32 v92, v82, v29
	v_fmac_f32_e32 v94, v82, v31
	v_fmac_f32_e32 v92, v89, v31
	v_fmac_f32_e32 v94, v89, v33
	v_fmac_f32_e32 v92, v80, v33
	v_fmac_f32_e32 v94, v80, v35
	v_fmac_f32_e32 v92, v87, v35
	v_fmac_f32_e32 v94, v87, v39
	v_fmac_f32_e32 v92, v79, v39
	v_fmac_f32_e32 v94, v79, v41
	v_fmac_f32_e32 v92, v85, v41
	v_fmac_f32_e32 v94, v85, v43
	v_fmac_f32_e32 v92, v78, v43
	v_fmac_f32_e32 v94, v78, v45
	v_fmac_f32_e32 v92, v83, v45
	v_fmac_f32_e32 v94, v83, v47
	v_fmac_f32_e32 v92, v77, v47
	v_fmac_f32_e32 v94, v77, v51
	v_fmac_f32_e32 v92, v81, v51
	v_fmac_f32_e32 v94, v81, v53
	v_fmac_f32_e32 v92, v48, v53
	v_fmac_f32_e32 v94, v48, v55
	v_fmac_f32_e32 v92, v37, v55
	v_fmac_f32_e32 v94, v37, v57
	v_fmac_f32_e32 v92, v2, v57
	v_fmac_f32_e32 v94, v2, v59
	v_fmac_f32_e32 v92, v4, v59
	v_fmac_f32_e32 v94, v4, v61
	v_fmac_f32_e32 v92, v6, v61
	v_fmac_f32_e32 v94, v6, v63
	v_fmac_f32_e32 v92, v8, v63
	v_fmac_f32_e32 v94, v8, v65
	v_fmac_f32_e32 v92, v10, v65
	v_fmac_f32_e32 v94, v10, v67
	v_fmac_f32_e32 v92, v22, v67
	v_fmac_f32_e32 v94, v22, v69
	v_fmac_f32_e32 v92, v24, v69
	v_fmac_f32_e32 v94, v24, v71
	v_fmac_f32_e32 v92, v26, v71
	v_fmac_f32_e32 v94, v26, v73
	v_fmac_f32_e32 v92, v28, v73
	ds_write2st64_b32 v15, v94, v92 offset0:64 offset1:72
	v_fma_f32 v92, v99, v0, v107
	v_fmac_f32_e32 v92, v90, v1
	v_fma_f32 v90, v90, v0, v107
	v_fmac_f32_e32 v90, v97, v1
	v_fmac_f32_e32 v92, v97, v3
	v_fmac_f32_e32 v90, v88, v3
	v_fmac_f32_e32 v92, v88, v5
	v_fmac_f32_e32 v90, v95, v5
	v_fmac_f32_e32 v92, v95, v7
	v_fmac_f32_e32 v90, v86, v7
	v_fmac_f32_e32 v92, v86, v9
	v_fmac_f32_e32 v90, v93, v9
	v_fmac_f32_e32 v92, v93, v11
	v_fmac_f32_e32 v90, v84, v11
	v_fmac_f32_e32 v92, v84, v23
	v_fmac_f32_e32 v90, v91, v23
	v_fmac_f32_e32 v92, v91, v25
	v_fmac_f32_e32 v90, v82, v25
	v_fmac_f32_e32 v92, v82, v27
	v_fmac_f32_e32 v90, v89, v27
	v_fmac_f32_e32 v92, v89, v29
	v_fmac_f32_e32 v90, v80, v29
	v_fmac_f32_e32 v92, v80, v31
	v_fmac_f32_e32 v90, v87, v31
	v_fmac_f32_e32 v92, v87, v33
	v_fmac_f32_e32 v90, v79, v33
	v_fmac_f32_e32 v92, v79, v35
	v_fmac_f32_e32 v90, v85, v35
	v_fmac_f32_e32 v92, v85, v39
	v_fmac_f32_e32 v90, v78, v39
	v_fmac_f32_e32 v92, v78, v41
	v_fmac_f32_e32 v90, v83, v41
	v_fmac_f32_e32 v92, v83, v43
	v_fmac_f32_e32 v90, v77, v43
	v_fmac_f32_e32 v92, v77, v45
	v_fmac_f32_e32 v90, v81, v45
	v_fmac_f32_e32 v92, v81, v47
	v_fmac_f32_e32 v90, v48, v47
	v_fmac_f32_e32 v92, v48, v51
	v_fmac_f32_e32 v90, v37, v51
	v_fmac_f32_e32 v92, v37, v53
	v_fmac_f32_e32 v90, v2, v53
	v_fmac_f32_e32 v92, v2, v55
	v_fmac_f32_e32 v90, v4, v55
	v_fmac_f32_e32 v92, v4, v57
	v_fmac_f32_e32 v90, v6, v57
	v_fmac_f32_e32 v92, v6, v59
	v_fmac_f32_e32 v90, v8, v59
	v_fmac_f32_e32 v92, v8, v61
	v_fmac_f32_e32 v90, v10, v61
	v_fmac_f32_e32 v92, v10, v63
	v_fmac_f32_e32 v90, v22, v63
	v_fmac_f32_e32 v92, v22, v65
	v_fmac_f32_e32 v90, v24, v65
	v_fmac_f32_e32 v92, v24, v67
	v_fmac_f32_e32 v90, v26, v67
	v_fmac_f32_e32 v92, v26, v69
	v_fmac_f32_e32 v90, v28, v69
	v_fmac_f32_e32 v92, v28, v71
	v_fmac_f32_e32 v90, v30, v71
	v_fmac_f32_e32 v92, v30, v73
	v_fmac_f32_e32 v90, v32, v73
	ds_write2st64_b32 v15, v92, v90 offset0:80 offset1:88
	v_fma_f32 v90, v97, v0, v107
	v_fmac_f32_e32 v90, v88, v1
	v_fma_f32 v88, v88, v0, v107
	v_fmac_f32_e32 v88, v95, v1
	v_fmac_f32_e32 v90, v95, v3
	v_fmac_f32_e32 v88, v86, v3
	v_fmac_f32_e32 v90, v86, v5
	v_fmac_f32_e32 v88, v93, v5
	v_fmac_f32_e32 v90, v93, v7
	v_fmac_f32_e32 v88, v84, v7
	v_fmac_f32_e32 v90, v84, v9
	v_fmac_f32_e32 v88, v91, v9
	v_fmac_f32_e32 v90, v91, v11
	v_fmac_f32_e32 v88, v82, v11
	v_fmac_f32_e32 v90, v82, v23
	v_fmac_f32_e32 v88, v89, v23
	v_fmac_f32_e32 v90, v89, v25
	v_fmac_f32_e32 v88, v80, v25
	v_fmac_f32_e32 v90, v80, v27
	v_fmac_f32_e32 v88, v87, v27
	v_fmac_f32_e32 v90, v87, v29
	v_fmac_f32_e32 v88, v79, v29
	v_fmac_f32_e32 v90, v79, v31
	v_fmac_f32_e32 v88, v85, v31
	v_fmac_f32_e32 v90, v85, v33
	v_fmac_f32_e32 v88, v78, v33
	v_fmac_f32_e32 v90, v78, v35
	v_fmac_f32_e32 v88, v83, v35
	v_fmac_f32_e32 v90, v83, v39
	v_fmac_f32_e32 v88, v77, v39
	v_fmac_f32_e32 v90, v77, v41
	v_fmac_f32_e32 v88, v81, v41
	v_fmac_f32_e32 v90, v81, v43
	v_fmac_f32_e32 v88, v48, v43
	v_fmac_f32_e32 v90, v48, v45
	v_fmac_f32_e32 v88, v37, v45
	v_fmac_f32_e32 v90, v37, v47
	v_fmac_f32_e32 v88, v2, v47
	v_fmac_f32_e32 v90, v2, v51
	v_fmac_f32_e32 v88, v4, v51
	v_fmac_f32_e32 v90, v4, v53
	v_fmac_f32_e32 v88, v6, v53
	v_fmac_f32_e32 v90, v6, v55
	v_fmac_f32_e32 v88, v8, v55
	v_fmac_f32_e32 v90, v8, v57
	v_fmac_f32_e32 v88, v10, v57
	v_fmac_f32_e32 v90, v10, v59
	v_fmac_f32_e32 v88, v22, v59
	v_fmac_f32_e32 v90, v22, v61
	v_fmac_f32_e32 v88, v24, v61
	v_fmac_f32_e32 v90, v24, v63
	v_fmac_f32_e32 v88, v26, v63
	v_fmac_f32_e32 v90, v26, v65
	v_fmac_f32_e32 v88, v28, v65
	v_fmac_f32_e32 v90, v28, v67
	v_fmac_f32_e32 v88, v30, v67
	v_fmac_f32_e32 v90, v30, v69
	v_fmac_f32_e32 v88, v32, v69
	v_fmac_f32_e32 v90, v32, v71
	v_fmac_f32_e32 v88, v34, v71
	v_fmac_f32_e32 v90, v34, v73
	v_fmac_f32_e32 v88, v36, v73
	ds_write2st64_b32 v15, v90, v88 offset0:96 offset1:104
	v_fma_f32 v88, v95, v0, v107
	v_fmac_f32_e32 v88, v86, v1
	v_fma_f32 v86, v86, v0, v107
	v_fmac_f32_e32 v86, v93, v1
	v_fmac_f32_e32 v88, v93, v3
	v_fmac_f32_e32 v86, v84, v3
	v_fmac_f32_e32 v88, v84, v5
	v_fmac_f32_e32 v86, v91, v5
	v_fmac_f32_e32 v88, v91, v7
	v_fmac_f32_e32 v86, v82, v7
	v_fmac_f32_e32 v88, v82, v9
	v_fmac_f32_e32 v86, v89, v9
	v_fmac_f32_e32 v88, v89, v11
	v_fmac_f32_e32 v86, v80, v11
	v_fmac_f32_e32 v88, v80, v23
	v_fmac_f32_e32 v86, v87, v23
	v_fmac_f32_e32 v88, v87, v25
	v_fmac_f32_e32 v86, v79, v25
	v_fmac_f32_e32 v88, v79, v27
	v_fmac_f32_e32 v86, v85, v27
	v_fmac_f32_e32 v88, v85, v29
	v_fmac_f32_e32 v86, v78, v29
	v_fmac_f32_e32 v88, v78, v31
	v_fmac_f32_e32 v86, v83, v31
	v_fmac_f32_e32 v88, v83, v33
	v_fmac_f32_e32 v86, v77, v33
	v_fmac_f32_e32 v88, v77, v35
	v_fmac_f32_e32 v86, v81, v35
	v_fmac_f32_e32 v88, v81, v39
	v_fmac_f32_e32 v86, v48, v39
	v_fmac_f32_e32 v88, v48, v41
	v_fmac_f32_e32 v86, v37, v41
	v_fmac_f32_e32 v88, v37, v43
	v_fmac_f32_e32 v86, v2, v43
	v_fmac_f32_e32 v88, v2, v45
	v_fmac_f32_e32 v86, v4, v45
	v_fmac_f32_e32 v88, v4, v47
	v_fmac_f32_e32 v86, v6, v47
	v_fmac_f32_e32 v88, v6, v51
	v_fmac_f32_e32 v86, v8, v51
	v_fmac_f32_e32 v88, v8, v53
	v_fmac_f32_e32 v86, v10, v53
	v_fmac_f32_e32 v88, v10, v55
	v_fmac_f32_e32 v86, v22, v55
	v_fmac_f32_e32 v88, v22, v57
	v_fmac_f32_e32 v86, v24, v57
	v_fmac_f32_e32 v88, v24, v59
	v_fmac_f32_e32 v86, v26, v59
	v_fmac_f32_e32 v88, v26, v61
	v_fmac_f32_e32 v86, v28, v61
	v_fmac_f32_e32 v88, v28, v63
	v_fmac_f32_e32 v86, v30, v63
	v_fmac_f32_e32 v88, v30, v65
	v_fmac_f32_e32 v86, v32, v65
	v_fmac_f32_e32 v88, v32, v67
	v_fmac_f32_e32 v86, v34, v67
	v_fmac_f32_e32 v88, v34, v69
	v_fmac_f32_e32 v86, v36, v69
	v_fmac_f32_e32 v88, v36, v71
	v_fmac_f32_e32 v86, v38, v71
	v_fmac_f32_e32 v88, v38, v73
	v_fmac_f32_e32 v86, v40, v73
	ds_write2st64_b32 v15, v88, v86 offset0:112 offset1:120
	v_fma_f32 v86, v93, v0, v107
	v_fmac_f32_e32 v86, v84, v1
	v_fma_f32 v84, v84, v0, v107
	v_fmac_f32_e32 v84, v91, v1
	v_fmac_f32_e32 v86, v91, v3
	v_fmac_f32_e32 v84, v82, v3
	v_fmac_f32_e32 v86, v82, v5
	v_fmac_f32_e32 v84, v89, v5
	v_fmac_f32_e32 v86, v89, v7
	v_fmac_f32_e32 v84, v80, v7
	v_fmac_f32_e32 v86, v80, v9
	v_fmac_f32_e32 v84, v87, v9
	v_fmac_f32_e32 v86, v87, v11
	v_fmac_f32_e32 v84, v79, v11
	v_fmac_f32_e32 v86, v79, v23
	v_fmac_f32_e32 v84, v85, v23
	v_fmac_f32_e32 v86, v85, v25
	v_fmac_f32_e32 v84, v78, v25
	v_fmac_f32_e32 v86, v78, v27
	v_fmac_f32_e32 v84, v83, v27
	v_fmac_f32_e32 v86, v83, v29
	v_fmac_f32_e32 v84, v77, v29
	v_fmac_f32_e32 v86, v77, v31
	v_fmac_f32_e32 v84, v81, v31
	v_fmac_f32_e32 v86, v81, v33
	v_fmac_f32_e32 v84, v48, v33
	v_fmac_f32_e32 v86, v48, v35
	v_fmac_f32_e32 v84, v37, v35
	v_fmac_f32_e32 v86, v37, v39
	v_fmac_f32_e32 v84, v2, v39
	v_fmac_f32_e32 v86, v2, v41
	v_fmac_f32_e32 v84, v4, v41
	v_fmac_f32_e32 v86, v4, v43
	v_fmac_f32_e32 v84, v6, v43
	v_fmac_f32_e32 v86, v6, v45
	v_fmac_f32_e32 v84, v8, v45
	v_fmac_f32_e32 v86, v8, v47
	v_fmac_f32_e32 v84, v10, v47
	v_fmac_f32_e32 v86, v10, v51
	v_fmac_f32_e32 v84, v22, v51
	v_fmac_f32_e32 v86, v22, v53
	v_fmac_f32_e32 v84, v24, v53
	v_fmac_f32_e32 v86, v24, v55
	v_fmac_f32_e32 v84, v26, v55
	v_fmac_f32_e32 v86, v26, v57
	v_fmac_f32_e32 v84, v28, v57
	v_fmac_f32_e32 v86, v28, v59
	v_fmac_f32_e32 v84, v30, v59
	v_fmac_f32_e32 v86, v30, v61
	v_fmac_f32_e32 v84, v32, v61
	v_fmac_f32_e32 v86, v32, v63
	v_fmac_f32_e32 v84, v34, v63
	v_fmac_f32_e32 v86, v34, v65
	v_fmac_f32_e32 v84, v36, v65
	v_fmac_f32_e32 v86, v36, v67
	v_fmac_f32_e32 v84, v38, v67
	v_fmac_f32_e32 v86, v38, v69
	v_fmac_f32_e32 v84, v40, v69
	v_fmac_f32_e32 v86, v40, v71
	v_fmac_f32_e32 v84, v42, v71
	v_fmac_f32_e32 v86, v42, v73
	v_fmac_f32_e32 v84, v44, v73
	ds_write2st64_b32 v15, v86, v84 offset0:128 offset1:136
	v_fma_f32 v84, v91, v0, v107
	v_fmac_f32_e32 v84, v82, v1
	v_fma_f32 v82, v82, v0, v107
	v_fmac_f32_e32 v82, v89, v1
	v_fmac_f32_e32 v84, v89, v3
	v_fmac_f32_e32 v82, v80, v3
	v_fmac_f32_e32 v84, v80, v5
	v_fmac_f32_e32 v82, v87, v5
	v_fmac_f32_e32 v84, v87, v7
	v_fmac_f32_e32 v82, v79, v7
	v_fmac_f32_e32 v84, v79, v9
	v_fmac_f32_e32 v82, v85, v9
	v_fmac_f32_e32 v84, v85, v11
	v_fmac_f32_e32 v82, v78, v11
	v_fmac_f32_e32 v84, v78, v23
	v_fmac_f32_e32 v82, v83, v23
	v_fmac_f32_e32 v84, v83, v25
	v_fmac_f32_e32 v82, v77, v25
	v_fmac_f32_e32 v84, v77, v27
	v_fmac_f32_e32 v82, v81, v27
	v_fmac_f32_e32 v84, v81, v29
	v_fmac_f32_e32 v82, v48, v29
	v_fmac_f32_e32 v84, v48, v31
	v_fmac_f32_e32 v82, v37, v31
	v_fmac_f32_e32 v84, v37, v33
	v_fmac_f32_e32 v82, v2, v33
	v_fmac_f32_e32 v84, v2, v35
	v_fmac_f32_e32 v82, v4, v35
	v_fmac_f32_e32 v84, v4, v39
	v_fmac_f32_e32 v82, v6, v39
	v_fmac_f32_e32 v84, v6, v41
	v_fmac_f32_e32 v82, v8, v41
	v_fmac_f32_e32 v84, v8, v43
	v_fmac_f32_e32 v82, v10, v43
	v_fmac_f32_e32 v84, v10, v45
	v_fmac_f32_e32 v82, v22, v45
	v_fmac_f32_e32 v84, v22, v47
	v_fmac_f32_e32 v82, v24, v47
	v_fmac_f32_e32 v84, v24, v51
	v_fmac_f32_e32 v82, v26, v51
	v_fmac_f32_e32 v84, v26, v53
	v_fmac_f32_e32 v82, v28, v53
	v_fmac_f32_e32 v84, v28, v55
	v_fmac_f32_e32 v82, v30, v55
	v_fmac_f32_e32 v84, v30, v57
	v_fmac_f32_e32 v82, v32, v57
	v_fmac_f32_e32 v84, v32, v59
	v_fmac_f32_e32 v82, v34, v59
	v_fmac_f32_e32 v84, v34, v61
	v_fmac_f32_e32 v82, v36, v61
	v_fmac_f32_e32 v84, v36, v63
	v_fmac_f32_e32 v82, v38, v63
	v_fmac_f32_e32 v84, v38, v65
	v_fmac_f32_e32 v82, v40, v65
	v_fmac_f32_e32 v84, v40, v67
	v_fmac_f32_e32 v82, v42, v67
	v_fmac_f32_e32 v84, v42, v69
	v_fmac_f32_e32 v82, v44, v69
	v_fmac_f32_e32 v84, v44, v71
	v_fmac_f32_e32 v82, v46, v71
	v_fmac_f32_e32 v84, v46, v73
	v_fmac_f32_e32 v82, v50, v73
	ds_write2st64_b32 v15, v84, v82 offset0:144 offset1:152
	v_fma_f32 v82, v89, v0, v107
	v_fmac_f32_e32 v82, v80, v1
	v_fma_f32 v80, v80, v0, v107
	v_fmac_f32_e32 v80, v87, v1
	v_fmac_f32_e32 v82, v87, v3
	v_fmac_f32_e32 v80, v79, v3
	v_fmac_f32_e32 v82, v79, v5
	v_fmac_f32_e32 v80, v85, v5
	v_fmac_f32_e32 v82, v85, v7
	v_fmac_f32_e32 v80, v78, v7
	v_fmac_f32_e32 v82, v78, v9
	v_fmac_f32_e32 v80, v83, v9
	v_fmac_f32_e32 v82, v83, v11
	v_fmac_f32_e32 v80, v77, v11
	v_fmac_f32_e32 v82, v77, v23
	v_fmac_f32_e32 v80, v81, v23
	v_fmac_f32_e32 v82, v81, v25
	v_fmac_f32_e32 v80, v48, v25
	v_fmac_f32_e32 v82, v48, v27
	v_fmac_f32_e32 v80, v37, v27
	v_fmac_f32_e32 v82, v37, v29
	v_fmac_f32_e32 v80, v2, v29
	v_fmac_f32_e32 v82, v2, v31
	v_fmac_f32_e32 v80, v4, v31
	v_fmac_f32_e32 v82, v4, v33
	v_fmac_f32_e32 v80, v6, v33
	v_fmac_f32_e32 v82, v6, v35
	v_fmac_f32_e32 v80, v8, v35
	v_fmac_f32_e32 v82, v8, v39
	v_fmac_f32_e32 v80, v10, v39
	v_fmac_f32_e32 v82, v10, v41
	v_fmac_f32_e32 v80, v22, v41
	v_fmac_f32_e32 v82, v22, v43
	v_fmac_f32_e32 v80, v24, v43
	v_fmac_f32_e32 v82, v24, v45
	v_fmac_f32_e32 v80, v26, v45
	v_fmac_f32_e32 v82, v26, v47
	v_fmac_f32_e32 v80, v28, v47
	v_fmac_f32_e32 v82, v28, v51
	v_fmac_f32_e32 v80, v30, v51
	v_fmac_f32_e32 v82, v30, v53
	v_fmac_f32_e32 v80, v32, v53
	v_fmac_f32_e32 v82, v32, v55
	v_fmac_f32_e32 v80, v34, v55
	v_fmac_f32_e32 v82, v34, v57
	v_fmac_f32_e32 v80, v36, v57
	v_fmac_f32_e32 v82, v36, v59
	v_fmac_f32_e32 v80, v38, v59
	v_fmac_f32_e32 v82, v38, v61
	v_fmac_f32_e32 v80, v40, v61
	v_fmac_f32_e32 v82, v40, v63
	v_fmac_f32_e32 v80, v42, v63
	v_fmac_f32_e32 v82, v42, v65
	v_fmac_f32_e32 v80, v44, v65
	v_fmac_f32_e32 v82, v44, v67
	v_fmac_f32_e32 v80, v46, v67
	v_fmac_f32_e32 v82, v46, v69
	v_fmac_f32_e32 v80, v50, v69
	v_fmac_f32_e32 v82, v50, v71
	v_fmac_f32_e32 v80, v52, v71
	v_fmac_f32_e32 v82, v52, v73
	v_fmac_f32_e32 v80, v54, v73
	ds_write2st64_b32 v15, v82, v80 offset0:160 offset1:168
	v_fma_f32 v80, v87, v0, v107
	v_fmac_f32_e32 v80, v79, v1
	v_fma_f32 v79, v79, v0, v107
	v_fmac_f32_e32 v79, v85, v1
	v_fmac_f32_e32 v80, v85, v3
	v_fmac_f32_e32 v79, v78, v3
	v_fmac_f32_e32 v80, v78, v5
	v_fmac_f32_e32 v79, v83, v5
	v_fmac_f32_e32 v80, v83, v7
	v_fmac_f32_e32 v79, v77, v7
	v_fmac_f32_e32 v80, v77, v9
	v_fmac_f32_e32 v79, v81, v9
	v_fmac_f32_e32 v80, v81, v11
	v_fmac_f32_e32 v79, v48, v11
	v_fmac_f32_e32 v80, v48, v23
	v_fmac_f32_e32 v79, v37, v23
	v_fmac_f32_e32 v80, v37, v25
	v_fmac_f32_e32 v79, v2, v25
	v_fmac_f32_e32 v80, v2, v27
	v_fmac_f32_e32 v79, v4, v27
	v_fmac_f32_e32 v80, v4, v29
	v_fmac_f32_e32 v79, v6, v29
	v_fmac_f32_e32 v80, v6, v31
	v_fmac_f32_e32 v79, v8, v31
	v_fmac_f32_e32 v80, v8, v33
	v_fmac_f32_e32 v79, v10, v33
	v_fmac_f32_e32 v80, v10, v35
	v_fmac_f32_e32 v79, v22, v35
	v_fmac_f32_e32 v80, v22, v39
	v_fmac_f32_e32 v79, v24, v39
	v_fmac_f32_e32 v80, v24, v41
	v_fmac_f32_e32 v79, v26, v41
	v_fmac_f32_e32 v80, v26, v43
	v_fmac_f32_e32 v79, v28, v43
	v_fmac_f32_e32 v80, v28, v45
	v_fmac_f32_e32 v79, v30, v45
	v_fmac_f32_e32 v80, v30, v47
	v_fmac_f32_e32 v79, v32, v47
	v_fmac_f32_e32 v80, v32, v51
	v_fmac_f32_e32 v79, v34, v51
	v_fmac_f32_e32 v80, v34, v53
	v_fmac_f32_e32 v79, v36, v53
	v_fmac_f32_e32 v80, v36, v55
	v_fmac_f32_e32 v79, v38, v55
	v_fmac_f32_e32 v80, v38, v57
	v_fmac_f32_e32 v79, v40, v57
	v_fmac_f32_e32 v80, v40, v59
	v_fmac_f32_e32 v79, v42, v59
	v_fmac_f32_e32 v80, v42, v61
	v_fmac_f32_e32 v79, v44, v61
	v_fmac_f32_e32 v80, v44, v63
	v_fmac_f32_e32 v79, v46, v63
	v_fmac_f32_e32 v80, v46, v65
	v_fmac_f32_e32 v79, v50, v65
	v_fmac_f32_e32 v80, v50, v67
	v_fmac_f32_e32 v79, v52, v67
	v_fmac_f32_e32 v80, v52, v69
	v_fmac_f32_e32 v79, v54, v69
	v_fmac_f32_e32 v80, v54, v71
	v_fmac_f32_e32 v79, v56, v71
	v_fmac_f32_e32 v80, v56, v73
	v_fmac_f32_e32 v79, v58, v73
	ds_write2st64_b32 v15, v80, v79 offset0:176 offset1:184
	v_fma_f32 v79, v85, v0, v107
	v_fmac_f32_e32 v79, v78, v1
	v_fma_f32 v78, v78, v0, v107
	v_fmac_f32_e32 v78, v83, v1
	v_fmac_f32_e32 v79, v83, v3
	v_fmac_f32_e32 v78, v77, v3
	v_fmac_f32_e32 v79, v77, v5
	v_fmac_f32_e32 v78, v81, v5
	v_fmac_f32_e32 v79, v81, v7
	v_fmac_f32_e32 v78, v48, v7
	v_fmac_f32_e32 v79, v48, v9
	v_fmac_f32_e32 v78, v37, v9
	v_fmac_f32_e32 v79, v37, v11
	v_fmac_f32_e32 v78, v2, v11
	v_fmac_f32_e32 v79, v2, v23
	v_fmac_f32_e32 v78, v4, v23
	v_fmac_f32_e32 v79, v4, v25
	v_fmac_f32_e32 v78, v6, v25
	v_fmac_f32_e32 v79, v6, v27
	v_fmac_f32_e32 v78, v8, v27
	v_fmac_f32_e32 v79, v8, v29
	v_fmac_f32_e32 v78, v10, v29
	v_fmac_f32_e32 v79, v10, v31
	v_fmac_f32_e32 v78, v22, v31
	v_fmac_f32_e32 v79, v22, v33
	v_fmac_f32_e32 v78, v24, v33
	v_fmac_f32_e32 v79, v24, v35
	v_fmac_f32_e32 v78, v26, v35
	v_fmac_f32_e32 v79, v26, v39
	v_fmac_f32_e32 v78, v28, v39
	v_fmac_f32_e32 v79, v28, v41
	v_fmac_f32_e32 v78, v30, v41
	v_fmac_f32_e32 v79, v30, v43
	v_fmac_f32_e32 v78, v32, v43
	v_fmac_f32_e32 v79, v32, v45
	v_fmac_f32_e32 v78, v34, v45
	v_fmac_f32_e32 v79, v34, v47
	v_fmac_f32_e32 v78, v36, v47
	v_fmac_f32_e32 v79, v36, v51
	v_fmac_f32_e32 v78, v38, v51
	v_fmac_f32_e32 v79, v38, v53
	v_fmac_f32_e32 v78, v40, v53
	v_fmac_f32_e32 v79, v40, v55
	v_fmac_f32_e32 v78, v42, v55
	v_fmac_f32_e32 v79, v42, v57
	v_fmac_f32_e32 v78, v44, v57
	v_fmac_f32_e32 v79, v44, v59
	v_fmac_f32_e32 v78, v46, v59
	v_fmac_f32_e32 v79, v46, v61
	v_fmac_f32_e32 v78, v50, v61
	v_fmac_f32_e32 v79, v50, v63
	v_fmac_f32_e32 v78, v52, v63
	v_fmac_f32_e32 v79, v52, v65
	v_fmac_f32_e32 v78, v54, v65
	v_fmac_f32_e32 v79, v54, v67
	v_fmac_f32_e32 v78, v56, v67
	v_fmac_f32_e32 v79, v56, v69
	v_fmac_f32_e32 v78, v58, v69
	v_fmac_f32_e32 v79, v58, v71
	v_fmac_f32_e32 v78, v60, v71
	v_fmac_f32_e32 v79, v60, v73
	v_fmac_f32_e32 v78, v62, v73
	ds_write2st64_b32 v15, v79, v78 offset0:192 offset1:200
	v_fma_f32 v78, v83, v0, v107
	v_fmac_f32_e32 v78, v77, v1
	v_fma_f32 v77, v77, v0, v107
	v_fmac_f32_e32 v77, v81, v1
	v_fmac_f32_e32 v78, v81, v3
	v_fmac_f32_e32 v77, v48, v3
	v_fmac_f32_e32 v78, v48, v5
	v_fmac_f32_e32 v77, v37, v5
	v_fmac_f32_e32 v78, v37, v7
	v_fmac_f32_e32 v77, v2, v7
	v_fmac_f32_e32 v78, v2, v9
	v_fmac_f32_e32 v77, v4, v9
	v_fmac_f32_e32 v78, v4, v11
	v_fmac_f32_e32 v77, v6, v11
	v_fmac_f32_e32 v78, v6, v23
	v_fmac_f32_e32 v77, v8, v23
	v_fmac_f32_e32 v78, v8, v25
	v_fmac_f32_e32 v77, v10, v25
	v_fmac_f32_e32 v78, v10, v27
	v_fmac_f32_e32 v77, v22, v27
	v_fmac_f32_e32 v78, v22, v29
	v_fmac_f32_e32 v77, v24, v29
	v_fmac_f32_e32 v78, v24, v31
	v_fmac_f32_e32 v77, v26, v31
	v_fmac_f32_e32 v78, v26, v33
	v_fmac_f32_e32 v77, v28, v33
	v_fmac_f32_e32 v78, v28, v35
	v_fmac_f32_e32 v77, v30, v35
	v_fmac_f32_e32 v78, v30, v39
	v_fmac_f32_e32 v77, v32, v39
	v_fmac_f32_e32 v78, v32, v41
	v_fmac_f32_e32 v77, v34, v41
	v_fmac_f32_e32 v78, v34, v43
	v_fmac_f32_e32 v77, v36, v43
	v_fmac_f32_e32 v78, v36, v45
	v_fmac_f32_e32 v77, v38, v45
	v_fmac_f32_e32 v78, v38, v47
	v_fmac_f32_e32 v77, v40, v47
	v_fmac_f32_e32 v78, v40, v51
	v_fmac_f32_e32 v77, v42, v51
	v_fmac_f32_e32 v78, v42, v53
	v_fmac_f32_e32 v77, v44, v53
	v_fmac_f32_e32 v78, v44, v55
	v_fmac_f32_e32 v77, v46, v55
	v_fmac_f32_e32 v78, v46, v57
	v_fmac_f32_e32 v77, v50, v57
	v_fmac_f32_e32 v78, v50, v59
	v_fmac_f32_e32 v77, v52, v59
	v_fmac_f32_e32 v78, v52, v61
	v_fmac_f32_e32 v77, v54, v61
	v_fmac_f32_e32 v78, v54, v63
	v_fmac_f32_e32 v77, v56, v63
	v_fmac_f32_e32 v78, v56, v65
	v_fmac_f32_e32 v77, v58, v65
	v_fmac_f32_e32 v78, v58, v67
	v_fmac_f32_e32 v77, v60, v67
	v_fmac_f32_e32 v78, v60, v69
	v_fmac_f32_e32 v77, v62, v69
	v_fmac_f32_e32 v78, v62, v71
	v_fmac_f32_e32 v77, v64, v71
	v_fmac_f32_e32 v78, v64, v73
	v_fmac_f32_e32 v77, v66, v73
	ds_write2st64_b32 v15, v78, v77 offset0:208 offset1:216
	v_fma_f32 v77, v81, v0, v107
	v_fmac_f32_e32 v77, v48, v1
	v_fma_f32 v48, v48, v0, v107
	v_fmac_f32_e32 v77, v37, v3
	v_fmac_f32_e32 v48, v37, v1
	v_fma_f32 v37, v37, v0, v107
	v_fmac_f32_e32 v107, v2, v0
	v_fmac_f32_e32 v77, v2, v5
	v_fmac_f32_e32 v48, v2, v3
	v_fmac_f32_e32 v37, v2, v1
	v_fmac_f32_e32 v107, v4, v1
	v_fmac_f32_e32 v77, v4, v7
	v_fmac_f32_e32 v48, v4, v5
	v_fmac_f32_e32 v37, v4, v3
	v_fmac_f32_e32 v107, v6, v3
	v_add_u32_e32 v2, s91, v74
	v_fmac_f32_e32 v77, v6, v9
	v_fmac_f32_e32 v48, v6, v7
	v_fmac_f32_e32 v37, v6, v5
	v_fmac_f32_e32 v107, v8, v5
	v_ashrrev_i32_e32 v3, 31, v2
	v_lshl_or_b32 v6, v2, 4, v75
	v_fmac_f32_e32 v37, v8, v7
	v_fmac_f32_e32 v107, v10, v7
	v_lshl_add_u64 v[0:1], s[44:45], 0, v[2:3]
	v_ashrrev_i32_e32 v7, 31, v6
	v_mad_u64_u32 v[4:5], s[6:7], v0, s8, v[18:19]
	v_lshlrev_b64 v[6:7], 2, v[6:7]
	v_fmac_f32_e32 v77, v8, v11
	v_fmac_f32_e32 v48, v8, v9
	v_fmac_f32_e32 v37, v10, v9
	v_fmac_f32_e32 v107, v22, v9
	v_mad_i32_i24 v5, v1, s8, v5
	v_lshl_add_u64 v[8:9], s[46:47], 0, v[6:7]
	global_load_ushort v3, v[4:5], off offset:768
	global_load_dword v2, v[8:9], off
	v_lshl_add_u64 v[6:7], s[48:49], 0, v[6:7]
	global_load_ushort v4, v[4:5], off offset:800
	v_fmac_f32_e32 v48, v10, v11
	global_load_dword v5, v[6:7], off
	v_fmac_f32_e32 v37, v22, v11
	v_fmac_f32_e32 v107, v24, v11
	v_fmac_f32_e32 v77, v10, v23
	v_fmac_f32_e32 v48, v22, v23
	v_fmac_f32_e32 v37, v24, v23
	v_fmac_f32_e32 v107, v26, v23
	v_fmac_f32_e32 v77, v22, v25
	v_fmac_f32_e32 v48, v24, v25
	v_fmac_f32_e32 v37, v26, v25
	v_fmac_f32_e32 v107, v28, v25
	v_fmac_f32_e32 v77, v24, v27
	v_fmac_f32_e32 v48, v26, v27
	v_fmac_f32_e32 v37, v28, v27
	v_fmac_f32_e32 v107, v30, v27
	v_fmac_f32_e32 v77, v26, v29
	v_fmac_f32_e32 v48, v28, v29
	v_fmac_f32_e32 v37, v30, v29
	v_fmac_f32_e32 v107, v32, v29
	v_fmac_f32_e32 v77, v28, v31
	v_fmac_f32_e32 v48, v30, v31
	v_fmac_f32_e32 v37, v32, v31
	v_fmac_f32_e32 v107, v34, v31
	v_fmac_f32_e32 v77, v30, v33
	v_fmac_f32_e32 v48, v32, v33
	v_fmac_f32_e32 v37, v34, v33
	v_fmac_f32_e32 v107, v36, v33
	v_fmac_f32_e32 v77, v32, v35
	v_fmac_f32_e32 v48, v34, v35
	v_fmac_f32_e32 v37, v36, v35
	v_fmac_f32_e32 v107, v38, v35
	v_fmac_f32_e32 v77, v34, v39
	v_fmac_f32_e32 v48, v36, v39
	v_fmac_f32_e32 v37, v38, v39
	v_fmac_f32_e32 v107, v40, v39
	v_fmac_f32_e32 v77, v36, v41
	v_fmac_f32_e32 v48, v38, v41
	v_fmac_f32_e32 v37, v40, v41
	v_fmac_f32_e32 v107, v42, v41
	v_fmac_f32_e32 v77, v38, v43
	v_fmac_f32_e32 v48, v40, v43
	v_fmac_f32_e32 v37, v42, v43
	v_fmac_f32_e32 v107, v44, v43
	v_fmac_f32_e32 v77, v40, v45
	v_fmac_f32_e32 v48, v42, v45
	v_fmac_f32_e32 v37, v44, v45
	v_fmac_f32_e32 v107, v46, v45
	v_fmac_f32_e32 v77, v42, v47
	v_fmac_f32_e32 v48, v44, v47
	v_fmac_f32_e32 v37, v46, v47
	v_fmac_f32_e32 v107, v50, v47
	v_fmac_f32_e32 v77, v44, v51
	v_fmac_f32_e32 v48, v46, v51
	v_fmac_f32_e32 v37, v50, v51
	v_fmac_f32_e32 v107, v52, v51
	v_fmac_f32_e32 v77, v46, v53
	v_fmac_f32_e32 v48, v50, v53
	v_fmac_f32_e32 v37, v52, v53
	v_fmac_f32_e32 v107, v54, v53
	v_fmac_f32_e32 v77, v50, v55
	v_fmac_f32_e32 v48, v52, v55
	v_fmac_f32_e32 v37, v54, v55
	v_fmac_f32_e32 v107, v56, v55
	v_fmac_f32_e32 v77, v52, v57
	v_fmac_f32_e32 v48, v54, v57
	v_fmac_f32_e32 v37, v56, v57
	v_fmac_f32_e32 v107, v58, v57
	v_fmac_f32_e32 v77, v54, v59
	v_fmac_f32_e32 v48, v56, v59
	v_fmac_f32_e32 v37, v58, v59
	v_fmac_f32_e32 v107, v60, v59
	v_fmac_f32_e32 v77, v56, v61
	v_fmac_f32_e32 v48, v58, v61
	v_fmac_f32_e32 v37, v60, v61
	v_fmac_f32_e32 v107, v62, v61
	s_waitcnt vmcnt(3)
	v_lshlrev_b32_e32 v3, 16, v3
	v_lshlrev_b64 v[0:1], 6, v[0:1]
	v_fmac_f32_e32 v77, v58, v63
	s_waitcnt vmcnt(1)
	v_lshlrev_b32_e32 v4, 16, v4
	v_fmac_f32_e32 v48, v60, v63
	s_waitcnt vmcnt(0)
	v_mul_f32_e32 v6, v5, v4
	v_fma_f32 v6, v2, v3, -v6
	v_mul_f32_e32 v2, v2, v4
	v_fmac_f32_e32 v2, v5, v3
	v_fmac_f32_e32 v37, v62, v63
	v_fmac_f32_e32 v107, v64, v63
	v_cvt_pk_bf16_f32 v6, v6, s0
	v_lshl_add_u64 v[0:1], v[12:13], 0, v[0:1]
	v_cvt_pk_bf16_f32 v2, v2, s0
	v_fmac_f32_e32 v77, v60, v65
	v_fmac_f32_e32 v48, v62, v65
	v_fmac_f32_e32 v37, v64, v65
	v_fmac_f32_e32 v107, v66, v65
	global_store_short v[0:1], v6, off
	global_store_short v[0:1], v2, off offset:8
	v_and_b32_e32 v1, 64, v205
	v_fmac_f32_e32 v77, v62, v67
	v_fmac_f32_e32 v48, v64, v67
	v_fmac_f32_e32 v37, v66, v67
	v_fmac_f32_e32 v107, v68, v67
	v_xor_b32_e32 v0, 16, v205
	v_add_u32_e32 v1, 64, v1
	v_fmac_f32_e32 v77, v64, v69
	v_fmac_f32_e32 v48, v66, v69
	v_fmac_f32_e32 v37, v68, v69
	v_fmac_f32_e32 v107, v70, v69
	v_cmp_lt_i32_e32 vcc, v0, v1
	v_fmac_f32_e32 v77, v66, v71
	v_fmac_f32_e32 v48, v68, v71
	v_fmac_f32_e32 v37, v70, v71
	v_fmac_f32_e32 v107, v72, v71
	v_cndmask_b32_e32 v0, v205, v0, vcc
	v_fmac_f32_e32 v77, v68, v73
	v_fmac_f32_e32 v48, v70, v73
	v_fmac_f32_e32 v37, v72, v73
	v_fmac_f32_e32 v107, v106, v73
	v_lshlrev_b32_e32 v28, 2, v0
	v_add_u32_e32 v0, s63, v76
	ds_write2st64_b32 v15, v77, v48 offset0:224 offset1:232
	ds_write2st64_b32 v15, v37, v107 offset0:240 offset1:248
	s_waitcnt lgkmcnt(0)
	s_barrier
	ds_read_b128 v[8:11], v0
	ds_read_b128 v[0:3], v0 offset:16
	v_lshlrev_b32_e32 v29, 2, v14
	s_add_u32 s6, s24, s62
	s_addc_u32 s7, s45, s64
	s_waitcnt lgkmcnt(1)
	v_add_f32_e32 v4, 0, v8
	v_add_f32_e32 v4, v9, v4
	v_add_f32_e32 v4, v10, v4
	v_add_f32_e32 v4, v11, v4
	s_waitcnt lgkmcnt(0)
	v_add_f32_e32 v4, v0, v4
	v_add_f32_e32 v4, v1, v4
	v_add_f32_e32 v4, v2, v4
	v_add_f32_e32 v4, v3, v4
	s_lshl_b64 s[6:7], s[6:7], 11
	s_add_u32 s6, s2, s6
	v_add_f32_dpp v4, v4, v4 row_mirror row_mask:0xf bank_mask:0xf bound_ctrl:1
	s_addc_u32 s7, s3, s7
	v_lshlrev_b32_e32 v48, 1, v14
	v_add_f32_dpp v4, v4, v4 row_half_mirror row_mask:0xf bank_mask:0xf bound_ctrl:1
	s_mov_b64 s[8:9], 0x7800400
	s_nop 0
	v_add_f32_dpp v4, v4, v4 quad_perm:[1,0,3,2] row_mask:0xf bank_mask:0xf bound_ctrl:1
	s_nop 1
	v_add_f32_dpp v4, v4, v4 quad_perm:[2,3,0,1] row_mask:0xf bank_mask:0xf bound_ctrl:1
	s_waitcnt lgkmcnt(0)
	v_mov_b32_e32 v5, v4
	s_nop 1
	v_permlane16_swap_b32_e32 v4, v5
	v_add_f32_e32 v4, v4, v5
	v_mov_b32_e32 v5, v4
	s_nop 1
	v_permlane32_swap_b32_e32 v4, v5
	v_add_f32_e32 v4, v4, v5
	v_mul_f32_e32 v24, 0x3b000000, v4
	v_pk_add_f32 v[22:23], v[2:3], v[24:25] op_sel_hi:[1,0] neg_lo:[0,1] neg_hi:[0,1]
	v_pk_add_f32 v[26:27], v[0:1], v[24:25] op_sel_hi:[1,0] neg_lo:[0,1] neg_hi:[0,1]
	global_load_dwordx4 v[0:3], v29, s[40:41] offset:16
	global_load_dwordx4 v[30:33], v29, s[40:41]
	global_load_dwordx4 v[4:7], v29, s[50:51] offset:16
	global_load_dwordx4 v[34:37], v29, s[50:51]
	v_pk_add_f32 v[8:9], v[8:9], v[24:25] op_sel_hi:[1,0] neg_lo:[0,1] neg_hi:[0,1]
	v_pk_add_f32 v[10:11], v[10:11], v[24:25] op_sel_hi:[1,0] neg_lo:[0,1] neg_hi:[0,1]
	v_pk_mul_f32 v[24:25], v[8:9], v[8:9]
	v_pk_mul_f32 v[42:43], v[10:11], v[10:11]
	v_add_f32_e32 v24, v24, v25
	v_add_f32_e32 v24, v42, v24
	v_pk_mul_f32 v[40:41], v[26:27], v[26:27]
	v_add_f32_e32 v24, v43, v24
	v_add_f32_e32 v24, v40, v24
	v_pk_mul_f32 v[38:39], v[22:23], v[22:23]
	v_add_f32_e32 v24, v41, v24
	v_add_f32_e32 v24, v38, v24
	v_add_f32_e32 v24, v39, v24
	s_nop 1
	v_add_f32_dpp v24, v24, v24 row_mirror row_mask:0xf bank_mask:0xf bound_ctrl:1
	s_nop 1
	v_add_f32_dpp v24, v24, v24 row_half_mirror row_mask:0xf bank_mask:0xf bound_ctrl:1
	s_nop 1
	v_add_f32_dpp v24, v24, v24 quad_perm:[1,0,3,2] row_mask:0xf bank_mask:0xf bound_ctrl:1
	s_nop 1
	v_add_f32_dpp v24, v24, v24 quad_perm:[2,3,0,1] row_mask:0xf bank_mask:0xf bound_ctrl:1
	s_waitcnt lgkmcnt(0)
	v_mov_b32_e32 v25, v24
	s_nop 1
	v_permlane16_swap_b32_e32 v24, v25
	v_add_f32_e32 v24, v24, v25
	v_mov_b32_e32 v25, v24
	s_nop 1
	v_permlane32_swap_b32_e32 v24, v25
	v_add_f32_e32 v24, v24, v25
	v_fmamk_f32 v24, v24, 0x3b000000, v206
	v_cmp_gt_f32_e32 vcc, s75, v24
	v_mul_f32_e32 v25, 0x4b800000, v24
	s_nop 0
	v_cndmask_b32_e32 v24, v24, v25, vcc
	v_rsq_f32_e32 v24, v24
	s_nop 0
	v_mul_f32_e32 v25, 0x45800000, v24
	v_cndmask_b32_e32 v24, v24, v25, vcc
	v_pk_mul_f32 v[8:9], v[8:9], v[24:25] op_sel_hi:[1,0]
	s_waitcnt vmcnt(0)
	v_pk_fma_f32 v[8:9], v[30:31], v[8:9], v[34:35]
	s_nop 0
	v_mul_f32_e32 v25, 0xbfb8aa3b, v8
	v_exp_f32_e32 v25, v25
	s_nop 0
	v_add_f32_e32 v25, 1.0, v25
	v_rcp_f32_e32 v30, v25
	v_mul_f32_e32 v25, 0xbfb8aa3b, v9
	v_exp_f32_e32 v25, v25
	s_nop 0
	v_add_f32_e32 v25, 1.0, v25
	v_pk_mul_f32 v[10:11], v[10:11], v[24:25] op_sel_hi:[1,0]
	v_rcp_f32_e32 v31, v25
	v_pk_fma_f32 v[10:11], v[32:33], v[10:11], v[36:37]
	v_pk_mul_f32 v[8:9], v[8:9], v[30:31]
	v_mul_f32_e32 v25, 0xbfb8aa3b, v10
	v_exp_f32_e32 v25, v25
	s_nop 0
	v_add_f32_e32 v25, 1.0, v25
	v_rcp_f32_e32 v30, v25
	v_mul_f32_e32 v25, 0xbfb8aa3b, v11
	v_exp_f32_e32 v25, v25
	s_nop 0
	v_add_f32_e32 v25, 1.0, v25
	v_pk_mul_f32 v[26:27], v[26:27], v[24:25] op_sel_hi:[1,0]
	v_rcp_f32_e32 v31, v25
	v_pk_fma_f32 v[0:1], v[0:1], v[26:27], v[4:5]
	v_pk_mul_f32 v[10:11], v[10:11], v[30:31]
	v_mul_f32_e32 v4, 0xbfb8aa3b, v0
	v_mul_f32_e32 v5, 0xbfb8aa3b, v1
	v_exp_f32_e32 v4, v4
	v_exp_f32_e32 v5, v5
	v_add_f32_e32 v4, 1.0, v4
	v_add_f32_e32 v5, 1.0, v5
	v_rcp_f32_e32 v4, v4
	v_rcp_f32_e32 v5, v5
	s_nop 0
	v_pk_mul_f32 v[4:5], v[0:1], v[4:5]
	v_pk_mul_f32 v[0:1], v[22:23], v[24:25] op_sel_hi:[1,0]
	s_nop 0
	v_pk_fma_f32 v[0:1], v[0:1], v[2:3], v[6:7]
	s_nop 0
	v_mul_f32_e32 v2, 0xbfb8aa3b, v0
	v_mul_f32_e32 v3, 0xbfb8aa3b, v1
	v_exp_f32_e32 v2, v2
	v_exp_f32_e32 v3, v3
	v_add_f32_e32 v2, 1.0, v2
	v_add_f32_e32 v3, 1.0, v3
	v_rcp_f32_e32 v2, v2
	v_rcp_f32_e32 v3, v3
	s_nop 0
	v_pk_mul_f32 v[6:7], v[0:1], v[2:3]
	v_cvt_pk_bf16_f32 v0, v8, v9
	v_cvt_pk_bf16_f32 v2, v4, v5
	v_lshl_add_u64 v[4:5], s[6:7], 0, v[48:49]
	v_cvt_pk_bf16_f32 v1, v10, v11
	v_cvt_pk_bf16_f32 v3, v6, v7
	v_lshl_add_u64 v[4:5], v[4:5], 0, s[8:9]
	global_store_dwordx4 v[4:5], v[0:3], off
	s_nop 1
	v_add_u32_e32 v0, s66, v76
	ds_read_b128 v[8:11], v0
	ds_read_b128 v[0:3], v0 offset:16
	s_add_u32 s6, s24, s65
	s_addc_u32 s7, s45, s67
	s_lshl_b64 s[6:7], s[6:7], 11
	s_waitcnt lgkmcnt(1)
	v_add_f32_e32 v4, 0, v8
	v_add_f32_e32 v4, v9, v4
	v_add_f32_e32 v4, v10, v4
	v_add_f32_e32 v4, v11, v4
	s_waitcnt lgkmcnt(0)
	v_add_f32_e32 v4, v0, v4
	v_add_f32_e32 v4, v1, v4
	v_add_f32_e32 v4, v2, v4
	v_add_f32_e32 v4, v3, v4
	s_add_u32 s6, s2, s6
	s_addc_u32 s7, s3, s7
	v_add_f32_dpp v4, v4, v4 row_mirror row_mask:0xf bank_mask:0xf bound_ctrl:1
	s_nop 1
	v_add_f32_dpp v4, v4, v4 row_half_mirror row_mask:0xf bank_mask:0xf bound_ctrl:1
	s_nop 1
	v_add_f32_dpp v4, v4, v4 quad_perm:[1,0,3,2] row_mask:0xf bank_mask:0xf bound_ctrl:1
	s_nop 1
	v_add_f32_dpp v4, v4, v4 quad_perm:[2,3,0,1] row_mask:0xf bank_mask:0xf bound_ctrl:1
	s_waitcnt lgkmcnt(0)
	v_mov_b32_e32 v5, v4
	s_nop 1
	v_permlane16_swap_b32_e32 v4, v5
	v_add_f32_e32 v4, v4, v5
	v_mov_b32_e32 v5, v4
	s_nop 1
	v_permlane32_swap_b32_e32 v4, v5
	v_add_f32_e32 v4, v4, v5
	v_mul_f32_e32 v26, 0x3b000000, v4
	v_pk_add_f32 v[22:23], v[2:3], v[26:27] op_sel_hi:[1,0] neg_lo:[0,1] neg_hi:[0,1]
	v_pk_add_f32 v[24:25], v[0:1], v[26:27] op_sel_hi:[1,0] neg_lo:[0,1] neg_hi:[0,1]
	global_load_dwordx4 v[0:3], v29, s[40:41] offset:16
	global_load_dwordx4 v[30:33], v29, s[40:41]
	global_load_dwordx4 v[4:7], v29, s[50:51] offset:16
	global_load_dwordx4 v[34:37], v29, s[50:51]
	v_pk_add_f32 v[8:9], v[8:9], v[26:27] op_sel_hi:[1,0] neg_lo:[0,1] neg_hi:[0,1]
	v_pk_add_f32 v[10:11], v[10:11], v[26:27] op_sel_hi:[1,0] neg_lo:[0,1] neg_hi:[0,1]
	v_pk_mul_f32 v[26:27], v[8:9], v[8:9]
	v_pk_mul_f32 v[42:43], v[10:11], v[10:11]
	v_add_f32_e32 v26, v26, v27
	v_add_f32_e32 v26, v42, v26
	v_pk_mul_f32 v[40:41], v[24:25], v[24:25]
	v_add_f32_e32 v26, v43, v26
	v_add_f32_e32 v26, v40, v26
	v_pk_mul_f32 v[38:39], v[22:23], v[22:23]
	v_add_f32_e32 v26, v41, v26
	v_add_f32_e32 v26, v38, v26
	v_add_f32_e32 v26, v39, v26
	s_nop 1
	v_add_f32_dpp v26, v26, v26 row_mirror row_mask:0xf bank_mask:0xf bound_ctrl:1
	s_nop 1
	v_add_f32_dpp v26, v26, v26 row_half_mirror row_mask:0xf bank_mask:0xf bound_ctrl:1
	s_nop 1
	v_add_f32_dpp v26, v26, v26 quad_perm:[1,0,3,2] row_mask:0xf bank_mask:0xf bound_ctrl:1
	s_nop 1
	v_add_f32_dpp v26, v26, v26 quad_perm:[2,3,0,1] row_mask:0xf bank_mask:0xf bound_ctrl:1
	s_waitcnt lgkmcnt(0)
	v_mov_b32_e32 v27, v26
	s_nop 1
	v_permlane16_swap_b32_e32 v26, v27
	v_add_f32_e32 v26, v26, v27
	v_mov_b32_e32 v27, v26
	s_nop 1
	v_permlane32_swap_b32_e32 v26, v27
	v_add_f32_e32 v26, v26, v27
	v_fmamk_f32 v26, v26, 0x3b000000, v206
	v_cmp_gt_f32_e32 vcc, s75, v26
	v_mul_f32_e32 v27, 0x4b800000, v26
	s_nop 0
	v_cndmask_b32_e32 v26, v26, v27, vcc
	v_rsq_f32_e32 v26, v26
	s_nop 0
	v_mul_f32_e32 v27, 0x45800000, v26
	v_cndmask_b32_e32 v26, v26, v27, vcc
	v_pk_mul_f32 v[8:9], v[8:9], v[26:27] op_sel_hi:[1,0]
	s_waitcnt vmcnt(0)
	v_pk_fma_f32 v[8:9], v[30:31], v[8:9], v[34:35]
	s_nop 0
	v_mul_f32_e32 v27, 0xbfb8aa3b, v8
	v_exp_f32_e32 v27, v27
	s_nop 0
	v_add_f32_e32 v27, 1.0, v27
	v_rcp_f32_e32 v30, v27
	v_mul_f32_e32 v27, 0xbfb8aa3b, v9
	v_exp_f32_e32 v27, v27
	s_nop 0
	v_add_f32_e32 v27, 1.0, v27
	v_pk_mul_f32 v[10:11], v[10:11], v[26:27] op_sel_hi:[1,0]
	v_rcp_f32_e32 v31, v27
	v_pk_fma_f32 v[10:11], v[32:33], v[10:11], v[36:37]
	v_pk_mul_f32 v[8:9], v[8:9], v[30:31]
	v_mul_f32_e32 v27, 0xbfb8aa3b, v10
	v_exp_f32_e32 v27, v27
	s_nop 0
	v_add_f32_e32 v27, 1.0, v27
	v_rcp_f32_e32 v30, v27
	v_mul_f32_e32 v27, 0xbfb8aa3b, v11
	v_exp_f32_e32 v27, v27
	s_nop 0
	v_add_f32_e32 v27, 1.0, v27
	v_pk_mul_f32 v[24:25], v[24:25], v[26:27] op_sel_hi:[1,0]
	v_rcp_f32_e32 v31, v27
	v_pk_fma_f32 v[0:1], v[0:1], v[24:25], v[4:5]
	v_pk_mul_f32 v[10:11], v[10:11], v[30:31]
	v_mul_f32_e32 v4, 0xbfb8aa3b, v0
	v_mul_f32_e32 v5, 0xbfb8aa3b, v1
	v_exp_f32_e32 v4, v4
	v_exp_f32_e32 v5, v5
	v_add_f32_e32 v4, 1.0, v4
	v_add_f32_e32 v5, 1.0, v5
	v_rcp_f32_e32 v4, v4
	v_rcp_f32_e32 v5, v5
	s_nop 0
	v_pk_mul_f32 v[4:5], v[0:1], v[4:5]
	v_pk_mul_f32 v[0:1], v[22:23], v[26:27] op_sel_hi:[1,0]
	s_nop 0
	v_pk_fma_f32 v[0:1], v[0:1], v[2:3], v[6:7]
	s_nop 0
	v_mul_f32_e32 v2, 0xbfb8aa3b, v0
	v_mul_f32_e32 v3, 0xbfb8aa3b, v1
	v_exp_f32_e32 v2, v2
	v_exp_f32_e32 v3, v3
	v_add_f32_e32 v2, 1.0, v2
	v_add_f32_e32 v3, 1.0, v3
	v_rcp_f32_e32 v2, v2
	v_rcp_f32_e32 v3, v3
	s_nop 0
	v_pk_mul_f32 v[6:7], v[0:1], v[2:3]
	v_cvt_pk_bf16_f32 v0, v8, v9
	v_cvt_pk_bf16_f32 v2, v4, v5
	v_lshl_add_u64 v[4:5], s[6:7], 0, v[48:49]
	v_cvt_pk_bf16_f32 v1, v10, v11
	v_cvt_pk_bf16_f32 v3, v6, v7
	v_lshl_add_u64 v[4:5], v[4:5], 0, s[8:9]
	global_store_dwordx4 v[4:5], v[0:3], off
	s_nop 1
	v_add_u32_e32 v0, s69, v76
	ds_read_b128 v[8:11], v0
	ds_read_b128 v[0:3], v0 offset:16
	s_add_u32 s6, s24, s68
	s_addc_u32 s7, s45, s86
	s_lshl_b64 s[6:7], s[6:7], 11
	s_waitcnt lgkmcnt(1)
	v_add_f32_e32 v4, 0, v8
	v_add_f32_e32 v4, v9, v4
	v_add_f32_e32 v4, v10, v4
	v_add_f32_e32 v4, v11, v4
	s_waitcnt lgkmcnt(0)
	v_add_f32_e32 v4, v0, v4
	v_add_f32_e32 v4, v1, v4
	v_add_f32_e32 v4, v2, v4
	v_add_f32_e32 v4, v3, v4
	s_add_u32 s6, s2, s6
	s_addc_u32 s7, s3, s7
	v_add_f32_dpp v4, v4, v4 row_mirror row_mask:0xf bank_mask:0xf bound_ctrl:1
	s_nop 1
	v_add_f32_dpp v4, v4, v4 row_half_mirror row_mask:0xf bank_mask:0xf bound_ctrl:1
	s_nop 1
	v_add_f32_dpp v4, v4, v4 quad_perm:[1,0,3,2] row_mask:0xf bank_mask:0xf bound_ctrl:1
	s_nop 1
	v_add_f32_dpp v4, v4, v4 quad_perm:[2,3,0,1] row_mask:0xf bank_mask:0xf bound_ctrl:1
	s_waitcnt lgkmcnt(0)
	v_mov_b32_e32 v5, v4
	s_nop 1
	v_permlane16_swap_b32_e32 v4, v5
	v_add_f32_e32 v4, v4, v5
	v_mov_b32_e32 v5, v4
	s_nop 1
	v_permlane32_swap_b32_e32 v4, v5
	v_add_f32_e32 v4, v4, v5
	v_mul_f32_e32 v26, 0x3b000000, v4
	v_pk_add_f32 v[22:23], v[2:3], v[26:27] op_sel_hi:[1,0] neg_lo:[0,1] neg_hi:[0,1]
	v_pk_add_f32 v[24:25], v[0:1], v[26:27] op_sel_hi:[1,0] neg_lo:[0,1] neg_hi:[0,1]
	global_load_dwordx4 v[0:3], v29, s[40:41] offset:16
	global_load_dwordx4 v[30:33], v29, s[40:41]
	global_load_dwordx4 v[4:7], v29, s[50:51] offset:16
	global_load_dwordx4 v[34:37], v29, s[50:51]
	v_pk_add_f32 v[8:9], v[8:9], v[26:27] op_sel_hi:[1,0] neg_lo:[0,1] neg_hi:[0,1]
	v_pk_add_f32 v[10:11], v[10:11], v[26:27] op_sel_hi:[1,0] neg_lo:[0,1] neg_hi:[0,1]
	v_pk_mul_f32 v[26:27], v[8:9], v[8:9]
	v_pk_mul_f32 v[42:43], v[10:11], v[10:11]
	v_add_f32_e32 v26, v26, v27
	v_add_f32_e32 v26, v42, v26
	v_pk_mul_f32 v[40:41], v[24:25], v[24:25]
	v_add_f32_e32 v26, v43, v26
	v_add_f32_e32 v26, v40, v26
	v_pk_mul_f32 v[38:39], v[22:23], v[22:23]
	v_add_f32_e32 v26, v41, v26
	v_add_f32_e32 v26, v38, v26
	v_add_f32_e32 v26, v39, v26
	s_nop 1
	v_add_f32_dpp v26, v26, v26 row_mirror row_mask:0xf bank_mask:0xf bound_ctrl:1
	s_nop 1
	v_add_f32_dpp v26, v26, v26 row_half_mirror row_mask:0xf bank_mask:0xf bound_ctrl:1
	s_nop 1
	v_add_f32_dpp v26, v26, v26 quad_perm:[1,0,3,2] row_mask:0xf bank_mask:0xf bound_ctrl:1
	s_nop 1
	v_add_f32_dpp v26, v26, v26 quad_perm:[2,3,0,1] row_mask:0xf bank_mask:0xf bound_ctrl:1
	s_waitcnt lgkmcnt(0)
	v_mov_b32_e32 v27, v26
	s_nop 1
	v_permlane16_swap_b32_e32 v26, v27
	v_add_f32_e32 v26, v26, v27
	v_mov_b32_e32 v27, v26
	s_nop 1
	v_permlane32_swap_b32_e32 v26, v27
	v_add_f32_e32 v26, v26, v27
	v_fmamk_f32 v26, v26, 0x3b000000, v206
	v_cmp_gt_f32_e32 vcc, s75, v26
	v_mul_f32_e32 v27, 0x4b800000, v26
	s_nop 0
	v_cndmask_b32_e32 v26, v26, v27, vcc
	v_rsq_f32_e32 v26, v26
	s_nop 0
	v_mul_f32_e32 v27, 0x45800000, v26
	v_cndmask_b32_e32 v26, v26, v27, vcc
	v_pk_mul_f32 v[8:9], v[8:9], v[26:27] op_sel_hi:[1,0]
	s_waitcnt vmcnt(0)
	v_pk_fma_f32 v[8:9], v[30:31], v[8:9], v[34:35]
	s_nop 0
	v_mul_f32_e32 v27, 0xbfb8aa3b, v8
	v_exp_f32_e32 v27, v27
	s_nop 0
	v_add_f32_e32 v27, 1.0, v27
	v_rcp_f32_e32 v30, v27
	v_mul_f32_e32 v27, 0xbfb8aa3b, v9
	v_exp_f32_e32 v27, v27
	s_nop 0
	v_add_f32_e32 v27, 1.0, v27
	v_pk_mul_f32 v[10:11], v[10:11], v[26:27] op_sel_hi:[1,0]
	v_rcp_f32_e32 v31, v27
	v_pk_fma_f32 v[10:11], v[32:33], v[10:11], v[36:37]
	v_pk_mul_f32 v[8:9], v[8:9], v[30:31]
	v_mul_f32_e32 v27, 0xbfb8aa3b, v10
	v_exp_f32_e32 v27, v27
	s_nop 0
	v_add_f32_e32 v27, 1.0, v27
	v_rcp_f32_e32 v30, v27
	v_mul_f32_e32 v27, 0xbfb8aa3b, v11
	v_exp_f32_e32 v27, v27
	s_nop 0
	v_add_f32_e32 v27, 1.0, v27
	v_pk_mul_f32 v[24:25], v[24:25], v[26:27] op_sel_hi:[1,0]
	v_rcp_f32_e32 v31, v27
	v_pk_fma_f32 v[0:1], v[0:1], v[24:25], v[4:5]
	v_pk_mul_f32 v[10:11], v[10:11], v[30:31]
	v_mul_f32_e32 v4, 0xbfb8aa3b, v0
	v_mul_f32_e32 v5, 0xbfb8aa3b, v1
	v_exp_f32_e32 v4, v4
	v_exp_f32_e32 v5, v5
	v_add_f32_e32 v4, 1.0, v4
	v_add_f32_e32 v5, 1.0, v5
	v_rcp_f32_e32 v4, v4
	v_rcp_f32_e32 v5, v5
	s_nop 0
	v_pk_mul_f32 v[4:5], v[0:1], v[4:5]
	v_pk_mul_f32 v[0:1], v[22:23], v[26:27] op_sel_hi:[1,0]
	s_nop 0
	v_pk_fma_f32 v[0:1], v[0:1], v[2:3], v[6:7]
	s_nop 0
	v_mul_f32_e32 v2, 0xbfb8aa3b, v0
	v_mul_f32_e32 v3, 0xbfb8aa3b, v1
	v_exp_f32_e32 v2, v2
	v_exp_f32_e32 v3, v3
	v_add_f32_e32 v2, 1.0, v2
	v_add_f32_e32 v3, 1.0, v3
	v_rcp_f32_e32 v2, v2
	v_rcp_f32_e32 v3, v3
	s_nop 0
	v_pk_mul_f32 v[6:7], v[0:1], v[2:3]
	v_cvt_pk_bf16_f32 v0, v8, v9
	v_cvt_pk_bf16_f32 v2, v4, v5
	v_lshl_add_u64 v[4:5], s[6:7], 0, v[48:49]
	v_cvt_pk_bf16_f32 v1, v10, v11
	v_cvt_pk_bf16_f32 v3, v6, v7
	v_lshl_add_u64 v[4:5], v[4:5], 0, s[8:9]
	global_store_dwordx4 v[4:5], v[0:3], off
	s_nop 1
	v_add_u32_e32 v0, s88, v76
	ds_read_b128 v[8:11], v0
	ds_read_b128 v[0:3], v0 offset:16
	s_add_u32 s6, s24, s87
	s_addc_u32 s7, s45, s89
	s_lshl_b64 s[6:7], s[6:7], 11
	s_waitcnt lgkmcnt(1)
	v_add_f32_e32 v4, 0, v8
	v_add_f32_e32 v4, v9, v4
	v_add_f32_e32 v4, v10, v4
	v_add_f32_e32 v4, v11, v4
	s_waitcnt lgkmcnt(0)
	v_add_f32_e32 v4, v0, v4
	v_add_f32_e32 v4, v1, v4
	v_add_f32_e32 v4, v2, v4
	v_add_f32_e32 v4, v3, v4
	s_add_u32 s6, s2, s6
	s_addc_u32 s7, s3, s7
	v_add_f32_dpp v4, v4, v4 row_mirror row_mask:0xf bank_mask:0xf bound_ctrl:1
	s_add_i32 s60, s60, s73
	s_nop 0
	v_add_f32_dpp v4, v4, v4 row_half_mirror row_mask:0xf bank_mask:0xf bound_ctrl:1
	s_nop 1
	v_add_f32_dpp v4, v4, v4 quad_perm:[1,0,3,2] row_mask:0xf bank_mask:0xf bound_ctrl:1
	s_nop 1
	v_add_f32_dpp v4, v4, v4 quad_perm:[2,3,0,1] row_mask:0xf bank_mask:0xf bound_ctrl:1
	s_waitcnt lgkmcnt(0)
	v_mov_b32_e32 v5, v4
	s_nop 1
	v_permlane16_swap_b32_e32 v4, v5
	v_add_f32_e32 v4, v4, v5
	v_mov_b32_e32 v5, v4
	s_nop 1
	v_permlane32_swap_b32_e32 v4, v5
	v_add_f32_e32 v4, v4, v5
	v_mul_f32_e32 v26, 0x3b000000, v4
	v_pk_add_f32 v[22:23], v[2:3], v[26:27] op_sel_hi:[1,0] neg_lo:[0,1] neg_hi:[0,1]
	v_pk_add_f32 v[24:25], v[0:1], v[26:27] op_sel_hi:[1,0] neg_lo:[0,1] neg_hi:[0,1]
	global_load_dwordx4 v[0:3], v29, s[40:41] offset:16
	global_load_dwordx4 v[30:33], v29, s[40:41]
	global_load_dwordx4 v[4:7], v29, s[50:51] offset:16
	global_load_dwordx4 v[34:37], v29, s[50:51]
	v_pk_add_f32 v[8:9], v[8:9], v[26:27] op_sel_hi:[1,0] neg_lo:[0,1] neg_hi:[0,1]
	v_pk_add_f32 v[10:11], v[10:11], v[26:27] op_sel_hi:[1,0] neg_lo:[0,1] neg_hi:[0,1]
	v_pk_mul_f32 v[26:27], v[8:9], v[8:9]
	v_pk_mul_f32 v[42:43], v[10:11], v[10:11]
	v_add_f32_e32 v26, v26, v27
	v_add_f32_e32 v26, v42, v26
	v_pk_mul_f32 v[40:41], v[24:25], v[24:25]
	v_add_f32_e32 v26, v43, v26
	v_add_f32_e32 v26, v40, v26
	v_pk_mul_f32 v[38:39], v[22:23], v[22:23]
	v_add_f32_e32 v26, v41, v26
	v_add_f32_e32 v26, v38, v26
	v_add_f32_e32 v26, v39, v26
	s_nop 1
	v_add_f32_dpp v26, v26, v26 row_mirror row_mask:0xf bank_mask:0xf bound_ctrl:1
	s_nop 1
	v_add_f32_dpp v26, v26, v26 row_half_mirror row_mask:0xf bank_mask:0xf bound_ctrl:1
	s_nop 1
	v_add_f32_dpp v26, v26, v26 quad_perm:[1,0,3,2] row_mask:0xf bank_mask:0xf bound_ctrl:1
	s_nop 1
	v_add_f32_dpp v26, v26, v26 quad_perm:[2,3,0,1] row_mask:0xf bank_mask:0xf bound_ctrl:1
	s_waitcnt lgkmcnt(0)
	v_mov_b32_e32 v27, v26
	s_nop 1
	v_permlane16_swap_b32_e32 v26, v27
	v_add_f32_e32 v26, v26, v27
	v_mov_b32_e32 v27, v26
	s_nop 1
	v_permlane32_swap_b32_e32 v26, v27
	v_add_f32_e32 v26, v26, v27
	v_fmamk_f32 v26, v26, 0x3b000000, v206
	v_cmp_gt_f32_e32 vcc, s75, v26
	v_mul_f32_e32 v27, 0x4b800000, v26
	s_nop 0
	v_cndmask_b32_e32 v26, v26, v27, vcc
	v_rsq_f32_e32 v26, v26
	s_nop 0
	v_mul_f32_e32 v27, 0x45800000, v26
	v_cndmask_b32_e32 v26, v26, v27, vcc
	v_pk_mul_f32 v[8:9], v[8:9], v[26:27] op_sel_hi:[1,0]
	s_waitcnt vmcnt(0)
	v_pk_fma_f32 v[8:9], v[30:31], v[8:9], v[34:35]
	s_nop 0
	v_mul_f32_e32 v27, 0xbfb8aa3b, v8
	v_exp_f32_e32 v27, v27
	s_nop 0
	v_add_f32_e32 v27, 1.0, v27
	v_rcp_f32_e32 v28, v27
	v_mul_f32_e32 v27, 0xbfb8aa3b, v9
	v_exp_f32_e32 v27, v27
	s_nop 0
	v_add_f32_e32 v27, 1.0, v27
	v_pk_mul_f32 v[10:11], v[10:11], v[26:27] op_sel_hi:[1,0]
	v_rcp_f32_e32 v29, v27
	v_pk_fma_f32 v[10:11], v[32:33], v[10:11], v[36:37]
	v_pk_mul_f32 v[8:9], v[8:9], v[28:29]
	v_mul_f32_e32 v27, 0xbfb8aa3b, v10
	v_exp_f32_e32 v27, v27
	s_nop 0
	v_add_f32_e32 v27, 1.0, v27
	v_rcp_f32_e32 v28, v27
	v_mul_f32_e32 v27, 0xbfb8aa3b, v11
	v_exp_f32_e32 v27, v27
	s_nop 0
	v_add_f32_e32 v27, 1.0, v27
	v_pk_mul_f32 v[24:25], v[24:25], v[26:27] op_sel_hi:[1,0]
	v_rcp_f32_e32 v29, v27
	v_pk_fma_f32 v[0:1], v[0:1], v[24:25], v[4:5]
	v_pk_mul_f32 v[10:11], v[10:11], v[28:29]
	v_mul_f32_e32 v4, 0xbfb8aa3b, v0
	v_mul_f32_e32 v5, 0xbfb8aa3b, v1
	v_exp_f32_e32 v4, v4
	v_exp_f32_e32 v5, v5
	v_add_f32_e32 v4, 1.0, v4
	v_add_f32_e32 v5, 1.0, v5
	v_rcp_f32_e32 v4, v4
	v_rcp_f32_e32 v5, v5
	s_nop 0
	v_pk_mul_f32 v[4:5], v[0:1], v[4:5]
	v_pk_mul_f32 v[0:1], v[22:23], v[26:27] op_sel_hi:[1,0]
	s_nop 0
	v_pk_fma_f32 v[0:1], v[0:1], v[2:3], v[6:7]
	s_nop 0
	v_mul_f32_e32 v2, 0xbfb8aa3b, v0
	v_mul_f32_e32 v3, 0xbfb8aa3b, v1
	v_exp_f32_e32 v2, v2
	v_exp_f32_e32 v3, v3
	v_add_f32_e32 v2, 1.0, v2
	v_add_f32_e32 v3, 1.0, v3
	v_rcp_f32_e32 v2, v2
	v_rcp_f32_e32 v3, v3
	s_nop 0
	v_pk_mul_f32 v[6:7], v[0:1], v[2:3]
	v_cvt_pk_bf16_f32 v2, v4, v5
	v_lshl_add_u64 v[4:5], s[6:7], 0, v[48:49]
	v_cvt_pk_bf16_f32 v0, v8, v9
	v_cvt_pk_bf16_f32 v1, v10, v11
	v_cvt_pk_bf16_f32 v3, v6, v7
	v_lshl_add_u64 v[4:5], v[4:5], 0, s[8:9]
	global_store_dwordx4 v[4:5], v[0:3], off
	s_nop 1
	v_readlane_b32 s6, v255, 5
	s_add_i32 s90, s90, s6
	s_cmp_gt_i32 s60, 63
	s_barrier
	s_cbranch_scc1 .LBB0_897

.LBB0_916:
	v_and_b32_e32 v124, 3, v177
	v_or_b32_e32 v2, s8, v124
	v_lshlrev_b32_e32 v48, 16, v2
	s_load_dwordx2 s[6:7], s[0:1], 0x50
	s_waitcnt lgkmcnt(0)
	v_mov_b32_e32 v117, v49
	v_lshl_add_u64 v[0:1], s[6:7], 0, v[48:49]
	v_lshl_add_u64 v[0:1], v[0:1], 0, v[112:113]
	s_load_dwordx2 s[6:7], s[0:1], 0x58
	s_waitcnt lgkmcnt(0)
	v_lshl_add_u64 v[0:1], v[0:1], 0, v[116:117]
	v_and_b32_e32 v117, 0xffffff80, v216
	s_load_dwordx2 s[20:21], s[0:1], 0x60
	s_waitcnt lgkmcnt(0)
	v_add_u32_e32 v36, s9, v117
	v_lshlrev_b32_e32 v48, 7, v2
	s_load_dwordx2 s[40:41], s[0:1], 0x68
	s_waitcnt lgkmcnt(0)
	v_mad_i64_i32 v[2:3], s[26:27], v36, s19, v[114:115]
	global_load_dwordx4 v[24:27], v[0:1], off offset:16
	global_load_dwordx4 v[28:31], v[0:1], off
	global_load_dwordx4 v[16:19], v[0:1], off offset:144
	global_load_dwordx4 v[20:23], v[0:1], off offset:128
	global_load_dwordx4 v[126:129], v[2:3], off offset:1024
	s_mov_b32 s47, s25
	v_lshl_add_u64 v[32:33], v[48:49], 2, s[6:7]
	v_lshl_add_u64 v[2:3], v[0:1], 0, s[24:25]
	v_lshl_add_u64 v[4:5], v[0:1], 0, s[46:47]
	v_lshl_add_u64 v[32:33], v[110:111], 2, v[32:33]
	global_load_dwordx4 v[8:11], v[2:3], off offset:16
	global_load_dwordx4 v[12:15], v[2:3], off
	s_nop 0
	global_load_dwordx4 v[0:3], v[4:5], off offset:16
	s_nop 0
	global_load_dwordx4 v[4:7], v[4:5], off
	v_or_b32_e32 v34, 3, v36
	global_load_dword v118, v[32:33], off
	v_or_b32_e32 v32, 1, v36
	v_mad_i64_i32 v[32:33], s[26:27], v32, s19, v[114:115]
	global_load_dwordx4 v[106:109], v[32:33], off offset:1024
	v_or_b32_e32 v32, 2, v36
	v_mad_i64_i32 v[32:33], s[26:27], v32, s19, v[114:115]
	v_mad_i64_i32 v[34:35], s[26:27], v34, s19, v[114:115]
	global_load_dwordx4 v[102:105], v[32:33], off offset:1024
	global_load_dwordx4 v[98:101], v[34:35], off offset:1024
	v_or_b32_e32 v32, 4, v36
	v_or_b32_e32 v34, 5, v36
	v_mad_i64_i32 v[32:33], s[26:27], v32, s19, v[114:115]
	v_mad_i64_i32 v[34:35], s[26:27], v34, s19, v[114:115]
	global_load_dwordx4 v[94:97], v[32:33], off offset:1024
	global_load_dwordx4 v[90:93], v[34:35], off offset:1024
	v_or_b32_e32 v32, 6, v36
	v_or_b32_e32 v34, 7, v36
	v_mad_i64_i32 v[32:33], s[26:27], v32, s19, v[114:115]
	v_mad_i64_i32 v[34:35], s[26:27], v34, s19, v[114:115]
	global_load_dwordx4 v[86:89], v[32:33], off offset:1024
	global_load_dwordx4 v[82:85], v[34:35], off offset:1024
	v_or_b32_e32 v32, 8, v36
	v_or_b32_e32 v34, 9, v36
	v_mad_i64_i32 v[32:33], s[26:27], v32, s19, v[114:115]
	v_mad_i64_i32 v[34:35], s[26:27], v34, s19, v[114:115]
	global_load_dwordx4 v[78:81], v[32:33], off offset:1024
	global_load_dwordx4 v[74:77], v[34:35], off offset:1024
	v_or_b32_e32 v32, 10, v36
	v_or_b32_e32 v34, 11, v36
	v_mad_i64_i32 v[32:33], s[26:27], v32, s19, v[114:115]
	v_mad_i64_i32 v[34:35], s[26:27], v34, s19, v[114:115]
	s_lshl_b64 s[6:7], s[50:51], 2
	global_load_dwordx4 v[70:73], v[32:33], off offset:1024
	global_load_dwordx4 v[66:69], v[34:35], off offset:1024
	v_or_b32_e32 v32, 12, v36
	v_or_b32_e32 v34, 13, v36
	s_add_u32 s20, s20, s6
	v_mad_i64_i32 v[32:33], s[26:27], v32, s19, v[114:115]
	v_mad_i64_i32 v[34:35], s[26:27], v34, s19, v[114:115]
	s_addc_u32 s21, s21, s7
	global_load_dwordx4 v[62:65], v[32:33], off offset:1024
	global_load_dwordx4 v[58:61], v[34:35], off offset:1024
	v_or_b32_e32 v32, 14, v36
	v_or_b32_e32 v34, 15, v36
	v_mad_i64_i32 v[32:33], s[26:27], v32, s19, v[114:115]
	v_mad_i64_i32 v[34:35], s[26:27], v34, s19, v[114:115]
	s_add_u32 s6, s40, s6
	global_load_dwordx4 v[54:57], v[32:33], off offset:1024
	global_load_dwordx4 v[50:53], v[34:35], off offset:1024
	s_addc_u32 s7, s41, s7
	global_load_dwordx4 v[40:43], v121, s[20:21]
	global_load_dwordx4 v[32:35], v121, s[20:21] offset:16
	global_load_dwordx4 v[44:47], v121, s[6:7]
	global_load_dwordx4 v[36:39], v121, s[6:7] offset:16
	v_cmp_eq_u32_e32 vcc, v119, v124
	s_waitcnt vmcnt(24)
	v_lshlrev_b32_e32 v125, 16, v126
	v_and_b32_e32 v126, 0xffff0000, v126
	v_mul_f32_e32 v48, 0x3d372713, v125
	v_lshlrev_b32_e32 v133, 16, v127
	v_lshlrev_b32_e32 v134, 16, v128
	v_mul_f32_e32 v48, v48, v125
	v_and_b32_e32 v135, 0xffff0000, v128
	v_mul_f32_e32 v128, 0x3d372713, v126
	v_fma_f32 v48, v48, v125, v125
	v_lshlrev_b32_e32 v136, 16, v129
	v_and_b32_e32 v137, 0xffff0000, v129
	v_mul_f32_e32 v128, v128, v126
	v_mul_f32_e32 v129, 0x3d372713, v133
	v_mul_f32_e32 v48, 0xbfcc422a, v48
	v_fma_f32 v128, v128, v126, v126
	v_mul_f32_e32 v129, v129, v133
	v_mul_f32_e32 v48, 0x3fb8aa3b, v48
	v_mul_f32_e32 v128, 0xbfcc422a, v128
	v_fma_f32 v129, v129, v133, v133
	v_exp_f32_e32 v48, v48
	v_mul_f32_e32 v128, 0x3fb8aa3b, v128
	v_mul_f32_e32 v129, 0xbfcc422a, v129
	v_exp_f32_e32 v128, v128
	v_mul_f32_e32 v129, 0x3fb8aa3b, v129
	v_exp_f32_e32 v129, v129
	v_add_f32_e32 v48, 1.0, v48
	v_rcp_f32_e32 v130, v48
	v_add_f32_e32 v48, 1.0, v128
	v_and_b32_e32 v127, 0xffff0000, v127
	v_rcp_f32_e32 v128, v48
	v_add_f32_e32 v48, 1.0, v129
	v_rcp_f32_e32 v129, v48
	v_mul_f32_e32 v48, 0x3d372713, v127
	v_mul_f32_e32 v48, v48, v127
	v_fma_f32 v48, v48, v127, v127
	v_mul_f32_e32 v48, 0xbfcc422a, v48
	v_mul_f32_e32 v48, 0x3fb8aa3b, v48
	v_exp_f32_e32 v48, v48
	v_mul_f32_e32 v139, 0x3d372713, v135
	v_mul_f32_e32 v139, v139, v135
	v_fma_f32 v139, v139, v135, v135
	v_add_f32_e32 v48, 1.0, v48
	v_rcp_f32_e32 v138, v48
	v_mul_f32_e32 v48, 0x3d372713, v134
	v_mul_f32_e32 v48, v48, v134
	v_fma_f32 v48, v48, v134, v134
	v_mul_f32_e32 v48, 0xbfcc422a, v48
	v_mul_f32_e32 v48, 0x3fb8aa3b, v48
	v_mul_f32_e32 v139, 0xbfcc422a, v139
	v_exp_f32_e32 v48, v48
	v_mul_f32_e32 v139, 0x3fb8aa3b, v139
	v_exp_f32_e32 v139, v139
	v_mul_f32_e32 v141, 0x3d372713, v137
	v_add_f32_e32 v48, 1.0, v48
	v_rcp_f32_e32 v140, v48
	v_add_f32_e32 v48, 1.0, v139
	v_mul_f32_e32 v139, 0x3d372713, v136
	v_mul_f32_e32 v139, v139, v136
	v_fma_f32 v139, v139, v136, v136
	v_mul_f32_e32 v141, v141, v137
	v_mul_f32_e32 v139, 0xbfcc422a, v139
	v_fma_f32 v141, v141, v137, v137
	v_mul_f32_e32 v139, 0x3fb8aa3b, v139
	v_mul_f32_e32 v141, 0xbfcc422a, v141
	v_exp_f32_e32 v139, v139
	v_mul_f32_e32 v141, 0x3fb8aa3b, v141
	v_exp_f32_e32 v141, v141
	v_fma_f32 v132, v130, v125, 0
	v_fmac_f32_e32 v132, v128, v126
	v_rcp_f32_e32 v142, v48
	v_add_f32_e32 v48, 1.0, v139
	v_fmac_f32_e32 v132, v129, v133
	v_rcp_f32_e32 v139, v48
	v_add_f32_e32 v48, 1.0, v141
	v_fmac_f32_e32 v132, v138, v127
	v_rcp_f32_e32 v141, v48
	v_fmac_f32_e32 v132, v140, v134
	v_fmac_f32_e32 v132, v142, v135
	v_fmac_f32_e32 v132, v139, v136
	v_fmac_f32_e32 v132, v141, v137
	s_nop 1
	v_add_f32_dpp v48, v132, v132 row_mirror row_mask:0xf bank_mask:0xf bound_ctrl:1
	s_nop 1
	v_add_f32_dpp v48, v48, v48 row_half_mirror row_mask:0xf bank_mask:0xf bound_ctrl:1
	s_nop 1
	v_add_f32_dpp v48, v48, v48 quad_perm:[1,0,3,2] row_mask:0xf bank_mask:0xf bound_ctrl:1
	s_nop 1
	v_add_f32_dpp v48, v48, v48 quad_perm:[2,3,0,1] row_mask:0xf bank_mask:0xf bound_ctrl:1
	s_waitcnt lgkmcnt(0)
	v_mov_b32_e32 v132, v48
	s_nop 1
	v_permlane16_swap_b32_e32 v48, v132
	v_add_f32_e32 v48, v48, v132
	v_mov_b32_e32 v132, v48
	s_nop 1
	v_permlane32_swap_b32_e32 v48, v132
	v_add_f32_e32 v48, v48, v132
	v_mul_f32_e32 v48, 0xbb000000, v48
	v_fma_f32 v132, v130, v125, v48
	v_fma_f32 v130, v128, v126, v48
	v_mul_f32_e32 v143, v130, v130
	v_fmac_f32_e32 v143, v132, v132
	v_fma_f32 v129, v129, v133, v48
	v_fmac_f32_e32 v143, v129, v129
	v_fma_f32 v128, v138, v127, v48
	v_fmac_f32_e32 v143, v128, v128
	v_fma_f32 v127, v140, v134, v48
	v_fmac_f32_e32 v143, v127, v127
	v_fma_f32 v126, v142, v135, v48
	v_fmac_f32_e32 v143, v126, v126
	v_fma_f32 v125, v139, v136, v48
	v_fmac_f32_e32 v143, v125, v125
	v_fmac_f32_e32 v48, v141, v137
	v_fmac_f32_e32 v143, v48, v48
	s_nop 1
	v_add_f32_dpp v133, v143, v143 row_mirror row_mask:0xf bank_mask:0xf bound_ctrl:1
	s_nop 1
	v_add_f32_dpp v133, v133, v133 row_half_mirror row_mask:0xf bank_mask:0xf bound_ctrl:1
	s_nop 1
	v_add_f32_dpp v133, v133, v133 quad_perm:[1,0,3,2] row_mask:0xf bank_mask:0xf bound_ctrl:1
	s_nop 1
	v_add_f32_dpp v133, v133, v133 quad_perm:[2,3,0,1] row_mask:0xf bank_mask:0xf bound_ctrl:1
	s_waitcnt lgkmcnt(0)
	v_mov_b32_e32 v134, v133
	s_nop 1
	v_permlane16_swap_b32_e32 v133, v134
	v_add_f32_e32 v133, v133, v134
	v_mov_b32_e32 v134, v133
	s_nop 1
	v_permlane32_swap_b32_e32 v133, v134
	s_and_saveexec_b64 s[52:53], vcc
	s_cbranch_execz .LBB0_918
	v_add_f32_e32 v133, v133, v134
	v_fmamk_f32 v133, v133, 0x3b000000, v206
	v_mul_f32_e32 v134, 0x4b800000, v133
	v_cmp_gt_f32_e64 s[40:41], s75, v133
	s_nop 1
	v_cndmask_b32_e64 v133, v133, v134, s[40:41]
	v_rsq_f32_e32 v133, v133
	s_nop 0
	v_mul_f32_e32 v134, 0x45800000, v133
	v_cndmask_b32_e64 v133, v133, v134, s[40:41]
	v_mul_f32_e32 v132, v132, v133
	v_mul_f32_e32 v130, v130, v133
	v_mul_f32_e32 v129, v129, v133
	v_mul_f32_e32 v128, v128, v133
	v_mul_f32_e32 v127, v127, v133
	v_mul_f32_e32 v126, v126, v133
	v_mul_f32_e32 v125, v125, v133
	v_mul_f32_e32 v48, v48, v133
	s_waitcnt vmcnt(1)
	v_fma_f32 v132, v40, v132, v44
	v_fma_f32 v130, v41, v130, v45
	v_fma_f32 v129, v42, v129, v46
	v_fma_f32 v128, v43, v128, v47
	s_waitcnt vmcnt(0)
	v_fma_f32 v127, v32, v127, v36
	v_fma_f32 v126, v33, v126, v37
	v_fma_f32 v125, v34, v125, v38
	v_fma_f32 v48, v35, v48, v39
	v_cvt_pk_bf16_f32 v132, v132, s0
	v_cvt_pk_bf16_f32 v130, v130, s0
	v_cvt_pk_bf16_f32 v129, v129, s0
	v_cvt_pk_bf16_f32 v128, v128, s0
	v_cvt_pk_bf16_f32 v127, v127, s0
	v_cvt_pk_bf16_f32 v126, v126, s0
	v_cvt_pk_bf16_f32 v125, v125, s0
	v_cvt_pk_bf16_f32 v48, v48, s0
	ds_write_b16 v120, v132
	ds_write_b16 v120, v130 offset:272
	ds_write_b16 v120, v129 offset:544
	ds_write_b16 v120, v128 offset:816
	ds_write_b16 v120, v127 offset:1088
	ds_write_b16 v120, v126 offset:1360
	ds_write_b16 v120, v125 offset:1632
	ds_write_b16 v120, v48 offset:1904
.LBB0_918:
	s_or_b64 exec, exec, s[52:53]
	s_waitcnt vmcnt(18)
	v_lshlrev_b32_e32 v125, 16, v106
	v_and_b32_e32 v106, 0xffff0000, v106
	v_mul_f32_e32 v48, 0x3d372713, v125
	v_lshlrev_b32_e32 v128, 16, v107
	v_lshlrev_b32_e32 v129, 16, v108
	v_mul_f32_e32 v48, v48, v125
	v_and_b32_e32 v130, 0xffff0000, v108
	v_mul_f32_e32 v108, 0x3d372713, v106
	v_fma_f32 v48, v48, v125, v125
	v_lshlrev_b32_e32 v132, 16, v109
	v_and_b32_e32 v133, 0xffff0000, v109
	v_mul_f32_e32 v108, v108, v106
	v_mul_f32_e32 v109, 0x3d372713, v128
	v_mul_f32_e32 v48, 0xbfcc422a, v48
	v_fma_f32 v108, v108, v106, v106
	v_mul_f32_e32 v109, v109, v128
	v_mul_f32_e32 v48, 0x3fb8aa3b, v48
	v_mul_f32_e32 v108, 0xbfcc422a, v108
	v_fma_f32 v109, v109, v128, v128
	v_exp_f32_e32 v48, v48
	v_mul_f32_e32 v108, 0x3fb8aa3b, v108
	v_mul_f32_e32 v109, 0xbfcc422a, v109
	v_exp_f32_e32 v108, v108
	v_mul_f32_e32 v109, 0x3fb8aa3b, v109
	v_exp_f32_e32 v109, v109
	v_add_f32_e32 v48, 1.0, v48
	v_rcp_f32_e32 v126, v48
	v_add_f32_e32 v48, 1.0, v108
	v_and_b32_e32 v107, 0xffff0000, v107
	v_rcp_f32_e32 v108, v48
	v_add_f32_e32 v48, 1.0, v109
	v_rcp_f32_e32 v109, v48
	v_mul_f32_e32 v48, 0x3d372713, v107
	v_mul_f32_e32 v48, v48, v107
	v_fma_f32 v48, v48, v107, v107
	v_mul_f32_e32 v48, 0xbfcc422a, v48
	v_mul_f32_e32 v48, 0x3fb8aa3b, v48
	v_exp_f32_e32 v48, v48
	v_mul_f32_e32 v135, 0x3d372713, v130
	v_mul_f32_e32 v135, v135, v130
	v_fma_f32 v135, v135, v130, v130
	v_add_f32_e32 v48, 1.0, v48
	v_rcp_f32_e32 v134, v48
	v_mul_f32_e32 v48, 0x3d372713, v129
	v_mul_f32_e32 v48, v48, v129
	v_fma_f32 v48, v48, v129, v129
	v_mul_f32_e32 v48, 0xbfcc422a, v48
	v_mul_f32_e32 v48, 0x3fb8aa3b, v48
	v_mul_f32_e32 v135, 0xbfcc422a, v135
	v_exp_f32_e32 v48, v48
	v_mul_f32_e32 v135, 0x3fb8aa3b, v135
	v_exp_f32_e32 v135, v135
	v_mul_f32_e32 v137, 0x3d372713, v133
	v_add_f32_e32 v48, 1.0, v48
	v_rcp_f32_e32 v136, v48
	v_add_f32_e32 v48, 1.0, v135
	v_mul_f32_e32 v135, 0x3d372713, v132
	v_mul_f32_e32 v135, v135, v132
	v_fma_f32 v135, v135, v132, v132
	v_mul_f32_e32 v137, v137, v133
	v_mul_f32_e32 v135, 0xbfcc422a, v135
	v_fma_f32 v137, v137, v133, v133
	v_mul_f32_e32 v135, 0x3fb8aa3b, v135
	v_mul_f32_e32 v137, 0xbfcc422a, v137
	v_exp_f32_e32 v135, v135
	v_mul_f32_e32 v137, 0x3fb8aa3b, v137
	v_exp_f32_e32 v137, v137
	v_fma_f32 v127, v126, v125, 0
	v_fmac_f32_e32 v127, v108, v106
	v_rcp_f32_e32 v138, v48
	v_add_f32_e32 v48, 1.0, v135
	v_fmac_f32_e32 v127, v109, v128
	v_rcp_f32_e32 v135, v48
	v_add_f32_e32 v48, 1.0, v137
	v_fmac_f32_e32 v127, v134, v107
	v_rcp_f32_e32 v137, v48
	v_fmac_f32_e32 v127, v136, v129
	v_fmac_f32_e32 v127, v138, v130
	v_fmac_f32_e32 v127, v135, v132
	v_fmac_f32_e32 v127, v137, v133
	s_nop 1
	v_add_f32_dpp v48, v127, v127 row_mirror row_mask:0xf bank_mask:0xf bound_ctrl:1
	s_nop 1
	v_add_f32_dpp v48, v48, v48 row_half_mirror row_mask:0xf bank_mask:0xf bound_ctrl:1
	s_nop 1
	v_add_f32_dpp v48, v48, v48 quad_perm:[1,0,3,2] row_mask:0xf bank_mask:0xf bound_ctrl:1
	s_nop 1
	v_add_f32_dpp v48, v48, v48 quad_perm:[2,3,0,1] row_mask:0xf bank_mask:0xf bound_ctrl:1
	s_waitcnt lgkmcnt(0)
	v_mov_b32_e32 v127, v48
	s_nop 1
	v_permlane16_swap_b32_e32 v48, v127
	v_add_f32_e32 v48, v48, v127
	v_mov_b32_e32 v127, v48
	s_nop 1
	v_permlane32_swap_b32_e32 v48, v127
	v_add_f32_e32 v48, v48, v127
	v_mul_f32_e32 v48, 0xbb000000, v48
	v_fma_f32 v127, v126, v125, v48
	v_fma_f32 v126, v108, v106, v48
	v_mul_f32_e32 v139, v126, v126
	v_fmac_f32_e32 v139, v127, v127
	v_fma_f32 v125, v109, v128, v48
	v_fmac_f32_e32 v139, v125, v125
	v_fma_f32 v109, v134, v107, v48
	v_fmac_f32_e32 v139, v109, v109
	v_fma_f32 v108, v136, v129, v48
	v_fmac_f32_e32 v139, v108, v108
	v_fma_f32 v107, v138, v130, v48
	v_fmac_f32_e32 v139, v107, v107
	v_fma_f32 v106, v135, v132, v48
	v_fmac_f32_e32 v139, v106, v106
	v_fmac_f32_e32 v48, v137, v133
	v_fmac_f32_e32 v139, v48, v48
	s_nop 1
	v_add_f32_dpp v128, v139, v139 row_mirror row_mask:0xf bank_mask:0xf bound_ctrl:1
	s_nop 1
	v_add_f32_dpp v128, v128, v128 row_half_mirror row_mask:0xf bank_mask:0xf bound_ctrl:1
	s_nop 1
	v_add_f32_dpp v128, v128, v128 quad_perm:[1,0,3,2] row_mask:0xf bank_mask:0xf bound_ctrl:1
	s_nop 1
	v_add_f32_dpp v128, v128, v128 quad_perm:[2,3,0,1] row_mask:0xf bank_mask:0xf bound_ctrl:1
	s_waitcnt lgkmcnt(0)
	v_mov_b32_e32 v129, v128
	s_nop 1
	v_permlane16_swap_b32_e32 v128, v129
	v_add_f32_e32 v128, v128, v129
	v_mov_b32_e32 v129, v128
	s_nop 1
	v_permlane32_swap_b32_e32 v128, v129
	s_and_saveexec_b64 s[52:53], vcc
	s_cbranch_execz .LBB0_920
	v_add_f32_e32 v128, v128, v129
	v_fmamk_f32 v128, v128, 0x3b000000, v206
	v_mul_f32_e32 v129, 0x4b800000, v128
	v_cmp_gt_f32_e64 s[40:41], s75, v128
	s_nop 1
	v_cndmask_b32_e64 v128, v128, v129, s[40:41]
	v_rsq_f32_e32 v128, v128
	s_nop 0
	v_mul_f32_e32 v129, 0x45800000, v128
	v_cndmask_b32_e64 v128, v128, v129, s[40:41]
	v_mul_f32_e32 v127, v127, v128
	v_mul_f32_e32 v126, v126, v128
	v_mul_f32_e32 v125, v125, v128
	v_mul_f32_e32 v109, v109, v128
	v_mul_f32_e32 v108, v108, v128
	v_mul_f32_e32 v107, v107, v128
	v_mul_f32_e32 v106, v106, v128
	v_mul_f32_e32 v48, v48, v128
	s_waitcnt vmcnt(1)
	v_fma_f32 v127, v40, v127, v44
	v_fma_f32 v126, v41, v126, v45
	v_fma_f32 v125, v42, v125, v46
	v_fma_f32 v109, v43, v109, v47
	s_waitcnt vmcnt(0)
	v_fma_f32 v108, v32, v108, v36
	v_fma_f32 v107, v33, v107, v37
	v_fma_f32 v106, v34, v106, v38
	v_fma_f32 v48, v35, v48, v39
	v_cvt_pk_bf16_f32 v127, v127, s0
	v_cvt_pk_bf16_f32 v126, v126, s0
	v_cvt_pk_bf16_f32 v125, v125, s0
	v_cvt_pk_bf16_f32 v109, v109, s0
	v_cvt_pk_bf16_f32 v108, v108, s0
	v_cvt_pk_bf16_f32 v107, v107, s0
	v_cvt_pk_bf16_f32 v106, v106, s0
	v_cvt_pk_bf16_f32 v48, v48, s0
	ds_write_b16 v120, v127 offset:2
	ds_write_b16 v120, v126 offset:274
	ds_write_b16 v120, v125 offset:546
	ds_write_b16 v120, v109 offset:818
	ds_write_b16 v120, v108 offset:1090
	ds_write_b16 v120, v107 offset:1362
	ds_write_b16 v120, v106 offset:1634
	ds_write_b16 v120, v48 offset:1906
.LBB0_920:
	s_or_b64 exec, exec, s[52:53]
	s_waitcnt vmcnt(17)
	v_lshlrev_b32_e32 v106, 16, v102
	v_and_b32_e32 v102, 0xffff0000, v102
	v_mul_f32_e32 v48, 0x3d372713, v106
	v_lshlrev_b32_e32 v109, 16, v103
	v_lshlrev_b32_e32 v125, 16, v104
	v_mul_f32_e32 v48, v48, v106
	v_and_b32_e32 v126, 0xffff0000, v104
	v_mul_f32_e32 v104, 0x3d372713, v102
	v_fma_f32 v48, v48, v106, v106
	v_lshlrev_b32_e32 v127, 16, v105
	v_and_b32_e32 v128, 0xffff0000, v105
	v_mul_f32_e32 v104, v104, v102
	v_mul_f32_e32 v105, 0x3d372713, v109
	v_mul_f32_e32 v48, 0xbfcc422a, v48
	v_fma_f32 v104, v104, v102, v102
	v_mul_f32_e32 v105, v105, v109
	v_mul_f32_e32 v48, 0x3fb8aa3b, v48
	v_mul_f32_e32 v104, 0xbfcc422a, v104
	v_fma_f32 v105, v105, v109, v109
	v_exp_f32_e32 v48, v48
	v_mul_f32_e32 v104, 0x3fb8aa3b, v104
	v_mul_f32_e32 v105, 0xbfcc422a, v105
	v_exp_f32_e32 v104, v104
	v_mul_f32_e32 v105, 0x3fb8aa3b, v105
	v_exp_f32_e32 v105, v105
	v_add_f32_e32 v48, 1.0, v48
	v_rcp_f32_e32 v107, v48
	v_add_f32_e32 v48, 1.0, v104
	v_and_b32_e32 v103, 0xffff0000, v103
	v_rcp_f32_e32 v104, v48
	v_add_f32_e32 v48, 1.0, v105
	v_rcp_f32_e32 v105, v48
	v_mul_f32_e32 v48, 0x3d372713, v103
	v_mul_f32_e32 v48, v48, v103
	v_fma_f32 v48, v48, v103, v103
	v_mul_f32_e32 v48, 0xbfcc422a, v48
	v_mul_f32_e32 v48, 0x3fb8aa3b, v48
	v_exp_f32_e32 v48, v48
	v_mul_f32_e32 v130, 0x3d372713, v126
	v_mul_f32_e32 v130, v130, v126
	v_fma_f32 v130, v130, v126, v126
	v_add_f32_e32 v48, 1.0, v48
	v_rcp_f32_e32 v129, v48
	v_mul_f32_e32 v48, 0x3d372713, v125
	v_mul_f32_e32 v48, v48, v125
	v_fma_f32 v48, v48, v125, v125
	v_mul_f32_e32 v48, 0xbfcc422a, v48
	v_mul_f32_e32 v48, 0x3fb8aa3b, v48
	v_mul_f32_e32 v130, 0xbfcc422a, v130
	v_exp_f32_e32 v48, v48
	v_mul_f32_e32 v130, 0x3fb8aa3b, v130
	v_exp_f32_e32 v130, v130
	v_mul_f32_e32 v133, 0x3d372713, v128
	v_add_f32_e32 v48, 1.0, v48
	v_rcp_f32_e32 v132, v48
	v_add_f32_e32 v48, 1.0, v130
	v_mul_f32_e32 v130, 0x3d372713, v127
	v_mul_f32_e32 v130, v130, v127
	v_fma_f32 v130, v130, v127, v127
	v_mul_f32_e32 v133, v133, v128
	v_mul_f32_e32 v130, 0xbfcc422a, v130
	v_fma_f32 v133, v133, v128, v128
	v_mul_f32_e32 v130, 0x3fb8aa3b, v130
	v_mul_f32_e32 v133, 0xbfcc422a, v133
	v_exp_f32_e32 v130, v130
	v_mul_f32_e32 v133, 0x3fb8aa3b, v133
	v_exp_f32_e32 v133, v133
	v_fma_f32 v108, v107, v106, 0
	v_fmac_f32_e32 v108, v104, v102
	v_rcp_f32_e32 v134, v48
	v_add_f32_e32 v48, 1.0, v130
	v_fmac_f32_e32 v108, v105, v109
	v_rcp_f32_e32 v130, v48
	v_add_f32_e32 v48, 1.0, v133
	v_fmac_f32_e32 v108, v129, v103
	v_rcp_f32_e32 v133, v48
	v_fmac_f32_e32 v108, v132, v125
	v_fmac_f32_e32 v108, v134, v126
	v_fmac_f32_e32 v108, v130, v127
	v_fmac_f32_e32 v108, v133, v128
	s_nop 1
	v_add_f32_dpp v48, v108, v108 row_mirror row_mask:0xf bank_mask:0xf bound_ctrl:1
	s_nop 1
	v_add_f32_dpp v48, v48, v48 row_half_mirror row_mask:0xf bank_mask:0xf bound_ctrl:1
	s_nop 1
	v_add_f32_dpp v48, v48, v48 quad_perm:[1,0,3,2] row_mask:0xf bank_mask:0xf bound_ctrl:1
	s_nop 1
	v_add_f32_dpp v48, v48, v48 quad_perm:[2,3,0,1] row_mask:0xf bank_mask:0xf bound_ctrl:1
	s_waitcnt lgkmcnt(0)
	v_mov_b32_e32 v108, v48
	s_nop 1
	v_permlane16_swap_b32_e32 v48, v108
	v_add_f32_e32 v48, v48, v108
	v_mov_b32_e32 v108, v48
	s_nop 1
	v_permlane32_swap_b32_e32 v48, v108
	v_add_f32_e32 v48, v48, v108
	v_mul_f32_e32 v48, 0xbb000000, v48
	v_fma_f32 v108, v107, v106, v48
	v_fma_f32 v107, v104, v102, v48
	v_mul_f32_e32 v135, v107, v107
	v_fmac_f32_e32 v135, v108, v108
	v_fma_f32 v106, v105, v109, v48
	v_fmac_f32_e32 v135, v106, v106
	v_fma_f32 v105, v129, v103, v48
	v_fmac_f32_e32 v135, v105, v105
	v_fma_f32 v104, v132, v125, v48
	v_fmac_f32_e32 v135, v104, v104
	v_fma_f32 v103, v134, v126, v48
	v_fmac_f32_e32 v135, v103, v103
	v_fma_f32 v102, v130, v127, v48
	v_fmac_f32_e32 v135, v102, v102
	v_fmac_f32_e32 v48, v133, v128
	v_fmac_f32_e32 v135, v48, v48
	s_nop 1
	v_add_f32_dpp v109, v135, v135 row_mirror row_mask:0xf bank_mask:0xf bound_ctrl:1
	s_nop 1
	v_add_f32_dpp v109, v109, v109 row_half_mirror row_mask:0xf bank_mask:0xf bound_ctrl:1
	s_nop 1
	v_add_f32_dpp v109, v109, v109 quad_perm:[1,0,3,2] row_mask:0xf bank_mask:0xf bound_ctrl:1
	s_nop 1
	v_add_f32_dpp v109, v109, v109 quad_perm:[2,3,0,1] row_mask:0xf bank_mask:0xf bound_ctrl:1
	s_waitcnt lgkmcnt(0)
	v_mov_b32_e32 v125, v109
	s_nop 1
	v_permlane16_swap_b32_e32 v109, v125
	v_add_f32_e32 v109, v109, v125
	v_mov_b32_e32 v125, v109
	s_nop 1
	v_permlane32_swap_b32_e32 v109, v125
	s_and_saveexec_b64 s[52:53], vcc
	s_cbranch_execz .LBB0_922
	v_add_f32_e32 v109, v109, v125
	v_fmamk_f32 v109, v109, 0x3b000000, v206
	v_mul_f32_e32 v125, 0x4b800000, v109
	v_cmp_gt_f32_e64 s[40:41], s75, v109
	s_nop 1
	v_cndmask_b32_e64 v109, v109, v125, s[40:41]
	v_rsq_f32_e32 v109, v109
	s_nop 0
	v_mul_f32_e32 v125, 0x45800000, v109
	v_cndmask_b32_e64 v109, v109, v125, s[40:41]
	v_mul_f32_e32 v108, v108, v109
	v_mul_f32_e32 v107, v107, v109
	v_mul_f32_e32 v106, v106, v109
	v_mul_f32_e32 v105, v105, v109
	v_mul_f32_e32 v104, v104, v109
	v_mul_f32_e32 v103, v103, v109
	v_mul_f32_e32 v102, v102, v109
	v_mul_f32_e32 v48, v48, v109
	s_waitcnt vmcnt(1)
	v_fma_f32 v108, v40, v108, v44
	v_fma_f32 v107, v41, v107, v45
	v_fma_f32 v106, v42, v106, v46
	v_fma_f32 v105, v43, v105, v47
	s_waitcnt vmcnt(0)
	v_fma_f32 v104, v32, v104, v36
	v_fma_f32 v103, v33, v103, v37
	v_fma_f32 v102, v34, v102, v38
	v_fma_f32 v48, v35, v48, v39
	v_cvt_pk_bf16_f32 v108, v108, s0
	v_cvt_pk_bf16_f32 v107, v107, s0
	v_cvt_pk_bf16_f32 v106, v106, s0
	v_cvt_pk_bf16_f32 v105, v105, s0
	v_cvt_pk_bf16_f32 v104, v104, s0
	v_cvt_pk_bf16_f32 v103, v103, s0
	v_cvt_pk_bf16_f32 v102, v102, s0
	v_cvt_pk_bf16_f32 v48, v48, s0
	ds_write_b16 v120, v108 offset:4
	ds_write_b16 v120, v107 offset:276
	ds_write_b16 v120, v106 offset:548
	ds_write_b16 v120, v105 offset:820
	ds_write_b16 v120, v104 offset:1092
	ds_write_b16 v120, v103 offset:1364
	ds_write_b16 v120, v102 offset:1636
	ds_write_b16 v120, v48 offset:1908
.LBB0_922:
	s_or_b64 exec, exec, s[52:53]
	s_waitcnt vmcnt(16)
	v_lshlrev_b32_e32 v102, 16, v98
	v_and_b32_e32 v98, 0xffff0000, v98
	v_mul_f32_e32 v48, 0x3d372713, v102
	v_lshlrev_b32_e32 v105, 16, v99
	v_lshlrev_b32_e32 v106, 16, v100
	v_mul_f32_e32 v48, v48, v102
	v_and_b32_e32 v107, 0xffff0000, v100
	v_mul_f32_e32 v100, 0x3d372713, v98
	v_fma_f32 v48, v48, v102, v102
	v_lshlrev_b32_e32 v108, 16, v101
	v_and_b32_e32 v109, 0xffff0000, v101
	v_mul_f32_e32 v100, v100, v98
	v_mul_f32_e32 v101, 0x3d372713, v105
	v_mul_f32_e32 v48, 0xbfcc422a, v48
	v_fma_f32 v100, v100, v98, v98
	v_mul_f32_e32 v101, v101, v105
	v_mul_f32_e32 v48, 0x3fb8aa3b, v48
	v_mul_f32_e32 v100, 0xbfcc422a, v100
	v_fma_f32 v101, v101, v105, v105
	v_exp_f32_e32 v48, v48
	v_mul_f32_e32 v100, 0x3fb8aa3b, v100
	v_mul_f32_e32 v101, 0xbfcc422a, v101
	v_exp_f32_e32 v100, v100
	v_mul_f32_e32 v101, 0x3fb8aa3b, v101
	v_exp_f32_e32 v101, v101
	v_add_f32_e32 v48, 1.0, v48
	v_rcp_f32_e32 v103, v48
	v_add_f32_e32 v48, 1.0, v100
	v_and_b32_e32 v99, 0xffff0000, v99
	v_rcp_f32_e32 v100, v48
	v_add_f32_e32 v48, 1.0, v101
	v_rcp_f32_e32 v101, v48
	v_mul_f32_e32 v48, 0x3d372713, v99
	v_mul_f32_e32 v48, v48, v99
	v_fma_f32 v48, v48, v99, v99
	v_mul_f32_e32 v48, 0xbfcc422a, v48
	v_mul_f32_e32 v48, 0x3fb8aa3b, v48
	v_exp_f32_e32 v48, v48
	v_mul_f32_e32 v126, 0x3d372713, v107
	v_mul_f32_e32 v126, v126, v107
	v_fma_f32 v126, v126, v107, v107
	v_add_f32_e32 v48, 1.0, v48
	v_rcp_f32_e32 v125, v48
	v_mul_f32_e32 v48, 0x3d372713, v106
	v_mul_f32_e32 v48, v48, v106
	v_fma_f32 v48, v48, v106, v106
	v_mul_f32_e32 v48, 0xbfcc422a, v48
	v_mul_f32_e32 v48, 0x3fb8aa3b, v48
	v_mul_f32_e32 v126, 0xbfcc422a, v126
	v_exp_f32_e32 v48, v48
	v_mul_f32_e32 v126, 0x3fb8aa3b, v126
	v_exp_f32_e32 v126, v126
	v_mul_f32_e32 v128, 0x3d372713, v109
	v_add_f32_e32 v48, 1.0, v48
	v_rcp_f32_e32 v127, v48
	v_add_f32_e32 v48, 1.0, v126
	v_mul_f32_e32 v126, 0x3d372713, v108
	v_mul_f32_e32 v126, v126, v108
	v_fma_f32 v126, v126, v108, v108
	v_mul_f32_e32 v128, v128, v109
	v_mul_f32_e32 v126, 0xbfcc422a, v126
	v_fma_f32 v128, v128, v109, v109
	v_mul_f32_e32 v126, 0x3fb8aa3b, v126
	v_mul_f32_e32 v128, 0xbfcc422a, v128
	v_exp_f32_e32 v126, v126
	v_mul_f32_e32 v128, 0x3fb8aa3b, v128
	v_exp_f32_e32 v128, v128
	v_fma_f32 v104, v103, v102, 0
	v_fmac_f32_e32 v104, v100, v98
	v_rcp_f32_e32 v129, v48
	v_add_f32_e32 v48, 1.0, v126
	v_fmac_f32_e32 v104, v101, v105
	v_rcp_f32_e32 v126, v48
	v_add_f32_e32 v48, 1.0, v128
	v_fmac_f32_e32 v104, v125, v99
	v_rcp_f32_e32 v128, v48
	v_fmac_f32_e32 v104, v127, v106
	v_fmac_f32_e32 v104, v129, v107
	v_fmac_f32_e32 v104, v126, v108
	v_fmac_f32_e32 v104, v128, v109
	s_nop 1
	v_add_f32_dpp v48, v104, v104 row_mirror row_mask:0xf bank_mask:0xf bound_ctrl:1
	s_nop 1
	v_add_f32_dpp v48, v48, v48 row_half_mirror row_mask:0xf bank_mask:0xf bound_ctrl:1
	s_nop 1
	v_add_f32_dpp v48, v48, v48 quad_perm:[1,0,3,2] row_mask:0xf bank_mask:0xf bound_ctrl:1
	s_nop 1
	v_add_f32_dpp v48, v48, v48 quad_perm:[2,3,0,1] row_mask:0xf bank_mask:0xf bound_ctrl:1
	s_waitcnt lgkmcnt(0)
	v_mov_b32_e32 v104, v48
	s_nop 1
	v_permlane16_swap_b32_e32 v48, v104
	v_add_f32_e32 v48, v48, v104
	v_mov_b32_e32 v104, v48
	s_nop 1
	v_permlane32_swap_b32_e32 v48, v104
	v_add_f32_e32 v48, v48, v104
	v_mul_f32_e32 v48, 0xbb000000, v48
	v_fma_f32 v104, v103, v102, v48
	v_fma_f32 v103, v100, v98, v48
	v_mul_f32_e32 v130, v103, v103
	v_fmac_f32_e32 v130, v104, v104
	v_fma_f32 v102, v101, v105, v48
	v_fmac_f32_e32 v130, v102, v102
	v_fma_f32 v101, v125, v99, v48
	v_fmac_f32_e32 v130, v101, v101
	v_fma_f32 v100, v127, v106, v48
	v_fmac_f32_e32 v130, v100, v100
	v_fma_f32 v99, v129, v107, v48
	v_fmac_f32_e32 v130, v99, v99
	v_fma_f32 v98, v126, v108, v48
	v_fmac_f32_e32 v130, v98, v98
	v_fmac_f32_e32 v48, v128, v109
	v_fmac_f32_e32 v130, v48, v48
	s_nop 1
	v_add_f32_dpp v105, v130, v130 row_mirror row_mask:0xf bank_mask:0xf bound_ctrl:1
	s_nop 1
	v_add_f32_dpp v105, v105, v105 row_half_mirror row_mask:0xf bank_mask:0xf bound_ctrl:1
	s_nop 1
	v_add_f32_dpp v105, v105, v105 quad_perm:[1,0,3,2] row_mask:0xf bank_mask:0xf bound_ctrl:1
	s_nop 1
	v_add_f32_dpp v105, v105, v105 quad_perm:[2,3,0,1] row_mask:0xf bank_mask:0xf bound_ctrl:1
	s_waitcnt lgkmcnt(0)
	v_mov_b32_e32 v106, v105
	s_nop 1
	v_permlane16_swap_b32_e32 v105, v106
	v_add_f32_e32 v105, v105, v106
	v_mov_b32_e32 v106, v105
	s_nop 1
	v_permlane32_swap_b32_e32 v105, v106
	s_and_saveexec_b64 s[52:53], vcc
	s_cbranch_execz .LBB0_924
	v_add_f32_e32 v105, v105, v106
	v_fmamk_f32 v105, v105, 0x3b000000, v206
	v_mul_f32_e32 v106, 0x4b800000, v105
	v_cmp_gt_f32_e64 s[40:41], s75, v105
	s_nop 1
	v_cndmask_b32_e64 v105, v105, v106, s[40:41]
	v_rsq_f32_e32 v105, v105
	s_nop 0
	v_mul_f32_e32 v106, 0x45800000, v105
	v_cndmask_b32_e64 v105, v105, v106, s[40:41]
	v_mul_f32_e32 v104, v104, v105
	v_mul_f32_e32 v103, v103, v105
	v_mul_f32_e32 v102, v102, v105
	v_mul_f32_e32 v101, v101, v105
	v_mul_f32_e32 v100, v100, v105
	v_mul_f32_e32 v99, v99, v105
	v_mul_f32_e32 v98, v98, v105
	v_mul_f32_e32 v48, v48, v105
	s_waitcnt vmcnt(1)
	v_fma_f32 v104, v40, v104, v44
	v_fma_f32 v103, v41, v103, v45
	v_fma_f32 v102, v42, v102, v46
	v_fma_f32 v101, v43, v101, v47
	s_waitcnt vmcnt(0)
	v_fma_f32 v100, v32, v100, v36
	v_fma_f32 v99, v33, v99, v37
	v_fma_f32 v98, v34, v98, v38
	v_fma_f32 v48, v35, v48, v39
	v_cvt_pk_bf16_f32 v104, v104, s0
	v_cvt_pk_bf16_f32 v103, v103, s0
	v_cvt_pk_bf16_f32 v102, v102, s0
	v_cvt_pk_bf16_f32 v101, v101, s0
	v_cvt_pk_bf16_f32 v100, v100, s0
	v_cvt_pk_bf16_f32 v99, v99, s0
	v_cvt_pk_bf16_f32 v98, v98, s0
	v_cvt_pk_bf16_f32 v48, v48, s0
	ds_write_b16 v120, v104 offset:6
	ds_write_b16 v120, v103 offset:278
	ds_write_b16 v120, v102 offset:550
	ds_write_b16 v120, v101 offset:822
	ds_write_b16 v120, v100 offset:1094
	ds_write_b16 v120, v99 offset:1366
	ds_write_b16 v120, v98 offset:1638
	ds_write_b16 v120, v48 offset:1910
.LBB0_924:
	s_or_b64 exec, exec, s[52:53]
	s_waitcnt vmcnt(15)
	v_lshlrev_b32_e32 v98, 16, v94
	v_and_b32_e32 v94, 0xffff0000, v94
	v_mul_f32_e32 v48, 0x3d372713, v98
	v_lshlrev_b32_e32 v101, 16, v95
	v_lshlrev_b32_e32 v102, 16, v96
	v_mul_f32_e32 v48, v48, v98
	v_and_b32_e32 v103, 0xffff0000, v96
	v_mul_f32_e32 v96, 0x3d372713, v94
	v_fma_f32 v48, v48, v98, v98
	v_lshlrev_b32_e32 v104, 16, v97
	v_and_b32_e32 v105, 0xffff0000, v97
	v_mul_f32_e32 v96, v96, v94
	v_mul_f32_e32 v97, 0x3d372713, v101
	v_mul_f32_e32 v48, 0xbfcc422a, v48
	v_fma_f32 v96, v96, v94, v94
	v_mul_f32_e32 v97, v97, v101
	v_mul_f32_e32 v48, 0x3fb8aa3b, v48
	v_mul_f32_e32 v96, 0xbfcc422a, v96
	v_fma_f32 v97, v97, v101, v101
	v_exp_f32_e32 v48, v48
	v_mul_f32_e32 v96, 0x3fb8aa3b, v96
	v_mul_f32_e32 v97, 0xbfcc422a, v97
	v_exp_f32_e32 v96, v96
	v_mul_f32_e32 v97, 0x3fb8aa3b, v97
	v_exp_f32_e32 v97, v97
	v_add_f32_e32 v48, 1.0, v48
	v_rcp_f32_e32 v99, v48
	v_add_f32_e32 v48, 1.0, v96
	v_and_b32_e32 v95, 0xffff0000, v95
	v_rcp_f32_e32 v96, v48
	v_add_f32_e32 v48, 1.0, v97
	v_rcp_f32_e32 v97, v48
	v_mul_f32_e32 v48, 0x3d372713, v95
	v_mul_f32_e32 v48, v48, v95
	v_fma_f32 v48, v48, v95, v95
	v_mul_f32_e32 v48, 0xbfcc422a, v48
	v_mul_f32_e32 v48, 0x3fb8aa3b, v48
	v_exp_f32_e32 v48, v48
	v_mul_f32_e32 v107, 0x3d372713, v103
	v_mul_f32_e32 v107, v107, v103
	v_fma_f32 v107, v107, v103, v103
	v_add_f32_e32 v48, 1.0, v48
	v_rcp_f32_e32 v106, v48
	v_mul_f32_e32 v48, 0x3d372713, v102
	v_mul_f32_e32 v48, v48, v102
	v_fma_f32 v48, v48, v102, v102
	v_mul_f32_e32 v48, 0xbfcc422a, v48
	v_mul_f32_e32 v48, 0x3fb8aa3b, v48
	v_mul_f32_e32 v107, 0xbfcc422a, v107
	v_exp_f32_e32 v48, v48
	v_mul_f32_e32 v107, 0x3fb8aa3b, v107
	v_exp_f32_e32 v107, v107
	v_mul_f32_e32 v109, 0x3d372713, v105
	v_add_f32_e32 v48, 1.0, v48
	v_rcp_f32_e32 v108, v48
	v_add_f32_e32 v48, 1.0, v107
	v_mul_f32_e32 v107, 0x3d372713, v104
	v_mul_f32_e32 v107, v107, v104
	v_fma_f32 v107, v107, v104, v104
	v_mul_f32_e32 v109, v109, v105
	v_mul_f32_e32 v107, 0xbfcc422a, v107
	v_fma_f32 v109, v109, v105, v105
	v_mul_f32_e32 v107, 0x3fb8aa3b, v107
	v_mul_f32_e32 v109, 0xbfcc422a, v109
	v_exp_f32_e32 v107, v107
	v_mul_f32_e32 v109, 0x3fb8aa3b, v109
	v_exp_f32_e32 v109, v109
	v_fma_f32 v100, v99, v98, 0
	v_fmac_f32_e32 v100, v96, v94
	v_rcp_f32_e32 v125, v48
	v_add_f32_e32 v48, 1.0, v107
	v_fmac_f32_e32 v100, v97, v101
	v_rcp_f32_e32 v107, v48
	v_add_f32_e32 v48, 1.0, v109
	v_fmac_f32_e32 v100, v106, v95
	v_rcp_f32_e32 v109, v48
	v_fmac_f32_e32 v100, v108, v102
	v_fmac_f32_e32 v100, v125, v103
	v_fmac_f32_e32 v100, v107, v104
	v_fmac_f32_e32 v100, v109, v105
	s_nop 1
	v_add_f32_dpp v48, v100, v100 row_mirror row_mask:0xf bank_mask:0xf bound_ctrl:1
	s_nop 1
	v_add_f32_dpp v48, v48, v48 row_half_mirror row_mask:0xf bank_mask:0xf bound_ctrl:1
	s_nop 1
	v_add_f32_dpp v48, v48, v48 quad_perm:[1,0,3,2] row_mask:0xf bank_mask:0xf bound_ctrl:1
	s_nop 1
	v_add_f32_dpp v48, v48, v48 quad_perm:[2,3,0,1] row_mask:0xf bank_mask:0xf bound_ctrl:1
	s_waitcnt lgkmcnt(0)
	v_mov_b32_e32 v100, v48
	s_nop 1
	v_permlane16_swap_b32_e32 v48, v100
	v_add_f32_e32 v48, v48, v100
	v_mov_b32_e32 v100, v48
	s_nop 1
	v_permlane32_swap_b32_e32 v48, v100
	v_add_f32_e32 v48, v48, v100
	v_mul_f32_e32 v48, 0xbb000000, v48
	v_fma_f32 v100, v99, v98, v48
	v_fma_f32 v99, v96, v94, v48
	v_mul_f32_e32 v126, v99, v99
	v_fmac_f32_e32 v126, v100, v100
	v_fma_f32 v98, v97, v101, v48
	v_fmac_f32_e32 v126, v98, v98
	v_fma_f32 v97, v106, v95, v48
	v_fmac_f32_e32 v126, v97, v97
	v_fma_f32 v96, v108, v102, v48
	v_fmac_f32_e32 v126, v96, v96
	v_fma_f32 v95, v125, v103, v48
	v_fmac_f32_e32 v126, v95, v95
	v_fma_f32 v94, v107, v104, v48
	v_fmac_f32_e32 v126, v94, v94
	v_fmac_f32_e32 v48, v109, v105
	v_fmac_f32_e32 v126, v48, v48
	s_nop 1
	v_add_f32_dpp v101, v126, v126 row_mirror row_mask:0xf bank_mask:0xf bound_ctrl:1
	s_nop 1
	v_add_f32_dpp v101, v101, v101 row_half_mirror row_mask:0xf bank_mask:0xf bound_ctrl:1
	s_nop 1
	v_add_f32_dpp v101, v101, v101 quad_perm:[1,0,3,2] row_mask:0xf bank_mask:0xf bound_ctrl:1
	s_nop 1
	v_add_f32_dpp v101, v101, v101 quad_perm:[2,3,0,1] row_mask:0xf bank_mask:0xf bound_ctrl:1
	s_waitcnt lgkmcnt(0)
	v_mov_b32_e32 v102, v101
	s_nop 1
	v_permlane16_swap_b32_e32 v101, v102
	v_add_f32_e32 v101, v101, v102
	v_mov_b32_e32 v102, v101
	s_nop 1
	v_permlane32_swap_b32_e32 v101, v102
	s_and_saveexec_b64 s[52:53], vcc
	s_cbranch_execz .LBB0_926
	v_add_f32_e32 v101, v101, v102
	v_fmamk_f32 v101, v101, 0x3b000000, v206
	v_mul_f32_e32 v102, 0x4b800000, v101
	v_cmp_gt_f32_e64 s[40:41], s75, v101
	s_nop 1
	v_cndmask_b32_e64 v101, v101, v102, s[40:41]
	v_rsq_f32_e32 v101, v101
	s_nop 0
	v_mul_f32_e32 v102, 0x45800000, v101
	v_cndmask_b32_e64 v101, v101, v102, s[40:41]
	v_mul_f32_e32 v100, v100, v101
	v_mul_f32_e32 v99, v99, v101
	v_mul_f32_e32 v98, v98, v101
	v_mul_f32_e32 v97, v97, v101
	v_mul_f32_e32 v96, v96, v101
	v_mul_f32_e32 v95, v95, v101
	v_mul_f32_e32 v94, v94, v101
	v_mul_f32_e32 v48, v48, v101
	s_waitcnt vmcnt(1)
	v_fma_f32 v100, v40, v100, v44
	v_fma_f32 v99, v41, v99, v45
	v_fma_f32 v98, v42, v98, v46
	v_fma_f32 v97, v43, v97, v47
	s_waitcnt vmcnt(0)
	v_fma_f32 v96, v32, v96, v36
	v_fma_f32 v95, v33, v95, v37
	v_fma_f32 v94, v34, v94, v38
	v_fma_f32 v48, v35, v48, v39
	v_cvt_pk_bf16_f32 v100, v100, s0
	v_cvt_pk_bf16_f32 v99, v99, s0
	v_cvt_pk_bf16_f32 v98, v98, s0
	v_cvt_pk_bf16_f32 v97, v97, s0
	v_cvt_pk_bf16_f32 v96, v96, s0
	v_cvt_pk_bf16_f32 v95, v95, s0
	v_cvt_pk_bf16_f32 v94, v94, s0
	v_cvt_pk_bf16_f32 v48, v48, s0
	ds_write_b16 v120, v100 offset:8
	ds_write_b16 v120, v99 offset:280
	ds_write_b16 v120, v98 offset:552
	ds_write_b16 v120, v97 offset:824
	ds_write_b16 v120, v96 offset:1096
	ds_write_b16 v120, v95 offset:1368
	ds_write_b16 v120, v94 offset:1640
	ds_write_b16 v120, v48 offset:1912
.LBB0_926:
	s_or_b64 exec, exec, s[52:53]
	s_waitcnt vmcnt(14)
	v_lshlrev_b32_e32 v94, 16, v90
	v_and_b32_e32 v90, 0xffff0000, v90
	v_mul_f32_e32 v48, 0x3d372713, v94
	v_lshlrev_b32_e32 v97, 16, v91
	v_lshlrev_b32_e32 v98, 16, v92
	v_mul_f32_e32 v48, v48, v94
	v_and_b32_e32 v99, 0xffff0000, v92
	v_mul_f32_e32 v92, 0x3d372713, v90
	v_fma_f32 v48, v48, v94, v94
	v_lshlrev_b32_e32 v100, 16, v93
	v_and_b32_e32 v101, 0xffff0000, v93
	v_mul_f32_e32 v92, v92, v90
	v_mul_f32_e32 v93, 0x3d372713, v97
	v_mul_f32_e32 v48, 0xbfcc422a, v48
	v_fma_f32 v92, v92, v90, v90
	v_mul_f32_e32 v93, v93, v97
	v_mul_f32_e32 v48, 0x3fb8aa3b, v48
	v_mul_f32_e32 v92, 0xbfcc422a, v92
	v_fma_f32 v93, v93, v97, v97
	v_exp_f32_e32 v48, v48
	v_mul_f32_e32 v92, 0x3fb8aa3b, v92
	v_mul_f32_e32 v93, 0xbfcc422a, v93
	v_exp_f32_e32 v92, v92
	v_mul_f32_e32 v93, 0x3fb8aa3b, v93
	v_exp_f32_e32 v93, v93
	v_add_f32_e32 v48, 1.0, v48
	v_rcp_f32_e32 v95, v48
	v_add_f32_e32 v48, 1.0, v92
	v_and_b32_e32 v91, 0xffff0000, v91
	v_rcp_f32_e32 v92, v48
	v_add_f32_e32 v48, 1.0, v93
	v_rcp_f32_e32 v93, v48
	v_mul_f32_e32 v48, 0x3d372713, v91
	v_mul_f32_e32 v48, v48, v91
	v_fma_f32 v48, v48, v91, v91
	v_mul_f32_e32 v48, 0xbfcc422a, v48
	v_mul_f32_e32 v48, 0x3fb8aa3b, v48
	v_exp_f32_e32 v48, v48
	v_mul_f32_e32 v103, 0x3d372713, v99
	v_mul_f32_e32 v103, v103, v99
	v_fma_f32 v103, v103, v99, v99
	v_add_f32_e32 v48, 1.0, v48
	v_rcp_f32_e32 v102, v48
	v_mul_f32_e32 v48, 0x3d372713, v98
	v_mul_f32_e32 v48, v48, v98
	v_fma_f32 v48, v48, v98, v98
	v_mul_f32_e32 v48, 0xbfcc422a, v48
	v_mul_f32_e32 v48, 0x3fb8aa3b, v48
	v_mul_f32_e32 v103, 0xbfcc422a, v103
	v_exp_f32_e32 v48, v48
	v_mul_f32_e32 v103, 0x3fb8aa3b, v103
	v_exp_f32_e32 v103, v103
	v_mul_f32_e32 v105, 0x3d372713, v101
	v_add_f32_e32 v48, 1.0, v48
	v_rcp_f32_e32 v104, v48
	v_add_f32_e32 v48, 1.0, v103
	v_mul_f32_e32 v103, 0x3d372713, v100
	v_mul_f32_e32 v103, v103, v100
	v_fma_f32 v103, v103, v100, v100
	v_mul_f32_e32 v105, v105, v101
	v_mul_f32_e32 v103, 0xbfcc422a, v103
	v_fma_f32 v105, v105, v101, v101
	v_mul_f32_e32 v103, 0x3fb8aa3b, v103
	v_mul_f32_e32 v105, 0xbfcc422a, v105
	v_exp_f32_e32 v103, v103
	v_mul_f32_e32 v105, 0x3fb8aa3b, v105
	v_exp_f32_e32 v105, v105
	v_fma_f32 v96, v95, v94, 0
	v_fmac_f32_e32 v96, v92, v90
	v_rcp_f32_e32 v106, v48
	v_add_f32_e32 v48, 1.0, v103
	v_fmac_f32_e32 v96, v93, v97
	v_rcp_f32_e32 v103, v48
	v_add_f32_e32 v48, 1.0, v105
	v_fmac_f32_e32 v96, v102, v91
	v_rcp_f32_e32 v105, v48
	v_fmac_f32_e32 v96, v104, v98
	v_fmac_f32_e32 v96, v106, v99
	v_fmac_f32_e32 v96, v103, v100
	v_fmac_f32_e32 v96, v105, v101
	s_nop 1
	v_add_f32_dpp v48, v96, v96 row_mirror row_mask:0xf bank_mask:0xf bound_ctrl:1
	s_nop 1
	v_add_f32_dpp v48, v48, v48 row_half_mirror row_mask:0xf bank_mask:0xf bound_ctrl:1
	s_nop 1
	v_add_f32_dpp v48, v48, v48 quad_perm:[1,0,3,2] row_mask:0xf bank_mask:0xf bound_ctrl:1
	s_nop 1
	v_add_f32_dpp v48, v48, v48 quad_perm:[2,3,0,1] row_mask:0xf bank_mask:0xf bound_ctrl:1
	s_waitcnt lgkmcnt(0)
	v_mov_b32_e32 v96, v48
	s_nop 1
	v_permlane16_swap_b32_e32 v48, v96
	v_add_f32_e32 v48, v48, v96
	v_mov_b32_e32 v96, v48
	s_nop 1
	v_permlane32_swap_b32_e32 v48, v96
	v_add_f32_e32 v48, v48, v96
	v_mul_f32_e32 v48, 0xbb000000, v48
	v_fma_f32 v96, v95, v94, v48
	v_fma_f32 v95, v92, v90, v48
	v_mul_f32_e32 v107, v95, v95
	v_fmac_f32_e32 v107, v96, v96
	v_fma_f32 v94, v93, v97, v48
	v_fmac_f32_e32 v107, v94, v94
	v_fma_f32 v93, v102, v91, v48
	v_fmac_f32_e32 v107, v93, v93
	v_fma_f32 v92, v104, v98, v48
	v_fmac_f32_e32 v107, v92, v92
	v_fma_f32 v91, v106, v99, v48
	v_fmac_f32_e32 v107, v91, v91
	v_fma_f32 v90, v103, v100, v48
	v_fmac_f32_e32 v107, v90, v90
	v_fmac_f32_e32 v48, v105, v101
	v_fmac_f32_e32 v107, v48, v48
	s_nop 1
	v_add_f32_dpp v97, v107, v107 row_mirror row_mask:0xf bank_mask:0xf bound_ctrl:1
	s_nop 1
	v_add_f32_dpp v97, v97, v97 row_half_mirror row_mask:0xf bank_mask:0xf bound_ctrl:1
	s_nop 1
	v_add_f32_dpp v97, v97, v97 quad_perm:[1,0,3,2] row_mask:0xf bank_mask:0xf bound_ctrl:1
	s_nop 1
	v_add_f32_dpp v97, v97, v97 quad_perm:[2,3,0,1] row_mask:0xf bank_mask:0xf bound_ctrl:1
	s_waitcnt lgkmcnt(0)
	v_mov_b32_e32 v98, v97
	s_nop 1
	v_permlane16_swap_b32_e32 v97, v98
	v_add_f32_e32 v97, v97, v98
	v_mov_b32_e32 v98, v97
	s_nop 1
	v_permlane32_swap_b32_e32 v97, v98
	s_and_saveexec_b64 s[52:53], vcc
	s_cbranch_execz .LBB0_928
	v_add_f32_e32 v97, v97, v98
	v_fmamk_f32 v97, v97, 0x3b000000, v206
	v_mul_f32_e32 v98, 0x4b800000, v97
	v_cmp_gt_f32_e64 s[40:41], s75, v97
	s_nop 1
	v_cndmask_b32_e64 v97, v97, v98, s[40:41]
	v_rsq_f32_e32 v97, v97
	s_nop 0
	v_mul_f32_e32 v98, 0x45800000, v97
	v_cndmask_b32_e64 v97, v97, v98, s[40:41]
	v_mul_f32_e32 v96, v96, v97
	v_mul_f32_e32 v95, v95, v97
	v_mul_f32_e32 v94, v94, v97
	v_mul_f32_e32 v93, v93, v97
	v_mul_f32_e32 v92, v92, v97
	v_mul_f32_e32 v91, v91, v97
	v_mul_f32_e32 v90, v90, v97
	v_mul_f32_e32 v48, v48, v97
	s_waitcnt vmcnt(1)
	v_fma_f32 v96, v40, v96, v44
	v_fma_f32 v95, v41, v95, v45
	v_fma_f32 v94, v42, v94, v46
	v_fma_f32 v93, v43, v93, v47
	s_waitcnt vmcnt(0)
	v_fma_f32 v92, v32, v92, v36
	v_fma_f32 v91, v33, v91, v37
	v_fma_f32 v90, v34, v90, v38
	v_fma_f32 v48, v35, v48, v39
	v_cvt_pk_bf16_f32 v96, v96, s0
	v_cvt_pk_bf16_f32 v95, v95, s0
	v_cvt_pk_bf16_f32 v94, v94, s0
	v_cvt_pk_bf16_f32 v93, v93, s0
	v_cvt_pk_bf16_f32 v92, v92, s0
	v_cvt_pk_bf16_f32 v91, v91, s0
	v_cvt_pk_bf16_f32 v90, v90, s0
	v_cvt_pk_bf16_f32 v48, v48, s0
	ds_write_b16 v120, v96 offset:10
	ds_write_b16 v120, v95 offset:282
	ds_write_b16 v120, v94 offset:554
	ds_write_b16 v120, v93 offset:826
	ds_write_b16 v120, v92 offset:1098
	ds_write_b16 v120, v91 offset:1370
	ds_write_b16 v120, v90 offset:1642
	ds_write_b16 v120, v48 offset:1914
.LBB0_928:
	s_or_b64 exec, exec, s[52:53]
	s_waitcnt vmcnt(13)
	v_lshlrev_b32_e32 v90, 16, v86
	v_and_b32_e32 v86, 0xffff0000, v86
	v_mul_f32_e32 v48, 0x3d372713, v90
	v_lshlrev_b32_e32 v93, 16, v87
	v_lshlrev_b32_e32 v94, 16, v88
	v_mul_f32_e32 v48, v48, v90
	v_and_b32_e32 v95, 0xffff0000, v88
	v_mul_f32_e32 v88, 0x3d372713, v86
	v_fma_f32 v48, v48, v90, v90
	v_lshlrev_b32_e32 v96, 16, v89
	v_and_b32_e32 v97, 0xffff0000, v89
	v_mul_f32_e32 v88, v88, v86
	v_mul_f32_e32 v89, 0x3d372713, v93
	v_mul_f32_e32 v48, 0xbfcc422a, v48
	v_fma_f32 v88, v88, v86, v86
	v_mul_f32_e32 v89, v89, v93
	v_mul_f32_e32 v48, 0x3fb8aa3b, v48
	v_mul_f32_e32 v88, 0xbfcc422a, v88
	v_fma_f32 v89, v89, v93, v93
	v_exp_f32_e32 v48, v48
	v_mul_f32_e32 v88, 0x3fb8aa3b, v88
	v_mul_f32_e32 v89, 0xbfcc422a, v89
	v_exp_f32_e32 v88, v88
	v_mul_f32_e32 v89, 0x3fb8aa3b, v89
	v_exp_f32_e32 v89, v89
	v_add_f32_e32 v48, 1.0, v48
	v_rcp_f32_e32 v91, v48
	v_add_f32_e32 v48, 1.0, v88
	v_and_b32_e32 v87, 0xffff0000, v87
	v_rcp_f32_e32 v88, v48
	v_add_f32_e32 v48, 1.0, v89
	v_rcp_f32_e32 v89, v48
	v_mul_f32_e32 v48, 0x3d372713, v87
	v_mul_f32_e32 v48, v48, v87
	v_fma_f32 v48, v48, v87, v87
	v_mul_f32_e32 v48, 0xbfcc422a, v48
	v_mul_f32_e32 v48, 0x3fb8aa3b, v48
	v_exp_f32_e32 v48, v48
	v_mul_f32_e32 v99, 0x3d372713, v95
	v_mul_f32_e32 v99, v99, v95
	v_fma_f32 v99, v99, v95, v95
	v_add_f32_e32 v48, 1.0, v48
	v_rcp_f32_e32 v98, v48
	v_mul_f32_e32 v48, 0x3d372713, v94
	v_mul_f32_e32 v48, v48, v94
	v_fma_f32 v48, v48, v94, v94
	v_mul_f32_e32 v48, 0xbfcc422a, v48
	v_mul_f32_e32 v48, 0x3fb8aa3b, v48
	v_mul_f32_e32 v99, 0xbfcc422a, v99
	v_exp_f32_e32 v48, v48
	v_mul_f32_e32 v99, 0x3fb8aa3b, v99
	v_exp_f32_e32 v99, v99
	v_mul_f32_e32 v101, 0x3d372713, v97
	v_add_f32_e32 v48, 1.0, v48
	v_rcp_f32_e32 v100, v48
	v_add_f32_e32 v48, 1.0, v99
	v_mul_f32_e32 v99, 0x3d372713, v96
	v_mul_f32_e32 v99, v99, v96
	v_fma_f32 v99, v99, v96, v96
	v_mul_f32_e32 v101, v101, v97
	v_mul_f32_e32 v99, 0xbfcc422a, v99
	v_fma_f32 v101, v101, v97, v97
	v_mul_f32_e32 v99, 0x3fb8aa3b, v99
	v_mul_f32_e32 v101, 0xbfcc422a, v101
	v_exp_f32_e32 v99, v99
	v_mul_f32_e32 v101, 0x3fb8aa3b, v101
	v_exp_f32_e32 v101, v101
	v_fma_f32 v92, v91, v90, 0
	v_fmac_f32_e32 v92, v88, v86
	v_rcp_f32_e32 v102, v48
	v_add_f32_e32 v48, 1.0, v99
	v_fmac_f32_e32 v92, v89, v93
	v_rcp_f32_e32 v99, v48
	v_add_f32_e32 v48, 1.0, v101
	v_fmac_f32_e32 v92, v98, v87
	v_rcp_f32_e32 v101, v48
	v_fmac_f32_e32 v92, v100, v94
	v_fmac_f32_e32 v92, v102, v95
	v_fmac_f32_e32 v92, v99, v96
	v_fmac_f32_e32 v92, v101, v97
	s_nop 1
	v_add_f32_dpp v48, v92, v92 row_mirror row_mask:0xf bank_mask:0xf bound_ctrl:1
	s_nop 1
	v_add_f32_dpp v48, v48, v48 row_half_mirror row_mask:0xf bank_mask:0xf bound_ctrl:1
	s_nop 1
	v_add_f32_dpp v48, v48, v48 quad_perm:[1,0,3,2] row_mask:0xf bank_mask:0xf bound_ctrl:1
	s_nop 1
	v_add_f32_dpp v48, v48, v48 quad_perm:[2,3,0,1] row_mask:0xf bank_mask:0xf bound_ctrl:1
	s_waitcnt lgkmcnt(0)
	v_mov_b32_e32 v92, v48
	s_nop 1
	v_permlane16_swap_b32_e32 v48, v92
	v_add_f32_e32 v48, v48, v92
	v_mov_b32_e32 v92, v48
	s_nop 1
	v_permlane32_swap_b32_e32 v48, v92
	v_add_f32_e32 v48, v48, v92
	v_mul_f32_e32 v48, 0xbb000000, v48
	v_fma_f32 v92, v91, v90, v48
	v_fma_f32 v91, v88, v86, v48
	v_mul_f32_e32 v103, v91, v91
	v_fmac_f32_e32 v103, v92, v92
	v_fma_f32 v90, v89, v93, v48
	v_fmac_f32_e32 v103, v90, v90
	v_fma_f32 v89, v98, v87, v48
	v_fmac_f32_e32 v103, v89, v89
	v_fma_f32 v88, v100, v94, v48
	v_fmac_f32_e32 v103, v88, v88
	v_fma_f32 v87, v102, v95, v48
	v_fmac_f32_e32 v103, v87, v87
	v_fma_f32 v86, v99, v96, v48
	v_fmac_f32_e32 v103, v86, v86
	v_fmac_f32_e32 v48, v101, v97
	v_fmac_f32_e32 v103, v48, v48
	s_nop 1
	v_add_f32_dpp v93, v103, v103 row_mirror row_mask:0xf bank_mask:0xf bound_ctrl:1
	s_nop 1
	v_add_f32_dpp v93, v93, v93 row_half_mirror row_mask:0xf bank_mask:0xf bound_ctrl:1
	s_nop 1
	v_add_f32_dpp v93, v93, v93 quad_perm:[1,0,3,2] row_mask:0xf bank_mask:0xf bound_ctrl:1
	s_nop 1
	v_add_f32_dpp v93, v93, v93 quad_perm:[2,3,0,1] row_mask:0xf bank_mask:0xf bound_ctrl:1
	s_waitcnt lgkmcnt(0)
	v_mov_b32_e32 v94, v93
	s_nop 1
	v_permlane16_swap_b32_e32 v93, v94
	v_add_f32_e32 v93, v93, v94
	v_mov_b32_e32 v94, v93
	s_nop 1
	v_permlane32_swap_b32_e32 v93, v94
	s_and_saveexec_b64 s[52:53], vcc
	s_cbranch_execz .LBB0_930
	v_add_f32_e32 v93, v93, v94
	v_fmamk_f32 v93, v93, 0x3b000000, v206
	v_mul_f32_e32 v94, 0x4b800000, v93
	v_cmp_gt_f32_e64 s[40:41], s75, v93
	s_nop 1
	v_cndmask_b32_e64 v93, v93, v94, s[40:41]
	v_rsq_f32_e32 v93, v93
	s_nop 0
	v_mul_f32_e32 v94, 0x45800000, v93
	v_cndmask_b32_e64 v93, v93, v94, s[40:41]
	v_mul_f32_e32 v92, v92, v93
	v_mul_f32_e32 v91, v91, v93
	v_mul_f32_e32 v90, v90, v93
	v_mul_f32_e32 v89, v89, v93
	v_mul_f32_e32 v88, v88, v93
	v_mul_f32_e32 v87, v87, v93
	v_mul_f32_e32 v86, v86, v93
	v_mul_f32_e32 v48, v48, v93
	s_waitcnt vmcnt(1)
	v_fma_f32 v92, v40, v92, v44
	v_fma_f32 v91, v41, v91, v45
	v_fma_f32 v90, v42, v90, v46
	v_fma_f32 v89, v43, v89, v47
	s_waitcnt vmcnt(0)
	v_fma_f32 v88, v32, v88, v36
	v_fma_f32 v87, v33, v87, v37
	v_fma_f32 v86, v34, v86, v38
	v_fma_f32 v48, v35, v48, v39
	v_cvt_pk_bf16_f32 v92, v92, s0
	v_cvt_pk_bf16_f32 v91, v91, s0
	v_cvt_pk_bf16_f32 v90, v90, s0
	v_cvt_pk_bf16_f32 v89, v89, s0
	v_cvt_pk_bf16_f32 v88, v88, s0
	v_cvt_pk_bf16_f32 v87, v87, s0
	v_cvt_pk_bf16_f32 v86, v86, s0
	v_cvt_pk_bf16_f32 v48, v48, s0
	ds_write_b16 v120, v92 offset:12
	ds_write_b16 v120, v91 offset:284
	ds_write_b16 v120, v90 offset:556
	ds_write_b16 v120, v89 offset:828
	ds_write_b16 v120, v88 offset:1100
	ds_write_b16 v120, v87 offset:1372
	ds_write_b16 v120, v86 offset:1644
	ds_write_b16 v120, v48 offset:1916
.LBB0_930:
	s_or_b64 exec, exec, s[52:53]
	s_waitcnt vmcnt(12)
	v_lshlrev_b32_e32 v86, 16, v82
	v_and_b32_e32 v82, 0xffff0000, v82
	v_mul_f32_e32 v48, 0x3d372713, v86
	v_lshlrev_b32_e32 v89, 16, v83
	v_lshlrev_b32_e32 v90, 16, v84
	v_mul_f32_e32 v48, v48, v86
	v_and_b32_e32 v91, 0xffff0000, v84
	v_mul_f32_e32 v84, 0x3d372713, v82
	v_fma_f32 v48, v48, v86, v86
	v_lshlrev_b32_e32 v92, 16, v85
	v_and_b32_e32 v93, 0xffff0000, v85
	v_mul_f32_e32 v84, v84, v82
	v_mul_f32_e32 v85, 0x3d372713, v89
	v_mul_f32_e32 v48, 0xbfcc422a, v48
	v_fma_f32 v84, v84, v82, v82
	v_mul_f32_e32 v85, v85, v89
	v_mul_f32_e32 v48, 0x3fb8aa3b, v48
	v_mul_f32_e32 v84, 0xbfcc422a, v84
	v_fma_f32 v85, v85, v89, v89
	v_exp_f32_e32 v48, v48
	v_mul_f32_e32 v84, 0x3fb8aa3b, v84
	v_mul_f32_e32 v85, 0xbfcc422a, v85
	v_exp_f32_e32 v84, v84
	v_mul_f32_e32 v85, 0x3fb8aa3b, v85
	v_exp_f32_e32 v85, v85
	v_add_f32_e32 v48, 1.0, v48
	v_rcp_f32_e32 v87, v48
	v_add_f32_e32 v48, 1.0, v84
	v_and_b32_e32 v83, 0xffff0000, v83
	v_rcp_f32_e32 v84, v48
	v_add_f32_e32 v48, 1.0, v85
	v_rcp_f32_e32 v85, v48
	v_mul_f32_e32 v48, 0x3d372713, v83
	v_mul_f32_e32 v48, v48, v83
	v_fma_f32 v48, v48, v83, v83
	v_mul_f32_e32 v48, 0xbfcc422a, v48
	v_mul_f32_e32 v48, 0x3fb8aa3b, v48
	v_exp_f32_e32 v48, v48
	v_mul_f32_e32 v95, 0x3d372713, v91
	v_mul_f32_e32 v95, v95, v91
	v_fma_f32 v95, v95, v91, v91
	v_add_f32_e32 v48, 1.0, v48
	v_rcp_f32_e32 v94, v48
	v_mul_f32_e32 v48, 0x3d372713, v90
	v_mul_f32_e32 v48, v48, v90
	v_fma_f32 v48, v48, v90, v90
	v_mul_f32_e32 v48, 0xbfcc422a, v48
	v_mul_f32_e32 v48, 0x3fb8aa3b, v48
	v_mul_f32_e32 v95, 0xbfcc422a, v95
	v_exp_f32_e32 v48, v48
	v_mul_f32_e32 v95, 0x3fb8aa3b, v95
	v_exp_f32_e32 v95, v95
	v_mul_f32_e32 v97, 0x3d372713, v93
	v_add_f32_e32 v48, 1.0, v48
	v_rcp_f32_e32 v96, v48
	v_add_f32_e32 v48, 1.0, v95
	v_mul_f32_e32 v95, 0x3d372713, v92
	v_mul_f32_e32 v95, v95, v92
	v_fma_f32 v95, v95, v92, v92
	v_mul_f32_e32 v97, v97, v93
	v_mul_f32_e32 v95, 0xbfcc422a, v95
	v_fma_f32 v97, v97, v93, v93
	v_mul_f32_e32 v95, 0x3fb8aa3b, v95
	v_mul_f32_e32 v97, 0xbfcc422a, v97
	v_exp_f32_e32 v95, v95
	v_mul_f32_e32 v97, 0x3fb8aa3b, v97
	v_exp_f32_e32 v97, v97
	v_fma_f32 v88, v87, v86, 0
	v_fmac_f32_e32 v88, v84, v82
	v_rcp_f32_e32 v98, v48
	v_add_f32_e32 v48, 1.0, v95
	v_fmac_f32_e32 v88, v85, v89
	v_rcp_f32_e32 v95, v48
	v_add_f32_e32 v48, 1.0, v97
	v_fmac_f32_e32 v88, v94, v83
	v_rcp_f32_e32 v97, v48
	v_fmac_f32_e32 v88, v96, v90
	v_fmac_f32_e32 v88, v98, v91
	v_fmac_f32_e32 v88, v95, v92
	v_fmac_f32_e32 v88, v97, v93
	s_nop 1
	v_add_f32_dpp v48, v88, v88 row_mirror row_mask:0xf bank_mask:0xf bound_ctrl:1
	s_nop 1
	v_add_f32_dpp v48, v48, v48 row_half_mirror row_mask:0xf bank_mask:0xf bound_ctrl:1
	s_nop 1
	v_add_f32_dpp v48, v48, v48 quad_perm:[1,0,3,2] row_mask:0xf bank_mask:0xf bound_ctrl:1
	s_nop 1
	v_add_f32_dpp v48, v48, v48 quad_perm:[2,3,0,1] row_mask:0xf bank_mask:0xf bound_ctrl:1
	s_waitcnt lgkmcnt(0)
	v_mov_b32_e32 v88, v48
	s_nop 1
	v_permlane16_swap_b32_e32 v48, v88
	v_add_f32_e32 v48, v48, v88
	v_mov_b32_e32 v88, v48
	s_nop 1
	v_permlane32_swap_b32_e32 v48, v88
	v_add_f32_e32 v48, v48, v88
	v_mul_f32_e32 v48, 0xbb000000, v48
	v_fma_f32 v88, v87, v86, v48
	v_fma_f32 v87, v84, v82, v48
	v_mul_f32_e32 v99, v87, v87
	v_fmac_f32_e32 v99, v88, v88
	v_fma_f32 v86, v85, v89, v48
	v_fmac_f32_e32 v99, v86, v86
	v_fma_f32 v85, v94, v83, v48
	v_fmac_f32_e32 v99, v85, v85
	v_fma_f32 v84, v96, v90, v48
	v_fmac_f32_e32 v99, v84, v84
	v_fma_f32 v83, v98, v91, v48
	v_fmac_f32_e32 v99, v83, v83
	v_fma_f32 v82, v95, v92, v48
	v_fmac_f32_e32 v99, v82, v82
	v_fmac_f32_e32 v48, v97, v93
	v_fmac_f32_e32 v99, v48, v48
	s_nop 1
	v_add_f32_dpp v89, v99, v99 row_mirror row_mask:0xf bank_mask:0xf bound_ctrl:1
	s_nop 1
	v_add_f32_dpp v89, v89, v89 row_half_mirror row_mask:0xf bank_mask:0xf bound_ctrl:1
	s_nop 1
	v_add_f32_dpp v89, v89, v89 quad_perm:[1,0,3,2] row_mask:0xf bank_mask:0xf bound_ctrl:1
	s_nop 1
	v_add_f32_dpp v89, v89, v89 quad_perm:[2,3,0,1] row_mask:0xf bank_mask:0xf bound_ctrl:1
	s_waitcnt lgkmcnt(0)
	v_mov_b32_e32 v90, v89
	s_nop 1
	v_permlane16_swap_b32_e32 v89, v90
	v_add_f32_e32 v89, v89, v90
	v_mov_b32_e32 v90, v89
	s_nop 1
	v_permlane32_swap_b32_e32 v89, v90
	s_and_saveexec_b64 s[52:53], vcc
	s_cbranch_execz .LBB0_932
	v_add_f32_e32 v89, v89, v90
	v_fmamk_f32 v89, v89, 0x3b000000, v206
	v_mul_f32_e32 v90, 0x4b800000, v89
	v_cmp_gt_f32_e64 s[40:41], s75, v89
	s_nop 1
	v_cndmask_b32_e64 v89, v89, v90, s[40:41]
	v_rsq_f32_e32 v89, v89
	s_nop 0
	v_mul_f32_e32 v90, 0x45800000, v89
	v_cndmask_b32_e64 v89, v89, v90, s[40:41]
	v_mul_f32_e32 v88, v88, v89
	v_mul_f32_e32 v87, v87, v89
	v_mul_f32_e32 v86, v86, v89
	v_mul_f32_e32 v85, v85, v89
	v_mul_f32_e32 v84, v84, v89
	v_mul_f32_e32 v83, v83, v89
	v_mul_f32_e32 v82, v82, v89
	v_mul_f32_e32 v48, v48, v89
	s_waitcnt vmcnt(1)
	v_fma_f32 v88, v40, v88, v44
	v_fma_f32 v87, v41, v87, v45
	v_fma_f32 v86, v42, v86, v46
	v_fma_f32 v85, v43, v85, v47
	s_waitcnt vmcnt(0)
	v_fma_f32 v84, v32, v84, v36
	v_fma_f32 v83, v33, v83, v37
	v_fma_f32 v82, v34, v82, v38
	v_fma_f32 v48, v35, v48, v39
	v_cvt_pk_bf16_f32 v88, v88, s0
	v_cvt_pk_bf16_f32 v87, v87, s0
	v_cvt_pk_bf16_f32 v86, v86, s0
	v_cvt_pk_bf16_f32 v85, v85, s0
	v_cvt_pk_bf16_f32 v84, v84, s0
	v_cvt_pk_bf16_f32 v83, v83, s0
	v_cvt_pk_bf16_f32 v82, v82, s0
	v_cvt_pk_bf16_f32 v48, v48, s0
	ds_write_b16 v120, v88 offset:14
	ds_write_b16 v120, v87 offset:286
	ds_write_b16 v120, v86 offset:558
	ds_write_b16 v120, v85 offset:830
	ds_write_b16 v120, v84 offset:1102
	ds_write_b16 v120, v83 offset:1374
	ds_write_b16 v120, v82 offset:1646
	ds_write_b16 v120, v48 offset:1918
.LBB0_932:
	s_or_b64 exec, exec, s[52:53]
	s_waitcnt vmcnt(11)
	v_lshlrev_b32_e32 v82, 16, v78
	v_and_b32_e32 v78, 0xffff0000, v78
	v_mul_f32_e32 v48, 0x3d372713, v82
	v_lshlrev_b32_e32 v85, 16, v79
	v_lshlrev_b32_e32 v86, 16, v80
	v_mul_f32_e32 v48, v48, v82
	v_and_b32_e32 v87, 0xffff0000, v80
	v_mul_f32_e32 v80, 0x3d372713, v78
	v_fma_f32 v48, v48, v82, v82
	v_lshlrev_b32_e32 v88, 16, v81
	v_and_b32_e32 v89, 0xffff0000, v81
	v_mul_f32_e32 v80, v80, v78
	v_mul_f32_e32 v81, 0x3d372713, v85
	v_mul_f32_e32 v48, 0xbfcc422a, v48
	v_fma_f32 v80, v80, v78, v78
	v_mul_f32_e32 v81, v81, v85
	v_mul_f32_e32 v48, 0x3fb8aa3b, v48
	v_mul_f32_e32 v80, 0xbfcc422a, v80
	v_fma_f32 v81, v81, v85, v85
	v_exp_f32_e32 v48, v48
	v_mul_f32_e32 v80, 0x3fb8aa3b, v80
	v_mul_f32_e32 v81, 0xbfcc422a, v81
	v_exp_f32_e32 v80, v80
	v_mul_f32_e32 v81, 0x3fb8aa3b, v81
	v_exp_f32_e32 v81, v81
	v_add_f32_e32 v48, 1.0, v48
	v_rcp_f32_e32 v83, v48
	v_add_f32_e32 v48, 1.0, v80
	v_and_b32_e32 v79, 0xffff0000, v79
	v_rcp_f32_e32 v80, v48
	v_add_f32_e32 v48, 1.0, v81
	v_rcp_f32_e32 v81, v48
	v_mul_f32_e32 v48, 0x3d372713, v79
	v_mul_f32_e32 v48, v48, v79
	v_fma_f32 v48, v48, v79, v79
	v_mul_f32_e32 v48, 0xbfcc422a, v48
	v_mul_f32_e32 v48, 0x3fb8aa3b, v48
	v_exp_f32_e32 v48, v48
	v_mul_f32_e32 v91, 0x3d372713, v87
	v_mul_f32_e32 v91, v91, v87
	v_fma_f32 v91, v91, v87, v87
	v_add_f32_e32 v48, 1.0, v48
	v_rcp_f32_e32 v90, v48
	v_mul_f32_e32 v48, 0x3d372713, v86
	v_mul_f32_e32 v48, v48, v86
	v_fma_f32 v48, v48, v86, v86
	v_mul_f32_e32 v48, 0xbfcc422a, v48
	v_mul_f32_e32 v48, 0x3fb8aa3b, v48
	v_mul_f32_e32 v91, 0xbfcc422a, v91
	v_exp_f32_e32 v48, v48
	v_mul_f32_e32 v91, 0x3fb8aa3b, v91
	v_exp_f32_e32 v91, v91
	v_mul_f32_e32 v93, 0x3d372713, v89
	v_add_f32_e32 v48, 1.0, v48
	v_rcp_f32_e32 v92, v48
	v_add_f32_e32 v48, 1.0, v91
	v_mul_f32_e32 v91, 0x3d372713, v88
	v_mul_f32_e32 v91, v91, v88
	v_fma_f32 v91, v91, v88, v88
	v_mul_f32_e32 v93, v93, v89
	v_mul_f32_e32 v91, 0xbfcc422a, v91
	v_fma_f32 v93, v93, v89, v89
	v_mul_f32_e32 v91, 0x3fb8aa3b, v91
	v_mul_f32_e32 v93, 0xbfcc422a, v93
	v_exp_f32_e32 v91, v91
	v_mul_f32_e32 v93, 0x3fb8aa3b, v93
	v_exp_f32_e32 v93, v93
	v_fma_f32 v84, v83, v82, 0
	v_fmac_f32_e32 v84, v80, v78
	v_rcp_f32_e32 v94, v48
	v_add_f32_e32 v48, 1.0, v91
	v_fmac_f32_e32 v84, v81, v85
	v_rcp_f32_e32 v91, v48
	v_add_f32_e32 v48, 1.0, v93
	v_fmac_f32_e32 v84, v90, v79
	v_rcp_f32_e32 v93, v48
	v_fmac_f32_e32 v84, v92, v86
	v_fmac_f32_e32 v84, v94, v87
	v_fmac_f32_e32 v84, v91, v88
	v_fmac_f32_e32 v84, v93, v89
	s_nop 1
	v_add_f32_dpp v48, v84, v84 row_mirror row_mask:0xf bank_mask:0xf bound_ctrl:1
	s_nop 1
	v_add_f32_dpp v48, v48, v48 row_half_mirror row_mask:0xf bank_mask:0xf bound_ctrl:1
	s_nop 1
	v_add_f32_dpp v48, v48, v48 quad_perm:[1,0,3,2] row_mask:0xf bank_mask:0xf bound_ctrl:1
	s_nop 1
	v_add_f32_dpp v48, v48, v48 quad_perm:[2,3,0,1] row_mask:0xf bank_mask:0xf bound_ctrl:1
	s_waitcnt lgkmcnt(0)
	v_mov_b32_e32 v84, v48
	s_nop 1
	v_permlane16_swap_b32_e32 v48, v84
	v_add_f32_e32 v48, v48, v84
	v_mov_b32_e32 v84, v48
	s_nop 1
	v_permlane32_swap_b32_e32 v48, v84
	v_add_f32_e32 v48, v48, v84
	v_mul_f32_e32 v48, 0xbb000000, v48
	v_fma_f32 v84, v83, v82, v48
	v_fma_f32 v83, v80, v78, v48
	v_mul_f32_e32 v95, v83, v83
	v_fmac_f32_e32 v95, v84, v84
	v_fma_f32 v82, v81, v85, v48
	v_fmac_f32_e32 v95, v82, v82
	v_fma_f32 v81, v90, v79, v48
	v_fmac_f32_e32 v95, v81, v81
	v_fma_f32 v80, v92, v86, v48
	v_fmac_f32_e32 v95, v80, v80
	v_fma_f32 v79, v94, v87, v48
	v_fmac_f32_e32 v95, v79, v79
	v_fma_f32 v78, v91, v88, v48
	v_fmac_f32_e32 v95, v78, v78
	v_fmac_f32_e32 v48, v93, v89
	v_fmac_f32_e32 v95, v48, v48
	s_nop 1
	v_add_f32_dpp v85, v95, v95 row_mirror row_mask:0xf bank_mask:0xf bound_ctrl:1
	s_nop 1
	v_add_f32_dpp v85, v85, v85 row_half_mirror row_mask:0xf bank_mask:0xf bound_ctrl:1
	s_nop 1
	v_add_f32_dpp v85, v85, v85 quad_perm:[1,0,3,2] row_mask:0xf bank_mask:0xf bound_ctrl:1
	s_nop 1
	v_add_f32_dpp v85, v85, v85 quad_perm:[2,3,0,1] row_mask:0xf bank_mask:0xf bound_ctrl:1
	s_waitcnt lgkmcnt(0)
	v_mov_b32_e32 v86, v85
	s_nop 1
	v_permlane16_swap_b32_e32 v85, v86
	v_add_f32_e32 v85, v85, v86
	v_mov_b32_e32 v86, v85
	s_nop 1
	v_permlane32_swap_b32_e32 v85, v86
	s_and_saveexec_b64 s[52:53], vcc
	s_cbranch_execz .LBB0_934
	v_add_f32_e32 v85, v85, v86
	v_fmamk_f32 v85, v85, 0x3b000000, v206
	v_mul_f32_e32 v86, 0x4b800000, v85
	v_cmp_gt_f32_e64 s[40:41], s75, v85
	s_nop 1
	v_cndmask_b32_e64 v85, v85, v86, s[40:41]
	v_rsq_f32_e32 v85, v85
	s_nop 0
	v_mul_f32_e32 v86, 0x45800000, v85
	v_cndmask_b32_e64 v85, v85, v86, s[40:41]
	v_mul_f32_e32 v84, v84, v85
	v_mul_f32_e32 v83, v83, v85
	v_mul_f32_e32 v82, v82, v85
	v_mul_f32_e32 v81, v81, v85
	v_mul_f32_e32 v80, v80, v85
	v_mul_f32_e32 v79, v79, v85
	v_mul_f32_e32 v78, v78, v85
	v_mul_f32_e32 v48, v48, v85
	s_waitcnt vmcnt(1)
	v_fma_f32 v84, v40, v84, v44
	v_fma_f32 v83, v41, v83, v45
	v_fma_f32 v82, v42, v82, v46
	v_fma_f32 v81, v43, v81, v47
	s_waitcnt vmcnt(0)
	v_fma_f32 v80, v32, v80, v36
	v_fma_f32 v79, v33, v79, v37
	v_fma_f32 v78, v34, v78, v38
	v_fma_f32 v48, v35, v48, v39
	v_cvt_pk_bf16_f32 v84, v84, s0
	v_cvt_pk_bf16_f32 v83, v83, s0
	v_cvt_pk_bf16_f32 v82, v82, s0
	v_cvt_pk_bf16_f32 v81, v81, s0
	v_cvt_pk_bf16_f32 v80, v80, s0
	v_cvt_pk_bf16_f32 v79, v79, s0
	v_cvt_pk_bf16_f32 v78, v78, s0
	v_cvt_pk_bf16_f32 v48, v48, s0
	ds_write_b16 v120, v84 offset:16
	ds_write_b16 v120, v83 offset:288
	ds_write_b16 v120, v82 offset:560
	ds_write_b16 v120, v81 offset:832
	ds_write_b16 v120, v80 offset:1104
	ds_write_b16 v120, v79 offset:1376
	ds_write_b16 v120, v78 offset:1648
	ds_write_b16 v120, v48 offset:1920
.LBB0_934:
	s_or_b64 exec, exec, s[52:53]
	s_waitcnt vmcnt(10)
	v_lshlrev_b32_e32 v78, 16, v74
	v_and_b32_e32 v74, 0xffff0000, v74
	v_mul_f32_e32 v48, 0x3d372713, v78
	v_lshlrev_b32_e32 v81, 16, v75
	v_lshlrev_b32_e32 v82, 16, v76
	v_mul_f32_e32 v48, v48, v78
	v_and_b32_e32 v83, 0xffff0000, v76
	v_mul_f32_e32 v76, 0x3d372713, v74
	v_fma_f32 v48, v48, v78, v78
	v_lshlrev_b32_e32 v84, 16, v77
	v_and_b32_e32 v85, 0xffff0000, v77
	v_mul_f32_e32 v76, v76, v74
	v_mul_f32_e32 v77, 0x3d372713, v81
	v_mul_f32_e32 v48, 0xbfcc422a, v48
	v_fma_f32 v76, v76, v74, v74
	v_mul_f32_e32 v77, v77, v81
	v_mul_f32_e32 v48, 0x3fb8aa3b, v48
	v_mul_f32_e32 v76, 0xbfcc422a, v76
	v_fma_f32 v77, v77, v81, v81
	v_exp_f32_e32 v48, v48
	v_mul_f32_e32 v76, 0x3fb8aa3b, v76
	v_mul_f32_e32 v77, 0xbfcc422a, v77
	v_exp_f32_e32 v76, v76
	v_mul_f32_e32 v77, 0x3fb8aa3b, v77
	v_exp_f32_e32 v77, v77
	v_add_f32_e32 v48, 1.0, v48
	v_rcp_f32_e32 v79, v48
	v_add_f32_e32 v48, 1.0, v76
	v_and_b32_e32 v75, 0xffff0000, v75
	v_rcp_f32_e32 v76, v48
	v_add_f32_e32 v48, 1.0, v77
	v_rcp_f32_e32 v77, v48
	v_mul_f32_e32 v48, 0x3d372713, v75
	v_mul_f32_e32 v48, v48, v75
	v_fma_f32 v48, v48, v75, v75
	v_mul_f32_e32 v48, 0xbfcc422a, v48
	v_mul_f32_e32 v48, 0x3fb8aa3b, v48
	v_exp_f32_e32 v48, v48
	v_mul_f32_e32 v87, 0x3d372713, v83
	v_mul_f32_e32 v87, v87, v83
	v_fma_f32 v87, v87, v83, v83
	v_add_f32_e32 v48, 1.0, v48
	v_rcp_f32_e32 v86, v48
	v_mul_f32_e32 v48, 0x3d372713, v82
	v_mul_f32_e32 v48, v48, v82
	v_fma_f32 v48, v48, v82, v82
	v_mul_f32_e32 v48, 0xbfcc422a, v48
	v_mul_f32_e32 v48, 0x3fb8aa3b, v48
	v_mul_f32_e32 v87, 0xbfcc422a, v87
	v_exp_f32_e32 v48, v48
	v_mul_f32_e32 v87, 0x3fb8aa3b, v87
	v_exp_f32_e32 v87, v87
	v_mul_f32_e32 v89, 0x3d372713, v85
	v_add_f32_e32 v48, 1.0, v48
	v_rcp_f32_e32 v88, v48
	v_add_f32_e32 v48, 1.0, v87
	v_mul_f32_e32 v87, 0x3d372713, v84
	v_mul_f32_e32 v87, v87, v84
	v_fma_f32 v87, v87, v84, v84
	v_mul_f32_e32 v89, v89, v85
	v_mul_f32_e32 v87, 0xbfcc422a, v87
	v_fma_f32 v89, v89, v85, v85
	v_mul_f32_e32 v87, 0x3fb8aa3b, v87
	v_mul_f32_e32 v89, 0xbfcc422a, v89
	v_exp_f32_e32 v87, v87
	v_mul_f32_e32 v89, 0x3fb8aa3b, v89
	v_exp_f32_e32 v89, v89
	v_fma_f32 v80, v79, v78, 0
	v_fmac_f32_e32 v80, v76, v74
	v_rcp_f32_e32 v90, v48
	v_add_f32_e32 v48, 1.0, v87
	v_fmac_f32_e32 v80, v77, v81
	v_rcp_f32_e32 v87, v48
	v_add_f32_e32 v48, 1.0, v89
	v_fmac_f32_e32 v80, v86, v75
	v_rcp_f32_e32 v89, v48
	v_fmac_f32_e32 v80, v88, v82
	v_fmac_f32_e32 v80, v90, v83
	v_fmac_f32_e32 v80, v87, v84
	v_fmac_f32_e32 v80, v89, v85
	s_nop 1
	v_add_f32_dpp v48, v80, v80 row_mirror row_mask:0xf bank_mask:0xf bound_ctrl:1
	s_nop 1
	v_add_f32_dpp v48, v48, v48 row_half_mirror row_mask:0xf bank_mask:0xf bound_ctrl:1
	s_nop 1
	v_add_f32_dpp v48, v48, v48 quad_perm:[1,0,3,2] row_mask:0xf bank_mask:0xf bound_ctrl:1
	s_nop 1
	v_add_f32_dpp v48, v48, v48 quad_perm:[2,3,0,1] row_mask:0xf bank_mask:0xf bound_ctrl:1
	s_waitcnt lgkmcnt(0)
	v_mov_b32_e32 v80, v48
	s_nop 1
	v_permlane16_swap_b32_e32 v48, v80
	v_add_f32_e32 v48, v48, v80
	v_mov_b32_e32 v80, v48
	s_nop 1
	v_permlane32_swap_b32_e32 v48, v80
	v_add_f32_e32 v48, v48, v80
	v_mul_f32_e32 v48, 0xbb000000, v48
	v_fma_f32 v80, v79, v78, v48
	v_fma_f32 v79, v76, v74, v48
	v_mul_f32_e32 v91, v79, v79
	v_fmac_f32_e32 v91, v80, v80
	v_fma_f32 v78, v77, v81, v48
	v_fmac_f32_e32 v91, v78, v78
	v_fma_f32 v77, v86, v75, v48
	v_fmac_f32_e32 v91, v77, v77
	v_fma_f32 v76, v88, v82, v48
	v_fmac_f32_e32 v91, v76, v76
	v_fma_f32 v75, v90, v83, v48
	v_fmac_f32_e32 v91, v75, v75
	v_fma_f32 v74, v87, v84, v48
	v_fmac_f32_e32 v91, v74, v74
	v_fmac_f32_e32 v48, v89, v85
	v_fmac_f32_e32 v91, v48, v48
	s_nop 1
	v_add_f32_dpp v81, v91, v91 row_mirror row_mask:0xf bank_mask:0xf bound_ctrl:1
	s_nop 1
	v_add_f32_dpp v81, v81, v81 row_half_mirror row_mask:0xf bank_mask:0xf bound_ctrl:1
	s_nop 1
	v_add_f32_dpp v81, v81, v81 quad_perm:[1,0,3,2] row_mask:0xf bank_mask:0xf bound_ctrl:1
	s_nop 1
	v_add_f32_dpp v81, v81, v81 quad_perm:[2,3,0,1] row_mask:0xf bank_mask:0xf bound_ctrl:1
	s_waitcnt lgkmcnt(0)
	v_mov_b32_e32 v82, v81
	s_nop 1
	v_permlane16_swap_b32_e32 v81, v82
	v_add_f32_e32 v81, v81, v82
	v_mov_b32_e32 v82, v81
	s_nop 1
	v_permlane32_swap_b32_e32 v81, v82
	s_and_saveexec_b64 s[52:53], vcc
	s_cbranch_execz .LBB0_936
	v_add_f32_e32 v81, v81, v82
	v_fmamk_f32 v81, v81, 0x3b000000, v206
	v_mul_f32_e32 v82, 0x4b800000, v81
	v_cmp_gt_f32_e64 s[40:41], s75, v81
	s_nop 1
	v_cndmask_b32_e64 v81, v81, v82, s[40:41]
	v_rsq_f32_e32 v81, v81
	s_nop 0
	v_mul_f32_e32 v82, 0x45800000, v81
	v_cndmask_b32_e64 v81, v81, v82, s[40:41]
	v_mul_f32_e32 v80, v80, v81
	v_mul_f32_e32 v79, v79, v81
	v_mul_f32_e32 v78, v78, v81
	v_mul_f32_e32 v77, v77, v81
	v_mul_f32_e32 v76, v76, v81
	v_mul_f32_e32 v75, v75, v81
	v_mul_f32_e32 v74, v74, v81
	v_mul_f32_e32 v48, v48, v81
	s_waitcnt vmcnt(1)
	v_fma_f32 v80, v40, v80, v44
	v_fma_f32 v79, v41, v79, v45
	v_fma_f32 v78, v42, v78, v46
	v_fma_f32 v77, v43, v77, v47
	s_waitcnt vmcnt(0)
	v_fma_f32 v76, v32, v76, v36
	v_fma_f32 v75, v33, v75, v37
	v_fma_f32 v74, v34, v74, v38
	v_fma_f32 v48, v35, v48, v39
	v_cvt_pk_bf16_f32 v80, v80, s0
	v_cvt_pk_bf16_f32 v79, v79, s0
	v_cvt_pk_bf16_f32 v78, v78, s0
	v_cvt_pk_bf16_f32 v77, v77, s0
	v_cvt_pk_bf16_f32 v76, v76, s0
	v_cvt_pk_bf16_f32 v75, v75, s0
	v_cvt_pk_bf16_f32 v74, v74, s0
	v_cvt_pk_bf16_f32 v48, v48, s0
	ds_write_b16 v120, v80 offset:18
	ds_write_b16 v120, v79 offset:290
	ds_write_b16 v120, v78 offset:562
	ds_write_b16 v120, v77 offset:834
	ds_write_b16 v120, v76 offset:1106
	ds_write_b16 v120, v75 offset:1378
	ds_write_b16 v120, v74 offset:1650
	ds_write_b16 v120, v48 offset:1922
.LBB0_936:
	s_or_b64 exec, exec, s[52:53]
	s_waitcnt vmcnt(9)
	v_lshlrev_b32_e32 v74, 16, v70
	v_and_b32_e32 v70, 0xffff0000, v70
	v_mul_f32_e32 v48, 0x3d372713, v74
	v_lshlrev_b32_e32 v77, 16, v71
	v_lshlrev_b32_e32 v78, 16, v72
	v_mul_f32_e32 v48, v48, v74
	v_and_b32_e32 v79, 0xffff0000, v72
	v_mul_f32_e32 v72, 0x3d372713, v70
	v_fma_f32 v48, v48, v74, v74
	v_lshlrev_b32_e32 v80, 16, v73
	v_and_b32_e32 v81, 0xffff0000, v73
	v_mul_f32_e32 v72, v72, v70
	v_mul_f32_e32 v73, 0x3d372713, v77
	v_mul_f32_e32 v48, 0xbfcc422a, v48
	v_fma_f32 v72, v72, v70, v70
	v_mul_f32_e32 v73, v73, v77
	v_mul_f32_e32 v48, 0x3fb8aa3b, v48
	v_mul_f32_e32 v72, 0xbfcc422a, v72
	v_fma_f32 v73, v73, v77, v77
	v_exp_f32_e32 v48, v48
	v_mul_f32_e32 v72, 0x3fb8aa3b, v72
	v_mul_f32_e32 v73, 0xbfcc422a, v73
	v_exp_f32_e32 v72, v72
	v_mul_f32_e32 v73, 0x3fb8aa3b, v73
	v_exp_f32_e32 v73, v73
	v_add_f32_e32 v48, 1.0, v48
	v_rcp_f32_e32 v75, v48
	v_add_f32_e32 v48, 1.0, v72
	v_and_b32_e32 v71, 0xffff0000, v71
	v_rcp_f32_e32 v72, v48
	v_add_f32_e32 v48, 1.0, v73
	v_rcp_f32_e32 v73, v48
	v_mul_f32_e32 v48, 0x3d372713, v71
	v_mul_f32_e32 v48, v48, v71
	v_fma_f32 v48, v48, v71, v71
	v_mul_f32_e32 v48, 0xbfcc422a, v48
	v_mul_f32_e32 v48, 0x3fb8aa3b, v48
	v_exp_f32_e32 v48, v48
	v_mul_f32_e32 v83, 0x3d372713, v79
	v_mul_f32_e32 v83, v83, v79
	v_fma_f32 v83, v83, v79, v79
	v_add_f32_e32 v48, 1.0, v48
	v_rcp_f32_e32 v82, v48
	v_mul_f32_e32 v48, 0x3d372713, v78
	v_mul_f32_e32 v48, v48, v78
	v_fma_f32 v48, v48, v78, v78
	v_mul_f32_e32 v48, 0xbfcc422a, v48
	v_mul_f32_e32 v48, 0x3fb8aa3b, v48
	v_mul_f32_e32 v83, 0xbfcc422a, v83
	v_exp_f32_e32 v48, v48
	v_mul_f32_e32 v83, 0x3fb8aa3b, v83
	v_exp_f32_e32 v83, v83
	v_mul_f32_e32 v85, 0x3d372713, v81
	v_add_f32_e32 v48, 1.0, v48
	v_rcp_f32_e32 v84, v48
	v_add_f32_e32 v48, 1.0, v83
	v_mul_f32_e32 v83, 0x3d372713, v80
	v_mul_f32_e32 v83, v83, v80
	v_fma_f32 v83, v83, v80, v80
	v_mul_f32_e32 v85, v85, v81
	v_mul_f32_e32 v83, 0xbfcc422a, v83
	v_fma_f32 v85, v85, v81, v81
	v_mul_f32_e32 v83, 0x3fb8aa3b, v83
	v_mul_f32_e32 v85, 0xbfcc422a, v85
	v_exp_f32_e32 v83, v83
	v_mul_f32_e32 v85, 0x3fb8aa3b, v85
	v_exp_f32_e32 v85, v85
	v_fma_f32 v76, v75, v74, 0
	v_fmac_f32_e32 v76, v72, v70
	v_rcp_f32_e32 v86, v48
	v_add_f32_e32 v48, 1.0, v83
	v_fmac_f32_e32 v76, v73, v77
	v_rcp_f32_e32 v83, v48
	v_add_f32_e32 v48, 1.0, v85
	v_fmac_f32_e32 v76, v82, v71
	v_rcp_f32_e32 v85, v48
	v_fmac_f32_e32 v76, v84, v78
	v_fmac_f32_e32 v76, v86, v79
	v_fmac_f32_e32 v76, v83, v80
	v_fmac_f32_e32 v76, v85, v81
	s_nop 1
	v_add_f32_dpp v48, v76, v76 row_mirror row_mask:0xf bank_mask:0xf bound_ctrl:1
	s_nop 1
	v_add_f32_dpp v48, v48, v48 row_half_mirror row_mask:0xf bank_mask:0xf bound_ctrl:1
	s_nop 1
	v_add_f32_dpp v48, v48, v48 quad_perm:[1,0,3,2] row_mask:0xf bank_mask:0xf bound_ctrl:1
	s_nop 1
	v_add_f32_dpp v48, v48, v48 quad_perm:[2,3,0,1] row_mask:0xf bank_mask:0xf bound_ctrl:1
	s_waitcnt lgkmcnt(0)
	v_mov_b32_e32 v76, v48
	s_nop 1
	v_permlane16_swap_b32_e32 v48, v76
	v_add_f32_e32 v48, v48, v76
	v_mov_b32_e32 v76, v48
	s_nop 1
	v_permlane32_swap_b32_e32 v48, v76
	v_add_f32_e32 v48, v48, v76
	v_mul_f32_e32 v48, 0xbb000000, v48
	v_fma_f32 v76, v75, v74, v48
	v_fma_f32 v75, v72, v70, v48
	v_mul_f32_e32 v87, v75, v75
	v_fmac_f32_e32 v87, v76, v76
	v_fma_f32 v74, v73, v77, v48
	v_fmac_f32_e32 v87, v74, v74
	v_fma_f32 v73, v82, v71, v48
	v_fmac_f32_e32 v87, v73, v73
	v_fma_f32 v72, v84, v78, v48
	v_fmac_f32_e32 v87, v72, v72
	v_fma_f32 v71, v86, v79, v48
	v_fmac_f32_e32 v87, v71, v71
	v_fma_f32 v70, v83, v80, v48
	v_fmac_f32_e32 v87, v70, v70
	v_fmac_f32_e32 v48, v85, v81
	v_fmac_f32_e32 v87, v48, v48
	s_nop 1
	v_add_f32_dpp v77, v87, v87 row_mirror row_mask:0xf bank_mask:0xf bound_ctrl:1
	s_nop 1
	v_add_f32_dpp v77, v77, v77 row_half_mirror row_mask:0xf bank_mask:0xf bound_ctrl:1
	s_nop 1
	v_add_f32_dpp v77, v77, v77 quad_perm:[1,0,3,2] row_mask:0xf bank_mask:0xf bound_ctrl:1
	s_nop 1
	v_add_f32_dpp v77, v77, v77 quad_perm:[2,3,0,1] row_mask:0xf bank_mask:0xf bound_ctrl:1
	s_waitcnt lgkmcnt(0)
	v_mov_b32_e32 v78, v77
	s_nop 1
	v_permlane16_swap_b32_e32 v77, v78
	v_add_f32_e32 v77, v77, v78
	v_mov_b32_e32 v78, v77
	s_nop 1
	v_permlane32_swap_b32_e32 v77, v78
	s_and_saveexec_b64 s[52:53], vcc
	s_cbranch_execz .LBB0_938
	v_add_f32_e32 v77, v77, v78
	v_fmamk_f32 v77, v77, 0x3b000000, v206
	v_mul_f32_e32 v78, 0x4b800000, v77
	v_cmp_gt_f32_e64 s[40:41], s75, v77
	s_nop 1
	v_cndmask_b32_e64 v77, v77, v78, s[40:41]
	v_rsq_f32_e32 v77, v77
	s_nop 0
	v_mul_f32_e32 v78, 0x45800000, v77
	v_cndmask_b32_e64 v77, v77, v78, s[40:41]
	v_mul_f32_e32 v76, v76, v77
	v_mul_f32_e32 v75, v75, v77
	v_mul_f32_e32 v74, v74, v77
	v_mul_f32_e32 v73, v73, v77
	v_mul_f32_e32 v72, v72, v77
	v_mul_f32_e32 v71, v71, v77
	v_mul_f32_e32 v70, v70, v77
	v_mul_f32_e32 v48, v48, v77
	s_waitcnt vmcnt(1)
	v_fma_f32 v76, v40, v76, v44
	v_fma_f32 v75, v41, v75, v45
	v_fma_f32 v74, v42, v74, v46
	v_fma_f32 v73, v43, v73, v47
	s_waitcnt vmcnt(0)
	v_fma_f32 v72, v32, v72, v36
	v_fma_f32 v71, v33, v71, v37
	v_fma_f32 v70, v34, v70, v38
	v_fma_f32 v48, v35, v48, v39
	v_cvt_pk_bf16_f32 v76, v76, s0
	v_cvt_pk_bf16_f32 v75, v75, s0
	v_cvt_pk_bf16_f32 v74, v74, s0
	v_cvt_pk_bf16_f32 v73, v73, s0
	v_cvt_pk_bf16_f32 v72, v72, s0
	v_cvt_pk_bf16_f32 v71, v71, s0
	v_cvt_pk_bf16_f32 v70, v70, s0
	v_cvt_pk_bf16_f32 v48, v48, s0
	ds_write_b16 v120, v76 offset:20
	ds_write_b16 v120, v75 offset:292
	ds_write_b16 v120, v74 offset:564
	ds_write_b16 v120, v73 offset:836
	ds_write_b16 v120, v72 offset:1108
	ds_write_b16 v120, v71 offset:1380
	ds_write_b16 v120, v70 offset:1652
	ds_write_b16 v120, v48 offset:1924
.LBB0_938:
	s_or_b64 exec, exec, s[52:53]
	s_waitcnt vmcnt(8)
	v_lshlrev_b32_e32 v70, 16, v66
	v_and_b32_e32 v66, 0xffff0000, v66
	v_mul_f32_e32 v48, 0x3d372713, v70
	v_lshlrev_b32_e32 v73, 16, v67
	v_lshlrev_b32_e32 v74, 16, v68
	v_mul_f32_e32 v48, v48, v70
	v_and_b32_e32 v75, 0xffff0000, v68
	v_mul_f32_e32 v68, 0x3d372713, v66
	v_fma_f32 v48, v48, v70, v70
	v_lshlrev_b32_e32 v76, 16, v69
	v_and_b32_e32 v77, 0xffff0000, v69
	v_mul_f32_e32 v68, v68, v66
	v_mul_f32_e32 v69, 0x3d372713, v73
	v_mul_f32_e32 v48, 0xbfcc422a, v48
	v_fma_f32 v68, v68, v66, v66
	v_mul_f32_e32 v69, v69, v73
	v_mul_f32_e32 v48, 0x3fb8aa3b, v48
	v_mul_f32_e32 v68, 0xbfcc422a, v68
	v_fma_f32 v69, v69, v73, v73
	v_exp_f32_e32 v48, v48
	v_mul_f32_e32 v68, 0x3fb8aa3b, v68
	v_mul_f32_e32 v69, 0xbfcc422a, v69
	v_exp_f32_e32 v68, v68
	v_mul_f32_e32 v69, 0x3fb8aa3b, v69
	v_exp_f32_e32 v69, v69
	v_add_f32_e32 v48, 1.0, v48
	v_rcp_f32_e32 v71, v48
	v_add_f32_e32 v48, 1.0, v68
	v_and_b32_e32 v67, 0xffff0000, v67
	v_rcp_f32_e32 v68, v48
	v_add_f32_e32 v48, 1.0, v69
	v_rcp_f32_e32 v69, v48
	v_mul_f32_e32 v48, 0x3d372713, v67
	v_mul_f32_e32 v48, v48, v67
	v_fma_f32 v48, v48, v67, v67
	v_mul_f32_e32 v48, 0xbfcc422a, v48
	v_mul_f32_e32 v48, 0x3fb8aa3b, v48
	v_exp_f32_e32 v48, v48
	v_mul_f32_e32 v79, 0x3d372713, v75
	v_mul_f32_e32 v79, v79, v75
	v_fma_f32 v79, v79, v75, v75
	v_add_f32_e32 v48, 1.0, v48
	v_rcp_f32_e32 v78, v48
	v_mul_f32_e32 v48, 0x3d372713, v74
	v_mul_f32_e32 v48, v48, v74
	v_fma_f32 v48, v48, v74, v74
	v_mul_f32_e32 v48, 0xbfcc422a, v48
	v_mul_f32_e32 v48, 0x3fb8aa3b, v48
	v_mul_f32_e32 v79, 0xbfcc422a, v79
	v_exp_f32_e32 v48, v48
	v_mul_f32_e32 v79, 0x3fb8aa3b, v79
	v_exp_f32_e32 v79, v79
	v_mul_f32_e32 v81, 0x3d372713, v77
	v_add_f32_e32 v48, 1.0, v48
	v_rcp_f32_e32 v80, v48
	v_add_f32_e32 v48, 1.0, v79
	v_mul_f32_e32 v79, 0x3d372713, v76
	v_mul_f32_e32 v79, v79, v76
	v_fma_f32 v79, v79, v76, v76
	v_mul_f32_e32 v81, v81, v77
	v_mul_f32_e32 v79, 0xbfcc422a, v79
	v_fma_f32 v81, v81, v77, v77
	v_mul_f32_e32 v79, 0x3fb8aa3b, v79
	v_mul_f32_e32 v81, 0xbfcc422a, v81
	v_exp_f32_e32 v79, v79
	v_mul_f32_e32 v81, 0x3fb8aa3b, v81
	v_exp_f32_e32 v81, v81
	v_fma_f32 v72, v71, v70, 0
	v_fmac_f32_e32 v72, v68, v66
	v_rcp_f32_e32 v82, v48
	v_add_f32_e32 v48, 1.0, v79
	v_fmac_f32_e32 v72, v69, v73
	v_rcp_f32_e32 v79, v48
	v_add_f32_e32 v48, 1.0, v81
	v_fmac_f32_e32 v72, v78, v67
	v_rcp_f32_e32 v81, v48
	v_fmac_f32_e32 v72, v80, v74
	v_fmac_f32_e32 v72, v82, v75
	v_fmac_f32_e32 v72, v79, v76
	v_fmac_f32_e32 v72, v81, v77
	s_nop 1
	v_add_f32_dpp v48, v72, v72 row_mirror row_mask:0xf bank_mask:0xf bound_ctrl:1
	s_nop 1
	v_add_f32_dpp v48, v48, v48 row_half_mirror row_mask:0xf bank_mask:0xf bound_ctrl:1
	s_nop 1
	v_add_f32_dpp v48, v48, v48 quad_perm:[1,0,3,2] row_mask:0xf bank_mask:0xf bound_ctrl:1
	s_nop 1
	v_add_f32_dpp v48, v48, v48 quad_perm:[2,3,0,1] row_mask:0xf bank_mask:0xf bound_ctrl:1
	s_waitcnt lgkmcnt(0)
	v_mov_b32_e32 v72, v48
	s_nop 1
	v_permlane16_swap_b32_e32 v48, v72
	v_add_f32_e32 v48, v48, v72
	v_mov_b32_e32 v72, v48
	s_nop 1
	v_permlane32_swap_b32_e32 v48, v72
	v_add_f32_e32 v48, v48, v72
	v_mul_f32_e32 v48, 0xbb000000, v48
	v_fma_f32 v72, v71, v70, v48
	v_fma_f32 v71, v68, v66, v48
	v_mul_f32_e32 v83, v71, v71
	v_fmac_f32_e32 v83, v72, v72
	v_fma_f32 v70, v69, v73, v48
	v_fmac_f32_e32 v83, v70, v70
	v_fma_f32 v69, v78, v67, v48
	v_fmac_f32_e32 v83, v69, v69
	v_fma_f32 v68, v80, v74, v48
	v_fmac_f32_e32 v83, v68, v68
	v_fma_f32 v67, v82, v75, v48
	v_fmac_f32_e32 v83, v67, v67
	v_fma_f32 v66, v79, v76, v48
	v_fmac_f32_e32 v83, v66, v66
	v_fmac_f32_e32 v48, v81, v77
	v_fmac_f32_e32 v83, v48, v48
	s_nop 1
	v_add_f32_dpp v73, v83, v83 row_mirror row_mask:0xf bank_mask:0xf bound_ctrl:1
	s_nop 1
	v_add_f32_dpp v73, v73, v73 row_half_mirror row_mask:0xf bank_mask:0xf bound_ctrl:1
	s_nop 1
	v_add_f32_dpp v73, v73, v73 quad_perm:[1,0,3,2] row_mask:0xf bank_mask:0xf bound_ctrl:1
	s_nop 1
	v_add_f32_dpp v73, v73, v73 quad_perm:[2,3,0,1] row_mask:0xf bank_mask:0xf bound_ctrl:1
	s_waitcnt lgkmcnt(0)
	v_mov_b32_e32 v74, v73
	s_nop 1
	v_permlane16_swap_b32_e32 v73, v74
	v_add_f32_e32 v73, v73, v74
	v_mov_b32_e32 v74, v73
	s_nop 1
	v_permlane32_swap_b32_e32 v73, v74
	s_and_saveexec_b64 s[52:53], vcc
	s_cbranch_execz .LBB0_940
	v_add_f32_e32 v73, v73, v74
	v_fmamk_f32 v73, v73, 0x3b000000, v206
	v_mul_f32_e32 v74, 0x4b800000, v73
	v_cmp_gt_f32_e64 s[40:41], s75, v73
	s_nop 1
	v_cndmask_b32_e64 v73, v73, v74, s[40:41]
	v_rsq_f32_e32 v73, v73
	s_nop 0
	v_mul_f32_e32 v74, 0x45800000, v73
	v_cndmask_b32_e64 v73, v73, v74, s[40:41]
	v_mul_f32_e32 v72, v72, v73
	v_mul_f32_e32 v71, v71, v73
	v_mul_f32_e32 v70, v70, v73
	v_mul_f32_e32 v69, v69, v73
	v_mul_f32_e32 v68, v68, v73
	v_mul_f32_e32 v67, v67, v73
	v_mul_f32_e32 v66, v66, v73
	v_mul_f32_e32 v48, v48, v73
	s_waitcnt vmcnt(1)
	v_fma_f32 v72, v40, v72, v44
	v_fma_f32 v71, v41, v71, v45
	v_fma_f32 v70, v42, v70, v46
	v_fma_f32 v69, v43, v69, v47
	s_waitcnt vmcnt(0)
	v_fma_f32 v68, v32, v68, v36
	v_fma_f32 v67, v33, v67, v37
	v_fma_f32 v66, v34, v66, v38
	v_fma_f32 v48, v35, v48, v39
	v_cvt_pk_bf16_f32 v72, v72, s0
	v_cvt_pk_bf16_f32 v71, v71, s0
	v_cvt_pk_bf16_f32 v70, v70, s0
	v_cvt_pk_bf16_f32 v69, v69, s0
	v_cvt_pk_bf16_f32 v68, v68, s0
	v_cvt_pk_bf16_f32 v67, v67, s0
	v_cvt_pk_bf16_f32 v66, v66, s0
	v_cvt_pk_bf16_f32 v48, v48, s0
	ds_write_b16 v120, v72 offset:22
	ds_write_b16 v120, v71 offset:294
	ds_write_b16 v120, v70 offset:566
	ds_write_b16 v120, v69 offset:838
	ds_write_b16 v120, v68 offset:1110
	ds_write_b16 v120, v67 offset:1382
	ds_write_b16 v120, v66 offset:1654
	ds_write_b16 v120, v48 offset:1926
.LBB0_940:
	s_or_b64 exec, exec, s[52:53]
	s_waitcnt vmcnt(7)
	v_lshlrev_b32_e32 v66, 16, v62
	v_and_b32_e32 v62, 0xffff0000, v62
	v_mul_f32_e32 v48, 0x3d372713, v66
	v_lshlrev_b32_e32 v69, 16, v63
	v_lshlrev_b32_e32 v70, 16, v64
	v_mul_f32_e32 v48, v48, v66
	v_and_b32_e32 v71, 0xffff0000, v64
	v_mul_f32_e32 v64, 0x3d372713, v62
	v_fma_f32 v48, v48, v66, v66
	v_lshlrev_b32_e32 v72, 16, v65
	v_and_b32_e32 v73, 0xffff0000, v65
	v_mul_f32_e32 v64, v64, v62
	v_mul_f32_e32 v65, 0x3d372713, v69
	v_mul_f32_e32 v48, 0xbfcc422a, v48
	v_fma_f32 v64, v64, v62, v62
	v_mul_f32_e32 v65, v65, v69
	v_mul_f32_e32 v48, 0x3fb8aa3b, v48
	v_mul_f32_e32 v64, 0xbfcc422a, v64
	v_fma_f32 v65, v65, v69, v69
	v_exp_f32_e32 v48, v48
	v_mul_f32_e32 v64, 0x3fb8aa3b, v64
	v_mul_f32_e32 v65, 0xbfcc422a, v65
	v_exp_f32_e32 v64, v64
	v_mul_f32_e32 v65, 0x3fb8aa3b, v65
	v_exp_f32_e32 v65, v65
	v_add_f32_e32 v48, 1.0, v48
	v_rcp_f32_e32 v67, v48
	v_add_f32_e32 v48, 1.0, v64
	v_and_b32_e32 v63, 0xffff0000, v63
	v_rcp_f32_e32 v64, v48
	v_add_f32_e32 v48, 1.0, v65
	v_rcp_f32_e32 v65, v48
	v_mul_f32_e32 v48, 0x3d372713, v63
	v_mul_f32_e32 v48, v48, v63
	v_fma_f32 v48, v48, v63, v63
	v_mul_f32_e32 v48, 0xbfcc422a, v48
	v_mul_f32_e32 v48, 0x3fb8aa3b, v48
	v_exp_f32_e32 v48, v48
	v_mul_f32_e32 v75, 0x3d372713, v71
	v_mul_f32_e32 v75, v75, v71
	v_fma_f32 v75, v75, v71, v71
	v_add_f32_e32 v48, 1.0, v48
	v_rcp_f32_e32 v74, v48
	v_mul_f32_e32 v48, 0x3d372713, v70
	v_mul_f32_e32 v48, v48, v70
	v_fma_f32 v48, v48, v70, v70
	v_mul_f32_e32 v48, 0xbfcc422a, v48
	v_mul_f32_e32 v48, 0x3fb8aa3b, v48
	v_mul_f32_e32 v75, 0xbfcc422a, v75
	v_exp_f32_e32 v48, v48
	v_mul_f32_e32 v75, 0x3fb8aa3b, v75
	v_exp_f32_e32 v75, v75
	v_mul_f32_e32 v77, 0x3d372713, v73
	v_add_f32_e32 v48, 1.0, v48
	v_rcp_f32_e32 v76, v48
	v_add_f32_e32 v48, 1.0, v75
	v_mul_f32_e32 v75, 0x3d372713, v72
	v_mul_f32_e32 v75, v75, v72
	v_fma_f32 v75, v75, v72, v72
	v_mul_f32_e32 v77, v77, v73
	v_mul_f32_e32 v75, 0xbfcc422a, v75
	v_fma_f32 v77, v77, v73, v73
	v_mul_f32_e32 v75, 0x3fb8aa3b, v75
	v_mul_f32_e32 v77, 0xbfcc422a, v77
	v_exp_f32_e32 v75, v75
	v_mul_f32_e32 v77, 0x3fb8aa3b, v77
	v_exp_f32_e32 v77, v77
	v_fma_f32 v68, v67, v66, 0
	v_fmac_f32_e32 v68, v64, v62
	v_rcp_f32_e32 v78, v48
	v_add_f32_e32 v48, 1.0, v75
	v_fmac_f32_e32 v68, v65, v69
	v_rcp_f32_e32 v75, v48
	v_add_f32_e32 v48, 1.0, v77
	v_fmac_f32_e32 v68, v74, v63
	v_rcp_f32_e32 v77, v48
	v_fmac_f32_e32 v68, v76, v70
	v_fmac_f32_e32 v68, v78, v71
	v_fmac_f32_e32 v68, v75, v72
	v_fmac_f32_e32 v68, v77, v73
	s_nop 1
	v_add_f32_dpp v48, v68, v68 row_mirror row_mask:0xf bank_mask:0xf bound_ctrl:1
	s_nop 1
	v_add_f32_dpp v48, v48, v48 row_half_mirror row_mask:0xf bank_mask:0xf bound_ctrl:1
	s_nop 1
	v_add_f32_dpp v48, v48, v48 quad_perm:[1,0,3,2] row_mask:0xf bank_mask:0xf bound_ctrl:1
	s_nop 1
	v_add_f32_dpp v48, v48, v48 quad_perm:[2,3,0,1] row_mask:0xf bank_mask:0xf bound_ctrl:1
	s_waitcnt lgkmcnt(0)
	v_mov_b32_e32 v68, v48
	s_nop 1
	v_permlane16_swap_b32_e32 v48, v68
	v_add_f32_e32 v48, v48, v68
	v_mov_b32_e32 v68, v48
	s_nop 1
	v_permlane32_swap_b32_e32 v48, v68
	v_add_f32_e32 v48, v48, v68
	v_mul_f32_e32 v48, 0xbb000000, v48
	v_fma_f32 v68, v67, v66, v48
	v_fma_f32 v67, v64, v62, v48
	v_mul_f32_e32 v79, v67, v67
	v_fmac_f32_e32 v79, v68, v68
	v_fma_f32 v66, v65, v69, v48
	v_fmac_f32_e32 v79, v66, v66
	v_fma_f32 v65, v74, v63, v48
	v_fmac_f32_e32 v79, v65, v65
	v_fma_f32 v64, v76, v70, v48
	v_fmac_f32_e32 v79, v64, v64
	v_fma_f32 v63, v78, v71, v48
	v_fmac_f32_e32 v79, v63, v63
	v_fma_f32 v62, v75, v72, v48
	v_fmac_f32_e32 v79, v62, v62
	v_fmac_f32_e32 v48, v77, v73
	v_fmac_f32_e32 v79, v48, v48
	s_nop 1
	v_add_f32_dpp v69, v79, v79 row_mirror row_mask:0xf bank_mask:0xf bound_ctrl:1
	s_nop 1
	v_add_f32_dpp v69, v69, v69 row_half_mirror row_mask:0xf bank_mask:0xf bound_ctrl:1
	s_nop 1
	v_add_f32_dpp v69, v69, v69 quad_perm:[1,0,3,2] row_mask:0xf bank_mask:0xf bound_ctrl:1
	s_nop 1
	v_add_f32_dpp v69, v69, v69 quad_perm:[2,3,0,1] row_mask:0xf bank_mask:0xf bound_ctrl:1
	s_waitcnt lgkmcnt(0)
	v_mov_b32_e32 v70, v69
	s_nop 1
	v_permlane16_swap_b32_e32 v69, v70
	v_add_f32_e32 v69, v69, v70
	v_mov_b32_e32 v70, v69
	s_nop 1
	v_permlane32_swap_b32_e32 v69, v70
	s_and_saveexec_b64 s[52:53], vcc
	s_cbranch_execz .LBB0_942
	v_add_f32_e32 v69, v69, v70
	v_fmamk_f32 v69, v69, 0x3b000000, v206
	v_mul_f32_e32 v70, 0x4b800000, v69
	v_cmp_gt_f32_e64 s[40:41], s75, v69
	s_nop 1
	v_cndmask_b32_e64 v69, v69, v70, s[40:41]
	v_rsq_f32_e32 v69, v69
	s_nop 0
	v_mul_f32_e32 v70, 0x45800000, v69
	v_cndmask_b32_e64 v69, v69, v70, s[40:41]
	v_mul_f32_e32 v68, v68, v69
	v_mul_f32_e32 v67, v67, v69
	v_mul_f32_e32 v66, v66, v69
	v_mul_f32_e32 v65, v65, v69
	v_mul_f32_e32 v64, v64, v69
	v_mul_f32_e32 v63, v63, v69
	v_mul_f32_e32 v62, v62, v69
	v_mul_f32_e32 v48, v48, v69
	s_waitcnt vmcnt(1)
	v_fma_f32 v68, v40, v68, v44
	v_fma_f32 v67, v41, v67, v45
	v_fma_f32 v66, v42, v66, v46
	v_fma_f32 v65, v43, v65, v47
	s_waitcnt vmcnt(0)
	v_fma_f32 v64, v32, v64, v36
	v_fma_f32 v63, v33, v63, v37
	v_fma_f32 v62, v34, v62, v38
	v_fma_f32 v48, v35, v48, v39
	v_cvt_pk_bf16_f32 v68, v68, s0
	v_cvt_pk_bf16_f32 v67, v67, s0
	v_cvt_pk_bf16_f32 v66, v66, s0
	v_cvt_pk_bf16_f32 v65, v65, s0
	v_cvt_pk_bf16_f32 v64, v64, s0
	v_cvt_pk_bf16_f32 v63, v63, s0
	v_cvt_pk_bf16_f32 v62, v62, s0
	v_cvt_pk_bf16_f32 v48, v48, s0
	ds_write_b16 v120, v68 offset:24
	ds_write_b16 v120, v67 offset:296
	ds_write_b16 v120, v66 offset:568
	ds_write_b16 v120, v65 offset:840
	ds_write_b16 v120, v64 offset:1112
	ds_write_b16 v120, v63 offset:1384
	ds_write_b16 v120, v62 offset:1656
	ds_write_b16 v120, v48 offset:1928

.LBB0_1055:
	v_add3_u32 v83, s18, v186, v188
	ds_read_b128 v[84:87], v83
	ds_read_b128 v[92:95], v83 offset:64
	s_waitcnt lgkmcnt(1)
	v_mfma_f32_16x16x32_bf16 v[88:91], v[84:87], v[0:3], 0
	ds_read_b128 v[98:101], v83 offset:3392
	ds_read_b128 v[102:105], v83 offset:6720
	ds_read_b128 v[156:159], v83 offset:10048
	v_mfma_f32_16x16x32_bf16 v[84:87], v[84:87], v[12:15], 0
	s_waitcnt lgkmcnt(3)
	v_mfma_f32_16x16x32_bf16 v[88:91], v[92:95], v[4:7], v[88:91]
	v_mfma_f32_16x16x32_bf16 v[84:87], v[92:95], v[16:19], v[84:87]
	ds_read_b128 v[92:95], v83 offset:128
	s_waitcnt lgkmcnt(0)
	v_mfma_f32_16x16x32_bf16 v[160:163], v[92:95], v[8:11], v[88:91]
	v_mfma_f32_16x16x32_bf16 v[90:93], v[92:95], v[20:23], v[84:87]
	s_nop 3
	ds_read_b128 v[84:87], v83 offset:3328
	s_waitcnt lgkmcnt(0)
	v_mfma_f32_16x16x32_bf16 v[94:97], v[84:87], v[0:3], 0
	s_nop 0
	v_max_f32_e32 v153, v91, v91
	v_mfma_f32_16x16x32_bf16 v[84:87], v[84:87], v[12:15], 0
	v_mfma_f32_16x16x32_bf16 v[94:97], v[98:101], v[4:7], v[94:97]
	v_mfma_f32_16x16x32_bf16 v[84:87], v[98:101], v[16:19], v[84:87]
	ds_read_b128 v[98:101], v83 offset:3456
	s_waitcnt lgkmcnt(0)
	v_mfma_f32_16x16x32_bf16 v[166:169], v[98:101], v[8:11], v[94:97]
	v_mfma_f32_16x16x32_bf16 v[94:97], v[98:101], v[20:23], v[84:87]
	s_nop 3
	ds_read_b128 v[84:87], v83 offset:6656
	s_waitcnt lgkmcnt(0)
	v_mfma_f32_16x16x32_bf16 v[98:101], v[84:87], v[0:3], 0
	v_mfma_f32_16x16x32_bf16 v[84:87], v[84:87], v[12:15], 0
	v_mfma_f32_16x16x32_bf16 v[98:101], v[102:105], v[4:7], v[98:101]
	v_mfma_f32_16x16x32_bf16 v[84:87], v[102:105], v[16:19], v[84:87]
	ds_read_b128 v[102:105], v83 offset:6784
	s_waitcnt lgkmcnt(0)
	v_mfma_f32_16x16x32_bf16 v[174:177], v[102:105], v[8:11], v[98:101]
	v_mfma_f32_16x16x32_bf16 v[98:101], v[102:105], v[20:23], v[84:87]
	s_nop 3
	ds_read_b128 v[84:87], v83 offset:9984
	s_waitcnt lgkmcnt(0)
	v_mfma_f32_16x16x32_bf16 v[102:105], v[84:87], v[0:3], 0
	v_mfma_f32_16x16x32_bf16 v[84:87], v[84:87], v[12:15], 0
	v_mfma_f32_16x16x32_bf16 v[102:105], v[156:159], v[4:7], v[102:105]
	v_mfma_f32_16x16x32_bf16 v[84:87], v[156:159], v[16:19], v[84:87]
	ds_read_b128 v[156:159], v83 offset:10112
	v_max_f32_e32 v83, v161, v161
	s_waitcnt lgkmcnt(0)
	v_mfma_f32_16x16x32_bf16 v[192:195], v[156:159], v[8:11], v[102:105]
	v_mfma_f32_16x16x32_bf16 v[102:105], v[156:159], v[20:23], v[84:87]
	v_max_f32_e32 v157, v90, v90
	v_max_f32_e32 v153, v157, v153
	v_max_f32_e32 v157, v93, v93
	v_max_f32_e32 v84, v160, v160
	v_max_f32_e32 v83, v84, v83
	v_max_f32_e32 v84, v163, v163
	v_max_f32_e32 v85, v162, v162
	v_max_f32_e32 v84, v85, v84
	v_max_f32_e32 v85, v169, v169
	v_max_f32_e32 v86, v168, v168
	v_max_f32_e32 v85, v86, v85
	v_max3_f32 v85, v166, v167, v85
	v_max3_f32 v83, v83, v84, v85
	v_max_f32_e32 v84, v177, v177
	v_max_f32_e32 v85, v176, v176
	v_max_f32_e32 v84, v85, v84
	v_max_f32_e32 v85, v195, v195
	v_max_f32_e32 v86, v194, v194
	v_max_f32_e32 v85, v86, v85
	v_max3_f32 v84, v174, v175, v84
	v_max3_f32 v85, v192, v193, v85
	v_max3_f32 v83, v83, v84, v85
	s_waitcnt lgkmcnt(0)
	v_max_f32_e32 v84, v84, v84
	v_mov_b32_e32 v84, v83
	s_nop 1
	v_permlane16_swap_b32_e32 v83, v84
	v_max_f32_e32 v83, v83, v84
	v_mov_b32_e32 v84, v83
	s_nop 1
	v_permlane32_swap_b32_e32 v83, v84
	v_max3_f32 v143, v82, v83, v84
	v_sub_f32_e32 v82, v82, v143
	v_exp_f32_e32 v158, v82
	v_sub_f32_e32 v82, v160, v143
	v_exp_f32_e32 v152, v82
	v_sub_f32_e32 v82, v161, v143
	v_exp_f32_e32 v156, v82
	v_sub_f32_e32 v82, v162, v143
	v_exp_f32_e32 v160, v82
	v_sub_f32_e32 v82, v163, v143
	v_exp_f32_e32 v162, v82
	v_sub_f32_e32 v82, v166, v143
	v_exp_f32_e32 v164, v82
	v_sub_f32_e32 v82, v167, v143
	v_exp_f32_e32 v166, v82
	v_sub_f32_e32 v82, v168, v143
	v_exp_f32_e32 v168, v82
	v_sub_f32_e32 v82, v169, v143
	v_exp_f32_e32 v170, v82
	v_sub_f32_e32 v82, v174, v143
	v_exp_f32_e32 v172, v82
	v_sub_f32_e32 v82, v175, v143
	v_exp_f32_e32 v174, v82
	v_sub_f32_e32 v82, v176, v143
	v_exp_f32_e32 v176, v82
	v_sub_f32_e32 v82, v177, v143
	v_exp_f32_e32 v178, v82
	v_sub_f32_e32 v82, v192, v143
	v_exp_f32_e32 v180, v82
	v_sub_f32_e32 v82, v193, v143
	v_exp_f32_e32 v182, v82
	v_sub_f32_e32 v82, v194, v143
	v_exp_f32_e32 v192, v82
	v_sub_f32_e32 v82, v195, v143
	v_exp_f32_e32 v194, v82
	v_pk_mul_f32 v[84:85], v[68:69], v[158:159] op_sel_hi:[1,0]
	v_pk_mul_f32 v[82:83], v[66:67], v[158:159] op_sel_hi:[1,0]
	v_pk_mul_f32 v[88:89], v[72:73], v[158:159] op_sel_hi:[1,0]
	v_pk_mul_f32 v[86:87], v[70:71], v[158:159] op_sel_hi:[1,0]
	v_pk_mul_f32 v[76:77], v[76:77], v[158:159] op_sel_hi:[1,0]
	v_pk_mul_f32 v[74:75], v[74:75], v[158:159] op_sel_hi:[1,0]
	v_pk_mul_f32 v[68:69], v[80:81], v[158:159] op_sel_hi:[1,0]
	v_pk_mul_f32 v[66:67], v[78:79], v[158:159] op_sel_hi:[1,0]
	v_max_f32_e32 v159, v92, v92
	v_max_f32_e32 v157, v159, v157
	v_max_f32_e32 v159, v97, v97
	v_max_f32_e32 v161, v96, v96
	v_max_f32_e32 v159, v161, v159
	v_max3_f32 v159, v94, v95, v159
	v_max3_f32 v153, v153, v157, v159
	v_max_f32_e32 v157, v101, v101
	v_max_f32_e32 v159, v100, v100
	v_max_f32_e32 v157, v159, v157
	v_max_f32_e32 v159, v105, v105
	v_max_f32_e32 v161, v104, v104
	v_max_f32_e32 v159, v161, v159
	v_max3_f32 v157, v98, v99, v157
	v_max3_f32 v159, v102, v103, v159
	v_max3_f32 v153, v153, v157, v159
	v_cvt_pk_bf16_f32 v70, v152, v156
	v_cvt_pk_bf16_f32 v71, v160, v162
	v_cvt_pk_bf16_f32 v72, v164, v166
	v_cvt_pk_bf16_f32 v73, v168, v170
	s_waitcnt lgkmcnt(0)
	v_max_f32_e32 v157, v157, v157
	v_mov_b32_e32 v157, v153
	s_nop 1
	v_permlane16_swap_b32_e32 v153, v157
	v_max_f32_e32 v153, v153, v157
	v_mov_b32_e32 v157, v153
	s_nop 1
	v_permlane32_swap_b32_e32 v153, v157
	v_max3_f32 v191, v127, v153, v157
	v_sub_f32_e32 v90, v90, v191
	v_exp_f32_e32 v153, v90
	v_sub_f32_e32 v90, v91, v191
	v_exp_f32_e32 v157, v90
	v_sub_f32_e32 v90, v92, v191
	v_exp_f32_e32 v161, v90
	v_sub_f32_e32 v90, v93, v191
	v_exp_f32_e32 v163, v90
	v_sub_f32_e32 v90, v94, v191
	v_exp_f32_e32 v165, v90
	v_sub_f32_e32 v90, v95, v191
	v_exp_f32_e32 v167, v90
	v_pk_add_f32 v[90:91], v[152:153], 0 op_sel_hi:[1,0]
	v_sub_f32_e32 v92, v96, v191
	v_pk_add_f32 v[90:91], v[156:157], v[90:91]
	v_exp_f32_e32 v169, v92
	v_pk_add_f32 v[90:91], v[160:161], v[90:91]
	v_sub_f32_e32 v92, v97, v191
	v_pk_add_f32 v[90:91], v[162:163], v[90:91]
	v_exp_f32_e32 v171, v92
	v_sub_f32_e32 v92, v98, v191
	v_pk_add_f32 v[90:91], v[164:165], v[90:91]
	v_exp_f32_e32 v173, v92
	v_sub_f32_e32 v92, v99, v191
	v_pk_add_f32 v[90:91], v[166:167], v[90:91]
	v_exp_f32_e32 v175, v92
	v_sub_f32_e32 v92, v100, v191
	v_exp_f32_e32 v177, v92
	v_sub_f32_e32 v92, v101, v191
	v_pk_add_f32 v[90:91], v[168:169], v[90:91]
	v_exp_f32_e32 v179, v92
	v_sub_f32_e32 v92, v102, v191
	v_pk_add_f32 v[90:91], v[170:171], v[90:91]
	v_exp_f32_e32 v181, v92
	v_sub_f32_e32 v92, v103, v191
	v_pk_add_f32 v[90:91], v[172:173], v[90:91]
	v_exp_f32_e32 v183, v92
	v_sub_f32_e32 v92, v104, v191
	v_pk_add_f32 v[90:91], v[174:175], v[90:91]
	v_sub_f32_e32 v127, v127, v191
	v_exp_f32_e32 v193, v92
	v_sub_f32_e32 v92, v105, v191
	v_pk_add_f32 v[90:91], v[176:177], v[90:91]
	v_exp_f32_e32 v159, v127
	v_exp_f32_e32 v195, v92
	v_pk_add_f32 v[90:91], v[178:179], v[90:91]
	v_cvt_pk_bf16_f32 v78, v172, v174
	v_pk_add_f32 v[90:91], v[180:181], v[90:91]
	v_mov_b32_e32 v98, v159
	v_pk_add_f32 v[90:91], v[182:183], v[90:91]
	v_pk_mul_f32 v[92:93], v[52:53], v[98:99] op_sel_hi:[1,0]
	v_pk_add_f32 v[90:91], v[192:193], v[90:91]
	v_pk_mul_f32 v[96:97], v[56:57], v[98:99] op_sel_hi:[1,0]
	v_pk_add_f32 v[90:91], v[194:195], v[90:91]
	v_pk_mul_f32 v[94:95], v[54:55], v[98:99] op_sel_hi:[1,0]
	v_pk_fma_f32 v[150:151], v[150:151], v[158:159], v[90:91]
	v_pk_mul_f32 v[90:91], v[50:51], v[98:99] op_sel_hi:[1,0]
	v_pk_mul_f32 v[60:61], v[60:61], v[98:99] op_sel_hi:[1,0]
	v_pk_mul_f32 v[58:59], v[58:59], v[98:99] op_sel_hi:[1,0]
	v_pk_mul_f32 v[52:53], v[64:65], v[98:99] op_sel_hi:[1,0]
	v_pk_mul_f32 v[50:51], v[62:63], v[98:99] op_sel_hi:[1,0]
	v_lshlrev_b32_e32 v98, 1, v187
	v_add3_u32 v127, s18, v98, v189
	ds_read_b64_tr_b16 v[100:101], v127 offset:15872
	ds_read_b64_tr_b16 v[98:99], v127 offset:13312
	ds_read_b64_tr_b16 v[102:103], v127 offset:13320
	v_cvt_pk_bf16_f32 v54, v153, v157
	v_cvt_pk_bf16_f32 v55, v161, v163
	v_cvt_pk_bf16_f32 v56, v165, v167
	v_cvt_pk_bf16_f32 v57, v169, v171
	s_waitcnt lgkmcnt(1)
	v_mfma_f32_16x16x32_bf16 v[82:85], v[98:101], v[70:73], v[82:85]
	ds_read_b64_tr_b16 v[104:105], v127 offset:15880
	v_cvt_pk_bf16_f32 v79, v176, v178
	v_cvt_pk_bf16_f32 v80, v180, v182
	v_mfma_f32_16x16x32_bf16 v[90:93], v[98:101], v[54:57], v[90:93]
	ds_read_b64_tr_b16 v[98:99], v127 offset:13376
	ds_read_b64_tr_b16 v[100:101], v127 offset:15936
	v_cvt_pk_bf16_f32 v81, v192, v194
	v_cvt_pk_bf16_f32 v62, v173, v175
	s_waitcnt lgkmcnt(0)
	v_mfma_f32_16x16x32_bf16 v[74:77], v[98:101], v[70:73], v[74:77]
	v_cvt_pk_bf16_f32 v63, v177, v179
	v_cvt_pk_bf16_f32 v64, v181, v183
	v_cvt_pk_bf16_f32 v65, v193, v195
	v_mfma_f32_16x16x32_bf16 v[58:61], v[98:101], v[54:57], v[58:61]
	ds_read_b64_tr_b16 v[98:99], v127 offset:13384
	ds_read_b64_tr_b16 v[100:101], v127 offset:15944
	v_mfma_f32_16x16x32_bf16 v[86:89], v[102:105], v[70:73], v[86:89]
	v_mfma_f32_16x16x32_bf16 v[94:97], v[102:105], v[54:57], v[94:97]
	s_waitcnt lgkmcnt(0)
	v_mfma_f32_16x16x32_bf16 v[102:105], v[98:101], v[70:73], v[66:69]
	v_mfma_f32_16x16x32_bf16 v[98:101], v[98:101], v[54:57], v[50:53]
	s_nop 2
	ds_read_b64_tr_b16 v[50:51], v127 offset:18432
	ds_read_b64_tr_b16 v[52:53], v127 offset:20992
	ds_read_b64_tr_b16 v[54:55], v127 offset:18440
	ds_read_b64_tr_b16 v[56:57], v127 offset:21000
	s_waitcnt lgkmcnt(2)
	v_mfma_f32_16x16x32_bf16 v[66:69], v[50:53], v[78:81], v[82:85]
	s_nop 2
	ds_read_b64_tr_b16 v[82:83], v127 offset:18496
	ds_read_b64_tr_b16 v[84:85], v127 offset:21056
	s_waitcnt lgkmcnt(0)
	v_mfma_f32_16x16x32_bf16 v[74:77], v[82:85], v[78:81], v[74:77]
	v_mfma_f32_16x16x32_bf16 v[58:61], v[82:85], v[62:65], v[58:61]
	ds_read_b64_tr_b16 v[82:83], v127 offset:18504
	ds_read_b64_tr_b16 v[84:85], v127 offset:21064
	v_mov_b32_e32 v127, v191
	v_mfma_f32_16x16x32_bf16 v[50:53], v[50:53], v[62:65], v[90:93]
	v_mfma_f32_16x16x32_bf16 v[70:73], v[54:57], v[78:81], v[86:89]
	v_mfma_f32_16x16x32_bf16 v[54:57], v[54:57], v[62:65], v[94:97]
	s_waitcnt lgkmcnt(0)
	v_mfma_f32_16x16x32_bf16 v[78:81], v[82:85], v[78:81], v[102:105]
	v_mfma_f32_16x16x32_bf16 v[62:65], v[82:85], v[62:65], v[98:101]
	v_mov_b32_e32 v82, v143
	s_add_i32 s6, s48, -2
	s_cmp_ge_i32 s6, s47
	s_cbranch_scc1 .LBB0_1042
.LBB0_1056:
	s_and_b32 s6, s6, 3
	s_mulk_i32 s6, 0x5c00
	s_add_i32 s18, s6, 0
	v_add3_u32 v83, s18, v186, v188
	ds_read_b128 v[84:87], v83
	ds_read_b128 v[92:95], v83 offset:64
	s_waitcnt lgkmcnt(1)
	v_mfma_f32_16x16x32_bf16 v[88:91], v[84:87], v[0:3], 0
	ds_read_b128 v[98:101], v83 offset:3392
	ds_read_b128 v[102:105], v83 offset:6720
	ds_read_b128 v[156:159], v83 offset:10048
	v_mfma_f32_16x16x32_bf16 v[84:87], v[84:87], v[12:15], 0
	s_waitcnt lgkmcnt(3)
	v_mfma_f32_16x16x32_bf16 v[88:91], v[92:95], v[4:7], v[88:91]
	v_mfma_f32_16x16x32_bf16 v[84:87], v[92:95], v[16:19], v[84:87]
	ds_read_b128 v[92:95], v83 offset:128
	s_waitcnt lgkmcnt(0)
	v_mfma_f32_16x16x32_bf16 v[160:163], v[92:95], v[8:11], v[88:91]
	v_mfma_f32_16x16x32_bf16 v[90:93], v[92:95], v[20:23], v[84:87]
	s_nop 3
	ds_read_b128 v[84:87], v83 offset:3328
	s_waitcnt lgkmcnt(0)
	v_mfma_f32_16x16x32_bf16 v[94:97], v[84:87], v[0:3], 0
	s_nop 0
	v_max_f32_e32 v153, v91, v91
	v_mfma_f32_16x16x32_bf16 v[84:87], v[84:87], v[12:15], 0
	v_mfma_f32_16x16x32_bf16 v[94:97], v[98:101], v[4:7], v[94:97]
	v_mfma_f32_16x16x32_bf16 v[84:87], v[98:101], v[16:19], v[84:87]
	ds_read_b128 v[98:101], v83 offset:3456
	s_waitcnt lgkmcnt(0)
	v_mfma_f32_16x16x32_bf16 v[166:169], v[98:101], v[8:11], v[94:97]
	v_mfma_f32_16x16x32_bf16 v[94:97], v[98:101], v[20:23], v[84:87]
	s_nop 3
	ds_read_b128 v[84:87], v83 offset:6656
	s_waitcnt lgkmcnt(0)
	v_mfma_f32_16x16x32_bf16 v[98:101], v[84:87], v[0:3], 0
	v_mfma_f32_16x16x32_bf16 v[84:87], v[84:87], v[12:15], 0
	v_mfma_f32_16x16x32_bf16 v[98:101], v[102:105], v[4:7], v[98:101]
	v_mfma_f32_16x16x32_bf16 v[84:87], v[102:105], v[16:19], v[84:87]
	ds_read_b128 v[102:105], v83 offset:6784
	s_waitcnt lgkmcnt(0)
	v_mfma_f32_16x16x32_bf16 v[174:177], v[102:105], v[8:11], v[98:101]
	v_mfma_f32_16x16x32_bf16 v[98:101], v[102:105], v[20:23], v[84:87]
	s_nop 3
	ds_read_b128 v[84:87], v83 offset:9984
	s_waitcnt lgkmcnt(0)
	v_mfma_f32_16x16x32_bf16 v[102:105], v[84:87], v[0:3], 0
	v_mfma_f32_16x16x32_bf16 v[84:87], v[84:87], v[12:15], 0
	v_mfma_f32_16x16x32_bf16 v[102:105], v[156:159], v[4:7], v[102:105]
	v_mfma_f32_16x16x32_bf16 v[84:87], v[156:159], v[16:19], v[84:87]
	ds_read_b128 v[156:159], v83 offset:10112
	v_max_f32_e32 v83, v161, v161
	s_waitcnt lgkmcnt(0)
	v_mfma_f32_16x16x32_bf16 v[180:183], v[156:159], v[8:11], v[102:105]
	v_mfma_f32_16x16x32_bf16 v[102:105], v[156:159], v[20:23], v[84:87]
	v_max_f32_e32 v157, v90, v90
	v_max_f32_e32 v153, v157, v153
	v_max_f32_e32 v157, v93, v93
	v_max_f32_e32 v84, v160, v160
	v_max_f32_e32 v83, v84, v83
	v_max_f32_e32 v84, v163, v163
	v_max_f32_e32 v85, v162, v162
	v_max_f32_e32 v84, v85, v84
	v_max_f32_e32 v85, v169, v169
	v_max_f32_e32 v86, v168, v168
	v_max_f32_e32 v85, v86, v85
	v_max3_f32 v85, v166, v167, v85
	v_max3_f32 v83, v83, v84, v85
	v_max_f32_e32 v84, v177, v177
	v_max_f32_e32 v85, v176, v176
	v_max_f32_e32 v84, v85, v84
	v_max_f32_e32 v85, v183, v183
	v_max_f32_e32 v86, v182, v182
	v_max_f32_e32 v85, v86, v85
	v_max3_f32 v84, v174, v175, v84
	v_max3_f32 v85, v180, v181, v85
	v_max3_f32 v83, v83, v84, v85
	s_waitcnt lgkmcnt(0)
	v_max_f32_e32 v84, v84, v84
	v_mov_b32_e32 v84, v83
	s_nop 1
	v_permlane16_swap_b32_e32 v83, v84
	v_max_f32_e32 v83, v83, v84
	v_mov_b32_e32 v84, v83
	s_nop 1
	v_permlane32_swap_b32_e32 v83, v84
	v_max3_f32 v143, v82, v83, v84
	v_sub_f32_e32 v82, v82, v143
	v_exp_f32_e32 v158, v82
	v_sub_f32_e32 v82, v160, v143
	v_exp_f32_e32 v152, v82
	v_sub_f32_e32 v82, v161, v143
	v_exp_f32_e32 v156, v82
	v_sub_f32_e32 v82, v162, v143
	v_exp_f32_e32 v160, v82
	v_sub_f32_e32 v82, v163, v143
	v_exp_f32_e32 v162, v82
	v_sub_f32_e32 v82, v166, v143
	v_exp_f32_e32 v164, v82
	v_sub_f32_e32 v82, v167, v143
	v_exp_f32_e32 v166, v82
	v_sub_f32_e32 v82, v168, v143
	v_exp_f32_e32 v168, v82
	v_sub_f32_e32 v82, v169, v143
	v_exp_f32_e32 v170, v82
	v_sub_f32_e32 v82, v174, v143
	v_exp_f32_e32 v172, v82
	v_sub_f32_e32 v82, v175, v143
	v_exp_f32_e32 v174, v82
	v_sub_f32_e32 v82, v176, v143
	v_exp_f32_e32 v176, v82
	v_sub_f32_e32 v82, v177, v143
	v_exp_f32_e32 v178, v82
	v_sub_f32_e32 v82, v180, v143
	v_exp_f32_e32 v180, v82
	v_sub_f32_e32 v82, v181, v143
	v_exp_f32_e32 v192, v82
	v_sub_f32_e32 v82, v182, v143
	v_exp_f32_e32 v194, v82
	v_sub_f32_e32 v82, v183, v143
	v_exp_f32_e32 v196, v82
	v_pk_mul_f32 v[84:85], v[68:69], v[158:159] op_sel_hi:[1,0]
	v_pk_mul_f32 v[82:83], v[66:67], v[158:159] op_sel_hi:[1,0]
	v_pk_mul_f32 v[88:89], v[72:73], v[158:159] op_sel_hi:[1,0]
	v_pk_mul_f32 v[86:87], v[70:71], v[158:159] op_sel_hi:[1,0]
	v_pk_mul_f32 v[76:77], v[76:77], v[158:159] op_sel_hi:[1,0]
	v_pk_mul_f32 v[74:75], v[74:75], v[158:159] op_sel_hi:[1,0]
	v_pk_mul_f32 v[68:69], v[80:81], v[158:159] op_sel_hi:[1,0]
	v_pk_mul_f32 v[66:67], v[78:79], v[158:159] op_sel_hi:[1,0]
	v_max_f32_e32 v159, v92, v92
	v_max_f32_e32 v157, v159, v157
	v_max_f32_e32 v159, v97, v97
	v_max_f32_e32 v161, v96, v96
	v_max_f32_e32 v159, v161, v159
	v_max3_f32 v159, v94, v95, v159
	v_max3_f32 v153, v153, v157, v159
	v_max_f32_e32 v157, v101, v101
	v_max_f32_e32 v159, v100, v100
	v_max_f32_e32 v157, v159, v157
	v_max_f32_e32 v159, v105, v105
	v_max_f32_e32 v161, v104, v104
	v_max_f32_e32 v159, v161, v159
	v_max3_f32 v157, v98, v99, v157
	v_max3_f32 v159, v102, v103, v159
	v_max3_f32 v153, v153, v157, v159
	v_cvt_pk_bf16_f32 v70, v152, v156
	v_cvt_pk_bf16_f32 v71, v160, v162
	v_cvt_pk_bf16_f32 v72, v164, v166
	v_cvt_pk_bf16_f32 v73, v168, v170
	s_waitcnt lgkmcnt(0)
	v_max_f32_e32 v157, v157, v157
	v_mov_b32_e32 v157, v153
	s_nop 1
	v_permlane16_swap_b32_e32 v153, v157
	v_max_f32_e32 v153, v153, v157
	v_mov_b32_e32 v157, v153
	s_nop 1
	v_permlane32_swap_b32_e32 v153, v157
	v_max3_f32 v182, v127, v153, v157
	v_sub_f32_e32 v90, v90, v182
	v_exp_f32_e32 v153, v90
	v_sub_f32_e32 v90, v91, v182
	v_exp_f32_e32 v157, v90
	v_sub_f32_e32 v90, v92, v182
	v_exp_f32_e32 v161, v90
	v_sub_f32_e32 v90, v93, v182
	v_exp_f32_e32 v163, v90
	v_sub_f32_e32 v90, v94, v182
	v_exp_f32_e32 v165, v90
	v_sub_f32_e32 v90, v95, v182
	v_exp_f32_e32 v167, v90
	v_pk_add_f32 v[90:91], v[152:153], 0 op_sel_hi:[1,0]
	v_sub_f32_e32 v92, v96, v182
	v_pk_add_f32 v[90:91], v[156:157], v[90:91]
	v_exp_f32_e32 v169, v92
	v_pk_add_f32 v[90:91], v[160:161], v[90:91]
	v_sub_f32_e32 v92, v97, v182
	v_pk_add_f32 v[90:91], v[162:163], v[90:91]
	v_exp_f32_e32 v171, v92
	v_sub_f32_e32 v92, v98, v182
	v_pk_add_f32 v[90:91], v[164:165], v[90:91]
	v_exp_f32_e32 v173, v92
	v_sub_f32_e32 v92, v99, v182
	v_pk_add_f32 v[90:91], v[166:167], v[90:91]
	v_exp_f32_e32 v175, v92
	v_sub_f32_e32 v92, v100, v182
	v_exp_f32_e32 v177, v92
	v_sub_f32_e32 v92, v101, v182
	v_pk_add_f32 v[90:91], v[168:169], v[90:91]
	v_exp_f32_e32 v179, v92
	v_sub_f32_e32 v92, v102, v182
	v_pk_add_f32 v[90:91], v[170:171], v[90:91]
	v_exp_f32_e32 v181, v92
	v_sub_f32_e32 v92, v103, v182
	v_pk_add_f32 v[90:91], v[172:173], v[90:91]
	v_exp_f32_e32 v193, v92
	v_sub_f32_e32 v92, v104, v182
	v_pk_add_f32 v[90:91], v[174:175], v[90:91]
	v_sub_f32_e32 v127, v127, v182
	v_exp_f32_e32 v195, v92
	v_sub_f32_e32 v92, v105, v182
	v_pk_add_f32 v[90:91], v[176:177], v[90:91]
	v_exp_f32_e32 v159, v127
	v_exp_f32_e32 v197, v92
	v_pk_add_f32 v[90:91], v[178:179], v[90:91]
	v_cvt_pk_bf16_f32 v78, v172, v174
	v_pk_add_f32 v[90:91], v[180:181], v[90:91]
	v_mov_b32_e32 v98, v159
	v_pk_add_f32 v[90:91], v[192:193], v[90:91]
	v_pk_mul_f32 v[92:93], v[52:53], v[98:99] op_sel_hi:[1,0]
	v_pk_add_f32 v[90:91], v[194:195], v[90:91]
	v_pk_mul_f32 v[96:97], v[56:57], v[98:99] op_sel_hi:[1,0]
	v_pk_add_f32 v[90:91], v[196:197], v[90:91]
	v_pk_mul_f32 v[94:95], v[54:55], v[98:99] op_sel_hi:[1,0]
	v_pk_fma_f32 v[150:151], v[150:151], v[158:159], v[90:91]
	v_pk_mul_f32 v[90:91], v[50:51], v[98:99] op_sel_hi:[1,0]
	v_pk_mul_f32 v[60:61], v[60:61], v[98:99] op_sel_hi:[1,0]
	v_pk_mul_f32 v[58:59], v[58:59], v[98:99] op_sel_hi:[1,0]
	v_pk_mul_f32 v[52:53], v[64:65], v[98:99] op_sel_hi:[1,0]
	v_pk_mul_f32 v[50:51], v[62:63], v[98:99] op_sel_hi:[1,0]
	v_lshlrev_b32_e32 v98, 1, v187
	v_add3_u32 v127, s18, v98, v189
	ds_read_b64_tr_b16 v[100:101], v127 offset:15872
	ds_read_b64_tr_b16 v[98:99], v127 offset:13312
	ds_read_b64_tr_b16 v[102:103], v127 offset:13320
	v_cvt_pk_bf16_f32 v54, v153, v157
	v_cvt_pk_bf16_f32 v55, v161, v163
	v_cvt_pk_bf16_f32 v56, v165, v167
	v_cvt_pk_bf16_f32 v57, v169, v171
	s_waitcnt lgkmcnt(1)
	v_mfma_f32_16x16x32_bf16 v[82:85], v[98:101], v[70:73], v[82:85]
	ds_read_b64_tr_b16 v[104:105], v127 offset:15880
	v_cvt_pk_bf16_f32 v79, v176, v178
	v_cvt_pk_bf16_f32 v80, v180, v192
	v_mfma_f32_16x16x32_bf16 v[90:93], v[98:101], v[54:57], v[90:93]
	ds_read_b64_tr_b16 v[98:99], v127 offset:13376
	ds_read_b64_tr_b16 v[100:101], v127 offset:15936
	v_cvt_pk_bf16_f32 v81, v194, v196
	v_cvt_pk_bf16_f32 v62, v173, v175
	s_waitcnt lgkmcnt(0)
	v_mfma_f32_16x16x32_bf16 v[74:77], v[98:101], v[70:73], v[74:77]
	v_cvt_pk_bf16_f32 v63, v177, v179
	v_cvt_pk_bf16_f32 v64, v181, v193
	v_cvt_pk_bf16_f32 v65, v195, v197
	v_mfma_f32_16x16x32_bf16 v[58:61], v[98:101], v[54:57], v[58:61]
	ds_read_b64_tr_b16 v[98:99], v127 offset:13384
	ds_read_b64_tr_b16 v[100:101], v127 offset:15944
	v_mfma_f32_16x16x32_bf16 v[86:89], v[102:105], v[70:73], v[86:89]
	v_mfma_f32_16x16x32_bf16 v[94:97], v[102:105], v[54:57], v[94:97]
	s_waitcnt lgkmcnt(0)
	v_mfma_f32_16x16x32_bf16 v[102:105], v[98:101], v[70:73], v[66:69]
	v_mfma_f32_16x16x32_bf16 v[98:101], v[98:101], v[54:57], v[50:53]
	s_nop 2
	ds_read_b64_tr_b16 v[50:51], v127 offset:18432
	ds_read_b64_tr_b16 v[52:53], v127 offset:20992
	ds_read_b64_tr_b16 v[54:55], v127 offset:18440
	ds_read_b64_tr_b16 v[56:57], v127 offset:21000
	s_waitcnt lgkmcnt(2)
	v_mfma_f32_16x16x32_bf16 v[66:69], v[50:53], v[78:81], v[82:85]
	s_nop 2
	ds_read_b64_tr_b16 v[82:83], v127 offset:18496
	ds_read_b64_tr_b16 v[84:85], v127 offset:21056
	s_waitcnt lgkmcnt(0)
	v_mfma_f32_16x16x32_bf16 v[74:77], v[82:85], v[78:81], v[74:77]
	v_mfma_f32_16x16x32_bf16 v[58:61], v[82:85], v[62:65], v[58:61]
	ds_read_b64_tr_b16 v[82:83], v127 offset:18504
	ds_read_b64_tr_b16 v[84:85], v127 offset:21064
	v_mov_b32_e32 v127, v182
	v_mfma_f32_16x16x32_bf16 v[50:53], v[50:53], v[62:65], v[90:93]
	v_mfma_f32_16x16x32_bf16 v[70:73], v[54:57], v[78:81], v[86:89]
	v_mfma_f32_16x16x32_bf16 v[54:57], v[54:57], v[62:65], v[94:97]
	s_waitcnt lgkmcnt(0)
	v_mfma_f32_16x16x32_bf16 v[78:81], v[82:85], v[78:81], v[102:105]
	v_mfma_f32_16x16x32_bf16 v[62:65], v[82:85], v[62:65], v[98:101]
	v_mov_b32_e32 v82, v143
	s_branch .LBB0_1042

.LBB0_1077:
	v_add3_u32 v83, s18, v186, v188
	ds_read_b128 v[84:87], v83
	ds_read_b128 v[92:95], v83 offset:64
	s_waitcnt lgkmcnt(1)
	v_mfma_f32_16x16x32_bf16 v[88:91], v[84:87], v[8:11], 0
	ds_read_b128 v[98:101], v83 offset:3392
	ds_read_b128 v[102:105], v83 offset:6720
	ds_read_b128 v[144:147], v83 offset:10048
	v_mfma_f32_16x16x32_bf16 v[84:87], v[84:87], v[12:15], 0
	s_waitcnt lgkmcnt(3)
	v_mfma_f32_16x16x32_bf16 v[88:91], v[92:95], v[0:3], v[88:91]
	v_mfma_f32_16x16x32_bf16 v[84:87], v[92:95], v[16:19], v[84:87]
	ds_read_b128 v[92:95], v83 offset:128
	s_waitcnt lgkmcnt(0)
	v_mfma_f32_16x16x32_bf16 v[150:153], v[92:95], v[4:7], v[88:91]
	v_mfma_f32_16x16x32_bf16 v[90:93], v[92:95], v[20:23], v[84:87]
	s_nop 3
	ds_read_b128 v[84:87], v83 offset:3328
	s_waitcnt lgkmcnt(0)
	v_mfma_f32_16x16x32_bf16 v[94:97], v[84:87], v[8:11], 0
	v_mfma_f32_16x16x32_bf16 v[84:87], v[84:87], v[12:15], 0
	v_mfma_f32_16x16x32_bf16 v[94:97], v[98:101], v[0:3], v[94:97]
	v_mfma_f32_16x16x32_bf16 v[84:87], v[98:101], v[16:19], v[84:87]
	ds_read_b128 v[98:101], v83 offset:3456
	s_waitcnt lgkmcnt(0)
	v_mfma_f32_16x16x32_bf16 v[158:161], v[98:101], v[4:7], v[94:97]
	v_mfma_f32_16x16x32_bf16 v[94:97], v[98:101], v[20:23], v[84:87]
	s_nop 3
	ds_read_b128 v[84:87], v83 offset:6656
	s_waitcnt lgkmcnt(0)
	v_mfma_f32_16x16x32_bf16 v[98:101], v[84:87], v[8:11], 0
	v_mfma_f32_16x16x32_bf16 v[84:87], v[84:87], v[12:15], 0
	v_mfma_f32_16x16x32_bf16 v[98:101], v[102:105], v[0:3], v[98:101]
	v_mfma_f32_16x16x32_bf16 v[84:87], v[102:105], v[16:19], v[84:87]
	ds_read_b128 v[102:105], v83 offset:6784
	s_waitcnt lgkmcnt(0)
	v_mfma_f32_16x16x32_bf16 v[166:169], v[102:105], v[4:7], v[98:101]
	v_mfma_f32_16x16x32_bf16 v[98:101], v[102:105], v[20:23], v[84:87]
	s_nop 3
	ds_read_b128 v[84:87], v83 offset:9984
	s_waitcnt lgkmcnt(0)
	v_mfma_f32_16x16x32_bf16 v[102:105], v[84:87], v[8:11], 0
	v_mfma_f32_16x16x32_bf16 v[84:87], v[84:87], v[12:15], 0
	v_mfma_f32_16x16x32_bf16 v[102:105], v[144:147], v[0:3], v[102:105]
	v_mfma_f32_16x16x32_bf16 v[84:87], v[144:147], v[16:19], v[84:87]
	ds_read_b128 v[144:147], v83 offset:10112
	v_max_f32_e32 v83, v151, v151
	s_waitcnt lgkmcnt(0)
	v_mfma_f32_16x16x32_bf16 v[178:181], v[144:147], v[4:7], v[102:105]
	v_mfma_f32_16x16x32_bf16 v[102:105], v[144:147], v[20:23], v[84:87]
	v_max_f32_e32 v145, v91, v91
	s_nop 1
	v_max_f32_e32 v84, v150, v150
	v_max_f32_e32 v83, v84, v83
	v_max_f32_e32 v84, v153, v153
	v_max_f32_e32 v85, v152, v152
	v_max_f32_e32 v84, v85, v84
	v_max_f32_e32 v85, v161, v161
	v_max_f32_e32 v86, v160, v160
	v_max_f32_e32 v85, v86, v85
	v_max3_f32 v85, v158, v159, v85
	v_max3_f32 v83, v83, v84, v85
	v_max_f32_e32 v84, v169, v169
	v_max_f32_e32 v85, v168, v168
	v_max_f32_e32 v84, v85, v84
	v_max_f32_e32 v85, v181, v181
	v_max_f32_e32 v86, v180, v180
	v_max_f32_e32 v85, v86, v85
	v_max3_f32 v84, v166, v167, v84
	v_max3_f32 v85, v178, v179, v85
	v_max3_f32 v83, v83, v84, v85
	s_waitcnt lgkmcnt(0)
	v_max_f32_e32 v84, v84, v84
	v_mov_b32_e32 v84, v83
	s_nop 1
	v_permlane16_swap_b32_e32 v83, v84
	v_max_f32_e32 v83, v83, v84
	v_mov_b32_e32 v84, v83
	s_nop 1
	v_permlane32_swap_b32_e32 v83, v84
	v_max3_f32 v176, v82, v83, v84
	v_sub_f32_e32 v82, v82, v176
	v_exp_f32_e32 v146, v82
	v_sub_f32_e32 v82, v150, v176
	v_exp_f32_e32 v142, v82
	v_sub_f32_e32 v82, v151, v176
	v_exp_f32_e32 v144, v82
	v_sub_f32_e32 v82, v152, v176
	v_exp_f32_e32 v150, v82
	v_sub_f32_e32 v82, v153, v176
	v_exp_f32_e32 v152, v82
	v_sub_f32_e32 v82, v158, v176
	v_exp_f32_e32 v156, v82
	v_sub_f32_e32 v82, v159, v176
	v_exp_f32_e32 v158, v82
	v_sub_f32_e32 v82, v160, v176
	v_exp_f32_e32 v160, v82
	v_sub_f32_e32 v82, v161, v176
	v_exp_f32_e32 v162, v82
	v_sub_f32_e32 v82, v166, v176
	v_exp_f32_e32 v164, v82
	v_sub_f32_e32 v82, v167, v176
	v_exp_f32_e32 v166, v82
	v_sub_f32_e32 v82, v168, v176
	v_exp_f32_e32 v168, v82
	v_sub_f32_e32 v82, v169, v176
	v_exp_f32_e32 v170, v82
	v_sub_f32_e32 v82, v178, v176
	v_exp_f32_e32 v172, v82
	v_sub_f32_e32 v82, v179, v176
	v_exp_f32_e32 v174, v82
	v_sub_f32_e32 v82, v180, v176
	v_exp_f32_e32 v178, v82
	v_sub_f32_e32 v82, v181, v176
	v_exp_f32_e32 v180, v82
	v_pk_mul_f32 v[84:85], v[68:69], v[146:147] op_sel_hi:[1,0]
	v_pk_mul_f32 v[82:83], v[66:67], v[146:147] op_sel_hi:[1,0]
	v_pk_mul_f32 v[88:89], v[72:73], v[146:147] op_sel_hi:[1,0]
	v_pk_mul_f32 v[86:87], v[70:71], v[146:147] op_sel_hi:[1,0]
	v_pk_mul_f32 v[76:77], v[76:77], v[146:147] op_sel_hi:[1,0]
	v_pk_mul_f32 v[74:75], v[74:75], v[146:147] op_sel_hi:[1,0]
	v_pk_mul_f32 v[68:69], v[80:81], v[146:147] op_sel_hi:[1,0]
	v_pk_mul_f32 v[66:67], v[78:79], v[146:147] op_sel_hi:[1,0]
	v_max_f32_e32 v147, v90, v90
	v_max_f32_e32 v145, v147, v145
	v_max_f32_e32 v147, v93, v93
	v_max_f32_e32 v151, v92, v92
	v_max_f32_e32 v147, v151, v147
	v_max_f32_e32 v151, v97, v97
	v_max_f32_e32 v153, v96, v96
	v_max_f32_e32 v151, v153, v151
	v_max3_f32 v151, v94, v95, v151
	v_max3_f32 v145, v145, v147, v151
	v_max_f32_e32 v147, v101, v101
	v_max_f32_e32 v151, v100, v100
	v_max_f32_e32 v147, v151, v147
	v_max_f32_e32 v151, v105, v105
	v_max_f32_e32 v153, v104, v104
	v_max_f32_e32 v151, v153, v151
	v_max3_f32 v147, v98, v99, v147
	v_max3_f32 v151, v102, v103, v151
	v_max3_f32 v145, v145, v147, v151
	v_cvt_pk_bf16_f32 v70, v142, v144
	v_cvt_pk_bf16_f32 v71, v150, v152
	v_cvt_pk_bf16_f32 v72, v156, v158
	v_cvt_pk_bf16_f32 v73, v160, v162
	s_waitcnt lgkmcnt(0)
	v_max_f32_e32 v147, v147, v147
	v_mov_b32_e32 v147, v145
	s_nop 1
	v_permlane16_swap_b32_e32 v145, v147
	v_max_f32_e32 v145, v145, v147
	v_mov_b32_e32 v147, v145
	s_nop 1
	v_permlane32_swap_b32_e32 v145, v147
	v_max3_f32 v177, v143, v145, v147
	v_sub_f32_e32 v143, v143, v177
	v_sub_f32_e32 v90, v90, v177
	v_exp_f32_e32 v147, v143
	v_exp_f32_e32 v143, v90
	v_sub_f32_e32 v90, v91, v177
	v_exp_f32_e32 v145, v90
	v_sub_f32_e32 v90, v92, v177
	v_exp_f32_e32 v151, v90
	v_sub_f32_e32 v90, v93, v177
	v_exp_f32_e32 v153, v90
	v_sub_f32_e32 v90, v94, v177
	v_exp_f32_e32 v157, v90
	v_sub_f32_e32 v90, v95, v177
	v_exp_f32_e32 v159, v90
	v_pk_add_f32 v[90:91], v[142:143], 0 op_sel_hi:[1,0]
	v_sub_f32_e32 v92, v96, v177
	v_pk_add_f32 v[90:91], v[144:145], v[90:91]
	v_exp_f32_e32 v161, v92
	v_pk_add_f32 v[90:91], v[150:151], v[90:91]
	v_sub_f32_e32 v92, v97, v177
	v_pk_add_f32 v[90:91], v[152:153], v[90:91]
	v_exp_f32_e32 v163, v92
	v_sub_f32_e32 v92, v98, v177
	v_pk_add_f32 v[90:91], v[156:157], v[90:91]
	v_exp_f32_e32 v165, v92
	v_sub_f32_e32 v92, v99, v177
	v_pk_add_f32 v[90:91], v[158:159], v[90:91]
	v_exp_f32_e32 v167, v92
	v_sub_f32_e32 v92, v100, v177
	v_exp_f32_e32 v169, v92
	v_sub_f32_e32 v92, v101, v177
	v_pk_add_f32 v[90:91], v[160:161], v[90:91]
	v_exp_f32_e32 v171, v92
	v_sub_f32_e32 v92, v102, v177
	v_pk_add_f32 v[90:91], v[162:163], v[90:91]
	v_exp_f32_e32 v173, v92
	v_sub_f32_e32 v92, v103, v177
	v_pk_add_f32 v[90:91], v[164:165], v[90:91]
	v_exp_f32_e32 v175, v92
	v_sub_f32_e32 v92, v104, v177
	v_pk_add_f32 v[90:91], v[166:167], v[90:91]
	v_exp_f32_e32 v179, v92
	v_sub_f32_e32 v92, v105, v177
	v_pk_add_f32 v[90:91], v[168:169], v[90:91]
	v_exp_f32_e32 v181, v92
	v_pk_add_f32 v[90:91], v[170:171], v[90:91]
	v_mov_b32_e32 v98, v147
	v_pk_add_f32 v[90:91], v[172:173], v[90:91]
	v_add3_u32 v142, s18, v127, v189
	v_pk_add_f32 v[90:91], v[174:175], v[90:91]
	v_pk_mul_f32 v[92:93], v[52:53], v[98:99] op_sel_hi:[1,0]
	v_pk_add_f32 v[90:91], v[178:179], v[90:91]
	v_pk_mul_f32 v[96:97], v[56:57], v[98:99] op_sel_hi:[1,0]
	v_pk_add_f32 v[90:91], v[180:181], v[90:91]
	v_pk_mul_f32 v[94:95], v[54:55], v[98:99] op_sel_hi:[1,0]
	v_pk_fma_f32 v[140:141], v[140:141], v[146:147], v[90:91]
	v_pk_mul_f32 v[90:91], v[50:51], v[98:99] op_sel_hi:[1,0]
	v_pk_mul_f32 v[60:61], v[60:61], v[98:99] op_sel_hi:[1,0]
	v_pk_mul_f32 v[58:59], v[58:59], v[98:99] op_sel_hi:[1,0]
	v_pk_mul_f32 v[52:53], v[64:65], v[98:99] op_sel_hi:[1,0]
	v_pk_mul_f32 v[50:51], v[62:63], v[98:99] op_sel_hi:[1,0]
	ds_read_b64_tr_b16 v[100:101], v142 offset:15872
	ds_read_b64_tr_b16 v[98:99], v142 offset:13312
	ds_read_b64_tr_b16 v[102:103], v142 offset:13320
	v_cvt_pk_bf16_f32 v54, v143, v145
	v_cvt_pk_bf16_f32 v55, v151, v153
	v_cvt_pk_bf16_f32 v56, v157, v159
	v_cvt_pk_bf16_f32 v57, v161, v163
	s_waitcnt lgkmcnt(1)
	v_mfma_f32_16x16x32_bf16 v[82:85], v[98:101], v[70:73], v[82:85]
	ds_read_b64_tr_b16 v[104:105], v142 offset:15880
	v_cvt_pk_bf16_f32 v78, v164, v166
	v_cvt_pk_bf16_f32 v79, v168, v170
	v_mfma_f32_16x16x32_bf16 v[90:93], v[98:101], v[54:57], v[90:93]
	ds_read_b64_tr_b16 v[98:99], v142 offset:13376
	ds_read_b64_tr_b16 v[100:101], v142 offset:15936
	v_cvt_pk_bf16_f32 v80, v172, v174
	v_cvt_pk_bf16_f32 v81, v178, v180
	s_waitcnt lgkmcnt(0)
	v_mfma_f32_16x16x32_bf16 v[74:77], v[98:101], v[70:73], v[74:77]
	v_cvt_pk_bf16_f32 v62, v165, v167
	v_cvt_pk_bf16_f32 v63, v169, v171
	v_cvt_pk_bf16_f32 v64, v173, v175
	v_mfma_f32_16x16x32_bf16 v[58:61], v[98:101], v[54:57], v[58:61]
	ds_read_b64_tr_b16 v[98:99], v142 offset:13384
	ds_read_b64_tr_b16 v[100:101], v142 offset:15944
	v_cvt_pk_bf16_f32 v65, v179, v181
	v_mov_b32_e32 v143, v177
	v_mfma_f32_16x16x32_bf16 v[86:89], v[102:105], v[70:73], v[86:89]
	v_mfma_f32_16x16x32_bf16 v[94:97], v[102:105], v[54:57], v[94:97]
	s_waitcnt lgkmcnt(0)
	v_mfma_f32_16x16x32_bf16 v[102:105], v[98:101], v[70:73], v[66:69]
	v_mfma_f32_16x16x32_bf16 v[98:101], v[98:101], v[54:57], v[50:53]
	s_nop 2
	ds_read_b64_tr_b16 v[50:51], v142 offset:18432
	ds_read_b64_tr_b16 v[52:53], v142 offset:20992
	ds_read_b64_tr_b16 v[54:55], v142 offset:18440
	ds_read_b64_tr_b16 v[56:57], v142 offset:21000
	s_waitcnt lgkmcnt(2)
	v_mfma_f32_16x16x32_bf16 v[66:69], v[50:53], v[78:81], v[82:85]
	s_nop 2
	ds_read_b64_tr_b16 v[82:83], v142 offset:18496
	ds_read_b64_tr_b16 v[84:85], v142 offset:21056
	s_waitcnt lgkmcnt(0)
	v_mfma_f32_16x16x32_bf16 v[74:77], v[82:85], v[78:81], v[74:77]
	v_mfma_f32_16x16x32_bf16 v[58:61], v[82:85], v[62:65], v[58:61]
	ds_read_b64_tr_b16 v[82:83], v142 offset:18504
	ds_read_b64_tr_b16 v[84:85], v142 offset:21064
	v_mfma_f32_16x16x32_bf16 v[50:53], v[50:53], v[62:65], v[90:93]
	v_mfma_f32_16x16x32_bf16 v[70:73], v[54:57], v[78:81], v[86:89]
	v_mfma_f32_16x16x32_bf16 v[54:57], v[54:57], v[62:65], v[94:97]
	s_waitcnt lgkmcnt(0)
	v_mfma_f32_16x16x32_bf16 v[78:81], v[82:85], v[78:81], v[102:105]
	v_mfma_f32_16x16x32_bf16 v[62:65], v[82:85], v[62:65], v[98:101]
	v_mov_b32_e32 v82, v176
	s_add_i32 s6, s46, -2
	s_cmp_ge_i32 s6, s52
	s_cbranch_scc1 .LBB0_1064
.LBB0_1078:
	s_and_b32 s6, s6, 3
	s_mulk_i32 s6, 0x5c00
	s_add_i32 s18, s6, 0
	v_add3_u32 v83, s18, v186, v188
	ds_read_b128 v[84:87], v83
	ds_read_b128 v[92:95], v83 offset:64
	v_add3_u32 v127, s18, v127, v189
	s_waitcnt lgkmcnt(1)
	v_mfma_f32_16x16x32_bf16 v[88:91], v[84:87], v[8:11], 0
	ds_read_b128 v[98:101], v83 offset:3392
	ds_read_b128 v[102:105], v83 offset:6720
	ds_read_b128 v[144:147], v83 offset:10048
	v_mfma_f32_16x16x32_bf16 v[84:87], v[84:87], v[12:15], 0
	s_waitcnt lgkmcnt(3)
	v_mfma_f32_16x16x32_bf16 v[88:91], v[92:95], v[0:3], v[88:91]
	v_mfma_f32_16x16x32_bf16 v[84:87], v[92:95], v[16:19], v[84:87]
	ds_read_b128 v[92:95], v83 offset:128
	s_waitcnt lgkmcnt(0)
	v_mfma_f32_16x16x32_bf16 v[150:153], v[92:95], v[4:7], v[88:91]
	v_mfma_f32_16x16x32_bf16 v[90:93], v[92:95], v[20:23], v[84:87]
	s_nop 3
	ds_read_b128 v[84:87], v83 offset:3328
	s_waitcnt lgkmcnt(0)
	v_mfma_f32_16x16x32_bf16 v[94:97], v[84:87], v[8:11], 0
	v_mfma_f32_16x16x32_bf16 v[84:87], v[84:87], v[12:15], 0
	v_mfma_f32_16x16x32_bf16 v[94:97], v[98:101], v[0:3], v[94:97]
	v_mfma_f32_16x16x32_bf16 v[84:87], v[98:101], v[16:19], v[84:87]
	ds_read_b128 v[98:101], v83 offset:3456
	s_waitcnt lgkmcnt(0)
	v_mfma_f32_16x16x32_bf16 v[158:161], v[98:101], v[4:7], v[94:97]
	v_mfma_f32_16x16x32_bf16 v[94:97], v[98:101], v[20:23], v[84:87]
	s_nop 3
	ds_read_b128 v[84:87], v83 offset:6656
	s_waitcnt lgkmcnt(0)
	v_mfma_f32_16x16x32_bf16 v[98:101], v[84:87], v[8:11], 0
	v_mfma_f32_16x16x32_bf16 v[84:87], v[84:87], v[12:15], 0
	v_mfma_f32_16x16x32_bf16 v[98:101], v[102:105], v[0:3], v[98:101]
	v_mfma_f32_16x16x32_bf16 v[84:87], v[102:105], v[16:19], v[84:87]
	ds_read_b128 v[102:105], v83 offset:6784
	s_waitcnt lgkmcnt(0)
	v_mfma_f32_16x16x32_bf16 v[166:169], v[102:105], v[4:7], v[98:101]
	v_mfma_f32_16x16x32_bf16 v[98:101], v[102:105], v[20:23], v[84:87]
	s_nop 3
	ds_read_b128 v[84:87], v83 offset:9984
	s_waitcnt lgkmcnt(0)
	v_mfma_f32_16x16x32_bf16 v[102:105], v[84:87], v[8:11], 0
	v_mfma_f32_16x16x32_bf16 v[84:87], v[84:87], v[12:15], 0
	v_mfma_f32_16x16x32_bf16 v[102:105], v[144:147], v[0:3], v[102:105]
	v_mfma_f32_16x16x32_bf16 v[84:87], v[144:147], v[16:19], v[84:87]
	ds_read_b128 v[144:147], v83 offset:10112
	v_max_f32_e32 v83, v151, v151
	s_waitcnt lgkmcnt(0)
	v_mfma_f32_16x16x32_bf16 v[176:179], v[144:147], v[4:7], v[102:105]
	v_mfma_f32_16x16x32_bf16 v[102:105], v[144:147], v[20:23], v[84:87]
	v_max_f32_e32 v145, v91, v91
	s_nop 1
	v_max_f32_e32 v84, v150, v150
	v_max_f32_e32 v83, v84, v83
	v_max_f32_e32 v84, v153, v153
	v_max_f32_e32 v85, v152, v152
	v_max_f32_e32 v84, v85, v84
	v_max_f32_e32 v85, v161, v161
	v_max_f32_e32 v86, v160, v160
	v_max_f32_e32 v85, v86, v85
	v_max3_f32 v85, v158, v159, v85
	v_max3_f32 v83, v83, v84, v85
	v_max_f32_e32 v84, v169, v169
	v_max_f32_e32 v85, v168, v168
	v_max_f32_e32 v84, v85, v84
	v_max_f32_e32 v85, v179, v179
	v_max_f32_e32 v86, v178, v178
	v_max_f32_e32 v85, v86, v85
	v_max3_f32 v84, v166, v167, v84
	v_max3_f32 v85, v176, v177, v85
	v_max3_f32 v83, v83, v84, v85
	s_waitcnt lgkmcnt(0)
	v_max_f32_e32 v84, v84, v84
	v_mov_b32_e32 v84, v83
	s_nop 1
	v_permlane16_swap_b32_e32 v83, v84
	v_max_f32_e32 v83, v83, v84
	v_mov_b32_e32 v84, v83
	s_nop 1
	v_permlane32_swap_b32_e32 v83, v84
	v_max3_f32 v174, v82, v83, v84
	v_sub_f32_e32 v82, v82, v174
	v_exp_f32_e32 v146, v82
	v_sub_f32_e32 v82, v150, v174
	v_exp_f32_e32 v142, v82
	v_sub_f32_e32 v82, v151, v174
	v_exp_f32_e32 v144, v82
	v_sub_f32_e32 v82, v152, v174
	v_exp_f32_e32 v150, v82
	v_sub_f32_e32 v82, v153, v174
	v_exp_f32_e32 v152, v82
	v_sub_f32_e32 v82, v158, v174
	v_exp_f32_e32 v156, v82
	v_sub_f32_e32 v82, v159, v174
	v_exp_f32_e32 v158, v82
	v_sub_f32_e32 v82, v160, v174
	v_exp_f32_e32 v160, v82
	v_sub_f32_e32 v82, v161, v174
	v_exp_f32_e32 v162, v82
	v_sub_f32_e32 v82, v166, v174
	v_exp_f32_e32 v164, v82
	v_sub_f32_e32 v82, v167, v174
	v_exp_f32_e32 v166, v82
	v_sub_f32_e32 v82, v168, v174
	v_exp_f32_e32 v168, v82
	v_sub_f32_e32 v82, v169, v174
	v_exp_f32_e32 v170, v82
	v_sub_f32_e32 v82, v176, v174
	v_exp_f32_e32 v172, v82
	v_sub_f32_e32 v82, v177, v174
	v_exp_f32_e32 v176, v82
	v_sub_f32_e32 v82, v178, v174
	v_exp_f32_e32 v178, v82
	v_sub_f32_e32 v82, v179, v174
	v_exp_f32_e32 v180, v82
	v_pk_mul_f32 v[84:85], v[68:69], v[146:147] op_sel_hi:[1,0]
	v_pk_mul_f32 v[82:83], v[66:67], v[146:147] op_sel_hi:[1,0]
	v_pk_mul_f32 v[88:89], v[72:73], v[146:147] op_sel_hi:[1,0]
	v_pk_mul_f32 v[86:87], v[70:71], v[146:147] op_sel_hi:[1,0]
	v_pk_mul_f32 v[76:77], v[76:77], v[146:147] op_sel_hi:[1,0]
	v_pk_mul_f32 v[74:75], v[74:75], v[146:147] op_sel_hi:[1,0]
	v_pk_mul_f32 v[68:69], v[80:81], v[146:147] op_sel_hi:[1,0]
	v_pk_mul_f32 v[66:67], v[78:79], v[146:147] op_sel_hi:[1,0]
	v_max_f32_e32 v147, v90, v90
	v_max_f32_e32 v145, v147, v145
	v_max_f32_e32 v147, v93, v93
	v_max_f32_e32 v151, v92, v92
	v_max_f32_e32 v147, v151, v147
	v_max_f32_e32 v151, v97, v97
	v_max_f32_e32 v153, v96, v96
	v_max_f32_e32 v151, v153, v151
	v_max3_f32 v151, v94, v95, v151
	v_max3_f32 v145, v145, v147, v151
	v_max_f32_e32 v147, v101, v101
	v_max_f32_e32 v151, v100, v100
	v_max_f32_e32 v147, v151, v147
	v_max_f32_e32 v151, v105, v105
	v_max_f32_e32 v153, v104, v104
	v_max_f32_e32 v151, v153, v151
	v_max3_f32 v147, v98, v99, v147
	v_max3_f32 v151, v102, v103, v151
	v_max3_f32 v145, v145, v147, v151
	v_cvt_pk_bf16_f32 v70, v142, v144
	v_cvt_pk_bf16_f32 v71, v150, v152
	v_cvt_pk_bf16_f32 v72, v156, v158
	v_cvt_pk_bf16_f32 v73, v160, v162
	s_waitcnt lgkmcnt(0)
	v_max_f32_e32 v147, v147, v147
	v_mov_b32_e32 v147, v145
	s_nop 1
	v_permlane16_swap_b32_e32 v145, v147
	v_max_f32_e32 v145, v145, v147
	v_mov_b32_e32 v147, v145
	s_nop 1
	v_permlane32_swap_b32_e32 v145, v147
	v_max3_f32 v175, v143, v145, v147
	v_sub_f32_e32 v143, v143, v175
	v_sub_f32_e32 v90, v90, v175
	v_exp_f32_e32 v147, v143
	v_exp_f32_e32 v143, v90
	v_sub_f32_e32 v90, v91, v175
	v_exp_f32_e32 v145, v90
	v_sub_f32_e32 v90, v92, v175
	v_exp_f32_e32 v151, v90
	v_sub_f32_e32 v90, v93, v175
	v_exp_f32_e32 v153, v90
	v_sub_f32_e32 v90, v94, v175
	v_exp_f32_e32 v157, v90
	v_sub_f32_e32 v90, v95, v175
	v_exp_f32_e32 v159, v90
	v_pk_add_f32 v[90:91], v[142:143], 0 op_sel_hi:[1,0]
	v_sub_f32_e32 v92, v96, v175
	v_pk_add_f32 v[90:91], v[144:145], v[90:91]
	v_exp_f32_e32 v161, v92
	v_pk_add_f32 v[90:91], v[150:151], v[90:91]
	v_sub_f32_e32 v92, v97, v175
	v_pk_add_f32 v[90:91], v[152:153], v[90:91]
	v_exp_f32_e32 v163, v92
	v_sub_f32_e32 v92, v98, v175
	v_pk_add_f32 v[90:91], v[156:157], v[90:91]
	v_exp_f32_e32 v165, v92
	v_sub_f32_e32 v92, v99, v175
	v_pk_add_f32 v[90:91], v[158:159], v[90:91]
	v_exp_f32_e32 v167, v92
	v_sub_f32_e32 v92, v100, v175
	v_exp_f32_e32 v169, v92
	v_sub_f32_e32 v92, v101, v175
	v_pk_add_f32 v[90:91], v[160:161], v[90:91]
	v_exp_f32_e32 v171, v92
	v_sub_f32_e32 v92, v102, v175
	v_pk_add_f32 v[90:91], v[162:163], v[90:91]
	v_exp_f32_e32 v173, v92
	v_sub_f32_e32 v92, v103, v175
	v_pk_add_f32 v[90:91], v[164:165], v[90:91]
	v_exp_f32_e32 v177, v92
	v_sub_f32_e32 v92, v104, v175
	v_pk_add_f32 v[90:91], v[166:167], v[90:91]
	v_exp_f32_e32 v179, v92
	v_sub_f32_e32 v92, v105, v175
	v_pk_add_f32 v[90:91], v[168:169], v[90:91]
	v_exp_f32_e32 v181, v92
	v_pk_add_f32 v[90:91], v[170:171], v[90:91]
	v_mov_b32_e32 v98, v147
	v_pk_add_f32 v[90:91], v[172:173], v[90:91]
	v_pk_mul_f32 v[92:93], v[52:53], v[98:99] op_sel_hi:[1,0]
	v_pk_add_f32 v[90:91], v[176:177], v[90:91]
	v_pk_mul_f32 v[96:97], v[56:57], v[98:99] op_sel_hi:[1,0]
	v_pk_add_f32 v[90:91], v[178:179], v[90:91]
	v_pk_mul_f32 v[94:95], v[54:55], v[98:99] op_sel_hi:[1,0]
	v_pk_add_f32 v[90:91], v[180:181], v[90:91]
	v_pk_mul_f32 v[60:61], v[60:61], v[98:99] op_sel_hi:[1,0]
	v_pk_fma_f32 v[140:141], v[140:141], v[146:147], v[90:91]
	v_pk_mul_f32 v[90:91], v[50:51], v[98:99] op_sel_hi:[1,0]
	v_pk_mul_f32 v[58:59], v[58:59], v[98:99] op_sel_hi:[1,0]
	v_pk_mul_f32 v[52:53], v[64:65], v[98:99] op_sel_hi:[1,0]
	v_pk_mul_f32 v[50:51], v[62:63], v[98:99] op_sel_hi:[1,0]
	ds_read_b64_tr_b16 v[100:101], v127 offset:15872
	ds_read_b64_tr_b16 v[98:99], v127 offset:13312
	ds_read_b64_tr_b16 v[102:103], v127 offset:13320
	v_cvt_pk_bf16_f32 v54, v143, v145
	v_cvt_pk_bf16_f32 v55, v151, v153
	v_cvt_pk_bf16_f32 v56, v157, v159
	v_cvt_pk_bf16_f32 v57, v161, v163
	s_waitcnt lgkmcnt(1)
	v_mfma_f32_16x16x32_bf16 v[82:85], v[98:101], v[70:73], v[82:85]
	ds_read_b64_tr_b16 v[104:105], v127 offset:15880
	v_cvt_pk_bf16_f32 v78, v164, v166
	v_cvt_pk_bf16_f32 v79, v168, v170
	v_mfma_f32_16x16x32_bf16 v[90:93], v[98:101], v[54:57], v[90:93]
	ds_read_b64_tr_b16 v[98:99], v127 offset:13376
	ds_read_b64_tr_b16 v[100:101], v127 offset:15936
	v_cvt_pk_bf16_f32 v80, v172, v176
	v_cvt_pk_bf16_f32 v81, v178, v180
	s_waitcnt lgkmcnt(0)
	v_mfma_f32_16x16x32_bf16 v[74:77], v[98:101], v[70:73], v[74:77]
	v_cvt_pk_bf16_f32 v62, v165, v167
	v_cvt_pk_bf16_f32 v63, v169, v171
	v_cvt_pk_bf16_f32 v64, v173, v177
	v_mfma_f32_16x16x32_bf16 v[58:61], v[98:101], v[54:57], v[58:61]
	ds_read_b64_tr_b16 v[98:99], v127 offset:13384
	ds_read_b64_tr_b16 v[100:101], v127 offset:15944
	v_cvt_pk_bf16_f32 v65, v179, v181
	v_mov_b32_e32 v143, v175
	v_mfma_f32_16x16x32_bf16 v[86:89], v[102:105], v[70:73], v[86:89]
	v_mfma_f32_16x16x32_bf16 v[94:97], v[102:105], v[54:57], v[94:97]
	s_waitcnt lgkmcnt(0)
	v_mfma_f32_16x16x32_bf16 v[102:105], v[98:101], v[70:73], v[66:69]
	v_mfma_f32_16x16x32_bf16 v[98:101], v[98:101], v[54:57], v[50:53]
	s_nop 2
	ds_read_b64_tr_b16 v[50:51], v127 offset:18432
	ds_read_b64_tr_b16 v[52:53], v127 offset:20992
	ds_read_b64_tr_b16 v[54:55], v127 offset:18440
	ds_read_b64_tr_b16 v[56:57], v127 offset:21000
	s_waitcnt lgkmcnt(2)
	v_mfma_f32_16x16x32_bf16 v[66:69], v[50:53], v[78:81], v[82:85]
	s_nop 2
	ds_read_b64_tr_b16 v[82:83], v127 offset:18496
	ds_read_b64_tr_b16 v[84:85], v127 offset:21056
	s_waitcnt lgkmcnt(0)
	v_mfma_f32_16x16x32_bf16 v[74:77], v[82:85], v[78:81], v[74:77]
	v_mfma_f32_16x16x32_bf16 v[58:61], v[82:85], v[62:65], v[58:61]
	ds_read_b64_tr_b16 v[82:83], v127 offset:18504
	ds_read_b64_tr_b16 v[84:85], v127 offset:21064
	v_mfma_f32_16x16x32_bf16 v[50:53], v[50:53], v[62:65], v[90:93]
	v_mfma_f32_16x16x32_bf16 v[70:73], v[54:57], v[78:81], v[86:89]
	v_mfma_f32_16x16x32_bf16 v[54:57], v[54:57], v[62:65], v[94:97]
	s_waitcnt lgkmcnt(0)
	v_mfma_f32_16x16x32_bf16 v[78:81], v[82:85], v[78:81], v[102:105]
	v_mfma_f32_16x16x32_bf16 v[62:65], v[82:85], v[62:65], v[98:101]
	v_mov_b32_e32 v82, v174
	s_branch .LBB0_1064

.LBB0_1304:
	v_lshl_add_u32 v122, s54, 8, v182
	s_lshl_b32 s6, s52, 8
	v_lshl_add_u32 v48, v122, 10, s6
	v_or_b32_e32 v48, v48, v184
	v_lshl_add_u64 v[194:195], v[48:49], 1, s[16:17]
	global_load_dwordx4 v[186:189], v[194:195], off
	s_lshl_b32 s6, s52, 16
	s_or_b32 s6, s6, s67
	v_add_u32_e32 v168, s6, v122
	v_or_b32_e32 v122, 0x80, v48
	v_mov_b32_e32 v123, v49
	v_lshl_add_u64 v[196:197], v[122:123], 1, s[16:17]
	global_load_dwordx4 v[190:193], v[196:197], off
	v_add_u32_e32 v122, 0x4000, v48
	v_lshl_add_u64 v[180:181], v[122:123], 1, s[16:17]
	v_add_u32_e32 v122, 0x4080, v48
	v_lshl_add_u64 v[178:179], v[122:123], 1, s[16:17]
	v_add_u32_e32 v122, 0x8000, v48
	v_lshl_add_u64 v[176:177], v[122:123], 1, s[16:17]
	v_add_u32_e32 v122, 0x8080, v48
	v_lshl_add_u64 v[174:175], v[122:123], 1, s[16:17]
	v_add_u32_e32 v122, 0xc000, v48
	v_add_u32_e32 v130, 0xc080, v48
	v_mov_b32_e32 v131, v49
	v_lshl_add_u64 v[172:173], v[122:123], 1, s[16:17]
	v_lshl_add_u64 v[170:171], v[130:131], 1, s[16:17]
	global_load_dwordx4 v[150:153], v[180:181], off
	global_load_dwordx4 v[146:149], v[178:179], off
	global_load_dwordx4 v[142:145], v[176:177], off
	global_load_dwordx4 v[138:141], v[174:175], off
	global_load_dwordx4 v[122:125], v[172:173], off
	global_load_dwordx4 v[130:133], v[170:171], off
	s_waitcnt vmcnt(0)
	v_lshlrev_b32_e32 v198, 16, v186
	v_and_b32_e32 v199, 0xffff0000, v186
	v_lshlrev_b32_e32 v186, 16, v187
	v_and_b32_e32 v187, 0xffff0000, v187
	v_pk_add_f32 v[136:137], v[136:137], v[186:187]
	v_pk_add_f32 v[134:135], v[134:135], v[198:199]
	v_lshlrev_b32_e32 v186, 16, v188
	v_and_b32_e32 v187, 0xffff0000, v188
	v_lshlrev_b32_e32 v188, 16, v189
	v_and_b32_e32 v189, 0xffff0000, v189
	v_pk_add_f32 v[188:189], v[128:129], v[188:189]
	v_pk_add_f32 v[186:187], v[126:127], v[186:187]
	v_cvt_pk_bf16_f32 v126, v134, v135
	v_cvt_pk_bf16_f32 v127, v136, v137
	v_cvt_pk_bf16_f32 v128, v186, v187
	v_cvt_pk_bf16_f32 v129, v188, v189
	global_store_dwordx4 v[194:195], v[126:129], off
	s_nop 1
	v_mul_f32_e32 v126, v135, v135
	v_mul_f32_e32 v127, v137, v137
	v_fmac_f32_e32 v126, v134, v134
	v_fmac_f32_e32 v127, v136, v136
	v_add_f32_e32 v126, v126, v127
	v_mul_f32_e32 v127, v187, v187
	v_mul_f32_e32 v128, v189, v189
	v_fmac_f32_e32 v127, v186, v186
	v_fmac_f32_e32 v128, v188, v188
	v_add_f32_e32 v127, v127, v128
	v_add_f32_e32 v134, v126, v127
	v_lshlrev_b32_e32 v126, 16, v190
	v_and_b32_e32 v127, 0xffff0000, v190
	v_lshlrev_b32_e32 v128, 16, v191
	v_and_b32_e32 v129, 0xffff0000, v191
	v_pk_add_f32 v[120:121], v[120:121], v[128:129]
	v_pk_add_f32 v[118:119], v[118:119], v[126:127]
	v_lshlrev_b32_e32 v126, 16, v192
	v_and_b32_e32 v127, 0xffff0000, v192
	v_lshlrev_b32_e32 v128, 16, v193
	v_and_b32_e32 v129, 0xffff0000, v193
	v_pk_add_f32 v[128:129], v[116:117], v[128:129]
	v_pk_add_f32 v[126:127], v[114:115], v[126:127]
	v_cvt_pk_bf16_f32 v114, v118, v119
	v_cvt_pk_bf16_f32 v115, v120, v121
	v_cvt_pk_bf16_f32 v116, v126, v127
	v_cvt_pk_bf16_f32 v117, v128, v129
	global_store_dwordx4 v[196:197], v[114:117], off
	s_nop 1
	v_mul_f32_e32 v114, v119, v119
	v_mul_f32_e32 v115, v121, v121
	v_fmac_f32_e32 v114, v118, v118
	v_fmac_f32_e32 v115, v120, v120
	v_add_f32_e32 v114, v114, v115
	v_mul_f32_e32 v115, v127, v127
	v_mul_f32_e32 v116, v129, v129
	v_fmac_f32_e32 v115, v126, v126
	v_fmac_f32_e32 v116, v128, v128
	v_add_f32_e32 v115, v115, v116
	v_add_f32_e32 v114, v114, v115
	v_and_b32_e32 v116, 64, v205
	v_add_f32_e32 v115, v134, v114
	v_xor_b32_e32 v114, 16, v205
	v_add_u32_e32 v116, 64, v116
	v_cmp_lt_i32_e32 vcc, v114, v116
	s_nop 1
	v_cndmask_b32_e32 v114, v205, v114, vcc
	v_lshlrev_b32_e32 v114, 2, v114
	s_waitcnt lgkmcnt(0)
	v_mov_b32_e32 v116, v115
	s_nop 1
	v_permlane16_swap_b32_e32 v115, v116
	v_add_f32_e32 v115, v115, v116
	v_mov_b32_e32 v116, v115
	s_nop 1
	v_permlane32_swap_b32_e32 v115, v116
	s_and_saveexec_b64 s[52:53], s[38:39]
	s_cbranch_execz .LBB0_1306
	v_mov_b32_e32 v169, v49
	v_lshl_add_u64 v[118:119], v[168:169], 2, s[22:23]
	v_add_f32_e32 v115, v115, v116
	global_store_dword v[118:119], v115, off

.LBB0_1414:
	v_lshl_add_u32 v177, s38, 8, v172
	v_add_u32_e32 v48, v177, v174
	v_add_u32_e32 v140, 0x40a0, v48
	v_mov_b32_e32 v141, v49
	v_lshl_add_u64 v[138:139], v[48:49], 2, s[22:23]
	v_lshl_add_u64 v[140:141], v[140:141], 2, s[22:23]
	global_load_dword v168, v[138:139], off
	global_load_dword v152, v[140:141], off
	v_add_u32_e32 v138, 0x4000, v48
	v_mov_b32_e32 v139, v49
	v_add_u32_e32 v156, 0x40b0, v48
	v_mov_b32_e32 v157, v49
	v_lshl_add_u64 v[138:139], v[138:139], 2, s[22:23]
	v_lshl_add_u64 v[156:157], v[156:157], 2, s[22:23]
	global_load_dword v170, v[138:139], off
	v_add_u32_e32 v140, 0x80a0, v48
	global_load_dword v156, v[156:157], off
	v_add_u32_e32 v138, 0x8000, v48
	v_mov_b32_e32 v139, v49
	v_lshl_add_u64 v[138:139], v[138:139], 2, s[22:23]
	global_load_dword v169, v[138:139], off
	v_add_u32_e32 v138, 0xc000, v48
	v_mov_b32_e32 v139, v49
	v_lshl_add_u64 v[138:139], v[138:139], 2, s[22:23]
	global_load_dword v171, v[138:139], off
	v_or_b32_e32 v138, 16, v48
	v_mov_b32_e32 v139, v49
	v_lshl_add_u64 v[138:139], v[138:139], 2, s[22:23]
	global_load_dword v150, v[138:139], off
	v_add_u32_e32 v138, 0x4010, v48
	v_mov_b32_e32 v139, v49
	v_lshl_add_u64 v[138:139], v[138:139], 2, s[22:23]
	global_load_dword v166, v[138:139], off
	v_add_u32_e32 v138, 0x8010, v48
	v_mov_b32_e32 v139, v49
	v_lshl_add_u64 v[138:139], v[138:139], 2, s[22:23]
	global_load_dword v151, v[138:139], off
	v_add_u32_e32 v138, 0xc010, v48
	v_mov_b32_e32 v139, v49
	v_lshl_add_u64 v[138:139], v[138:139], 2, s[22:23]
	global_load_dword v167, v[138:139], off
	v_or_b32_e32 v138, 32, v48
	v_mov_b32_e32 v139, v49
	v_lshl_add_u64 v[138:139], v[138:139], 2, s[22:23]
	global_load_dword v146, v[138:139], off
	v_add_u32_e32 v138, 0x4020, v48
	v_mov_b32_e32 v139, v49
	v_lshl_add_u64 v[138:139], v[138:139], 2, s[22:23]
	global_load_dword v162, v[138:139], off
	v_add_u32_e32 v138, 0x8020, v48
	v_mov_b32_e32 v139, v49
	v_lshl_add_u64 v[138:139], v[138:139], 2, s[22:23]
	global_load_dword v147, v[138:139], off
	v_add_u32_e32 v138, 0xc020, v48
	v_mov_b32_e32 v139, v49
	v_lshl_add_u64 v[138:139], v[138:139], 2, s[22:23]
	global_load_dword v163, v[138:139], off
	v_or_b32_e32 v138, 48, v48
	v_mov_b32_e32 v139, v49
	v_lshl_add_u64 v[138:139], v[138:139], 2, s[22:23]
	global_load_dword v148, v[138:139], off
	v_add_u32_e32 v138, 0x4030, v48
	v_mov_b32_e32 v139, v49
	v_lshl_add_u64 v[138:139], v[138:139], 2, s[22:23]
	global_load_dword v164, v[138:139], off
	v_add_u32_e32 v138, 0x8030, v48
	v_mov_b32_e32 v139, v49
	v_lshl_add_u64 v[138:139], v[138:139], 2, s[22:23]
	global_load_dword v149, v[138:139], off
	v_add_u32_e32 v138, 0xc030, v48
	v_mov_b32_e32 v139, v49
	v_lshl_add_u64 v[138:139], v[138:139], 2, s[22:23]
	global_load_dword v165, v[138:139], off
	v_add_u32_e32 v138, 0x80, v48
	v_mov_b32_e32 v139, v49
	v_lshl_add_u64 v[138:139], v[138:139], 2, s[22:23]
	global_load_dword v142, v[138:139], off
	v_add_u32_e32 v138, 0x4080, v48
	v_mov_b32_e32 v139, v49
	v_lshl_add_u64 v[138:139], v[138:139], 2, s[22:23]
	global_load_dword v158, v[138:139], off
	v_add_u32_e32 v138, 0x8080, v48
	v_mov_b32_e32 v139, v49
	v_lshl_add_u64 v[138:139], v[138:139], 2, s[22:23]
	global_load_dword v143, v[138:139], off
	v_add_u32_e32 v138, 0xc080, v48
	v_mov_b32_e32 v139, v49
	v_lshl_add_u64 v[138:139], v[138:139], 2, s[22:23]
	global_load_dword v159, v[138:139], off
	v_add_u32_e32 v138, 0x90, v48
	v_mov_b32_e32 v139, v49
	v_lshl_add_u64 v[138:139], v[138:139], 2, s[22:23]
	global_load_dword v144, v[138:139], off
	v_add_u32_e32 v138, 0x4090, v48
	v_mov_b32_e32 v139, v49
	v_lshl_add_u64 v[138:139], v[138:139], 2, s[22:23]
	global_load_dword v160, v[138:139], off
	v_add_u32_e32 v138, 0x8090, v48
	v_mov_b32_e32 v139, v49
	v_lshl_add_u64 v[138:139], v[138:139], 2, s[22:23]
	global_load_dword v145, v[138:139], off
	v_add_u32_e32 v138, 0xc090, v48
	v_mov_b32_e32 v139, v49
	v_lshl_add_u64 v[138:139], v[138:139], 2, s[22:23]
	global_load_dword v161, v[138:139], off
	v_add_u32_e32 v138, 0xa0, v48
	v_mov_b32_e32 v139, v49
	v_mov_b32_e32 v141, v49
	v_lshl_add_u64 v[138:139], v[138:139], 2, s[22:23]
	v_lshl_add_u64 v[140:141], v[140:141], 2, s[22:23]
	global_load_dword v138, v[138:139], off
	v_add_u32_e32 v178, 0x80b0, v48
	global_load_dword v139, v[140:141], off
	v_add_u32_e32 v140, 0xc0a0, v48
	v_mov_b32_e32 v141, v49
	v_lshl_add_u64 v[140:141], v[140:141], 2, s[22:23]
	global_load_dword v153, v[140:141], off
	v_add_u32_e32 v140, 0xb0, v48
	v_mov_b32_e32 v141, v49
	v_mov_b32_e32 v179, v49
	v_lshl_add_u64 v[140:141], v[140:141], 2, s[22:23]
	v_lshl_add_u64 v[178:179], v[178:179], 2, s[22:23]
	v_add_u32_e32 v48, 0xc0b0, v48
	global_load_dword v140, v[140:141], off
	s_waitcnt vmcnt(0)
	v_pk_add_f32 v[168:169], v[168:169], v[170:171]
	global_load_dword v141, v[178:179], off
	v_lshl_add_u64 v[178:179], v[48:49], 2, s[22:23]
	global_load_dword v157, v[178:179], off
	v_and_b32_e32 v178, 64, v205
	v_xor_b32_e32 v48, 16, v205
	v_add_u32_e32 v178, 64, v178
	v_cmp_lt_i32_e32 vcc, v48, v178
	v_pk_add_f32 v[150:151], v[150:151], v[166:167]
	s_mov_b32 s6, 0x358637bd
	v_cndmask_b32_e32 v48, v205, v48, vcc
	v_lshlrev_b32_e32 v178, 2, v48
	v_add_f32_e32 v48, v168, v169
	ds_bpermute_b32 v168, v178, v48
	v_pk_add_f32 v[146:147], v[146:147], v[162:163]
	v_mov_b64_e32 v[166:167], s[6:7]
	v_add_f32_e32 v146, v146, v147
	ds_bpermute_b32 v147, v178, v146
	s_waitcnt lgkmcnt(1)
	v_add_f32_e32 v169, v48, v168
	v_add_f32_e32 v48, v150, v151
	ds_bpermute_b32 v150, v178, v48
	v_mov_b32_e32 v171, v169
	s_waitcnt lgkmcnt(1)
	v_add_f32_e32 v147, v146, v147
	v_permlane32_swap_b32_e32 v169, v171
	s_waitcnt lgkmcnt(0)
	v_add_f32_e32 v168, v48, v150
	v_mov_b32_e32 v170, v168
	s_nop 1
	v_permlane32_swap_b32_e32 v168, v170
	v_pk_add_f32 v[148:149], v[148:149], v[164:165]
	v_pk_add_f32 v[150:151], v[168:169], v[170:171]
	v_add_f32_e32 v146, v148, v149
	v_pk_fma_f32 v[168:169], v[150:151], s[36:37], v[166:167] op_sel_hi:[1,0,0]
	v_mov_b32_e32 v163, v147
	v_mul_f32_e32 v48, 0x4b800000, v169
	v_cmp_gt_f32_e64 s[38:39], s75, v169
	s_waitcnt lgkmcnt(0)
	v_mov_b32_e32 v148, v146
	s_nop 1
	v_permlane16_swap_b32_e32 v146, v148
	v_add_f32_e32 v146, v146, v148
	v_mov_b32_e32 v162, v146
	v_cndmask_b32_e64 v48, v169, v48, s[38:39]
	v_rsq_f32_e32 v48, v48
	v_permlane32_swap_b32_e32 v147, v163
	v_permlane32_swap_b32_e32 v146, v162
	v_pk_add_f32 v[142:143], v[142:143], v[158:159]
	v_pk_add_f32 v[146:147], v[146:147], v[162:163]
	v_add_f32_e32 v142, v142, v143
	ds_bpermute_b32 v143, v178, v142
	v_mul_f32_e32 v150, 0x45800000, v48
	v_pk_fma_f32 v[146:147], v[146:147], s[36:37], v[166:167] op_sel_hi:[1,0,0]
	v_cmp_gt_f32_e32 vcc, s75, v168
	v_cndmask_b32_e64 v150, v48, v150, s[38:39]
	s_waitcnt lgkmcnt(0)
	v_add_f32_e32 v143, v142, v143
	v_mul_f32_e32 v48, 0x4b800000, v168
	v_mul_f32_e32 v148, 0x4b800000, v147
	v_cmp_gt_f32_e64 s[38:39], s75, v147
	v_cndmask_b32_e32 v48, v168, v48, vcc
	v_rsq_f32_e32 v48, v48
	v_cndmask_b32_e64 v147, v147, v148, s[38:39]
	v_pk_add_f32 v[144:145], v[144:145], v[160:161]
	v_rsq_f32_e32 v147, v147
	v_add_f32_e32 v142, v144, v145
	v_mov_b32_e32 v159, v143
	s_nop 1
	v_permlane32_swap_b32_e32 v143, v159
	v_mul_f32_e32 v151, 0x45800000, v48
	s_waitcnt lgkmcnt(0)
	v_mov_b32_e32 v144, v142
	s_nop 1
	v_permlane16_swap_b32_e32 v142, v144
	v_add_f32_e32 v142, v142, v144
	v_mov_b32_e32 v158, v142
	s_nop 1
	v_permlane32_swap_b32_e32 v142, v158
	v_pk_add_f32 v[138:139], v[138:139], v[152:153]
	v_pk_add_f32 v[142:143], v[142:143], v[158:159]
	v_add_f32_e32 v138, v138, v139
	ds_bpermute_b32 v139, v178, v138
	v_mul_f32_e32 v148, 0x45800000, v147
	v_pk_fma_f32 v[142:143], v[142:143], s[36:37], v[166:167] op_sel_hi:[1,0,0]
	v_cndmask_b32_e32 v48, v48, v151, vcc
	v_cmp_gt_f32_e32 vcc, s75, v146
	s_waitcnt lgkmcnt(0)
	v_add_f32_e32 v139, v138, v139
	v_cndmask_b32_e64 v148, v147, v148, s[38:39]
	v_mul_f32_e32 v147, 0x4b800000, v146
	s_waitcnt vmcnt(0)
	v_pk_add_f32 v[140:141], v[140:141], v[156:157]
	v_mul_f32_e32 v144, 0x4b800000, v143
	v_add_f32_e32 v138, v140, v141
	v_cmp_gt_f32_e64 s[38:39], s75, v143
	v_cndmask_b32_e32 v146, v146, v147, vcc
	v_rsq_f32_e32 v146, v146
	v_cndmask_b32_e64 v143, v143, v144, s[38:39]
	v_rsq_f32_e32 v143, v143
	s_waitcnt lgkmcnt(0)
	v_mov_b32_e32 v140, v138
	s_nop 1
	v_permlane16_swap_b32_e32 v138, v140
	v_add_f32_e32 v138, v138, v140
	v_mov_b32_e32 v153, v139
	v_mov_b32_e32 v152, v138
	s_nop 0
	v_permlane32_swap_b32_e32 v139, v153
	v_permlane32_swap_b32_e32 v138, v152
	v_pk_add_f32 v[138:139], v[138:139], v[152:153]
	v_mul_f32_e32 v147, 0x45800000, v146
	v_mul_f32_e32 v144, 0x45800000, v143
	v_pk_fma_f32 v[138:139], v[138:139], s[36:37], v[166:167] op_sel_hi:[1,0,0]
	v_cndmask_b32_e32 v146, v146, v147, vcc
	v_cmp_gt_f32_e32 vcc, s75, v142
	v_cndmask_b32_e64 v144, v143, v144, s[38:39]
	v_mul_f32_e32 v143, 0x4b800000, v142
	v_mul_f32_e32 v140, 0x4b800000, v139
	v_cmp_gt_f32_e64 s[38:39], s75, v139
	v_cndmask_b32_e32 v142, v142, v143, vcc
	v_rsq_f32_e32 v142, v142
	v_cndmask_b32_e64 v139, v139, v140, s[38:39]
	v_rsq_f32_e32 v139, v139
	v_pk_mul_f32 v[126:127], v[126:127], v[150:151] op_sel_hi:[1,0]
	v_mul_f32_e32 v143, 0x45800000, v142
	v_cndmask_b32_e32 v142, v142, v143, vcc
	v_mul_f32_e32 v140, 0x45800000, v139
	v_cmp_gt_f32_e32 vcc, s75, v138
	v_cndmask_b32_e64 v140, v139, v140, s[38:39]
	v_mul_f32_e32 v139, 0x4b800000, v138
	v_cndmask_b32_e32 v138, v138, v139, vcc
	v_rsq_f32_e32 v138, v138
	v_pk_mul_f32 v[122:123], v[122:123], v[150:151] op_sel_hi:[1,0]
	v_pk_mul_f32 v[124:125], v[124:125], v[150:151] op_sel_hi:[1,0]
	v_pk_mul_f32 v[122:123], v[126:127], v[122:123]
	v_mul_f32_e32 v139, 0x45800000, v138
	v_cndmask_b32_e32 v138, v138, v139, vcc
	v_mul_f32_e32 v139, 0xbfb8aa3b, v126
	v_mul_f32_e32 v126, 0xbfb8aa3b, v127
	v_exp_f32_e32 v126, v126
	v_exp_f32_e32 v139, v139
	v_pk_mul_f32 v[118:119], v[118:119], v[150:151] op_sel_hi:[1,0]
	v_pk_mul_f32 v[114:115], v[114:115], v[150:151] op_sel_hi:[1,0]
	v_add_f32_e32 v126, 1.0, v126
	v_rcp_f32_e32 v157, v126
	v_pk_mul_f32 v[126:127], v[128:129], v[150:151] op_sel_hi:[1,0]
	v_add_f32_e32 v139, 1.0, v139
	v_mul_f32_e32 v128, 0xbfb8aa3b, v126
	v_pk_mul_f32 v[124:125], v[126:127], v[124:125]
	v_mul_f32_e32 v126, 0xbfb8aa3b, v127
	v_exp_f32_e32 v128, v128
	v_exp_f32_e32 v126, v126
	v_rcp_f32_e32 v156, v139
	v_pk_mul_f32 v[114:115], v[118:119], v[114:115]
	v_add_f32_e32 v128, 1.0, v128
	v_add_f32_e32 v126, 1.0, v126
	v_rcp_f32_e32 v128, v128
	v_rcp_f32_e32 v129, v126
	v_pk_mul_f32 v[122:123], v[122:123], v[156:157]
	v_pk_mul_f32 v[116:117], v[116:117], v[150:151] op_sel_hi:[1,0]
	v_cvt_pk_bf16_f32 v122, v122, v123
	v_pk_mul_f32 v[124:125], v[124:125], v[128:129]
	v_lshl_or_b32 v152, s18, 7, v175
	v_cvt_pk_bf16_f32 v123, v124, v125
	v_mul_f32_e32 v124, 0xbfb8aa3b, v118
	v_mul_f32_e32 v118, 0xbfb8aa3b, v119
	v_exp_f32_e32 v118, v118
	v_exp_f32_e32 v124, v124
	s_movk_i32 s6, 0xb00
	v_pk_mul_f32 v[110:111], v[110:111], v[48:49] op_sel_hi:[1,0]
	v_add_f32_e32 v118, 1.0, v118
	v_rcp_f32_e32 v125, v118
	v_pk_mul_f32 v[118:119], v[120:121], v[150:151] op_sel_hi:[1,0]
	v_add_f32_e32 v124, 1.0, v124
	v_mul_f32_e32 v120, 0xbfb8aa3b, v118
	v_pk_mul_f32 v[116:117], v[118:119], v[116:117]
	v_mul_f32_e32 v118, 0xbfb8aa3b, v119
	v_exp_f32_e32 v120, v120
	v_exp_f32_e32 v118, v118
	v_rcp_f32_e32 v124, v124
	v_pk_mul_f32 v[106:107], v[106:107], v[48:49] op_sel_hi:[1,0]
	v_add_f32_e32 v120, 1.0, v120
	v_add_f32_e32 v118, 1.0, v118
	v_rcp_f32_e32 v120, v120
	v_rcp_f32_e32 v121, v118
	v_pk_mul_f32 v[114:115], v[114:115], v[124:125]
	v_pk_mul_f32 v[106:107], v[110:111], v[106:107]
	v_cvt_pk_bf16_f32 v124, v114, v115
	v_mad_u64_u32 v[114:115], s[20:21], v177, s6, v[152:153]
	v_pk_mul_f32 v[116:117], v[116:117], v[120:121]
	v_mov_b32_e32 v115, v49
	v_cvt_pk_bf16_f32 v125, v116, v117
	v_lshl_add_u64 v[116:117], v[114:115], 1, s[12:13]
	v_mul_f32_e32 v115, 0xbfb8aa3b, v110
	v_mul_f32_e32 v110, 0xbfb8aa3b, v111
	v_exp_f32_e32 v110, v110
	global_store_dwordx4 v[116:117], v[122:125], off
	s_nop 1
	v_pk_mul_f32 v[108:109], v[108:109], v[48:49] op_sel_hi:[1,0]
	v_exp_f32_e32 v115, v115
	v_add_f32_e32 v110, 1.0, v110
	v_rcp_f32_e32 v117, v110
	v_pk_mul_f32 v[110:111], v[112:113], v[48:49] op_sel_hi:[1,0]
	v_add_f32_e32 v115, 1.0, v115
	v_mul_f32_e32 v112, 0xbfb8aa3b, v110
	v_pk_mul_f32 v[108:109], v[110:111], v[108:109]
	v_mul_f32_e32 v110, 0xbfb8aa3b, v111
	v_exp_f32_e32 v112, v112
	v_exp_f32_e32 v110, v110
	v_rcp_f32_e32 v116, v115
	v_pk_mul_f32 v[102:103], v[102:103], v[48:49] op_sel_hi:[1,0]
	v_add_f32_e32 v112, 1.0, v112
	v_add_f32_e32 v110, 1.0, v110
	v_rcp_f32_e32 v112, v112
	v_rcp_f32_e32 v113, v110
	v_pk_mul_f32 v[106:107], v[106:107], v[116:117]
	v_pk_mul_f32 v[98:99], v[98:99], v[48:49] op_sel_hi:[1,0]
	v_cvt_pk_bf16_f32 v106, v106, v107
	v_pk_mul_f32 v[108:109], v[108:109], v[112:113]
	v_pk_mul_f32 v[98:99], v[102:103], v[98:99]
	v_cvt_pk_bf16_f32 v107, v108, v109
	v_mul_f32_e32 v108, 0xbfb8aa3b, v102
	v_mul_f32_e32 v102, 0xbfb8aa3b, v103
	v_exp_f32_e32 v102, v102
	v_exp_f32_e32 v108, v108
	v_pk_mul_f32 v[100:101], v[100:101], v[48:49] op_sel_hi:[1,0]
	v_pk_mul_f32 v[94:95], v[94:95], v[148:149] op_sel_hi:[1,0]
	v_add_f32_e32 v102, 1.0, v102
	v_rcp_f32_e32 v109, v102
	v_pk_mul_f32 v[102:103], v[104:105], v[48:49] op_sel_hi:[1,0]
	v_add_f32_e32 v108, 1.0, v108
	v_mul_f32_e32 v48, 0xbfb8aa3b, v103
	v_exp_f32_e32 v48, v48
	v_rcp_f32_e32 v108, v108
	v_mul_f32_e32 v104, 0xbfb8aa3b, v102
	v_exp_f32_e32 v104, v104
	v_add_f32_e32 v48, 1.0, v48
	v_pk_mul_f32 v[98:99], v[98:99], v[108:109]
	v_rcp_f32_e32 v105, v48
	v_add_u32_e32 v48, 0xb000, v114
	v_add_f32_e32 v104, 1.0, v104
	v_cvt_pk_bf16_f32 v108, v98, v99
	v_lshl_add_u64 v[98:99], v[48:49], 1, s[12:13]
	v_mul_f32_e32 v48, 0xbfb8aa3b, v94
	v_rcp_f32_e32 v104, v104
	v_exp_f32_e32 v48, v48
	v_pk_mul_f32 v[100:101], v[102:103], v[100:101]
	v_pk_mul_f32 v[90:91], v[90:91], v[148:149] op_sel_hi:[1,0]
	v_pk_mul_f32 v[100:101], v[100:101], v[104:105]
	v_add_f32_e32 v48, 1.0, v48
	v_cvt_pk_bf16_f32 v109, v100, v101
	global_store_dwordx4 v[98:99], v[106:109], off
	s_nop 1
	v_rcp_f32_e32 v98, v48
	v_mul_f32_e32 v48, 0xbfb8aa3b, v95
	v_exp_f32_e32 v48, v48
	v_pk_mul_f32 v[90:91], v[94:95], v[90:91]
	v_pk_mul_f32 v[94:95], v[96:97], v[148:149] op_sel_hi:[1,0]
	v_pk_mul_f32 v[86:87], v[86:87], v[148:149] op_sel_hi:[1,0]
	v_add_f32_e32 v48, 1.0, v48
	v_rcp_f32_e32 v99, v48
	v_mul_f32_e32 v48, 0xbfb8aa3b, v94
	v_exp_f32_e32 v48, v48
	v_pk_mul_f32 v[92:93], v[92:93], v[148:149] op_sel_hi:[1,0]
	v_pk_mul_f32 v[90:91], v[90:91], v[98:99]
	v_pk_mul_f32 v[92:93], v[94:95], v[92:93]
	v_add_f32_e32 v48, 1.0, v48
	v_rcp_f32_e32 v96, v48
	v_mul_f32_e32 v48, 0xbfb8aa3b, v95
	v_exp_f32_e32 v48, v48
	v_cvt_pk_bf16_f32 v90, v90, v91
	v_pk_mul_f32 v[82:83], v[82:83], v[148:149] op_sel_hi:[1,0]
	v_pk_mul_f32 v[78:79], v[78:79], v[146:147] op_sel_hi:[1,0]
	v_add_f32_e32 v48, 1.0, v48
	v_rcp_f32_e32 v97, v48
	v_mul_f32_e32 v48, 0xbfb8aa3b, v86
	v_exp_f32_e32 v48, v48
	v_pk_mul_f32 v[82:83], v[86:87], v[82:83]
	v_pk_mul_f32 v[92:93], v[92:93], v[96:97]
	v_pk_mul_f32 v[84:85], v[84:85], v[148:149] op_sel_hi:[1,0]
	v_add_f32_e32 v48, 1.0, v48
	v_cvt_pk_bf16_f32 v91, v92, v93
	v_rcp_f32_e32 v92, v48
	v_mul_f32_e32 v48, 0xbfb8aa3b, v87
	v_exp_f32_e32 v48, v48
	v_pk_mul_f32 v[86:87], v[88:89], v[148:149] op_sel_hi:[1,0]
	v_pk_mul_f32 v[74:75], v[74:75], v[146:147] op_sel_hi:[1,0]
	v_pk_mul_f32 v[84:85], v[86:87], v[84:85]
	v_add_f32_e32 v48, 1.0, v48
	v_rcp_f32_e32 v93, v48
	v_mul_f32_e32 v48, 0xbfb8aa3b, v86
	v_exp_f32_e32 v48, v48
	v_pk_mul_f32 v[74:75], v[78:79], v[74:75]
	v_pk_mul_f32 v[82:83], v[82:83], v[92:93]
	v_pk_mul_f32 v[70:71], v[70:71], v[146:147] op_sel_hi:[1,0]
	v_add_f32_e32 v48, 1.0, v48
	v_rcp_f32_e32 v88, v48
	v_mul_f32_e32 v48, 0xbfb8aa3b, v87
	v_exp_f32_e32 v48, v48
	v_cvt_pk_bf16_f32 v92, v82, v83
	v_pk_mul_f32 v[76:77], v[76:77], v[146:147] op_sel_hi:[1,0]
	v_pk_mul_f32 v[66:67], v[66:67], v[146:147] op_sel_hi:[1,0]
	v_add_f32_e32 v48, 1.0, v48
	v_rcp_f32_e32 v89, v48
	v_add_u32_e32 v48, 0x16000, v114
	v_lshl_add_u64 v[82:83], v[48:49], 1, s[12:13]
	v_mul_f32_e32 v48, 0xbfb8aa3b, v78
	v_exp_f32_e32 v48, v48
	v_pk_mul_f32 v[84:85], v[84:85], v[88:89]
	v_pk_mul_f32 v[66:67], v[70:71], v[66:67]
	v_cvt_pk_bf16_f32 v93, v84, v85
	v_add_f32_e32 v48, 1.0, v48
	global_store_dwordx4 v[82:83], v[90:93], off
	s_nop 1
	v_rcp_f32_e32 v82, v48
	v_mul_f32_e32 v48, 0xbfb8aa3b, v79
	v_exp_f32_e32 v48, v48
	v_pk_mul_f32 v[78:79], v[80:81], v[146:147] op_sel_hi:[1,0]
	v_pk_mul_f32 v[62:63], v[62:63], v[144:145] op_sel_hi:[1,0]
	v_pk_mul_f32 v[76:77], v[78:79], v[76:77]
	v_add_f32_e32 v48, 1.0, v48
	v_rcp_f32_e32 v83, v48
	v_mul_f32_e32 v48, 0xbfb8aa3b, v78
	v_exp_f32_e32 v48, v48
	v_pk_mul_f32 v[68:69], v[68:69], v[146:147] op_sel_hi:[1,0]
	v_pk_mul_f32 v[74:75], v[74:75], v[82:83]
	v_pk_mul_f32 v[58:59], v[58:59], v[144:145] op_sel_hi:[1,0]
	v_add_f32_e32 v48, 1.0, v48
	v_rcp_f32_e32 v80, v48
	v_mul_f32_e32 v48, 0xbfb8aa3b, v79
	v_exp_f32_e32 v48, v48
	v_cvt_pk_bf16_f32 v74, v74, v75
	v_pk_mul_f32 v[58:59], v[62:63], v[58:59]
	v_pk_mul_f32 v[54:55], v[54:55], v[144:145] op_sel_hi:[1,0]
	v_add_f32_e32 v48, 1.0, v48
	v_rcp_f32_e32 v81, v48
	v_mul_f32_e32 v48, 0xbfb8aa3b, v70
	v_exp_f32_e32 v48, v48
	v_pk_mul_f32 v[60:61], v[60:61], v[144:145] op_sel_hi:[1,0]
	v_pk_mul_f32 v[76:77], v[76:77], v[80:81]
	v_pk_mul_f32 v[50:51], v[50:51], v[144:145] op_sel_hi:[1,0]
	v_add_f32_e32 v48, 1.0, v48
	v_cvt_pk_bf16_f32 v75, v76, v77
	v_rcp_f32_e32 v76, v48
	v_mul_f32_e32 v48, 0xbfb8aa3b, v71
	v_exp_f32_e32 v48, v48
	v_pk_mul_f32 v[70:71], v[72:73], v[146:147] op_sel_hi:[1,0]
	v_pk_mul_f32 v[50:51], v[54:55], v[50:51]
	v_pk_mul_f32 v[68:69], v[70:71], v[68:69]
	v_add_f32_e32 v48, 1.0, v48
	v_rcp_f32_e32 v77, v48
	v_mul_f32_e32 v48, 0xbfb8aa3b, v70
	v_exp_f32_e32 v48, v48
	v_pk_mul_f32 v[44:45], v[44:45], v[142:143] op_sel_hi:[1,0]
	v_pk_mul_f32 v[66:67], v[66:67], v[76:77]
	v_pk_mul_f32 v[40:41], v[40:41], v[142:143] op_sel_hi:[1,0]
	v_add_f32_e32 v48, 1.0, v48
	v_rcp_f32_e32 v72, v48
	v_mul_f32_e32 v48, 0xbfb8aa3b, v71
	v_exp_f32_e32 v48, v48
	v_cvt_pk_bf16_f32 v76, v66, v67
	v_pk_mul_f32 v[40:41], v[44:45], v[40:41]
	v_pk_mul_f32 v[52:53], v[52:53], v[144:145] op_sel_hi:[1,0]
	v_add_f32_e32 v48, 1.0, v48
	v_rcp_f32_e32 v73, v48
	v_add_u32_e32 v48, 0x21000, v114
	v_lshl_add_u64 v[66:67], v[48:49], 1, s[12:13]
	v_mul_f32_e32 v48, 0xbfb8aa3b, v62
	v_exp_f32_e32 v48, v48
	v_pk_mul_f32 v[68:69], v[68:69], v[72:73]
	v_pk_mul_f32 v[42:43], v[42:43], v[142:143] op_sel_hi:[1,0]
	v_cvt_pk_bf16_f32 v77, v68, v69
	v_add_f32_e32 v48, 1.0, v48
	global_store_dwordx4 v[66:67], v[74:77], off
	s_nop 1
	v_rcp_f32_e32 v66, v48
	v_mul_f32_e32 v48, 0xbfb8aa3b, v63
	v_exp_f32_e32 v48, v48
	v_pk_mul_f32 v[62:63], v[64:65], v[144:145] op_sel_hi:[1,0]
	v_pk_mul_f32 v[36:37], v[36:37], v[142:143] op_sel_hi:[1,0]
	v_pk_mul_f32 v[60:61], v[62:63], v[60:61]
	v_add_f32_e32 v48, 1.0, v48
	v_rcp_f32_e32 v67, v48
	v_mul_f32_e32 v48, 0xbfb8aa3b, v62
	v_exp_f32_e32 v48, v48
	v_pk_mul_f32 v[32:33], v[32:33], v[142:143] op_sel_hi:[1,0]
	v_pk_mul_f32 v[58:59], v[58:59], v[66:67]
	v_pk_mul_f32 v[32:33], v[36:37], v[32:33]
	v_add_f32_e32 v48, 1.0, v48
	v_rcp_f32_e32 v64, v48
	v_mul_f32_e32 v48, 0xbfb8aa3b, v63
	v_exp_f32_e32 v48, v48
	v_cvt_pk_bf16_f32 v58, v58, v59
	v_pk_mul_f32 v[34:35], v[34:35], v[142:143] op_sel_hi:[1,0]
	v_pk_mul_f32 v[28:29], v[28:29], v[140:141] op_sel_hi:[1,0]
	v_add_f32_e32 v48, 1.0, v48
	v_rcp_f32_e32 v65, v48
	v_mul_f32_e32 v48, 0xbfb8aa3b, v54
	v_exp_f32_e32 v48, v48
	v_pk_mul_f32 v[24:25], v[24:25], v[140:141] op_sel_hi:[1,0]
	v_pk_mul_f32 v[60:61], v[60:61], v[64:65]
	v_pk_mul_f32 v[24:25], v[28:29], v[24:25]
	v_add_f32_e32 v48, 1.0, v48
	v_cvt_pk_bf16_f32 v59, v60, v61
	v_rcp_f32_e32 v60, v48
	v_mul_f32_e32 v48, 0xbfb8aa3b, v55
	v_exp_f32_e32 v48, v48
	v_pk_mul_f32 v[54:55], v[56:57], v[144:145] op_sel_hi:[1,0]
	v_pk_mul_f32 v[26:27], v[26:27], v[140:141] op_sel_hi:[1,0]
	v_pk_mul_f32 v[52:53], v[54:55], v[52:53]
	v_add_f32_e32 v48, 1.0, v48
	v_rcp_f32_e32 v61, v48
	v_mul_f32_e32 v48, 0xbfb8aa3b, v54
	v_exp_f32_e32 v48, v48
	v_pk_mul_f32 v[20:21], v[20:21], v[140:141] op_sel_hi:[1,0]
	v_pk_mul_f32 v[50:51], v[50:51], v[60:61]
	v_pk_mul_f32 v[16:17], v[16:17], v[140:141] op_sel_hi:[1,0]
	v_add_f32_e32 v48, 1.0, v48
	v_rcp_f32_e32 v56, v48
	v_mul_f32_e32 v48, 0xbfb8aa3b, v55
	v_exp_f32_e32 v48, v48
	v_cvt_pk_bf16_f32 v60, v50, v51
	v_pk_mul_f32 v[16:17], v[20:21], v[16:17]
	v_pk_mul_f32 v[18:19], v[18:19], v[140:141] op_sel_hi:[1,0]
	v_add_f32_e32 v48, 1.0, v48
	v_rcp_f32_e32 v57, v48
	v_add_u32_e32 v48, 0x58000, v114
	v_lshl_add_u64 v[50:51], v[48:49], 1, s[12:13]
	v_mul_f32_e32 v48, 0xbfb8aa3b, v44
	v_mul_f32_e32 v44, 0xbfb8aa3b, v45
	v_exp_f32_e32 v44, v44
	v_pk_mul_f32 v[52:53], v[52:53], v[56:57]
	v_exp_f32_e32 v48, v48
	v_cvt_pk_bf16_f32 v61, v52, v53
	v_add_f32_e32 v44, 1.0, v44
	global_store_dwordx4 v[50:51], v[58:61], off
	s_nop 1
	v_rcp_f32_e32 v51, v44
	v_pk_mul_f32 v[44:45], v[46:47], v[142:143] op_sel_hi:[1,0]
	v_add_f32_e32 v48, 1.0, v48
	v_mul_f32_e32 v46, 0xbfb8aa3b, v44
	v_pk_mul_f32 v[42:43], v[44:45], v[42:43]
	v_mul_f32_e32 v44, 0xbfb8aa3b, v45
	v_exp_f32_e32 v46, v46
	v_exp_f32_e32 v44, v44
	v_rcp_f32_e32 v50, v48
	v_add_u32_e32 v48, 0x63000, v114
	v_add_f32_e32 v46, 1.0, v46
	v_add_f32_e32 v44, 1.0, v44
	v_rcp_f32_e32 v46, v46
	v_rcp_f32_e32 v47, v44
	v_pk_mul_f32 v[40:41], v[40:41], v[50:51]
	v_pk_mul_f32 v[12:13], v[12:13], v[138:139] op_sel_hi:[1,0]
	v_cvt_pk_bf16_f32 v40, v40, v41
	v_pk_mul_f32 v[42:43], v[42:43], v[46:47]
	v_pk_mul_f32 v[8:9], v[8:9], v[138:139] op_sel_hi:[1,0]
	v_cvt_pk_bf16_f32 v41, v42, v43
	v_mul_f32_e32 v42, 0xbfb8aa3b, v36
	v_mul_f32_e32 v36, 0xbfb8aa3b, v37
	v_exp_f32_e32 v36, v36
	v_exp_f32_e32 v42, v42
	v_pk_mul_f32 v[8:9], v[12:13], v[8:9]
	v_pk_mul_f32 v[10:11], v[10:11], v[138:139] op_sel_hi:[1,0]
	v_add_f32_e32 v36, 1.0, v36
	v_rcp_f32_e32 v43, v36
	v_pk_mul_f32 v[36:37], v[38:39], v[142:143] op_sel_hi:[1,0]
	v_add_f32_e32 v42, 1.0, v42
	v_mul_f32_e32 v38, 0xbfb8aa3b, v36
	v_pk_mul_f32 v[34:35], v[36:37], v[34:35]
	v_mul_f32_e32 v36, 0xbfb8aa3b, v37
	v_exp_f32_e32 v38, v38
	v_exp_f32_e32 v36, v36
	v_rcp_f32_e32 v42, v42
	v_pk_mul_f32 v[4:5], v[4:5], v[138:139] op_sel_hi:[1,0]
	v_add_f32_e32 v38, 1.0, v38
	v_add_f32_e32 v36, 1.0, v36
	v_rcp_f32_e32 v38, v38
	v_rcp_f32_e32 v39, v36
	v_pk_mul_f32 v[32:33], v[32:33], v[42:43]
	v_pk_mul_f32 v[0:1], v[0:1], v[138:139] op_sel_hi:[1,0]
	v_cvt_pk_bf16_f32 v42, v32, v33
	v_pk_mul_f32 v[34:35], v[34:35], v[38:39]
	v_lshl_add_u64 v[32:33], v[48:49], 1, s[12:13]
	v_cvt_pk_bf16_f32 v43, v34, v35
	global_store_dwordx4 v[32:33], v[40:43], off
	s_nop 1
	v_mul_f32_e32 v32, 0xbfb8aa3b, v28
	v_mul_f32_e32 v28, 0xbfb8aa3b, v29
	v_exp_f32_e32 v28, v28
	v_exp_f32_e32 v32, v32
	v_add_u32_e32 v48, 0x6e000, v114
	v_pk_mul_f32 v[0:1], v[4:5], v[0:1]
	v_add_f32_e32 v28, 1.0, v28
	v_rcp_f32_e32 v33, v28
	v_pk_mul_f32 v[28:29], v[30:31], v[140:141] op_sel_hi:[1,0]
	v_add_f32_e32 v32, 1.0, v32
	v_mul_f32_e32 v30, 0xbfb8aa3b, v28
	v_pk_mul_f32 v[26:27], v[28:29], v[26:27]
	v_mul_f32_e32 v28, 0xbfb8aa3b, v29
	v_exp_f32_e32 v30, v30
	v_exp_f32_e32 v28, v28
	v_rcp_f32_e32 v32, v32
	v_pk_mul_f32 v[2:3], v[2:3], v[138:139] op_sel_hi:[1,0]
	v_add_f32_e32 v30, 1.0, v30
	v_add_f32_e32 v28, 1.0, v28
	v_rcp_f32_e32 v30, v30
	v_rcp_f32_e32 v31, v28
	v_pk_mul_f32 v[24:25], v[24:25], v[32:33]
	s_mov_b64 s[38:39], -1
	v_cvt_pk_bf16_f32 v24, v24, v25
	v_pk_mul_f32 v[26:27], v[26:27], v[30:31]
	s_andn2_b64 vcc, exec, s[46:47]
	v_cvt_pk_bf16_f32 v25, v26, v27
	v_mul_f32_e32 v26, 0xbfb8aa3b, v20
	v_mul_f32_e32 v20, 0xbfb8aa3b, v21
	v_exp_f32_e32 v20, v20
	v_exp_f32_e32 v26, v26
	v_add_f32_e32 v20, 1.0, v20
	v_rcp_f32_e32 v27, v20
	v_pk_mul_f32 v[20:21], v[22:23], v[140:141] op_sel_hi:[1,0]
	v_add_f32_e32 v26, 1.0, v26
	v_mul_f32_e32 v22, 0xbfb8aa3b, v20
	v_pk_mul_f32 v[18:19], v[20:21], v[18:19]
	v_mul_f32_e32 v20, 0xbfb8aa3b, v21
	v_exp_f32_e32 v22, v22
	v_exp_f32_e32 v20, v20
	v_rcp_f32_e32 v26, v26
	v_add_f32_e32 v22, 1.0, v22
	v_add_f32_e32 v20, 1.0, v20
	v_rcp_f32_e32 v22, v22
	v_rcp_f32_e32 v23, v20
	v_pk_mul_f32 v[16:17], v[16:17], v[26:27]
	v_pk_mul_f32 v[18:19], v[18:19], v[22:23]
	v_cvt_pk_bf16_f32 v26, v16, v17
	v_lshl_add_u64 v[16:17], v[48:49], 1, s[12:13]
	v_cvt_pk_bf16_f32 v27, v18, v19
	global_store_dwordx4 v[16:17], v[24:27], off
	s_nop 1
	v_mul_f32_e32 v16, 0xbfb8aa3b, v12
	v_mul_f32_e32 v12, 0xbfb8aa3b, v13
	v_exp_f32_e32 v12, v12
	v_exp_f32_e32 v16, v16
	v_add_u32_e32 v48, 0x79000, v114
	v_add_f32_e32 v12, 1.0, v12
	v_rcp_f32_e32 v17, v12
	v_pk_mul_f32 v[12:13], v[14:15], v[138:139] op_sel_hi:[1,0]
	v_add_f32_e32 v16, 1.0, v16
	v_mul_f32_e32 v14, 0xbfb8aa3b, v12
	v_pk_mul_f32 v[10:11], v[12:13], v[10:11]
	v_mul_f32_e32 v12, 0xbfb8aa3b, v13
	v_exp_f32_e32 v14, v14
	v_exp_f32_e32 v12, v12
	v_rcp_f32_e32 v16, v16
	v_add_f32_e32 v14, 1.0, v14
	v_add_f32_e32 v12, 1.0, v12
	v_rcp_f32_e32 v14, v14
	v_rcp_f32_e32 v15, v12
	v_pk_mul_f32 v[8:9], v[8:9], v[16:17]
	v_pk_mul_f32 v[10:11], v[10:11], v[14:15]
	v_cvt_pk_bf16_f32 v8, v8, v9
	v_cvt_pk_bf16_f32 v9, v10, v11
	v_mul_f32_e32 v10, 0xbfb8aa3b, v4
	v_mul_f32_e32 v4, 0xbfb8aa3b, v5
	v_exp_f32_e32 v4, v4
	v_exp_f32_e32 v10, v10
	v_add_f32_e32 v4, 1.0, v4
	v_rcp_f32_e32 v11, v4
	v_pk_mul_f32 v[4:5], v[6:7], v[138:139] op_sel_hi:[1,0]
	v_add_f32_e32 v10, 1.0, v10
	v_mul_f32_e32 v6, 0xbfb8aa3b, v4
	v_pk_mul_f32 v[2:3], v[4:5], v[2:3]
	v_mul_f32_e32 v4, 0xbfb8aa3b, v5
	v_exp_f32_e32 v6, v6
	v_exp_f32_e32 v4, v4
	v_rcp_f32_e32 v10, v10
	v_add_f32_e32 v6, 1.0, v6
	v_add_f32_e32 v4, 1.0, v4
	v_rcp_f32_e32 v6, v6
	v_rcp_f32_e32 v7, v4
	v_pk_mul_f32 v[0:1], v[0:1], v[10:11]
	v_pk_mul_f32 v[2:3], v[2:3], v[6:7]
	v_cvt_pk_bf16_f32 v10, v0, v1
	v_cvt_pk_bf16_f32 v11, v2, v3
	v_lshl_add_u64 v[0:1], v[48:49], 1, s[12:13]
	global_store_dwordx4 v[0:1], v[8:11], off
	s_nop 1
	s_cbranch_vccnz .LBB0_1407
	s_andn2_b64 vcc, exec, s[2:3]
	s_cbranch_vccnz .LBB0_1406
	s_barrier
	s_branch .LBB0_1406

.LBB0_1981:
	v_lshl_add_u32 v122, s33, 8, v182
	s_lshl_b32 s6, s18, 8
	v_lshl_add_u32 v48, v122, 10, s6
	v_or_b32_e32 v48, v48, v184
	v_lshl_add_u64 v[194:195], v[48:49], 1, s[16:17]
	global_load_dwordx4 v[186:189], v[194:195], off
	s_lshl_b32 s6, s18, 16
	s_or_b32 s6, s6, s62
	v_add_u32_e32 v168, s6, v122
	v_or_b32_e32 v122, 0x80, v48
	v_mov_b32_e32 v123, v49
	v_lshl_add_u64 v[196:197], v[122:123], 1, s[16:17]
	global_load_dwordx4 v[190:193], v[196:197], off
	v_add_u32_e32 v122, 0x4000, v48
	v_lshl_add_u64 v[180:181], v[122:123], 1, s[16:17]
	v_add_u32_e32 v122, 0x4080, v48
	v_lshl_add_u64 v[178:179], v[122:123], 1, s[16:17]
	v_add_u32_e32 v122, 0x8000, v48
	v_lshl_add_u64 v[176:177], v[122:123], 1, s[16:17]
	v_add_u32_e32 v122, 0x8080, v48
	v_lshl_add_u64 v[174:175], v[122:123], 1, s[16:17]
	v_add_u32_e32 v122, 0xc000, v48
	v_add_u32_e32 v130, 0xc080, v48
	v_mov_b32_e32 v131, v49
	v_lshl_add_u64 v[172:173], v[122:123], 1, s[16:17]
	v_lshl_add_u64 v[170:171], v[130:131], 1, s[16:17]
	global_load_dwordx4 v[150:153], v[180:181], off
	global_load_dwordx4 v[146:149], v[178:179], off
	global_load_dwordx4 v[142:145], v[176:177], off
	global_load_dwordx4 v[138:141], v[174:175], off
	global_load_dwordx4 v[122:125], v[172:173], off
	global_load_dwordx4 v[130:133], v[170:171], off
	s_waitcnt vmcnt(0)
	v_lshlrev_b32_e32 v198, 16, v186
	v_and_b32_e32 v199, 0xffff0000, v186
	v_lshlrev_b32_e32 v186, 16, v187
	v_and_b32_e32 v187, 0xffff0000, v187
	v_pk_fma_f32 v[136:137], v[136:137], 0.5, v[186:187] op_sel_hi:[1,0,1]
	v_pk_fma_f32 v[134:135], v[134:135], 0.5, v[198:199] op_sel_hi:[1,0,1]
	v_lshlrev_b32_e32 v186, 16, v188
	v_and_b32_e32 v187, 0xffff0000, v188
	v_lshlrev_b32_e32 v188, 16, v189
	v_and_b32_e32 v189, 0xffff0000, v189
	v_pk_fma_f32 v[188:189], v[128:129], 0.5, v[188:189] op_sel_hi:[1,0,1]
	v_pk_fma_f32 v[186:187], v[126:127], 0.5, v[186:187] op_sel_hi:[1,0,1]
	v_cvt_pk_bf16_f32 v126, v134, v135
	v_cvt_pk_bf16_f32 v127, v136, v137
	v_cvt_pk_bf16_f32 v128, v186, v187
	v_cvt_pk_bf16_f32 v129, v188, v189
	global_store_dwordx4 v[194:195], v[126:129], off
	s_nop 1
	v_mul_f32_e32 v126, v135, v135
	v_mul_f32_e32 v127, v137, v137
	v_fmac_f32_e32 v126, v134, v134
	v_fmac_f32_e32 v127, v136, v136
	v_add_f32_e32 v126, v126, v127
	v_mul_f32_e32 v127, v187, v187
	v_mul_f32_e32 v128, v189, v189
	v_fmac_f32_e32 v127, v186, v186
	v_fmac_f32_e32 v128, v188, v188
	v_add_f32_e32 v127, v127, v128
	v_add_f32_e32 v134, v126, v127
	v_lshlrev_b32_e32 v126, 16, v190
	v_and_b32_e32 v127, 0xffff0000, v190
	v_lshlrev_b32_e32 v128, 16, v191
	v_and_b32_e32 v129, 0xffff0000, v191
	v_pk_fma_f32 v[120:121], v[120:121], 0.5, v[128:129] op_sel_hi:[1,0,1]
	v_pk_fma_f32 v[118:119], v[118:119], 0.5, v[126:127] op_sel_hi:[1,0,1]
	v_lshlrev_b32_e32 v126, 16, v192
	v_and_b32_e32 v127, 0xffff0000, v192
	v_lshlrev_b32_e32 v128, 16, v193
	v_and_b32_e32 v129, 0xffff0000, v193
	v_pk_fma_f32 v[128:129], v[116:117], 0.5, v[128:129] op_sel_hi:[1,0,1]
	v_pk_fma_f32 v[126:127], v[114:115], 0.5, v[126:127] op_sel_hi:[1,0,1]
	v_cvt_pk_bf16_f32 v114, v118, v119
	v_cvt_pk_bf16_f32 v115, v120, v121
	v_cvt_pk_bf16_f32 v116, v126, v127
	v_cvt_pk_bf16_f32 v117, v128, v129
	global_store_dwordx4 v[196:197], v[114:117], off
	s_nop 1
	v_mul_f32_e32 v114, v119, v119
	v_mul_f32_e32 v115, v121, v121
	v_fmac_f32_e32 v114, v118, v118
	v_fmac_f32_e32 v115, v120, v120
	v_add_f32_e32 v114, v114, v115
	v_mul_f32_e32 v115, v127, v127
	v_mul_f32_e32 v116, v129, v129
	v_fmac_f32_e32 v115, v126, v126
	v_fmac_f32_e32 v116, v128, v128
	v_add_f32_e32 v115, v115, v116
	v_add_f32_e32 v114, v114, v115
	v_and_b32_e32 v116, 64, v205
	v_add_f32_e32 v115, v134, v114
	v_xor_b32_e32 v114, 16, v205
	v_add_u32_e32 v116, 64, v116
	v_cmp_lt_i32_e32 vcc, v114, v116
	s_nop 1
	v_cndmask_b32_e32 v114, v205, v114, vcc
	v_lshlrev_b32_e32 v114, 2, v114
	s_waitcnt lgkmcnt(0)
	v_mov_b32_e32 v116, v115
	s_nop 1
	v_permlane16_swap_b32_e32 v115, v116
	v_add_f32_e32 v115, v115, v116
	v_mov_b32_e32 v116, v115
	s_nop 1
	v_permlane32_swap_b32_e32 v115, v116
	s_and_saveexec_b64 s[48:49], s[38:39]
	s_cbranch_execz .LBB0_1983
	v_mov_b32_e32 v169, v49
	v_lshl_add_u64 v[118:119], v[168:169], 2, s[22:23]
	v_add_f32_e32 v115, v115, v116
	global_store_dword v[118:119], v115, off

.LBB0_2056:
	global_load_dwordx2 v[12:13], v[4:5], off offset:-1024
	global_load_dwordx2 v[14:15], v[4:5], off offset:-512
	global_load_dwordx2 v[16:17], v[4:5], off
	global_load_dwordx2 v[18:19], v[4:5], off offset:512
	global_load_dwordx4 v[8:11], v[0:1], off
	s_add_i32 s2, s2, s70
	v_lshl_add_u64 v[4:5], v[4:5], 0, s[4:5]
	s_cmpk_lt_i32 s2, 0x4000
	s_waitcnt vmcnt(4)
	v_lshlrev_b32_e32 v20, 16, v12
	v_and_b32_e32 v21, 0xffff0000, v12
	v_lshlrev_b32_e32 v12, 16, v13
	v_and_b32_e32 v13, 0xffff0000, v13
	s_waitcnt vmcnt(3)
	v_lshlrev_b32_e32 v22, 16, v14
	v_and_b32_e32 v23, 0xffff0000, v14
	v_lshlrev_b32_e32 v14, 16, v15
	v_and_b32_e32 v15, 0xffff0000, v15
	s_waitcnt vmcnt(2)
	v_lshlrev_b32_e32 v24, 16, v16
	v_and_b32_e32 v25, 0xffff0000, v16
	v_lshlrev_b32_e32 v16, 16, v17
	v_and_b32_e32 v17, 0xffff0000, v17
	v_mul_f32_e32 v28, v21, v21
	v_mul_f32_e32 v29, v13, v13
	v_mul_f32_e32 v30, v23, v23
	v_mul_f32_e32 v31, v15, v15
	s_waitcnt vmcnt(1)
	v_lshlrev_b32_e32 v26, 16, v18
	v_and_b32_e32 v27, 0xffff0000, v18
	v_lshlrev_b32_e32 v18, 16, v19
	v_and_b32_e32 v19, 0xffff0000, v19
	v_mul_f32_e32 v32, v25, v25
	v_mul_f32_e32 v33, v17, v17
	v_fmac_f32_e32 v28, v20, v20
	v_fmac_f32_e32 v29, v12, v12
	v_fmac_f32_e32 v30, v22, v22
	v_fmac_f32_e32 v31, v14, v14
	v_mul_f32_e32 v34, v27, v27
	v_mul_f32_e32 v35, v19, v19
	v_fmac_f32_e32 v32, v24, v24
	v_fmac_f32_e32 v33, v16, v16
	v_add_f32_e32 v28, v28, v29
	v_add_f32_e32 v29, v30, v31
	v_fmac_f32_e32 v34, v26, v26
	v_fmac_f32_e32 v35, v18, v18
	v_add_f32_e32 v30, v32, v33
	v_add_f32_e32 v28, v28, v29
	v_add_f32_e32 v31, v34, v35
	v_add_f32_e32 v28, v28, v30
	v_add_f32_e32 v28, v28, v31
	s_nop 1
	v_add_f32_dpp v28, v28, v28 row_mirror row_mask:0xf bank_mask:0xf bound_ctrl:1
	s_nop 1
	v_add_f32_dpp v28, v28, v28 row_half_mirror row_mask:0xf bank_mask:0xf bound_ctrl:1
	s_nop 1
	v_add_f32_dpp v28, v28, v28 quad_perm:[1,0,3,2] row_mask:0xf bank_mask:0xf bound_ctrl:1
	s_nop 1
	v_add_f32_dpp v28, v28, v28 quad_perm:[2,3,0,1] row_mask:0xf bank_mask:0xf bound_ctrl:1
	s_waitcnt lgkmcnt(0)
	v_mov_b32_e32 v29, v28
	s_nop 1
	v_permlane16_swap_b32_e32 v28, v29
	v_add_f32_e32 v28, v28, v29
	v_mov_b32_e32 v29, v28
	s_nop 1
	v_permlane32_swap_b32_e32 v28, v29
	v_add_f32_e32 v28, v28, v29
	v_fmamk_f32 v28, v28, 0x3a800000, v7
	v_mul_f32_e32 v29, 0x4b800000, v28
	v_cmp_gt_f32_e32 vcc, s3, v28
	s_nop 1
	v_cndmask_b32_e32 v28, v28, v29, vcc
	v_rsq_f32_e32 v28, v28
	s_nop 0
	v_mul_f32_e32 v29, 0x45800000, v28
	v_cndmask_b32_e32 v28, v28, v29, vcc
	v_pk_mul_f32 v[20:21], v[20:21], v[28:29] op_sel_hi:[1,0]
	v_pk_mul_f32 v[12:13], v[12:13], v[28:29] op_sel_hi:[1,0]
	s_waitcnt vmcnt(0)
	v_pk_mul_f32 v[8:9], v[8:9], v[20:21]
	v_pk_mul_f32 v[10:11], v[10:11], v[12:13]
	global_store_dwordx4 v[2:3], v[8:11], off offset:-2048
	global_load_dwordx4 v[8:11], v[0:1], off offset:1024
	v_pk_mul_f32 v[12:13], v[14:15], v[28:29] op_sel_hi:[1,0]
	v_pk_mul_f32 v[14:15], v[22:23], v[28:29] op_sel_hi:[1,0]
	s_waitcnt vmcnt(0)
	v_pk_mul_f32 v[10:11], v[10:11], v[12:13]
	v_pk_mul_f32 v[8:9], v[8:9], v[14:15]
	global_store_dwordx4 v[2:3], v[8:11], off offset:-1024
	global_load_dwordx4 v[8:11], v[0:1], off offset:2048
	v_pk_mul_f32 v[12:13], v[16:17], v[28:29] op_sel_hi:[1,0]
	v_pk_mul_f32 v[14:15], v[24:25], v[28:29] op_sel_hi:[1,0]
	s_waitcnt vmcnt(0)
	v_pk_mul_f32 v[10:11], v[10:11], v[12:13]
	v_pk_mul_f32 v[8:9], v[8:9], v[14:15]
	global_store_dwordx4 v[2:3], v[8:11], off
	global_load_dwordx4 v[8:11], v[0:1], off offset:3072
	v_pk_mul_f32 v[12:13], v[18:19], v[28:29] op_sel_hi:[1,0]
	v_pk_mul_f32 v[14:15], v[26:27], v[28:29] op_sel_hi:[1,0]
	s_waitcnt vmcnt(0)
	v_pk_mul_f32 v[10:11], v[10:11], v[12:13]
	v_pk_mul_f32 v[8:9], v[8:9], v[14:15]
	global_store_dwordx4 v[2:3], v[8:11], off offset:1024
	v_lshl_add_u64 v[2:3], v[2:3], 0, s[0:1]
	s_cbranch_scc1 .LBB0_2056
